# GEMM K-loops: M0 hazard slot filled with an LDS read instead of s_nop
# speedup vs baseline: 1.0097x; 1.0011x over previous
; #define PG8_STAGE(bufoff, gbase, voff) do { _Pragma("unroll") for (int _i = 0; _i < 2; ++_i) \
;         __builtin_amdgcn_global_load_lds((const unsigned*)((const char*)(gbase) + (voff)[_i]), (PG8_LAS unsigned*)(lds + (bufoff) + ldsw + _i * 8192), 16, 0, 0); } while (0)
; #define PG8_LDA(dst, b, h) do { _Pragma("unroll") for (int m = 0; m < 4; ++m) _Pragma("unroll") for (int k = 0; k < 2; ++k) dst[m][k] = *(const PG8_LAS bf16x8*)(lds + PG8_SA(b, h) + aoff + m * 2048 + k * 1024); } while (0)
; #define PG8_LDB(dst, b, h) do { _Pragma("unroll") for (int n = 0; n < 2; ++n) _Pragma("unroll") for (int k = 0; k < 2; ++k) dst[n][k] = *(const PG8_LAS bf16x8*)(lds + PG8_SB(b, h) + boff + n * 2048 + k * 1024); } while (0)
; #define PG8_MMA(ai, bj, At, Bt) do { __builtin_amdgcn_s_setprio(1); _Pragma("unroll") for (int m = 0; m < 4; ++m) _Pragma("unroll") for (int n = 0; n < 2; ++n) _Pragma("unroll") for (int k = 0; k < 2; ++k) \
;         acc[ai][bj][m][n] = __builtin_amdgcn_mfma_f32_16x16x32_bf16(Bt[n][k], At[m][k], acc[ai][bj][m][n], 0, 0, 0); __builtin_amdgcn_s_setprio(0); } while (0)
; #define PG8_WAIT_V(n) asm volatile("s_waitcnt vmcnt(" #n ")" ::: "memory")
; #define PG8_WAIT_L(n) asm volatile("s_waitcnt lgkmcnt(" #n ")" ::: "memory")
; #define PG8_BAR __builtin_amdgcn_s_barrier()
; #define PG8_SCHED __builtin_amdgcn_sched_barrier(0)
; template <class Epi, class Sched, bool STAMP = false>
; __device__ __forceinline__ void gemm_phase(PG8_LAS unsigned char* lds, const Gemm g, const Sched& S, const Epi& E, unsigned long long* stamps) {
;     ...
;             PG8_LDB(B0, 0, 0); PG8_SCHED; PG8_LDA(At, 0, 0); PG8_STAGE(PG8_SA(1, 1), a1 + hstep, voffA);
;             PG8_WAIT_L(8); PG8_BAR; PG8_WAIT_L(0); PG8_MMA(0, 0, At, B0); PG8_BAR; PG8_SCHED;
;             PG8_LDB(B1, 0, 1); PG8_STAGE(PG8_SB(0, 0), b2, voffB);
;             PG8_BAR; PG8_WAIT_L(0); PG8_MMA(0, 1, At, B1); PG8_BAR;
;             PG8_LDA(At, 0, 1); PG8_STAGE(PG8_SA(0, 0), a2, voffA);
;             PG8_BAR; PG8_WAIT_L(0); PG8_MMA(1, 0, At, B0); PG8_BAR; PG8_SCHED;
;             PG8_STAGE(PG8_SB(0, 1), b2 + hstep, voffB);
;             PG8_WAIT_V(6); PG8_BAR; PG8_MMA(1, 1, At, B1); PG8_BAR;
.LBB0_44:
	s_add_u32 s14, s24, 0xfffc0080
	s_addc_u32 s15, s25, -1
	s_add_i32 s16, 0, 0x10000
	ds_read_b128 v[158:161], v248
	ds_read_b128 v[162:165], v248 offset:1024
	ds_read_b128 v[170:173], v248 offset:2048
	ds_read_b128 v[174:177], v248 offset:3072
	s_cmp_eq_u32 s61, 12
	s_cselect_b32 s31, s7, s15
	s_cselect_b32 s30, s57, s14
	s_cselect_b32 s27, s5, s60
	s_cselect_b32 s26, s58, s59
	s_add_i32 m0, s23, 0xc000
	ds_read_b128 v[178:181], v168
	ds_read_b128 v[192:195], v168 offset:1024
	ds_read_b128 v[196:199], v168 offset:2048
	ds_read_b128 v[200:203], v168 offset:3072
	ds_read_b128 v[204:207], v168 offset:4096
	ds_read_b128 v[208:211], v168 offset:5120
	ds_read_b128 v[212:215], v168 offset:6144
	global_load_lds_dwordx4 v154, s[24:25]
	s_add_i32 m0, s23, 0xe000
	ds_read_b128 v[216:219], v168 offset:7168
	global_load_lds_dwordx4 v156, s[24:25]
	s_waitcnt lgkmcnt(8)
	s_barrier
	s_waitcnt lgkmcnt(0)
	v_mfma_f32_16x16x32_bf16 v[124:127], v[158:161], v[178:181], v[124:127]
	v_mfma_f32_16x16x32_bf16 v[120:123], v[170:173], v[178:181], v[120:123]
	v_mfma_f32_16x16x32_bf16 v[108:111], v[158:161], v[196:199], v[108:111]
	v_mfma_f32_16x16x32_bf16 v[104:107], v[170:173], v[196:199], v[104:107]
	v_mfma_f32_16x16x32_bf16 v[92:95], v[158:161], v[204:207], v[92:95]
	v_mfma_f32_16x16x32_bf16 v[88:91], v[170:173], v[204:207], v[88:91]
	v_mfma_f32_16x16x32_bf16 v[76:79], v[158:161], v[212:215], v[76:79]
	v_mfma_f32_16x16x32_bf16 v[72:75], v[170:173], v[212:215], v[72:75]
	v_mfma_f32_16x16x32_bf16 v[124:127], v[162:165], v[192:195], v[124:127]
	v_mfma_f32_16x16x32_bf16 v[120:123], v[174:177], v[192:195], v[120:123]
	v_mfma_f32_16x16x32_bf16 v[108:111], v[162:165], v[200:203], v[108:111]
	v_mfma_f32_16x16x32_bf16 v[104:107], v[174:177], v[200:203], v[104:107]
	v_mfma_f32_16x16x32_bf16 v[92:95], v[162:165], v[208:211], v[92:95]
	v_mfma_f32_16x16x32_bf16 v[88:91], v[174:177], v[208:211], v[88:91]
	v_mfma_f32_16x16x32_bf16 v[76:79], v[162:165], v[216:219], v[76:79]
	v_mfma_f32_16x16x32_bf16 v[72:75], v[174:177], v[216:219], v[72:75]
	s_barrier
	s_add_i32 s17, 0, 0x14000
	s_add_i32 s14, s16, s43
	s_mov_b32 m0, s14
	ds_read_b128 v[220:223], v249
	ds_read_b128 v[224:227], v249 offset:1024
	ds_read_b128 v[228:231], v249 offset:2048
	global_load_lds_dwordx4 v128, s[26:27]
	s_add_i32 m0, s14, 0x2000
	ds_read_b128 v[232:235], v249 offset:3072
	global_load_lds_dwordx4 v148, s[26:27]
	s_barrier
	s_waitcnt lgkmcnt(0)
	v_mfma_f32_16x16x32_bf16 v[116:119], v[220:223], v[178:181], v[116:119]
	v_mfma_f32_16x16x32_bf16 v[112:115], v[228:231], v[178:181], v[112:115]
	v_mfma_f32_16x16x32_bf16 v[100:103], v[220:223], v[196:199], v[100:103]
	v_mfma_f32_16x16x32_bf16 v[96:99], v[228:231], v[196:199], v[96:99]
	v_mfma_f32_16x16x32_bf16 v[84:87], v[220:223], v[204:207], v[84:87]
	v_mfma_f32_16x16x32_bf16 v[80:83], v[228:231], v[204:207], v[80:83]
	v_mfma_f32_16x16x32_bf16 v[68:71], v[220:223], v[212:215], v[68:71]
	v_mfma_f32_16x16x32_bf16 v[64:67], v[228:231], v[212:215], v[64:67]
	v_mfma_f32_16x16x32_bf16 v[116:119], v[224:227], v[192:195], v[116:119]
	v_mfma_f32_16x16x32_bf16 v[112:115], v[232:235], v[192:195], v[112:115]
	v_mfma_f32_16x16x32_bf16 v[100:103], v[224:227], v[200:203], v[100:103]
	v_mfma_f32_16x16x32_bf16 v[96:99], v[232:235], v[200:203], v[96:99]
	v_mfma_f32_16x16x32_bf16 v[84:87], v[224:227], v[208:211], v[84:87]
	v_mfma_f32_16x16x32_bf16 v[80:83], v[232:235], v[208:211], v[80:83]
	v_mfma_f32_16x16x32_bf16 v[68:71], v[224:227], v[216:219], v[68:71]
	v_mfma_f32_16x16x32_bf16 v[64:67], v[232:235], v[216:219], v[64:67]
	s_mov_b32 m0, s23
	s_barrier
	ds_read_b128 v[178:181], v168 offset:16384
	ds_read_b128 v[192:195], v168 offset:17408
	ds_read_b128 v[196:199], v168 offset:18432
	ds_read_b128 v[200:203], v168 offset:19456
	ds_read_b128 v[204:207], v168 offset:20480
	ds_read_b128 v[208:211], v168 offset:21504
	ds_read_b128 v[212:215], v168 offset:22528
	global_load_lds_dwordx4 v152, s[30:31]
	s_mov_b32 m0, s45
	ds_read_b128 v[216:219], v168 offset:23552
	global_load_lds_dwordx4 v150, s[30:31]
	s_barrier
	s_waitcnt lgkmcnt(0)
	v_mfma_f32_16x16x32_bf16 v[60:63], v[158:161], v[178:181], v[60:63]
	v_mfma_f32_16x16x32_bf16 v[56:59], v[170:173], v[178:181], v[56:59]
	v_mfma_f32_16x16x32_bf16 v[44:47], v[158:161], v[196:199], v[44:47]
	v_mfma_f32_16x16x32_bf16 v[40:43], v[170:173], v[196:199], v[40:43]
	v_mfma_f32_16x16x32_bf16 v[28:31], v[158:161], v[204:207], v[28:31]
	v_mfma_f32_16x16x32_bf16 v[24:27], v[170:173], v[204:207], v[24:27]
	v_mfma_f32_16x16x32_bf16 v[12:15], v[158:161], v[212:215], v[12:15]
	v_mfma_f32_16x16x32_bf16 v[8:11], v[170:173], v[212:215], v[8:11]
	v_mfma_f32_16x16x32_bf16 v[60:63], v[162:165], v[192:195], v[60:63]
	v_mfma_f32_16x16x32_bf16 v[56:59], v[174:177], v[192:195], v[56:59]
	v_mfma_f32_16x16x32_bf16 v[44:47], v[162:165], v[200:203], v[44:47]
	v_mfma_f32_16x16x32_bf16 v[40:43], v[174:177], v[200:203], v[40:43]
	v_mfma_f32_16x16x32_bf16 v[28:31], v[162:165], v[208:211], v[28:31]
	v_mfma_f32_16x16x32_bf16 v[24:27], v[174:177], v[208:211], v[24:27]
	v_mfma_f32_16x16x32_bf16 v[12:15], v[162:165], v[216:219], v[12:15]
	v_mfma_f32_16x16x32_bf16 v[8:11], v[174:177], v[216:219], v[8:11]
	s_barrier
	s_add_u32 s14, s26, 0x40000
	s_addc_u32 s15, s27, 0
	s_add_i32 s16, s17, s43
	s_mov_b32 m0, s16
	s_nop 0
	global_load_lds_dwordx4 v128, s[14:15]
	s_add_i32 m0, s16, 0x2000
	s_nop 0
	global_load_lds_dwordx4 v148, s[14:15]
	s_waitcnt vmcnt(6)
	s_barrier
; #define PG8_STAGE(bufoff, gbase, voff) do { _Pragma("unroll") for (int _i = 0; _i < 2; ++_i) \
;         __builtin_amdgcn_global_load_lds((const unsigned*)((const char*)(gbase) + (voff)[_i]), (PG8_LAS unsigned*)(lds + (bufoff) + ldsw + _i * 8192), 16, 0, 0); } while (0)
; #define PG8_LDA(dst, b, h) do { _Pragma("unroll") for (int m = 0; m < 4; ++m) _Pragma("unroll") for (int k = 0; k < 2; ++k) dst[m][k] = *(const PG8_LAS bf16x8*)(lds + PG8_SA(b, h) + aoff + m * 2048 + k * 1024); } while (0)
; #define PG8_LDB(dst, b, h) do { _Pragma("unroll") for (int n = 0; n < 2; ++n) _Pragma("unroll") for (int k = 0; k < 2; ++k) dst[n][k] = *(const PG8_LAS bf16x8*)(lds + PG8_SB(b, h) + boff + n * 2048 + k * 1024); } while (0)
; #define PG8_MMA(ai, bj, At, Bt) do { __builtin_amdgcn_s_setprio(1); _Pragma("unroll") for (int m = 0; m < 4; ++m) _Pragma("unroll") for (int n = 0; n < 2; ++n) _Pragma("unroll") for (int k = 0; k < 2; ++k) \
;         acc[ai][bj][m][n] = __builtin_amdgcn_mfma_f32_16x16x32_bf16(Bt[n][k], At[m][k], acc[ai][bj][m][n], 0, 0, 0); __builtin_amdgcn_s_setprio(0); } while (0)
; #define PG8_WAIT_V(n) asm volatile("s_waitcnt vmcnt(" #n ")" ::: "memory")
; #define PG8_WAIT_L(n) asm volatile("s_waitcnt lgkmcnt(" #n ")" ::: "memory")
; #define PG8_BAR __builtin_amdgcn_s_barrier()
; #define PG8_SCHED __builtin_amdgcn_sched_barrier(0)
; template <class Epi, class Sched, bool STAMP = false>
; __device__ __forceinline__ void gemm_phase(PG8_LAS unsigned char* lds, const Gemm g, const Sched& S, const Epi& E, unsigned long long* stamps) {
;     ...
;             PG8_WAIT_V(6); PG8_BAR; PG8_MMA(1, 1, At, B1); PG8_BAR;
;             PG8_LDB(B0, 1, 0); PG8_SCHED; PG8_LDA(At, 1, 0); PG8_STAGE(PG8_SA(0, 1), a2 + hstep, voffA);
;             PG8_WAIT_L(8); PG8_BAR; PG8_WAIT_L(0); PG8_MMA(0, 0, At, B0); PG8_BAR; PG8_SCHED;
;             PG8_LDB(B1, 1, 1); PG8_STAGE(PG8_SB(1, 0), b3, voffB);
;             PG8_BAR; PG8_WAIT_L(0); PG8_MMA(0, 1, At, B1); PG8_BAR;
;             PG8_LDA(At, 1, 1); PG8_STAGE(PG8_SA(1, 0), a3, voffA);
;             PG8_BAR; PG8_WAIT_L(0); PG8_MMA(1, 0, At, B0); PG8_BAR; PG8_SCHED;
	v_mfma_f32_16x16x32_bf16 v[52:55], v[220:223], v[178:181], v[52:55]
	v_mfma_f32_16x16x32_bf16 v[48:51], v[228:231], v[178:181], v[48:51]
	v_mfma_f32_16x16x32_bf16 v[36:39], v[220:223], v[196:199], v[36:39]
	v_mfma_f32_16x16x32_bf16 v[32:35], v[228:231], v[196:199], v[32:35]
	v_mfma_f32_16x16x32_bf16 v[20:23], v[220:223], v[204:207], v[20:23]
	v_mfma_f32_16x16x32_bf16 v[16:19], v[228:231], v[204:207], v[16:19]
	v_mfma_f32_16x16x32_bf16 v[4:7], v[220:223], v[212:215], v[4:7]
	v_mfma_f32_16x16x32_bf16 v[0:3], v[228:231], v[212:215], v[0:3]
	v_mfma_f32_16x16x32_bf16 v[52:55], v[224:227], v[192:195], v[52:55]
	v_mfma_f32_16x16x32_bf16 v[48:51], v[232:235], v[192:195], v[48:51]
	v_mfma_f32_16x16x32_bf16 v[36:39], v[224:227], v[200:203], v[36:39]
	v_mfma_f32_16x16x32_bf16 v[32:35], v[232:235], v[200:203], v[32:35]
	v_mfma_f32_16x16x32_bf16 v[20:23], v[224:227], v[208:211], v[20:23]
	v_mfma_f32_16x16x32_bf16 v[16:19], v[232:235], v[208:211], v[16:19]
	v_mfma_f32_16x16x32_bf16 v[4:7], v[224:227], v[216:219], v[4:7]
	v_mfma_f32_16x16x32_bf16 v[0:3], v[232:235], v[216:219], v[0:3]
	s_add_i32 s16, 0, 0x18000
	s_barrier
	ds_read_b128 v[158:161], v250
	ds_read_b128 v[162:165], v250 offset:1024
	ds_read_b128 v[170:173], v250 offset:2048
	ds_read_b128 v[174:177], v250 offset:3072
	s_add_u32 s14, s30, 0x40000
	s_addc_u32 s15, s31, 0
	s_mov_b32 m0, s46
	ds_read_b128 v[178:181], v168 offset:32768
	ds_read_b128 v[192:195], v168 offset:33792
	ds_read_b128 v[196:199], v168 offset:34816
	ds_read_b128 v[200:203], v168 offset:35840
	ds_read_b128 v[204:207], v168 offset:36864
	ds_read_b128 v[208:211], v168 offset:37888
	ds_read_b128 v[212:215], v168 offset:38912
	global_load_lds_dwordx4 v152, s[14:15]
	s_mov_b32 m0, s47
	ds_read_b128 v[216:219], v168 offset:39936
	global_load_lds_dwordx4 v150, s[14:15]
	s_waitcnt lgkmcnt(8)
	s_barrier
	s_waitcnt lgkmcnt(0)
	v_mfma_f32_16x16x32_bf16 v[124:127], v[158:161], v[178:181], v[124:127]
	v_mfma_f32_16x16x32_bf16 v[120:123], v[170:173], v[178:181], v[120:123]
	v_mfma_f32_16x16x32_bf16 v[108:111], v[158:161], v[196:199], v[108:111]
	v_mfma_f32_16x16x32_bf16 v[104:107], v[170:173], v[196:199], v[104:107]
	v_mfma_f32_16x16x32_bf16 v[92:95], v[158:161], v[204:207], v[92:95]
	v_mfma_f32_16x16x32_bf16 v[88:91], v[170:173], v[204:207], v[88:91]
	v_mfma_f32_16x16x32_bf16 v[76:79], v[158:161], v[212:215], v[76:79]
	v_mfma_f32_16x16x32_bf16 v[72:75], v[170:173], v[212:215], v[72:75]
	v_mfma_f32_16x16x32_bf16 v[124:127], v[162:165], v[192:195], v[124:127]
	v_mfma_f32_16x16x32_bf16 v[120:123], v[174:177], v[192:195], v[120:123]
	v_mfma_f32_16x16x32_bf16 v[108:111], v[162:165], v[200:203], v[108:111]
	v_mfma_f32_16x16x32_bf16 v[104:107], v[174:177], v[200:203], v[104:107]
	v_mfma_f32_16x16x32_bf16 v[92:95], v[162:165], v[208:211], v[92:95]
	v_mfma_f32_16x16x32_bf16 v[88:91], v[174:177], v[208:211], v[88:91]
	v_mfma_f32_16x16x32_bf16 v[76:79], v[162:165], v[216:219], v[76:79]
	v_mfma_f32_16x16x32_bf16 v[72:75], v[174:177], v[216:219], v[72:75]
	s_barrier
	s_add_i32 s17, 0, 0x1c000
	s_add_i32 s14, s16, s43
	s_mov_b32 m0, s14
	ds_read_b128 v[220:223], v251
	ds_read_b128 v[224:227], v251 offset:1024
	ds_read_b128 v[228:231], v251 offset:2048
	global_load_lds_dwordx4 v244, s[26:27]
	s_add_i32 m0, s14, 0x2000
	ds_read_b128 v[232:235], v251 offset:3072
	global_load_lds_dwordx4 v245, s[26:27]
	s_barrier
	s_waitcnt lgkmcnt(0)
	v_mfma_f32_16x16x32_bf16 v[116:119], v[220:223], v[178:181], v[116:119]
	v_mfma_f32_16x16x32_bf16 v[112:115], v[228:231], v[178:181], v[112:115]
	v_mfma_f32_16x16x32_bf16 v[100:103], v[220:223], v[196:199], v[100:103]
	v_mfma_f32_16x16x32_bf16 v[96:99], v[228:231], v[196:199], v[96:99]
	v_mfma_f32_16x16x32_bf16 v[84:87], v[220:223], v[204:207], v[84:87]
	v_mfma_f32_16x16x32_bf16 v[80:83], v[228:231], v[204:207], v[80:83]
	v_mfma_f32_16x16x32_bf16 v[68:71], v[220:223], v[212:215], v[68:71]
	v_mfma_f32_16x16x32_bf16 v[64:67], v[228:231], v[212:215], v[64:67]
	v_mfma_f32_16x16x32_bf16 v[116:119], v[224:227], v[192:195], v[116:119]
	v_mfma_f32_16x16x32_bf16 v[112:115], v[232:235], v[192:195], v[112:115]
	v_mfma_f32_16x16x32_bf16 v[100:103], v[224:227], v[200:203], v[100:103]
	v_mfma_f32_16x16x32_bf16 v[96:99], v[232:235], v[200:203], v[96:99]
	v_mfma_f32_16x16x32_bf16 v[84:87], v[224:227], v[208:211], v[84:87]
	v_mfma_f32_16x16x32_bf16 v[80:83], v[232:235], v[208:211], v[80:83]
	v_mfma_f32_16x16x32_bf16 v[68:71], v[224:227], v[216:219], v[68:71]
	v_mfma_f32_16x16x32_bf16 v[64:67], v[232:235], v[216:219], v[64:67]
	s_mov_b32 m0, s49
	s_barrier
	ds_read_b128 v[178:181], v168 offset:49152
	ds_read_b128 v[192:195], v168 offset:50176
	ds_read_b128 v[196:199], v168 offset:51200
	ds_read_b128 v[200:203], v168 offset:52224
	ds_read_b128 v[204:207], v168 offset:53248
	ds_read_b128 v[208:211], v168 offset:54272
	ds_read_b128 v[212:215], v168 offset:55296
	global_load_lds_dwordx4 v246, s[30:31]
	s_mov_b32 m0, s53
	ds_read_b128 v[216:219], v168 offset:56320
	global_load_lds_dwordx4 v247, s[30:31]
	s_barrier
	s_waitcnt lgkmcnt(0)
	v_mfma_f32_16x16x32_bf16 v[60:63], v[158:161], v[178:181], v[60:63]
	v_mfma_f32_16x16x32_bf16 v[56:59], v[170:173], v[178:181], v[56:59]
	v_mfma_f32_16x16x32_bf16 v[44:47], v[158:161], v[196:199], v[44:47]
	v_mfma_f32_16x16x32_bf16 v[40:43], v[170:173], v[196:199], v[40:43]
	v_mfma_f32_16x16x32_bf16 v[28:31], v[158:161], v[204:207], v[28:31]
	v_mfma_f32_16x16x32_bf16 v[24:27], v[170:173], v[204:207], v[24:27]
	v_mfma_f32_16x16x32_bf16 v[12:15], v[158:161], v[212:215], v[12:15]
	v_mfma_f32_16x16x32_bf16 v[8:11], v[170:173], v[212:215], v[8:11]
	v_mfma_f32_16x16x32_bf16 v[60:63], v[162:165], v[192:195], v[60:63]
	v_mfma_f32_16x16x32_bf16 v[56:59], v[174:177], v[192:195], v[56:59]
	v_mfma_f32_16x16x32_bf16 v[44:47], v[162:165], v[200:203], v[44:47]
	v_mfma_f32_16x16x32_bf16 v[40:43], v[174:177], v[200:203], v[40:43]
	v_mfma_f32_16x16x32_bf16 v[28:31], v[162:165], v[208:211], v[28:31]
	v_mfma_f32_16x16x32_bf16 v[24:27], v[174:177], v[208:211], v[24:27]
	v_mfma_f32_16x16x32_bf16 v[12:15], v[162:165], v[216:219], v[12:15]
	v_mfma_f32_16x16x32_bf16 v[8:11], v[174:177], v[216:219], v[8:11]
	s_barrier
; __device__ __forceinline__ unsigned cvt_pk_bf16(float lo, float hi) { const f32x2_cv v = {lo, hi}; const bf16x2_cv b = __builtin_convertvector(v, bf16x2_cv); return __builtin_bit_cast(unsigned, b); }
; #define PG8_STAGE(bufoff, gbase, voff) do { _Pragma("unroll") for (int _i = 0; _i < 2; ++_i) \
;         __builtin_amdgcn_global_load_lds((const unsigned*)((const char*)(gbase) + (voff)[_i]), (PG8_LAS unsigned*)(lds + (bufoff) + ldsw + _i * 8192), 16, 0, 0); } while (0)
; #define PG8_MMA(ai, bj, At, Bt) do { __builtin_amdgcn_s_setprio(1); _Pragma("unroll") for (int m = 0; m < 4; ++m) _Pragma("unroll") for (int n = 0; n < 2; ++n) _Pragma("unroll") for (int k = 0; k < 2; ++k) \
;         acc[ai][bj][m][n] = __builtin_amdgcn_mfma_f32_16x16x32_bf16(Bt[n][k], At[m][k], acc[ai][bj][m][n], 0, 0, 0); __builtin_amdgcn_s_setprio(0); } while (0)
; #define PG8_WAIT_V(n) asm volatile("s_waitcnt vmcnt(" #n ")" ::: "memory")
; template <class Epi, class Sched, bool STAMP = false>
; __device__ __forceinline__ void gemm_phase(PG8_LAS unsigned char* lds, const Gemm g, const Sched& S, const Epi& E, unsigned long long* stamps) {
;     ...
;             PG8_STAGE(PG8_SB(1, 1), b3 + hstep, voffB);
;             PG8_WAIT_V(6); PG8_BAR; PG8_MMA(1, 1, At, B1); PG8_BAR;
;     __device__ __forceinline__ void operator()(const f32x4 (&acc)[2][2][4][2], const pg8::Unit& u, int wr, int wc, int fr, int fq) const {
;         const int row0 = u.pm * 256 + wr * 64 + fr, col0 = u.pn * 256 + wc * 32 + 8 * fq;
; #pragma unroll
;         for (int ai = 0; ai < 2; ++ai)
; #pragma unroll
;             for (int m = 0; m < 4; ++m) {
;                 const int row = row0 + ai * 128 + m * 16;
;                 const float s = (MODE == 2) ? 1.0f : rstd_of(rowss, row);
;                 bf16_t* rowp = O + (size_t)row * ldc + col0;
; #pragma unroll
;                 for (int bj = 0; bj < 2; ++bj) {
;                     f32x4 v0 = acc[ai][bj][m][0] * s, v1 = acc[ai][bj][m][1] * s;
;                     if (MODE == 1) {
; #pragma unroll
;                         for (int j = 0; j < 4; ++j) { const float a = fmaxf(v0[j], 0.f), b = fmaxf(v1[j], 0.f); v0[j] = a * a; v1[j] = b * b; } }
;                     u32x4 w; w.x = cvt_pk_bf16(v0[0], v0[1]); w.y = cvt_pk_bf16(v0[2], v0[3]); w.z = cvt_pk_bf16(v1[0], v1[1]); w.w = cvt_pk_bf16(v1[2], v1[3]);
;                     *(u32x4*)(rowp + bj * 128) = w; } }
	s_add_u32 s14, s26, 0x40080
	s_addc_u32 s15, s27, 0
	s_add_i32 s16, s17, s43
	s_mov_b32 m0, s16
	s_nop 0
	global_load_lds_dwordx4 v128, s[14:15]
	s_add_i32 m0, s16, 0x2000
	s_nop 0
	global_load_lds_dwordx4 v148, s[14:15]
	s_waitcnt vmcnt(6)
	s_barrier
	v_mfma_f32_16x16x32_bf16 v[52:55], v[220:223], v[178:181], v[52:55]
	v_mfma_f32_16x16x32_bf16 v[48:51], v[228:231], v[178:181], v[48:51]
	v_mfma_f32_16x16x32_bf16 v[36:39], v[220:223], v[196:199], v[36:39]
	v_mfma_f32_16x16x32_bf16 v[32:35], v[228:231], v[196:199], v[32:35]
	v_mfma_f32_16x16x32_bf16 v[20:23], v[220:223], v[204:207], v[20:23]
	v_mfma_f32_16x16x32_bf16 v[16:19], v[228:231], v[204:207], v[16:19]
	v_mfma_f32_16x16x32_bf16 v[4:7], v[220:223], v[212:215], v[4:7]
	v_mfma_f32_16x16x32_bf16 v[0:3], v[228:231], v[212:215], v[0:3]
	v_mfma_f32_16x16x32_bf16 v[52:55], v[224:227], v[192:195], v[52:55]
	v_mfma_f32_16x16x32_bf16 v[48:51], v[232:235], v[192:195], v[48:51]
	v_mfma_f32_16x16x32_bf16 v[36:39], v[224:227], v[200:203], v[36:39]
	v_mfma_f32_16x16x32_bf16 v[32:35], v[232:235], v[200:203], v[32:35]
	v_mfma_f32_16x16x32_bf16 v[20:23], v[224:227], v[208:211], v[20:23]
	v_mfma_f32_16x16x32_bf16 v[16:19], v[232:235], v[208:211], v[16:19]
	v_mfma_f32_16x16x32_bf16 v[4:7], v[224:227], v[216:219], v[4:7]
	v_mfma_f32_16x16x32_bf16 v[0:3], v[232:235], v[216:219], v[0:3]
	s_add_i32 s61, s61, 2
	s_add_u32 s24, s24, 0x100
	s_addc_u32 s25, s25, 0
	s_add_u32 s59, s59, 0x100
	s_addc_u32 s60, s60, 0
	s_cmp_gt_u32 s61, 13
	s_barrier
	s_cbranch_scc0 .LBB0_44
	v_lshl_add_u32 v162, s22, 8, v139
	v_ashrrev_i32_e32 v163, 31, v162
	v_lshl_add_u64 v[158:159], v[162:163], 2, s[0:1]
	global_load_dword v164, v[158:159], off
	global_load_dword v193, v[158:159], off offset:64
	global_load_dword v194, v[158:159], off offset:128
	global_load_dword v195, v[158:159], off offset:192
	global_load_dword v196, v[158:159], off offset:512
	global_load_dword v197, v[158:159], off offset:576
	global_load_dword v198, v[158:159], off offset:640
	global_load_dword v199, v[158:159], off offset:704
	v_lshl_or_b32 v160, s56, 8, v167
	v_ashrrev_i32_e32 v161, 31, v160
	s_mov_b32 s5, 0x100000
	s_mov_b64 s[14:15], 0x100000
	s_mov_b32 s56, s4
	s_mov_b32 s22, s6
	s_mov_b64 s[26:27], s[20:21]
	s_mov_b64 s[24:25], s[12:13]
	s_waitcnt vmcnt(0)
	v_fmamk_f32 v164, v164, 0x3a800000, v187
	v_cmp_gt_f32_e32 vcc, s67, v164
	v_mul_f32_e32 v165, 0x4b800000, v164
	s_nop 0
	v_cndmask_b32_e32 v164, v164, v165, vcc
	v_rsq_f32_e32 v164, v164
	s_nop 0
	v_mul_f32_e32 v165, 0x45800000, v164
	v_cndmask_b32_e32 v170, v164, v165, vcc
	v_lshlrev_b64 v[164:165], 13, v[162:163]
	v_pk_mul_f32 v[120:121], v[120:121], v[170:171] op_sel_hi:[1,0]
	v_lshl_add_u64 v[172:173], s[2:3], 0, v[164:165]
	v_lshlrev_b64 v[164:165], 1, v[160:161]
	v_pk_mul_f32 v[126:127], v[126:127], v[170:171] op_sel_hi:[1,0]
	v_pk_mul_f32 v[124:125], v[124:125], v[170:171] op_sel_hi:[1,0]
	v_pk_mul_f32 v[122:123], v[122:123], v[170:171] op_sel_hi:[1,0]
	v_max_f32_e32 v120, 0, v120
	v_max_f32_e32 v121, 0, v121
	v_lshl_add_u64 v[160:161], v[172:173], 0, v[164:165]
	v_max_f32_e32 v124, 0, v124
	v_max_f32_e32 v125, 0, v125
	v_pk_mul_f32 v[172:173], v[120:121], v[120:121]
	v_max_f32_e32 v120, 0, v126
	v_max_f32_e32 v122, 0, v122
	v_max_f32_e32 v121, 0, v127
	v_max_f32_e32 v123, 0, v123
	v_pk_mul_f32 v[124:125], v[124:125], v[124:125]
	v_pk_mul_f32 v[126:127], v[120:121], v[120:121]
	v_pk_mul_f32 v[174:175], v[122:123], v[122:123]
	v_pk_mul_f32 v[112:113], v[112:113], v[170:171] op_sel_hi:[1,0]
	v_cvt_pk_bf16_f32 v120, v124, v125
	v_cvt_pk_bf16_f32 v121, v126, v127
	v_cvt_pk_bf16_f32 v122, v172, v173
	v_cvt_pk_bf16_f32 v123, v174, v175
	v_pk_mul_f32 v[118:119], v[118:119], v[170:171] op_sel_hi:[1,0]
	v_pk_mul_f32 v[116:117], v[116:117], v[170:171] op_sel_hi:[1,0]
	v_pk_mul_f32 v[114:115], v[114:115], v[170:171] op_sel_hi:[1,0]
	v_max_f32_e32 v112, 0, v112
	v_max_f32_e32 v113, 0, v113
	global_store_dwordx4 v[160:161], v[120:123], off
	v_max_f32_e32 v116, 0, v116
	v_max_f32_e32 v117, 0, v117
	v_pk_mul_f32 v[120:121], v[112:113], v[112:113]
	v_max_f32_e32 v112, 0, v118
	v_max_f32_e32 v114, 0, v114
	v_max_f32_e32 v113, 0, v119
	v_max_f32_e32 v115, 0, v115
	v_pk_mul_f32 v[116:117], v[116:117], v[116:117]
	v_pk_mul_f32 v[118:119], v[112:113], v[112:113]
	v_pk_mul_f32 v[122:123], v[114:115], v[114:115]
	v_cvt_pk_bf16_f32 v112, v116, v117
	v_cvt_pk_bf16_f32 v113, v118, v119
	v_cvt_pk_bf16_f32 v114, v120, v121
	v_cvt_pk_bf16_f32 v115, v122, v123
	global_store_dwordx4 v[160:161], v[112:115], off offset:256
	s_nop 1
	v_mov_b32_e32 v114, v193
	s_nop 0
	v_or_b32_e32 v112, 16, v162
	v_ashrrev_i32_e32 v113, 31, v112
	v_lshlrev_b64 v[112:113], 13, v[112:113]
	v_lshl_add_u64 v[112:113], s[2:3], 0, v[112:113]
	v_lshl_add_u64 v[112:113], v[112:113], 0, v[164:165]
	v_fmamk_f32 v114, v114, 0x3a800000, v187
	v_cmp_gt_f32_e32 vcc, s67, v114
	v_mul_f32_e32 v115, 0x4b800000, v114
	s_nop 0
	v_cndmask_b32_e32 v114, v114, v115, vcc
	v_rsq_f32_e32 v114, v114
	s_nop 0
	v_mul_f32_e32 v115, 0x45800000, v114
	v_cndmask_b32_e32 v114, v114, v115, vcc
	v_pk_mul_f32 v[104:105], v[104:105], v[114:115] op_sel_hi:[1,0]
	v_pk_mul_f32 v[110:111], v[110:111], v[114:115] op_sel_hi:[1,0]
	v_pk_mul_f32 v[108:109], v[108:109], v[114:115] op_sel_hi:[1,0]
	v_pk_mul_f32 v[106:107], v[106:107], v[114:115] op_sel_hi:[1,0]
	v_max_f32_e32 v104, 0, v104
	v_max_f32_e32 v105, 0, v105
	v_max_f32_e32 v108, 0, v108
	v_max_f32_e32 v109, 0, v109
	v_pk_mul_f32 v[116:117], v[104:105], v[104:105]
	v_max_f32_e32 v104, 0, v110
	v_max_f32_e32 v106, 0, v106
	v_max_f32_e32 v105, 0, v111
	v_max_f32_e32 v107, 0, v107
	v_pk_mul_f32 v[108:109], v[108:109], v[108:109]
; __device__ __forceinline__ unsigned cvt_pk_bf16(float lo, float hi) { const f32x2_cv v = {lo, hi}; const bf16x2_cv b = __builtin_convertvector(v, bf16x2_cv); return __builtin_bit_cast(unsigned, b); }
; __device__ __forceinline__ float rstd_of(const float* rowss, int row) { return rsqrtf(rowss[row] * (1.0f / 1024.0f) + 1e-6f); }
;     __device__ __forceinline__ void operator()(const f32x4 (&acc)[2][2][4][2], const pg8::Unit& u, int wr, int wc, int fr, int fq) const {
;     ...
;             for (int m = 0; m < 4; ++m) {
;                 const int row = row0 + ai * 128 + m * 16;
;                 const float s = (MODE == 2) ? 1.0f : rstd_of(rowss, row);
;                 bf16_t* rowp = O + (size_t)row * ldc + col0;
; #pragma unroll
;                 for (int bj = 0; bj < 2; ++bj) {
;                     f32x4 v0 = acc[ai][bj][m][0] * s, v1 = acc[ai][bj][m][1] * s;
;                     if (MODE == 1) {
; #pragma unroll
;                         for (int j = 0; j < 4; ++j) { const float a = fmaxf(v0[j], 0.f), b = fmaxf(v1[j], 0.f); v0[j] = a * a; v1[j] = b * b; } }
;                     u32x4 w; w.x = cvt_pk_bf16(v0[0], v0[1]); w.y = cvt_pk_bf16(v0[2], v0[3]); w.z = cvt_pk_bf16(v1[0], v1[1]); w.w = cvt_pk_bf16(v1[2], v1[3]);
;                     *(u32x4*)(rowp + bj * 128) = w; } }
	v_pk_mul_f32 v[110:111], v[104:105], v[104:105]
	v_pk_mul_f32 v[118:119], v[106:107], v[106:107]
	v_pk_mul_f32 v[96:97], v[96:97], v[114:115] op_sel_hi:[1,0]
	v_cvt_pk_bf16_f32 v104, v108, v109
	v_cvt_pk_bf16_f32 v105, v110, v111
	v_cvt_pk_bf16_f32 v106, v116, v117
	v_cvt_pk_bf16_f32 v107, v118, v119
	v_pk_mul_f32 v[102:103], v[102:103], v[114:115] op_sel_hi:[1,0]
	v_pk_mul_f32 v[100:101], v[100:101], v[114:115] op_sel_hi:[1,0]
	v_pk_mul_f32 v[98:99], v[98:99], v[114:115] op_sel_hi:[1,0]
	v_max_f32_e32 v96, 0, v96
	v_max_f32_e32 v97, 0, v97
	global_store_dwordx4 v[112:113], v[104:107], off
	v_max_f32_e32 v100, 0, v100
	v_max_f32_e32 v101, 0, v101
	v_pk_mul_f32 v[104:105], v[96:97], v[96:97]
	v_max_f32_e32 v96, 0, v102
	v_max_f32_e32 v98, 0, v98
	v_max_f32_e32 v97, 0, v103
	v_max_f32_e32 v99, 0, v99
	v_pk_mul_f32 v[100:101], v[100:101], v[100:101]
	v_pk_mul_f32 v[102:103], v[96:97], v[96:97]
	v_pk_mul_f32 v[106:107], v[98:99], v[98:99]
	v_cvt_pk_bf16_f32 v96, v100, v101
	v_cvt_pk_bf16_f32 v97, v102, v103
	v_cvt_pk_bf16_f32 v98, v104, v105
	v_cvt_pk_bf16_f32 v99, v106, v107
	global_store_dwordx4 v[112:113], v[96:99], off offset:256
	s_nop 1
	v_mov_b32_e32 v98, v194
	s_nop 0
	v_or_b32_e32 v96, 32, v162
	v_ashrrev_i32_e32 v97, 31, v96
	v_lshlrev_b64 v[96:97], 13, v[96:97]
	v_lshl_add_u64 v[96:97], s[2:3], 0, v[96:97]
	v_lshl_add_u64 v[96:97], v[96:97], 0, v[164:165]
	v_fmamk_f32 v98, v98, 0x3a800000, v187
	v_cmp_gt_f32_e32 vcc, s67, v98
	v_mul_f32_e32 v99, 0x4b800000, v98
	s_nop 0
	v_cndmask_b32_e32 v98, v98, v99, vcc
	v_rsq_f32_e32 v98, v98
	s_nop 0
	v_mul_f32_e32 v99, 0x45800000, v98
	v_cndmask_b32_e32 v98, v98, v99, vcc
	v_pk_mul_f32 v[88:89], v[88:89], v[98:99] op_sel_hi:[1,0]
	v_pk_mul_f32 v[94:95], v[94:95], v[98:99] op_sel_hi:[1,0]
	v_pk_mul_f32 v[92:93], v[92:93], v[98:99] op_sel_hi:[1,0]
	v_pk_mul_f32 v[90:91], v[90:91], v[98:99] op_sel_hi:[1,0]
	v_max_f32_e32 v88, 0, v88
	v_max_f32_e32 v89, 0, v89
	v_max_f32_e32 v92, 0, v92
	v_max_f32_e32 v93, 0, v93
	v_pk_mul_f32 v[100:101], v[88:89], v[88:89]
	v_max_f32_e32 v88, 0, v94
	v_max_f32_e32 v90, 0, v90
	v_max_f32_e32 v89, 0, v95
	v_max_f32_e32 v91, 0, v91
	v_pk_mul_f32 v[92:93], v[92:93], v[92:93]
	v_pk_mul_f32 v[94:95], v[88:89], v[88:89]
	v_pk_mul_f32 v[102:103], v[90:91], v[90:91]
	v_pk_mul_f32 v[80:81], v[80:81], v[98:99] op_sel_hi:[1,0]
	v_cvt_pk_bf16_f32 v88, v92, v93
	v_cvt_pk_bf16_f32 v89, v94, v95
	v_cvt_pk_bf16_f32 v90, v100, v101
	v_cvt_pk_bf16_f32 v91, v102, v103
	v_pk_mul_f32 v[86:87], v[86:87], v[98:99] op_sel_hi:[1,0]
	v_pk_mul_f32 v[84:85], v[84:85], v[98:99] op_sel_hi:[1,0]
	v_pk_mul_f32 v[82:83], v[82:83], v[98:99] op_sel_hi:[1,0]
	v_max_f32_e32 v80, 0, v80
	v_max_f32_e32 v81, 0, v81
	global_store_dwordx4 v[96:97], v[88:91], off
	v_max_f32_e32 v84, 0, v84
	v_max_f32_e32 v85, 0, v85
	v_pk_mul_f32 v[88:89], v[80:81], v[80:81]
	v_max_f32_e32 v80, 0, v86
	v_max_f32_e32 v82, 0, v82
	v_max_f32_e32 v81, 0, v87
	v_max_f32_e32 v83, 0, v83
	v_pk_mul_f32 v[84:85], v[84:85], v[84:85]
	v_pk_mul_f32 v[86:87], v[80:81], v[80:81]
	v_pk_mul_f32 v[90:91], v[82:83], v[82:83]
	v_cvt_pk_bf16_f32 v80, v84, v85
	v_cvt_pk_bf16_f32 v81, v86, v87
	v_cvt_pk_bf16_f32 v82, v88, v89
	v_cvt_pk_bf16_f32 v83, v90, v91
	global_store_dwordx4 v[96:97], v[80:83], off offset:256
	s_nop 1
	v_mov_b32_e32 v82, v195
	s_nop 0
	v_or_b32_e32 v80, 48, v162
	v_ashrrev_i32_e32 v81, 31, v80
	v_lshlrev_b64 v[80:81], 13, v[80:81]
	v_lshl_add_u64 v[80:81], s[2:3], 0, v[80:81]
	v_lshl_add_u64 v[80:81], v[80:81], 0, v[164:165]
	v_fmamk_f32 v82, v82, 0x3a800000, v187
	v_cmp_gt_f32_e32 vcc, s67, v82
	v_mul_f32_e32 v83, 0x4b800000, v82
	s_nop 0
	v_cndmask_b32_e32 v82, v82, v83, vcc
	v_rsq_f32_e32 v82, v82
	s_nop 0
	v_mul_f32_e32 v83, 0x45800000, v82
	v_cndmask_b32_e32 v82, v82, v83, vcc
	v_pk_mul_f32 v[72:73], v[72:73], v[82:83] op_sel_hi:[1,0]
	v_pk_mul_f32 v[78:79], v[78:79], v[82:83] op_sel_hi:[1,0]
	v_pk_mul_f32 v[76:77], v[76:77], v[82:83] op_sel_hi:[1,0]
	v_pk_mul_f32 v[74:75], v[74:75], v[82:83] op_sel_hi:[1,0]
	v_max_f32_e32 v72, 0, v72
	v_max_f32_e32 v73, 0, v73
	v_max_f32_e32 v76, 0, v76
	v_max_f32_e32 v77, 0, v77
	v_pk_mul_f32 v[84:85], v[72:73], v[72:73]
	v_max_f32_e32 v72, 0, v78
	v_max_f32_e32 v74, 0, v74
	v_max_f32_e32 v73, 0, v79
	v_max_f32_e32 v75, 0, v75
	v_pk_mul_f32 v[76:77], v[76:77], v[76:77]
	v_pk_mul_f32 v[78:79], v[72:73], v[72:73]
	v_pk_mul_f32 v[86:87], v[74:75], v[74:75]
	v_pk_mul_f32 v[64:65], v[64:65], v[82:83] op_sel_hi:[1,0]
	v_cvt_pk_bf16_f32 v72, v76, v77
	v_cvt_pk_bf16_f32 v73, v78, v79
	v_cvt_pk_bf16_f32 v74, v84, v85
	v_cvt_pk_bf16_f32 v75, v86, v87
	v_pk_mul_f32 v[70:71], v[70:71], v[82:83] op_sel_hi:[1,0]
	v_pk_mul_f32 v[68:69], v[68:69], v[82:83] op_sel_hi:[1,0]
	v_pk_mul_f32 v[66:67], v[66:67], v[82:83] op_sel_hi:[1,0]
	v_max_f32_e32 v64, 0, v64
	v_max_f32_e32 v65, 0, v65
	global_store_dwordx4 v[80:81], v[72:75], off
	v_max_f32_e32 v68, 0, v68
	v_max_f32_e32 v69, 0, v69
	v_pk_mul_f32 v[72:73], v[64:65], v[64:65]
	v_max_f32_e32 v64, 0, v70
	v_max_f32_e32 v66, 0, v66
	v_max_f32_e32 v65, 0, v71
	v_max_f32_e32 v67, 0, v67
	v_pk_mul_f32 v[68:69], v[68:69], v[68:69]
	v_pk_mul_f32 v[70:71], v[64:65], v[64:65]
	v_pk_mul_f32 v[74:75], v[66:67], v[66:67]
	v_cvt_pk_bf16_f32 v64, v68, v69
	v_cvt_pk_bf16_f32 v65, v70, v71
	v_cvt_pk_bf16_f32 v66, v72, v73
	v_cvt_pk_bf16_f32 v67, v74, v75
	global_store_dwordx4 v[80:81], v[64:67], off offset:256
	s_nop 1
	v_mov_b32_e32 v64, v196
	v_fmamk_f32 v64, v64, 0x3a800000, v187
	v_cmp_gt_f32_e32 vcc, s67, v64
	v_mul_f32_e32 v65, 0x4b800000, v64
	s_nop 0
	v_cndmask_b32_e32 v64, v64, v65, vcc
	v_rsq_f32_e32 v64, v64
	s_nop 0
	v_mul_f32_e32 v65, 0x45800000, v64
; __device__ __forceinline__ unsigned cvt_pk_bf16(float lo, float hi) { const f32x2_cv v = {lo, hi}; const bf16x2_cv b = __builtin_convertvector(v, bf16x2_cv); return __builtin_bit_cast(unsigned, b); }
; __device__ __forceinline__ float rstd_of(const float* rowss, int row) { return rsqrtf(rowss[row] * (1.0f / 1024.0f) + 1e-6f); }
;     __device__ __forceinline__ void operator()(const f32x4 (&acc)[2][2][4][2], const pg8::Unit& u, int wr, int wc, int fr, int fq) const {
;     ...
;             for (int m = 0; m < 4; ++m) {
;                 const int row = row0 + ai * 128 + m * 16;
;                 const float s = (MODE == 2) ? 1.0f : rstd_of(rowss, row);
;                 bf16_t* rowp = O + (size_t)row * ldc + col0;
; #pragma unroll
;                 for (int bj = 0; bj < 2; ++bj) {
;                     f32x4 v0 = acc[ai][bj][m][0] * s, v1 = acc[ai][bj][m][1] * s;
;                     if (MODE == 1) {
; #pragma unroll
;                         for (int j = 0; j < 4; ++j) { const float a = fmaxf(v0[j], 0.f), b = fmaxf(v1[j], 0.f); v0[j] = a * a; v1[j] = b * b; } }
;                     u32x4 w; w.x = cvt_pk_bf16(v0[0], v0[1]); w.y = cvt_pk_bf16(v0[2], v0[3]); w.z = cvt_pk_bf16(v1[0], v1[1]); w.w = cvt_pk_bf16(v1[2], v1[3]);
;                     *(u32x4*)(rowp + bj * 128) = w; } }
	v_cndmask_b32_e32 v66, v64, v65, vcc
	v_pk_mul_f32 v[60:61], v[60:61], v[66:67] op_sel_hi:[1,0]
	v_pk_mul_f32 v[56:57], v[56:57], v[66:67] op_sel_hi:[1,0]
	v_pk_mul_f32 v[62:63], v[62:63], v[66:67] op_sel_hi:[1,0]
	v_pk_mul_f32 v[58:59], v[58:59], v[66:67] op_sel_hi:[1,0]
	v_max_f32_e32 v60, 0, v60
	v_max_f32_e32 v56, 0, v56
	v_max_f32_e32 v61, 0, v61
	v_max_f32_e32 v57, 0, v57
	v_pk_mul_f32 v[60:61], v[60:61], v[60:61]
	v_pk_mul_f32 v[68:69], v[56:57], v[56:57]
	v_max_f32_e32 v56, 0, v62
	v_max_f32_e32 v58, 0, v58
	v_max_f32_e32 v57, 0, v63
	v_max_f32_e32 v59, 0, v59
	v_pk_mul_f32 v[62:63], v[56:57], v[56:57]
	v_pk_mul_f32 v[70:71], v[58:59], v[58:59]
	v_cvt_pk_bf16_f32 v56, v60, v61
	v_add_co_u32_e32 v60, vcc, s5, v160
	v_pk_mul_f32 v[48:49], v[48:49], v[66:67] op_sel_hi:[1,0]
	v_cvt_pk_bf16_f32 v57, v62, v63
	v_cvt_pk_bf16_f32 v58, v68, v69
	v_cvt_pk_bf16_f32 v59, v70, v71
	v_addc_co_u32_e32 v61, vcc, 0, v161, vcc
	v_pk_mul_f32 v[54:55], v[54:55], v[66:67] op_sel_hi:[1,0]
	v_pk_mul_f32 v[52:53], v[52:53], v[66:67] op_sel_hi:[1,0]
	v_pk_mul_f32 v[50:51], v[50:51], v[66:67] op_sel_hi:[1,0]
	v_max_f32_e32 v48, 0, v48
	v_max_f32_e32 v49, 0, v49
	global_store_dwordx4 v[60:61], v[56:59], off
	v_max_f32_e32 v52, 0, v52
	v_max_f32_e32 v53, 0, v53
	v_pk_mul_f32 v[56:57], v[48:49], v[48:49]
	v_max_f32_e32 v48, 0, v54
	v_max_f32_e32 v50, 0, v50
	v_max_f32_e32 v49, 0, v55
	v_max_f32_e32 v51, 0, v51
	v_pk_mul_f32 v[52:53], v[52:53], v[52:53]
	v_pk_mul_f32 v[54:55], v[48:49], v[48:49]
	v_pk_mul_f32 v[58:59], v[50:51], v[50:51]
	v_lshl_add_u64 v[64:65], v[160:161], 0, s[14:15]
	v_cvt_pk_bf16_f32 v48, v52, v53
	v_cvt_pk_bf16_f32 v49, v54, v55
	v_cvt_pk_bf16_f32 v50, v56, v57
	v_cvt_pk_bf16_f32 v51, v58, v59
	global_store_dwordx4 v[64:65], v[48:51], off offset:256
	s_nop 1
	v_mov_b32_e32 v48, v197
	s_mov_b32 s5, 0x120000
	s_mov_b64 s[14:15], 0x120000
	v_fmamk_f32 v48, v48, 0x3a800000, v187
	v_cmp_gt_f32_e32 vcc, s67, v48
	v_mul_f32_e32 v49, 0x4b800000, v48
	s_nop 0
	v_cndmask_b32_e32 v48, v48, v49, vcc
	v_rsq_f32_e32 v48, v48
	s_nop 0
	v_mul_f32_e32 v49, 0x45800000, v48
	v_cndmask_b32_e32 v50, v48, v49, vcc
	v_pk_mul_f32 v[44:45], v[44:45], v[50:51] op_sel_hi:[1,0]
	v_pk_mul_f32 v[40:41], v[40:41], v[50:51] op_sel_hi:[1,0]
	v_pk_mul_f32 v[46:47], v[46:47], v[50:51] op_sel_hi:[1,0]
	v_pk_mul_f32 v[42:43], v[42:43], v[50:51] op_sel_hi:[1,0]
	v_max_f32_e32 v44, 0, v44
	v_max_f32_e32 v40, 0, v40
	v_max_f32_e32 v45, 0, v45
	v_max_f32_e32 v41, 0, v41
	v_pk_mul_f32 v[44:45], v[44:45], v[44:45]
	v_pk_mul_f32 v[52:53], v[40:41], v[40:41]
	v_max_f32_e32 v40, 0, v46
	v_max_f32_e32 v42, 0, v42
	v_max_f32_e32 v41, 0, v47
	v_max_f32_e32 v43, 0, v43
	v_pk_mul_f32 v[46:47], v[40:41], v[40:41]
	v_pk_mul_f32 v[54:55], v[42:43], v[42:43]
	v_cvt_pk_bf16_f32 v40, v44, v45
	v_add_co_u32_e32 v44, vcc, s5, v160
	v_pk_mul_f32 v[32:33], v[32:33], v[50:51] op_sel_hi:[1,0]
	v_cvt_pk_bf16_f32 v41, v46, v47
	v_cvt_pk_bf16_f32 v42, v52, v53
	v_cvt_pk_bf16_f32 v43, v54, v55
	v_addc_co_u32_e32 v45, vcc, 0, v161, vcc
	v_pk_mul_f32 v[38:39], v[38:39], v[50:51] op_sel_hi:[1,0]
	v_pk_mul_f32 v[36:37], v[36:37], v[50:51] op_sel_hi:[1,0]
	v_pk_mul_f32 v[34:35], v[34:35], v[50:51] op_sel_hi:[1,0]
	v_max_f32_e32 v32, 0, v32
	v_max_f32_e32 v33, 0, v33
	global_store_dwordx4 v[44:45], v[40:43], off
	v_max_f32_e32 v36, 0, v36
	v_max_f32_e32 v37, 0, v37
	v_pk_mul_f32 v[40:41], v[32:33], v[32:33]
	v_max_f32_e32 v32, 0, v38
	v_max_f32_e32 v34, 0, v34
	v_max_f32_e32 v33, 0, v39
	v_max_f32_e32 v35, 0, v35
	v_pk_mul_f32 v[36:37], v[36:37], v[36:37]
	v_pk_mul_f32 v[38:39], v[32:33], v[32:33]
	v_pk_mul_f32 v[42:43], v[34:35], v[34:35]
	v_lshl_add_u64 v[48:49], v[160:161], 0, s[14:15]
	v_cvt_pk_bf16_f32 v32, v36, v37
	v_cvt_pk_bf16_f32 v33, v38, v39
	v_cvt_pk_bf16_f32 v34, v40, v41
	v_cvt_pk_bf16_f32 v35, v42, v43
	global_store_dwordx4 v[48:49], v[32:35], off offset:256
	s_nop 1
	v_mov_b32_e32 v32, v198
	s_mov_b32 s5, 0x140000
	s_mov_b64 s[14:15], 0x140000
	v_fmamk_f32 v32, v32, 0x3a800000, v187
	v_cmp_gt_f32_e32 vcc, s67, v32
; __device__ __forceinline__ unsigned cvt_pk_bf16(float lo, float hi) { const f32x2_cv v = {lo, hi}; const bf16x2_cv b = __builtin_convertvector(v, bf16x2_cv); return __builtin_bit_cast(unsigned, b); }
; #define PG8_WAIT_V(n) asm volatile("s_waitcnt vmcnt(" #n ")" ::: "memory")
; #define PG8_BAR __builtin_amdgcn_s_barrier()
; __device__ __forceinline__ float rstd_of(const float* rowss, int row) { return rsqrtf(rowss[row] * (1.0f / 1024.0f) + 1e-6f); }
; template <class Epi, class Sched, bool STAMP = false>
; __device__ __forceinline__ void gemm_phase(PG8_LAS unsigned char* lds, const Gemm g, const Sched& S, const Epi& E, unsigned long long* stamps) {
;     ...
;         if (!has_next) break;
; #pragma unroll
;         for (int a = 0; a < 2; ++a)
; #pragma unroll
;             for (int b = 0; b < 2; ++b)
; #pragma unroll
;                 for (int m = 0; m < 4; ++m)
; #pragma unroll
;                     for (int n = 0; n < 2; ++n) acc[a][b][m][n] = (f32x4){0.f, 0.f, 0.f, 0.f};
;         cur = nxt; cA = nA; cB = nB; ++ui;
;     }
;     PG8_WAIT_V(0);
;     if (wr == 0) PG8_BAR;
;     __device__ __forceinline__ void operator()(const f32x4 (&acc)[2][2][4][2], const pg8::Unit& u, int wr, int wc, int fr, int fq) const {
;     ...
;             for (int m = 0; m < 4; ++m) {
;                 const int row = row0 + ai * 128 + m * 16;
;                 const float s = (MODE == 2) ? 1.0f : rstd_of(rowss, row);
;                 bf16_t* rowp = O + (size_t)row * ldc + col0;
; #pragma unroll
;                 for (int bj = 0; bj < 2; ++bj) {
;                     f32x4 v0 = acc[ai][bj][m][0] * s, v1 = acc[ai][bj][m][1] * s;
;                     if (MODE == 1) {
; #pragma unroll
;                         for (int j = 0; j < 4; ++j) { const float a = fmaxf(v0[j], 0.f), b = fmaxf(v1[j], 0.f); v0[j] = a * a; v1[j] = b * b; } }
;                     u32x4 w; w.x = cvt_pk_bf16(v0[0], v0[1]); w.y = cvt_pk_bf16(v0[2], v0[3]); w.z = cvt_pk_bf16(v1[0], v1[1]); w.w = cvt_pk_bf16(v1[2], v1[3]);
;                     *(u32x4*)(rowp + bj * 128) = w; } }
	v_mul_f32_e32 v33, 0x4b800000, v32
	s_nop 0
	v_cndmask_b32_e32 v32, v32, v33, vcc
	v_rsq_f32_e32 v32, v32
	s_nop 0
	v_mul_f32_e32 v33, 0x45800000, v32
	v_cndmask_b32_e32 v34, v32, v33, vcc
	v_pk_mul_f32 v[28:29], v[28:29], v[34:35] op_sel_hi:[1,0]
	v_pk_mul_f32 v[24:25], v[24:25], v[34:35] op_sel_hi:[1,0]
	v_pk_mul_f32 v[30:31], v[30:31], v[34:35] op_sel_hi:[1,0]
	v_pk_mul_f32 v[26:27], v[26:27], v[34:35] op_sel_hi:[1,0]
	v_max_f32_e32 v28, 0, v28
	v_max_f32_e32 v24, 0, v24
	v_max_f32_e32 v29, 0, v29
	v_max_f32_e32 v25, 0, v25
	v_pk_mul_f32 v[28:29], v[28:29], v[28:29]
	v_pk_mul_f32 v[36:37], v[24:25], v[24:25]
	v_max_f32_e32 v24, 0, v30
	v_max_f32_e32 v26, 0, v26
	v_max_f32_e32 v25, 0, v31
	v_max_f32_e32 v27, 0, v27
	v_pk_mul_f32 v[30:31], v[24:25], v[24:25]
	v_pk_mul_f32 v[38:39], v[26:27], v[26:27]
	v_cvt_pk_bf16_f32 v24, v28, v29
	v_add_co_u32_e32 v28, vcc, s5, v160
	v_pk_mul_f32 v[16:17], v[16:17], v[34:35] op_sel_hi:[1,0]
	v_cvt_pk_bf16_f32 v25, v30, v31
	v_cvt_pk_bf16_f32 v26, v36, v37
	v_cvt_pk_bf16_f32 v27, v38, v39
	v_addc_co_u32_e32 v29, vcc, 0, v161, vcc
	v_pk_mul_f32 v[22:23], v[22:23], v[34:35] op_sel_hi:[1,0]
	v_pk_mul_f32 v[20:21], v[20:21], v[34:35] op_sel_hi:[1,0]
	v_pk_mul_f32 v[18:19], v[18:19], v[34:35] op_sel_hi:[1,0]
	v_max_f32_e32 v16, 0, v16
	v_max_f32_e32 v17, 0, v17
	global_store_dwordx4 v[28:29], v[24:27], off
	v_max_f32_e32 v20, 0, v20
	v_max_f32_e32 v21, 0, v21
	v_pk_mul_f32 v[24:25], v[16:17], v[16:17]
	v_max_f32_e32 v16, 0, v22
	v_max_f32_e32 v18, 0, v18
	v_max_f32_e32 v17, 0, v23
	v_max_f32_e32 v19, 0, v19
	v_pk_mul_f32 v[20:21], v[20:21], v[20:21]
	v_pk_mul_f32 v[22:23], v[16:17], v[16:17]
	v_pk_mul_f32 v[26:27], v[18:19], v[18:19]
	v_lshl_add_u64 v[32:33], v[160:161], 0, s[14:15]
	v_cvt_pk_bf16_f32 v16, v20, v21
	v_cvt_pk_bf16_f32 v17, v22, v23
	v_cvt_pk_bf16_f32 v18, v24, v25
	v_cvt_pk_bf16_f32 v19, v26, v27
	global_store_dwordx4 v[32:33], v[16:19], off offset:256
	s_nop 1
	v_mov_b32_e32 v16, v199
	s_mov_b32 s5, 0x160000
	s_mov_b64 s[14:15], 0x160000
	v_lshl_add_u64 v[18:19], v[160:161], 0, s[14:15]
	v_fmamk_f32 v16, v16, 0x3a800000, v187
	v_cmp_gt_f32_e32 vcc, s67, v16
	v_mul_f32_e32 v17, 0x4b800000, v16
	s_nop 0
	v_cndmask_b32_e32 v16, v16, v17, vcc
	v_rsq_f32_e32 v16, v16
	s_nop 0
	v_mul_f32_e32 v17, 0x45800000, v16
	v_cndmask_b32_e32 v16, v16, v17, vcc
	v_pk_mul_f32 v[12:13], v[12:13], v[16:17] op_sel_hi:[1,0]
	v_pk_mul_f32 v[8:9], v[8:9], v[16:17] op_sel_hi:[1,0]
	v_pk_mul_f32 v[14:15], v[14:15], v[16:17] op_sel_hi:[1,0]
	v_pk_mul_f32 v[10:11], v[10:11], v[16:17] op_sel_hi:[1,0]
	v_max_f32_e32 v12, 0, v12
	v_max_f32_e32 v8, 0, v8
	v_max_f32_e32 v13, 0, v13
	v_max_f32_e32 v9, 0, v9
	v_pk_mul_f32 v[12:13], v[12:13], v[12:13]
	v_pk_mul_f32 v[20:21], v[8:9], v[8:9]
	v_max_f32_e32 v8, 0, v14
	v_max_f32_e32 v10, 0, v10
	v_max_f32_e32 v9, 0, v15
	v_max_f32_e32 v11, 0, v11
	v_pk_mul_f32 v[14:15], v[8:9], v[8:9]
	v_pk_mul_f32 v[22:23], v[10:11], v[10:11]
	v_cvt_pk_bf16_f32 v8, v12, v13
	v_add_co_u32_e32 v12, vcc, s5, v160
	v_pk_mul_f32 v[0:1], v[0:1], v[16:17] op_sel_hi:[1,0]
	v_cvt_pk_bf16_f32 v9, v14, v15
	v_cvt_pk_bf16_f32 v10, v20, v21
	v_cvt_pk_bf16_f32 v11, v22, v23
	v_addc_co_u32_e32 v13, vcc, 0, v161, vcc
	v_pk_mul_f32 v[6:7], v[6:7], v[16:17] op_sel_hi:[1,0]
	v_pk_mul_f32 v[4:5], v[4:5], v[16:17] op_sel_hi:[1,0]
	v_pk_mul_f32 v[2:3], v[2:3], v[16:17] op_sel_hi:[1,0]
	v_max_f32_e32 v0, 0, v0
	v_max_f32_e32 v1, 0, v1
	global_store_dwordx4 v[12:13], v[8:11], off
	v_max_f32_e32 v4, 0, v4
	v_max_f32_e32 v5, 0, v5
	v_pk_mul_f32 v[8:9], v[0:1], v[0:1]
	v_max_f32_e32 v0, 0, v6
	v_max_f32_e32 v2, 0, v2
	v_max_f32_e32 v1, 0, v7
	v_max_f32_e32 v3, 0, v3
	v_pk_mul_f32 v[4:5], v[4:5], v[4:5]
	v_pk_mul_f32 v[6:7], v[0:1], v[0:1]
	v_pk_mul_f32 v[10:11], v[2:3], v[2:3]
	v_cvt_pk_bf16_f32 v0, v4, v5
	v_cvt_pk_bf16_f32 v1, v6, v7
	v_cvt_pk_bf16_f32 v2, v8, v9
	v_cvt_pk_bf16_f32 v3, v10, v11
	s_and_b64 vcc, exec, s[38:39]
	global_store_dwordx4 v[18:19], v[0:3], off offset:256
	s_cbranch_vccz .LBB0_41
	s_cmpk_gt_u32 s36, 0xff
	s_cbranch_scc1 .LBB0_48
	s_barrier

; #define PG8_STAGE(bufoff, gbase, voff) do { _Pragma("unroll") for (int _i = 0; _i < 2; ++_i) \
;         __builtin_amdgcn_global_load_lds((const unsigned*)((const char*)(gbase) + (voff)[_i]), (PG8_LAS unsigned*)(lds + (bufoff) + ldsw + _i * 8192), 16, 0, 0); } while (0)
; #define PG8_LDA(dst, b, h) do { _Pragma("unroll") for (int m = 0; m < 4; ++m) _Pragma("unroll") for (int k = 0; k < 2; ++k) dst[m][k] = *(const PG8_LAS bf16x8*)(lds + PG8_SA(b, h) + aoff + m * 2048 + k * 1024); } while (0)
; #define PG8_LDB(dst, b, h) do { _Pragma("unroll") for (int n = 0; n < 2; ++n) _Pragma("unroll") for (int k = 0; k < 2; ++k) dst[n][k] = *(const PG8_LAS bf16x8*)(lds + PG8_SB(b, h) + boff + n * 2048 + k * 1024); } while (0)
; #define PG8_MMA(ai, bj, At, Bt) do { __builtin_amdgcn_s_setprio(1); _Pragma("unroll") for (int m = 0; m < 4; ++m) _Pragma("unroll") for (int n = 0; n < 2; ++n) _Pragma("unroll") for (int k = 0; k < 2; ++k) \
;         acc[ai][bj][m][n] = __builtin_amdgcn_mfma_f32_16x16x32_bf16(Bt[n][k], At[m][k], acc[ai][bj][m][n], 0, 0, 0); __builtin_amdgcn_s_setprio(0); } while (0)
; #define PG8_WAIT_V(n) asm volatile("s_waitcnt vmcnt(" #n ")" ::: "memory")
; #define PG8_WAIT_L(n) asm volatile("s_waitcnt lgkmcnt(" #n ")" ::: "memory")
; #define PG8_BAR __builtin_amdgcn_s_barrier()
; #define PG8_SCHED __builtin_amdgcn_sched_barrier(0)
; template <class Epi, class Sched, bool STAMP = false>
; __device__ __forceinline__ void gemm_phase(PG8_LAS unsigned char* lds, const Gemm g, const Sched& S, const Epi& E, unsigned long long* stamps) {
;     ...
;             PG8_LDB(B0, 0, 0); PG8_SCHED; PG8_LDA(At, 0, 0); PG8_STAGE(PG8_SA(1, 1), a1 + hstep, voffA);
;             PG8_WAIT_L(8); PG8_BAR; PG8_WAIT_L(0); PG8_MMA(0, 0, At, B0); PG8_BAR; PG8_SCHED;
;             PG8_LDB(B1, 0, 1); PG8_STAGE(PG8_SB(0, 0), b2, voffB);
;             PG8_BAR; PG8_WAIT_L(0); PG8_MMA(0, 1, At, B1); PG8_BAR;
;             PG8_LDA(At, 0, 1); PG8_STAGE(PG8_SA(0, 0), a2, voffA);
;             PG8_BAR; PG8_WAIT_L(0); PG8_MMA(1, 0, At, B0); PG8_BAR; PG8_SCHED;
;             PG8_STAGE(PG8_SB(0, 1), b2 + hstep, voffB);
;             PG8_WAIT_V(6); PG8_BAR; PG8_MMA(1, 1, At, B1); PG8_BAR;
.LBB0_141:
	s_add_u32 s48, s44, 0x100
	s_addc_u32 s49, s45, 0
	s_add_i32 s14, 0, 0x10000
	ds_read_b128 v[156:159], v248
	ds_read_b128 v[160:163], v248 offset:1024
	ds_read_b128 v[170:173], v248 offset:2048
	ds_read_b128 v[174:177], v248 offset:3072
	s_cmp_eq_u32 s39, 12
	s_cselect_b32 s59, s23, s49
	s_cselect_b32 s58, s31, s48
	s_cselect_b32 s57, s21, s38
	s_cselect_b32 s56, vcc_lo, vcc_hi
	s_add_i32 m0, s37, 0xc000
	ds_read_b128 v[178:181], v168
	ds_read_b128 v[192:195], v168 offset:1024
	ds_read_b128 v[196:199], v168 offset:2048
	ds_read_b128 v[200:203], v168 offset:3072
	ds_read_b128 v[204:207], v168 offset:4096
	ds_read_b128 v[208:211], v168 offset:5120
	ds_read_b128 v[212:215], v168 offset:6144
	global_load_lds_dwordx4 v152, s[44:45]
	s_add_i32 m0, s37, 0xe000
	ds_read_b128 v[216:219], v168 offset:7168
	global_load_lds_dwordx4 v154, s[44:45]
	s_waitcnt lgkmcnt(8)
	s_barrier
	s_waitcnt lgkmcnt(0)
	v_mfma_f32_16x16x32_bf16 v[124:127], v[156:159], v[178:181], v[124:127]
	v_mfma_f32_16x16x32_bf16 v[120:123], v[170:173], v[178:181], v[120:123]
	v_mfma_f32_16x16x32_bf16 v[108:111], v[156:159], v[196:199], v[108:111]
	v_mfma_f32_16x16x32_bf16 v[104:107], v[170:173], v[196:199], v[104:107]
	v_mfma_f32_16x16x32_bf16 v[92:95], v[156:159], v[204:207], v[92:95]
	v_mfma_f32_16x16x32_bf16 v[88:91], v[170:173], v[204:207], v[88:91]
	v_mfma_f32_16x16x32_bf16 v[76:79], v[156:159], v[212:215], v[76:79]
	v_mfma_f32_16x16x32_bf16 v[72:75], v[170:173], v[212:215], v[72:75]
	v_mfma_f32_16x16x32_bf16 v[124:127], v[160:163], v[192:195], v[124:127]
	v_mfma_f32_16x16x32_bf16 v[120:123], v[174:177], v[192:195], v[120:123]
	v_mfma_f32_16x16x32_bf16 v[108:111], v[160:163], v[200:203], v[108:111]
	v_mfma_f32_16x16x32_bf16 v[104:107], v[174:177], v[200:203], v[104:107]
	v_mfma_f32_16x16x32_bf16 v[92:95], v[160:163], v[208:211], v[92:95]
	v_mfma_f32_16x16x32_bf16 v[88:91], v[174:177], v[208:211], v[88:91]
	v_mfma_f32_16x16x32_bf16 v[76:79], v[160:163], v[216:219], v[76:79]
	v_mfma_f32_16x16x32_bf16 v[72:75], v[174:177], v[216:219], v[72:75]
	s_barrier
	s_add_i32 s16, 0, 0x14000
	s_add_i32 s14, s14, s64
	s_mov_b32 m0, s14
	ds_read_b128 v[220:223], v249
	ds_read_b128 v[224:227], v249 offset:1024
	ds_read_b128 v[228:231], v249 offset:2048
	global_load_lds_dwordx4 v148, s[56:57]
	s_add_i32 m0, s14, 0x2000
	ds_read_b128 v[232:235], v249 offset:3072
	global_load_lds_dwordx4 v150, s[56:57]
	s_barrier
	s_waitcnt lgkmcnt(0)
	v_mfma_f32_16x16x32_bf16 v[116:119], v[220:223], v[178:181], v[116:119]
	v_mfma_f32_16x16x32_bf16 v[112:115], v[228:231], v[178:181], v[112:115]
	v_mfma_f32_16x16x32_bf16 v[100:103], v[220:223], v[196:199], v[100:103]
	v_mfma_f32_16x16x32_bf16 v[96:99], v[228:231], v[196:199], v[96:99]
	v_mfma_f32_16x16x32_bf16 v[84:87], v[220:223], v[204:207], v[84:87]
	v_mfma_f32_16x16x32_bf16 v[80:83], v[228:231], v[204:207], v[80:83]
	v_mfma_f32_16x16x32_bf16 v[68:71], v[220:223], v[212:215], v[68:71]
	v_mfma_f32_16x16x32_bf16 v[64:67], v[228:231], v[212:215], v[64:67]
	v_mfma_f32_16x16x32_bf16 v[116:119], v[224:227], v[192:195], v[116:119]
	v_mfma_f32_16x16x32_bf16 v[112:115], v[232:235], v[192:195], v[112:115]
	v_mfma_f32_16x16x32_bf16 v[100:103], v[224:227], v[200:203], v[100:103]
	v_mfma_f32_16x16x32_bf16 v[96:99], v[232:235], v[200:203], v[96:99]
	v_mfma_f32_16x16x32_bf16 v[84:87], v[224:227], v[208:211], v[84:87]
	v_mfma_f32_16x16x32_bf16 v[80:83], v[232:235], v[208:211], v[80:83]
	v_mfma_f32_16x16x32_bf16 v[68:71], v[224:227], v[216:219], v[68:71]
	v_mfma_f32_16x16x32_bf16 v[64:67], v[232:235], v[216:219], v[64:67]
	s_mov_b32 m0, s37
	s_barrier
	ds_read_b128 v[178:181], v168 offset:16384
	ds_read_b128 v[192:195], v168 offset:17408
	ds_read_b128 v[196:199], v168 offset:18432
	ds_read_b128 v[200:203], v168 offset:19456
	ds_read_b128 v[204:207], v168 offset:20480
	ds_read_b128 v[208:211], v168 offset:21504
	ds_read_b128 v[212:215], v168 offset:22528
	global_load_lds_dwordx4 v148, s[58:59]
	s_mov_b32 m0, s65
	ds_read_b128 v[216:219], v168 offset:23552
	global_load_lds_dwordx4 v150, s[58:59]
	s_barrier
	s_waitcnt lgkmcnt(0)
	v_mfma_f32_16x16x32_bf16 v[60:63], v[156:159], v[178:181], v[60:63]
	v_mfma_f32_16x16x32_bf16 v[56:59], v[170:173], v[178:181], v[56:59]
	v_mfma_f32_16x16x32_bf16 v[44:47], v[156:159], v[196:199], v[44:47]
	v_mfma_f32_16x16x32_bf16 v[40:43], v[170:173], v[196:199], v[40:43]
	v_mfma_f32_16x16x32_bf16 v[28:31], v[156:159], v[204:207], v[28:31]
	v_mfma_f32_16x16x32_bf16 v[24:27], v[170:173], v[204:207], v[24:27]
	v_mfma_f32_16x16x32_bf16 v[12:15], v[156:159], v[212:215], v[12:15]
	v_mfma_f32_16x16x32_bf16 v[8:11], v[170:173], v[212:215], v[8:11]
	v_mfma_f32_16x16x32_bf16 v[60:63], v[160:163], v[192:195], v[60:63]
	v_mfma_f32_16x16x32_bf16 v[56:59], v[174:177], v[192:195], v[56:59]
	v_mfma_f32_16x16x32_bf16 v[44:47], v[160:163], v[200:203], v[44:47]
	v_mfma_f32_16x16x32_bf16 v[40:43], v[174:177], v[200:203], v[40:43]
	v_mfma_f32_16x16x32_bf16 v[28:31], v[160:163], v[208:211], v[28:31]
	v_mfma_f32_16x16x32_bf16 v[24:27], v[174:177], v[208:211], v[24:27]
	v_mfma_f32_16x16x32_bf16 v[12:15], v[160:163], v[216:219], v[12:15]
	v_mfma_f32_16x16x32_bf16 v[8:11], v[174:177], v[216:219], v[8:11]
	s_barrier
	s_add_u32 s14, s56, 0x40000
	s_addc_u32 s15, s57, 0
	s_add_i32 s16, s16, s64
	s_mov_b32 m0, s16
	s_nop 0
	global_load_lds_dwordx4 v148, s[14:15]
	s_add_i32 m0, s16, 0x2000
	s_nop 0
	global_load_lds_dwordx4 v150, s[14:15]
	s_waitcnt vmcnt(6)
	s_barrier
; #define PG8_STAGE(bufoff, gbase, voff) do { _Pragma("unroll") for (int _i = 0; _i < 2; ++_i) \
;         __builtin_amdgcn_global_load_lds((const unsigned*)((const char*)(gbase) + (voff)[_i]), (PG8_LAS unsigned*)(lds + (bufoff) + ldsw + _i * 8192), 16, 0, 0); } while (0)
; #define PG8_LDA(dst, b, h) do { _Pragma("unroll") for (int m = 0; m < 4; ++m) _Pragma("unroll") for (int k = 0; k < 2; ++k) dst[m][k] = *(const PG8_LAS bf16x8*)(lds + PG8_SA(b, h) + aoff + m * 2048 + k * 1024); } while (0)
; #define PG8_LDB(dst, b, h) do { _Pragma("unroll") for (int n = 0; n < 2; ++n) _Pragma("unroll") for (int k = 0; k < 2; ++k) dst[n][k] = *(const PG8_LAS bf16x8*)(lds + PG8_SB(b, h) + boff + n * 2048 + k * 1024); } while (0)
; #define PG8_MMA(ai, bj, At, Bt) do { __builtin_amdgcn_s_setprio(1); _Pragma("unroll") for (int m = 0; m < 4; ++m) _Pragma("unroll") for (int n = 0; n < 2; ++n) _Pragma("unroll") for (int k = 0; k < 2; ++k) \
;         acc[ai][bj][m][n] = __builtin_amdgcn_mfma_f32_16x16x32_bf16(Bt[n][k], At[m][k], acc[ai][bj][m][n], 0, 0, 0); __builtin_amdgcn_s_setprio(0); } while (0)
; #define PG8_WAIT_V(n) asm volatile("s_waitcnt vmcnt(" #n ")" ::: "memory")
; #define PG8_WAIT_L(n) asm volatile("s_waitcnt lgkmcnt(" #n ")" ::: "memory")
; #define PG8_BAR __builtin_amdgcn_s_barrier()
; #define PG8_SCHED __builtin_amdgcn_sched_barrier(0)
; template <class Epi, class Sched, bool STAMP = false>
; __device__ __forceinline__ void gemm_phase(PG8_LAS unsigned char* lds, const Gemm g, const Sched& S, const Epi& E, unsigned long long* stamps) {
;     ...
;             PG8_WAIT_V(6); PG8_BAR; PG8_MMA(1, 1, At, B1); PG8_BAR;
;             PG8_LDB(B0, 1, 0); PG8_SCHED; PG8_LDA(At, 1, 0); PG8_STAGE(PG8_SA(0, 1), a2 + hstep, voffA);
;             PG8_WAIT_L(8); PG8_BAR; PG8_WAIT_L(0); PG8_MMA(0, 0, At, B0); PG8_BAR; PG8_SCHED;
;             PG8_LDB(B1, 1, 1); PG8_STAGE(PG8_SB(1, 0), b3, voffB);
;             PG8_BAR; PG8_WAIT_L(0); PG8_MMA(0, 1, At, B1); PG8_BAR;
;             PG8_LDA(At, 1, 1); PG8_STAGE(PG8_SA(1, 0), a3, voffA);
	v_mfma_f32_16x16x32_bf16 v[52:55], v[220:223], v[178:181], v[52:55]
	v_mfma_f32_16x16x32_bf16 v[48:51], v[228:231], v[178:181], v[48:51]
	v_mfma_f32_16x16x32_bf16 v[36:39], v[220:223], v[196:199], v[36:39]
	v_mfma_f32_16x16x32_bf16 v[32:35], v[228:231], v[196:199], v[32:35]
	v_mfma_f32_16x16x32_bf16 v[20:23], v[220:223], v[204:207], v[20:23]
	v_mfma_f32_16x16x32_bf16 v[16:19], v[228:231], v[204:207], v[16:19]
	v_mfma_f32_16x16x32_bf16 v[4:7], v[220:223], v[212:215], v[4:7]
	v_mfma_f32_16x16x32_bf16 v[0:3], v[228:231], v[212:215], v[0:3]
	v_mfma_f32_16x16x32_bf16 v[52:55], v[224:227], v[192:195], v[52:55]
	v_mfma_f32_16x16x32_bf16 v[48:51], v[232:235], v[192:195], v[48:51]
	v_mfma_f32_16x16x32_bf16 v[36:39], v[224:227], v[200:203], v[36:39]
	v_mfma_f32_16x16x32_bf16 v[32:35], v[232:235], v[200:203], v[32:35]
	v_mfma_f32_16x16x32_bf16 v[20:23], v[224:227], v[208:211], v[20:23]
	v_mfma_f32_16x16x32_bf16 v[16:19], v[232:235], v[208:211], v[16:19]
	v_mfma_f32_16x16x32_bf16 v[4:7], v[224:227], v[216:219], v[4:7]
	v_mfma_f32_16x16x32_bf16 v[0:3], v[232:235], v[216:219], v[0:3]
	s_add_i32 s16, 0, 0x18000
	s_barrier
	ds_read_b128 v[156:159], v250
	ds_read_b128 v[160:163], v250 offset:1024
	ds_read_b128 v[170:173], v250 offset:2048
	ds_read_b128 v[174:177], v250 offset:3072
	s_add_u32 s14, s58, 0x40000
	s_addc_u32 s15, s59, 0
	s_mov_b32 m0, s76
	ds_read_b128 v[178:181], v168 offset:32768
	ds_read_b128 v[192:195], v168 offset:33792
	ds_read_b128 v[196:199], v168 offset:34816
	ds_read_b128 v[200:203], v168 offset:35840
	ds_read_b128 v[204:207], v168 offset:36864
	ds_read_b128 v[208:211], v168 offset:37888
	ds_read_b128 v[212:215], v168 offset:38912
	global_load_lds_dwordx4 v148, s[14:15]
	s_mov_b32 m0, s77
	ds_read_b128 v[216:219], v168 offset:39936
	global_load_lds_dwordx4 v150, s[14:15]
	s_waitcnt lgkmcnt(8)
	s_barrier
	s_waitcnt lgkmcnt(0)
	v_mfma_f32_16x16x32_bf16 v[124:127], v[156:159], v[178:181], v[124:127]
	v_mfma_f32_16x16x32_bf16 v[120:123], v[170:173], v[178:181], v[120:123]
	v_mfma_f32_16x16x32_bf16 v[108:111], v[156:159], v[196:199], v[108:111]
	v_mfma_f32_16x16x32_bf16 v[104:107], v[170:173], v[196:199], v[104:107]
	v_mfma_f32_16x16x32_bf16 v[92:95], v[156:159], v[204:207], v[92:95]
	v_mfma_f32_16x16x32_bf16 v[88:91], v[170:173], v[204:207], v[88:91]
	v_mfma_f32_16x16x32_bf16 v[76:79], v[156:159], v[212:215], v[76:79]
	v_mfma_f32_16x16x32_bf16 v[72:75], v[170:173], v[212:215], v[72:75]
	v_mfma_f32_16x16x32_bf16 v[124:127], v[160:163], v[192:195], v[124:127]
	v_mfma_f32_16x16x32_bf16 v[120:123], v[174:177], v[192:195], v[120:123]
	v_mfma_f32_16x16x32_bf16 v[108:111], v[160:163], v[200:203], v[108:111]
	v_mfma_f32_16x16x32_bf16 v[104:107], v[174:177], v[200:203], v[104:107]
	v_mfma_f32_16x16x32_bf16 v[92:95], v[160:163], v[208:211], v[92:95]
	v_mfma_f32_16x16x32_bf16 v[88:91], v[174:177], v[208:211], v[88:91]
	v_mfma_f32_16x16x32_bf16 v[76:79], v[160:163], v[216:219], v[76:79]
	v_mfma_f32_16x16x32_bf16 v[72:75], v[174:177], v[216:219], v[72:75]
	s_barrier
	s_add_i32 s17, 0, 0x1c000
	s_add_i32 s14, s16, s64
	s_mov_b32 m0, s14
	ds_read_b128 v[220:223], v251
	ds_read_b128 v[224:227], v251 offset:1024
	ds_read_b128 v[228:231], v251 offset:2048
	global_load_lds_dwordx4 v244, s[56:57]
	s_add_i32 m0, s14, 0x2000
	ds_read_b128 v[232:235], v251 offset:3072
	global_load_lds_dwordx4 v245, s[56:57]
	s_barrier
	s_waitcnt lgkmcnt(0)
	v_mfma_f32_16x16x32_bf16 v[116:119], v[220:223], v[178:181], v[116:119]
	v_mfma_f32_16x16x32_bf16 v[112:115], v[228:231], v[178:181], v[112:115]
	v_mfma_f32_16x16x32_bf16 v[100:103], v[220:223], v[196:199], v[100:103]
	v_mfma_f32_16x16x32_bf16 v[96:99], v[228:231], v[196:199], v[96:99]
	v_mfma_f32_16x16x32_bf16 v[84:87], v[220:223], v[204:207], v[84:87]
	v_mfma_f32_16x16x32_bf16 v[80:83], v[228:231], v[204:207], v[80:83]
	v_mfma_f32_16x16x32_bf16 v[68:71], v[220:223], v[212:215], v[68:71]
	v_mfma_f32_16x16x32_bf16 v[64:67], v[228:231], v[212:215], v[64:67]
	v_mfma_f32_16x16x32_bf16 v[116:119], v[224:227], v[192:195], v[116:119]
	v_mfma_f32_16x16x32_bf16 v[112:115], v[232:235], v[192:195], v[112:115]
	v_mfma_f32_16x16x32_bf16 v[100:103], v[224:227], v[200:203], v[100:103]
	v_mfma_f32_16x16x32_bf16 v[96:99], v[232:235], v[200:203], v[96:99]
	v_mfma_f32_16x16x32_bf16 v[84:87], v[224:227], v[208:211], v[84:87]
	v_mfma_f32_16x16x32_bf16 v[80:83], v[232:235], v[208:211], v[80:83]
	v_mfma_f32_16x16x32_bf16 v[68:71], v[224:227], v[216:219], v[68:71]
	v_mfma_f32_16x16x32_bf16 v[64:67], v[232:235], v[216:219], v[64:67]
	s_mov_b32 m0, s88
	s_barrier
; #define PG8_STAGE(bufoff, gbase, voff) do { _Pragma("unroll") for (int _i = 0; _i < 2; ++_i) \
;         __builtin_amdgcn_global_load_lds((const unsigned*)((const char*)(gbase) + (voff)[_i]), (PG8_LAS unsigned*)(lds + (bufoff) + ldsw + _i * 8192), 16, 0, 0); } while (0)
; #define PG8_LDA(dst, b, h) do { _Pragma("unroll") for (int m = 0; m < 4; ++m) _Pragma("unroll") for (int k = 0; k < 2; ++k) dst[m][k] = *(const PG8_LAS bf16x8*)(lds + PG8_SA(b, h) + aoff + m * 2048 + k * 1024); } while (0)
; #define PG8_MMA(ai, bj, At, Bt) do { __builtin_amdgcn_s_setprio(1); _Pragma("unroll") for (int m = 0; m < 4; ++m) _Pragma("unroll") for (int n = 0; n < 2; ++n) _Pragma("unroll") for (int k = 0; k < 2; ++k) \
;         acc[ai][bj][m][n] = __builtin_amdgcn_mfma_f32_16x16x32_bf16(Bt[n][k], At[m][k], acc[ai][bj][m][n], 0, 0, 0); __builtin_amdgcn_s_setprio(0); } while (0)
; #define PG8_WAIT_V(n) asm volatile("s_waitcnt vmcnt(" #n ")" ::: "memory")
; #define PG8_WAIT_L(n) asm volatile("s_waitcnt lgkmcnt(" #n ")" ::: "memory")
; #define PG8_BAR __builtin_amdgcn_s_barrier()
; #define PG8_SCHED __builtin_amdgcn_sched_barrier(0)
; template <class Epi, class Sched, bool STAMP = false>
; __device__ __forceinline__ void gemm_phase(PG8_LAS unsigned char* lds, const Gemm g, const Sched& S, const Epi& E, unsigned long long* stamps) {
;     ...
;             PG8_LDA(At, 1, 1); PG8_STAGE(PG8_SA(1, 0), a3, voffA);
;             PG8_BAR; PG8_WAIT_L(0); PG8_MMA(1, 0, At, B0); PG8_BAR; PG8_SCHED;
;             PG8_STAGE(PG8_SB(1, 1), b3 + hstep, voffB);
;             PG8_WAIT_V(6); PG8_BAR; PG8_MMA(1, 1, At, B1); PG8_BAR;
;     __device__ __forceinline__ void operator()(const f32x4 (&acc)[2][2][4][2], const pg8::Unit& u, int wr, int wc, int fr, int fq) const {
;         const int row0 = u.pm * 256 + wr * 64 + fr, col0 = u.pn * 256 + wc * 32 + 4 * fq;
; #pragma unroll
;         for (int ai = 0; ai < 2; ++ai)
; #pragma unroll
;             for (int m = 0; m < 4; ++m) {
;                 const int row = row0 + ai * 128 + m * 16;
;                 float* xp = X + (size_t)row * 1024 + col0; bf16_t* bp = XB + (size_t)row * 1024 + col0;
;                 const float* xi = Xp0 ? (row < T_P ? Xp0 + (size_t)row * 1024 + col0 : Xs0 + (size_t)(row - T_P) * 1024 + col0) : xp;
	ds_read_b128 v[178:181], v168 offset:49152
	ds_read_b128 v[192:195], v168 offset:50176
	ds_read_b128 v[196:199], v168 offset:51200
	ds_read_b128 v[200:203], v168 offset:52224
	ds_read_b128 v[204:207], v168 offset:53248
	ds_read_b128 v[208:211], v168 offset:54272
	ds_read_b128 v[212:215], v168 offset:55296
	global_load_lds_dwordx4 v244, s[58:59]
	s_mov_b32 m0, s89
	ds_read_b128 v[216:219], v168 offset:56320
	global_load_lds_dwordx4 v245, s[58:59]
	s_barrier
	s_waitcnt lgkmcnt(0)
	v_mfma_f32_16x16x32_bf16 v[60:63], v[156:159], v[178:181], v[60:63]
	v_mfma_f32_16x16x32_bf16 v[56:59], v[170:173], v[178:181], v[56:59]
	v_mfma_f32_16x16x32_bf16 v[44:47], v[156:159], v[196:199], v[44:47]
	v_mfma_f32_16x16x32_bf16 v[40:43], v[170:173], v[196:199], v[40:43]
	v_mfma_f32_16x16x32_bf16 v[28:31], v[156:159], v[204:207], v[28:31]
	v_mfma_f32_16x16x32_bf16 v[24:27], v[170:173], v[204:207], v[24:27]
	v_mfma_f32_16x16x32_bf16 v[12:15], v[156:159], v[212:215], v[12:15]
	v_mfma_f32_16x16x32_bf16 v[8:11], v[170:173], v[212:215], v[8:11]
	v_mfma_f32_16x16x32_bf16 v[60:63], v[160:163], v[192:195], v[60:63]
	v_mfma_f32_16x16x32_bf16 v[56:59], v[174:177], v[192:195], v[56:59]
	v_mfma_f32_16x16x32_bf16 v[44:47], v[160:163], v[200:203], v[44:47]
	v_mfma_f32_16x16x32_bf16 v[40:43], v[174:177], v[200:203], v[40:43]
	v_mfma_f32_16x16x32_bf16 v[28:31], v[160:163], v[208:211], v[28:31]
	v_mfma_f32_16x16x32_bf16 v[24:27], v[174:177], v[208:211], v[24:27]
	v_mfma_f32_16x16x32_bf16 v[12:15], v[160:163], v[216:219], v[12:15]
	v_mfma_f32_16x16x32_bf16 v[8:11], v[174:177], v[216:219], v[8:11]
	s_barrier
	s_add_u32 s14, s56, 0x40080
	s_addc_u32 s15, s57, 0
	s_add_i32 s16, s17, s64
	s_mov_b32 m0, s16
	s_nop 0
	global_load_lds_dwordx4 v148, s[14:15]
	s_add_i32 m0, s16, 0x2000
	s_nop 0
	global_load_lds_dwordx4 v150, s[14:15]
	s_waitcnt vmcnt(6)
	s_barrier
	v_mfma_f32_16x16x32_bf16 v[52:55], v[220:223], v[178:181], v[52:55]
	v_mfma_f32_16x16x32_bf16 v[48:51], v[228:231], v[178:181], v[48:51]
	v_mfma_f32_16x16x32_bf16 v[36:39], v[220:223], v[196:199], v[36:39]
	v_mfma_f32_16x16x32_bf16 v[32:35], v[228:231], v[196:199], v[32:35]
	v_mfma_f32_16x16x32_bf16 v[20:23], v[220:223], v[204:207], v[20:23]
	v_mfma_f32_16x16x32_bf16 v[16:19], v[228:231], v[204:207], v[16:19]
	v_mfma_f32_16x16x32_bf16 v[4:7], v[220:223], v[212:215], v[4:7]
	v_mfma_f32_16x16x32_bf16 v[0:3], v[228:231], v[212:215], v[0:3]
	v_mfma_f32_16x16x32_bf16 v[52:55], v[224:227], v[192:195], v[52:55]
	v_mfma_f32_16x16x32_bf16 v[48:51], v[232:235], v[192:195], v[48:51]
	v_mfma_f32_16x16x32_bf16 v[36:39], v[224:227], v[200:203], v[36:39]
	v_mfma_f32_16x16x32_bf16 v[32:35], v[232:235], v[200:203], v[32:35]
	v_mfma_f32_16x16x32_bf16 v[20:23], v[224:227], v[208:211], v[20:23]
	v_mfma_f32_16x16x32_bf16 v[16:19], v[232:235], v[208:211], v[16:19]
	v_mfma_f32_16x16x32_bf16 v[4:7], v[224:227], v[216:219], v[4:7]
	v_mfma_f32_16x16x32_bf16 v[0:3], v[232:235], v[216:219], v[0:3]
	s_add_i32 s39, s39, 2
	s_add_u32 vcc_hi, vcc_hi, 0x100
	s_addc_u32 s38, s38, 0
	s_cmp_gt_u32 s39, 13
	s_mov_b64 s[44:45], s[48:49]
	s_barrier
	s_cbranch_scc0 .LBB0_141
	v_lshl_add_u32 v158, s30, 8, v139
	v_ashrrev_i32_e32 v159, 31, v158
	v_lshl_or_b32 v156, s36, 8, v167
	v_lshlrev_b64 v[160:161], 12, v[158:159]
	v_ashrrev_i32_e32 v157, 31, v156
	v_lshl_add_u64 v[160:161], s[84:85], 0, v[160:161]
	v_lshl_add_u64 v[160:161], v[156:157], 2, v[160:161]
	v_cndmask_b32_e64 v128, 0, 1, s[12:13]
	v_lshlrev_b64 v[164:165], 10, v[158:159]
	v_cmp_ne_u32_e64 s[44:45], 1, v128
	s_andn2_b64 vcc, exec, s[12:13]
	v_mov_b64_e32 v[162:163], v[160:161]
	v_readlane_b32 s39, v242, 28
	s_movk_i32 s21, 0x3fff
	s_mov_b32 s38, 0x1ffff
	s_cbranch_vccnz .LBB0_148
	v_cmp_lt_i32_e32 vcc, s21, v158
	s_and_saveexec_b64 s[14:15], vcc
	s_xor_b64 s[30:31], exec, s[14:15]
	v_add_u32_e32 v128, 0xffffc000, v158
	v_lshlrev_b64 v[162:163], 12, v[128:129]
	v_lshl_add_u64 v[162:163], s[4:5], 0, v[162:163]
	v_lshl_add_u64 v[162:163], v[156:157], 2, v[162:163]
	s_andn2_saveexec_b64 s[30:31], s[30:31]
	v_lshl_add_u64 v[162:163], v[164:165], 2, s[0:1]
	v_lshl_add_u64 v[162:163], v[156:157], 2, v[162:163]
	s_or_b64 exec, exec, s[30:31]

; #define PG8_STAGE(bufoff, gbase, voff) do { _Pragma("unroll") for (int _i = 0; _i < 2; ++_i) \
;         __builtin_amdgcn_global_load_lds((const unsigned*)((const char*)(gbase) + (voff)[_i]), (PG8_LAS unsigned*)(lds + (bufoff) + ldsw + _i * 8192), 16, 0, 0); } while (0)
; #define PG8_LDA(dst, b, h) do { _Pragma("unroll") for (int m = 0; m < 4; ++m) _Pragma("unroll") for (int k = 0; k < 2; ++k) dst[m][k] = *(const PG8_LAS bf16x8*)(lds + PG8_SA(b, h) + aoff + m * 2048 + k * 1024); } while (0)
; #define PG8_LDB(dst, b, h) do { _Pragma("unroll") for (int n = 0; n < 2; ++n) _Pragma("unroll") for (int k = 0; k < 2; ++k) dst[n][k] = *(const PG8_LAS bf16x8*)(lds + PG8_SB(b, h) + boff + n * 2048 + k * 1024); } while (0)
; #define PG8_MMA(ai, bj, At, Bt) do { __builtin_amdgcn_s_setprio(1); _Pragma("unroll") for (int m = 0; m < 4; ++m) _Pragma("unroll") for (int n = 0; n < 2; ++n) _Pragma("unroll") for (int k = 0; k < 2; ++k) \
;         acc[ai][bj][m][n] = __builtin_amdgcn_mfma_f32_16x16x32_bf16(Bt[n][k], At[m][k], acc[ai][bj][m][n], 0, 0, 0); __builtin_amdgcn_s_setprio(0); } while (0)
; #define PG8_WAIT_L(n) asm volatile("s_waitcnt lgkmcnt(" #n ")" ::: "memory")
; #define PG8_BAR __builtin_amdgcn_s_barrier()
; #define PG8_SCHED __builtin_amdgcn_sched_barrier(0)
; template <class Epi, class Sched, bool STAMP = false>
; __device__ __forceinline__ void gemm_phase(PG8_LAS unsigned char* lds, const Gemm g, const Sched& S, const Epi& E, unsigned long long* stamps) {
;     ...
;             PG8_LDB(B0, 0, 0); PG8_SCHED; PG8_LDA(At, 0, 0); PG8_STAGE(PG8_SA(1, 1), a1 + hstep, voffA);
;             PG8_WAIT_L(8); PG8_BAR; PG8_WAIT_L(0); PG8_MMA(0, 0, At, B0); PG8_BAR; PG8_SCHED;
;             PG8_LDB(B1, 0, 1); PG8_STAGE(PG8_SB(0, 0), b2, voffB);
;             PG8_BAR; PG8_WAIT_L(0); PG8_MMA(0, 1, At, B1); PG8_BAR;
;             PG8_LDA(At, 0, 1); PG8_STAGE(PG8_SA(0, 0), a2, voffA);
;             PG8_BAR; PG8_WAIT_L(0); PG8_MMA(1, 0, At, B0); PG8_BAR; PG8_SCHED;
;             PG8_STAGE(PG8_SB(0, 1), b2 + hstep, voffB);
.LBB0_213:
	s_add_i32 s15, s14, 0x100
	s_and_b64 s[16:17], s[20:21], exec
	s_cselect_b32 s15, 0, s15
	s_cselect_b32 s16, 0, 0
	s_add_u32 s26, s4, s15
	s_addc_u32 s27, s5, s16
	s_add_i32 s21, 0, 0x10000
	s_add_u32 s30, s0, s15
	s_addc_u32 s31, s1, s16
	s_add_u32 s36, s6, s14
	s_addc_u32 s37, s7, 0
	s_add_i32 s61, s21, s44
	s_add_i32 m0, s45, 0xc000
	s_add_i32 s62, s45, 0xe000
	s_add_i32 s60, 0, 0x14000
	s_add_i32 s59, s61, 0x2000
	s_add_u32 s24, s30, 0x40000
	s_addc_u32 s25, s31, 0
	s_add_i32 s38, s60, s44
	ds_read_b128 v[154:157], v248
	ds_read_b128 v[158:161], v248 offset:1024
	ds_read_b128 v[162:165], v248 offset:2048
	ds_read_b128 v[166:169], v248 offset:3072
	s_add_i32 s29, s38, 0x2000
	s_add_i32 s17, 0, 0x18000
	s_add_u32 s22, s26, 0x40000
	s_addc_u32 s23, s27, 0
	s_add_i32 s16, s17, s44
	s_add_i32 s15, 0, 0x1c000
	s_add_i32 s14, s16, 0x2000
	s_add_u32 s20, s30, 0x40080
	s_addc_u32 s21, s31, 0
	s_add_i32 s52, s15, s44
	s_add_i32 s39, s52, 0x2000
	v_lshl_add_u64 v[182:183], s[36:37], 0, v[128:129]
	v_lshl_add_u64 v[182:183], v[182:183], 0, s[18:19]
	ds_read_b128 v[170:173], v152
	ds_read_b128 v[174:177], v152 offset:1024
	ds_read_b128 v[178:181], v152 offset:2048
	ds_read_b128 v[192:195], v152 offset:3072
	ds_read_b128 v[196:199], v152 offset:4096
	ds_read_b128 v[200:203], v152 offset:5120
	ds_read_b128 v[204:207], v152 offset:6144
	ds_read_b128 v[208:211], v152 offset:7168
	global_load_lds_dwordx4 v244, s[36:37]
	v_lshl_add_u64 v[182:183], s[36:37], 0, v[148:149]
	v_lshl_add_u64 v[182:183], v[182:183], 0, s[18:19]
	s_mov_b32 m0, s62
	s_nop 0
	global_load_lds_dwordx4 v245, s[36:37]
	s_waitcnt lgkmcnt(8)
	s_barrier
	s_waitcnt lgkmcnt(0)
	v_mfma_f32_16x16x32_bf16 v[124:127], v[154:157], v[170:173], v[124:127]
	v_mfma_f32_16x16x32_bf16 v[120:123], v[162:165], v[170:173], v[120:123]
	v_mfma_f32_16x16x32_bf16 v[116:119], v[154:157], v[178:181], v[116:119]
	v_mfma_f32_16x16x32_bf16 v[112:115], v[162:165], v[178:181], v[112:115]
	v_mfma_f32_16x16x32_bf16 v[104:107], v[154:157], v[196:199], v[104:107]
	v_mfma_f32_16x16x32_bf16 v[96:99], v[162:165], v[196:199], v[96:99]
	v_mfma_f32_16x16x32_bf16 v[88:91], v[154:157], v[204:207], v[88:91]
	v_mfma_f32_16x16x32_bf16 v[80:83], v[162:165], v[204:207], v[80:83]
	v_mfma_f32_16x16x32_bf16 v[124:127], v[158:161], v[174:177], v[124:127]
	v_mfma_f32_16x16x32_bf16 v[120:123], v[166:169], v[174:177], v[120:123]
	v_mfma_f32_16x16x32_bf16 v[116:119], v[158:161], v[192:195], v[116:119]
	v_mfma_f32_16x16x32_bf16 v[112:115], v[166:169], v[192:195], v[112:115]
	v_mfma_f32_16x16x32_bf16 v[104:107], v[158:161], v[200:203], v[104:107]
	v_mfma_f32_16x16x32_bf16 v[96:99], v[166:169], v[200:203], v[96:99]
	v_mfma_f32_16x16x32_bf16 v[88:91], v[158:161], v[208:211], v[88:91]
	v_mfma_f32_16x16x32_bf16 v[80:83], v[166:169], v[208:211], v[80:83]
	s_barrier
	s_mov_b32 m0, s61
	v_lshl_add_u64 v[182:183], s[30:31], 0, v[128:129]
	ds_read_b128 v[212:215], v249
	ds_read_b128 v[216:219], v249 offset:1024
	ds_read_b128 v[220:223], v249 offset:2048
	ds_read_b128 v[224:227], v249 offset:3072
	global_load_lds_dwordx4 v128, s[30:31]
	v_lshl_add_u64 v[228:229], s[30:31], 0, v[148:149]
	s_mov_b32 m0, s59
	s_nop 0
	global_load_lds_dwordx4 v148, s[30:31]
	s_barrier
	s_waitcnt lgkmcnt(0)
	v_mfma_f32_16x16x32_bf16 v[108:111], v[212:215], v[170:173], v[108:111]
	v_mfma_f32_16x16x32_bf16 v[100:103], v[220:223], v[170:173], v[100:103]
	v_mfma_f32_16x16x32_bf16 v[92:95], v[212:215], v[178:181], v[92:95]
	v_mfma_f32_16x16x32_bf16 v[84:87], v[220:223], v[178:181], v[84:87]
	v_mfma_f32_16x16x32_bf16 v[76:79], v[212:215], v[196:199], v[76:79]
	v_mfma_f32_16x16x32_bf16 v[72:75], v[220:223], v[196:199], v[72:75]
	v_mfma_f32_16x16x32_bf16 v[68:71], v[212:215], v[204:207], v[68:71]
	v_mfma_f32_16x16x32_bf16 v[64:67], v[220:223], v[204:207], v[64:67]
	v_mfma_f32_16x16x32_bf16 v[108:111], v[216:219], v[174:177], v[108:111]
	v_mfma_f32_16x16x32_bf16 v[100:103], v[224:227], v[174:177], v[100:103]
	v_mfma_f32_16x16x32_bf16 v[92:95], v[216:219], v[192:195], v[92:95]
	v_mfma_f32_16x16x32_bf16 v[84:87], v[224:227], v[192:195], v[84:87]
	v_mfma_f32_16x16x32_bf16 v[76:79], v[216:219], v[200:203], v[76:79]
	v_mfma_f32_16x16x32_bf16 v[72:75], v[224:227], v[200:203], v[72:75]
	v_mfma_f32_16x16x32_bf16 v[68:71], v[216:219], v[208:211], v[68:71]
	v_mfma_f32_16x16x32_bf16 v[64:67], v[224:227], v[208:211], v[64:67]
	s_mov_b32 m0, s45
	v_lshl_add_u64 v[230:231], s[26:27], 0, v[128:129]
	s_barrier
	ds_read_b128 v[170:173], v152 offset:16384
	ds_read_b128 v[174:177], v152 offset:17408
	ds_read_b128 v[178:181], v152 offset:18432
	ds_read_b128 v[192:195], v152 offset:19456
	ds_read_b128 v[196:199], v152 offset:20480
	ds_read_b128 v[200:203], v152 offset:21504
	ds_read_b128 v[204:207], v152 offset:22528
	ds_read_b128 v[208:211], v152 offset:23552
	global_load_lds_dwordx4 v128, s[26:27]
	v_lshl_add_u64 v[232:233], s[26:27], 0, v[148:149]
	s_mov_b32 m0, s47
	s_nop 0
	global_load_lds_dwordx4 v148, s[26:27]
	s_barrier
	s_waitcnt lgkmcnt(0)
	v_mfma_f32_16x16x32_bf16 v[60:63], v[154:157], v[170:173], v[60:63]
	v_mfma_f32_16x16x32_bf16 v[56:59], v[162:165], v[170:173], v[56:59]
	v_mfma_f32_16x16x32_bf16 v[52:55], v[154:157], v[178:181], v[52:55]
	v_mfma_f32_16x16x32_bf16 v[48:51], v[162:165], v[178:181], v[48:51]
	v_mfma_f32_16x16x32_bf16 v[36:39], v[154:157], v[196:199], v[36:39]
	v_mfma_f32_16x16x32_bf16 v[32:35], v[162:165], v[196:199], v[32:35]
	v_mfma_f32_16x16x32_bf16 v[20:23], v[154:157], v[204:207], v[20:23]
	v_mfma_f32_16x16x32_bf16 v[16:19], v[162:165], v[204:207], v[16:19]
	v_mfma_f32_16x16x32_bf16 v[60:63], v[158:161], v[174:177], v[60:63]
	v_mfma_f32_16x16x32_bf16 v[56:59], v[166:169], v[174:177], v[56:59]
	v_mfma_f32_16x16x32_bf16 v[52:55], v[158:161], v[192:195], v[52:55]
	v_mfma_f32_16x16x32_bf16 v[48:51], v[166:169], v[192:195], v[48:51]
	v_mfma_f32_16x16x32_bf16 v[36:39], v[158:161], v[200:203], v[36:39]
	v_mfma_f32_16x16x32_bf16 v[32:35], v[166:169], v[200:203], v[32:35]
	v_mfma_f32_16x16x32_bf16 v[20:23], v[158:161], v[208:211], v[20:23]
	v_mfma_f32_16x16x32_bf16 v[16:19], v[166:169], v[208:211], v[16:19]
	s_barrier
; #define PG8_STAGE(bufoff, gbase, voff) do { _Pragma("unroll") for (int _i = 0; _i < 2; ++_i) \
;         __builtin_amdgcn_global_load_lds((const unsigned*)((const char*)(gbase) + (voff)[_i]), (PG8_LAS unsigned*)(lds + (bufoff) + ldsw + _i * 8192), 16, 0, 0); } while (0)
; #define PG8_LDA(dst, b, h) do { _Pragma("unroll") for (int m = 0; m < 4; ++m) _Pragma("unroll") for (int k = 0; k < 2; ++k) dst[m][k] = *(const PG8_LAS bf16x8*)(lds + PG8_SA(b, h) + aoff + m * 2048 + k * 1024); } while (0)
; #define PG8_LDB(dst, b, h) do { _Pragma("unroll") for (int n = 0; n < 2; ++n) _Pragma("unroll") for (int k = 0; k < 2; ++k) dst[n][k] = *(const PG8_LAS bf16x8*)(lds + PG8_SB(b, h) + boff + n * 2048 + k * 1024); } while (0)
; #define PG8_MMA(ai, bj, At, Bt) do { __builtin_amdgcn_s_setprio(1); _Pragma("unroll") for (int m = 0; m < 4; ++m) _Pragma("unroll") for (int n = 0; n < 2; ++n) _Pragma("unroll") for (int k = 0; k < 2; ++k) \
;         acc[ai][bj][m][n] = __builtin_amdgcn_mfma_f32_16x16x32_bf16(Bt[n][k], At[m][k], acc[ai][bj][m][n], 0, 0, 0); __builtin_amdgcn_s_setprio(0); } while (0)
; #define PG8_WAIT_V(n) asm volatile("s_waitcnt vmcnt(" #n ")" ::: "memory")
; #define PG8_WAIT_L(n) asm volatile("s_waitcnt lgkmcnt(" #n ")" ::: "memory")
; #define PG8_BAR __builtin_amdgcn_s_barrier()
; #define PG8_SCHED __builtin_amdgcn_sched_barrier(0)
; template <class Epi, class Sched, bool STAMP = false>
; __device__ __forceinline__ void gemm_phase(PG8_LAS unsigned char* lds, const Gemm g, const Sched& S, const Epi& E, unsigned long long* stamps) {
;     ...
;             PG8_STAGE(PG8_SB(0, 1), b2 + hstep, voffB);
;             PG8_WAIT_V(6); PG8_BAR; PG8_MMA(1, 1, At, B1); PG8_BAR;
;             PG8_LDB(B0, 1, 0); PG8_SCHED; PG8_LDA(At, 1, 0); PG8_STAGE(PG8_SA(0, 1), a2 + hstep, voffA);
;             PG8_WAIT_L(8); PG8_BAR; PG8_WAIT_L(0); PG8_MMA(0, 0, At, B0); PG8_BAR; PG8_SCHED;
;             PG8_LDB(B1, 1, 1); PG8_STAGE(PG8_SB(1, 0), b3, voffB);
;             PG8_BAR; PG8_WAIT_L(0); PG8_MMA(0, 1, At, B1); PG8_BAR;
;             PG8_LDA(At, 1, 1); PG8_STAGE(PG8_SA(1, 0), a3, voffA);
	s_mov_b32 m0, s38
	s_nop 0
	global_load_lds_dwordx4 v128, s[24:25]
	s_mov_b32 m0, s29
	s_nop 0
	global_load_lds_dwordx4 v148, s[24:25]
	s_waitcnt vmcnt(6)
	s_barrier
	v_mfma_f32_16x16x32_bf16 v[44:47], v[212:215], v[170:173], v[44:47]
	v_mfma_f32_16x16x32_bf16 v[40:43], v[220:223], v[170:173], v[40:43]
	v_mfma_f32_16x16x32_bf16 v[28:31], v[212:215], v[178:181], v[28:31]
	v_mfma_f32_16x16x32_bf16 v[24:27], v[220:223], v[178:181], v[24:27]
	v_mfma_f32_16x16x32_bf16 v[12:15], v[212:215], v[196:199], v[12:15]
	v_mfma_f32_16x16x32_bf16 v[8:11], v[220:223], v[196:199], v[8:11]
	v_mfma_f32_16x16x32_bf16 v[4:7], v[212:215], v[204:207], v[4:7]
	v_mfma_f32_16x16x32_bf16 v[0:3], v[220:223], v[204:207], v[0:3]
	v_mfma_f32_16x16x32_bf16 v[44:47], v[216:219], v[174:177], v[44:47]
	v_mfma_f32_16x16x32_bf16 v[40:43], v[224:227], v[174:177], v[40:43]
	v_mfma_f32_16x16x32_bf16 v[28:31], v[216:219], v[192:195], v[28:31]
	v_mfma_f32_16x16x32_bf16 v[24:27], v[224:227], v[192:195], v[24:27]
	v_mfma_f32_16x16x32_bf16 v[12:15], v[216:219], v[200:203], v[12:15]
	v_mfma_f32_16x16x32_bf16 v[8:11], v[224:227], v[200:203], v[8:11]
	v_mfma_f32_16x16x32_bf16 v[4:7], v[216:219], v[208:211], v[4:7]
	v_mfma_f32_16x16x32_bf16 v[0:3], v[224:227], v[208:211], v[0:3]
	s_barrier
	ds_read_b128 v[154:157], v250
	ds_read_b128 v[158:161], v250 offset:1024
	ds_read_b128 v[162:165], v250 offset:2048
	ds_read_b128 v[166:169], v250 offset:3072
	s_mov_b32 m0, s48
	ds_read_b128 v[170:173], v152 offset:32768
	ds_read_b128 v[174:177], v152 offset:33792
	ds_read_b128 v[178:181], v152 offset:34816
	ds_read_b128 v[192:195], v152 offset:35840
	ds_read_b128 v[196:199], v152 offset:36864
	ds_read_b128 v[200:203], v152 offset:37888
	ds_read_b128 v[204:207], v152 offset:38912
	global_load_lds_dwordx4 v128, s[22:23]
	s_mov_b32 m0, s49
	ds_read_b128 v[208:211], v152 offset:39936
	global_load_lds_dwordx4 v148, s[22:23]
	s_waitcnt lgkmcnt(8)
	s_barrier
	s_waitcnt lgkmcnt(0)
	v_mfma_f32_16x16x32_bf16 v[124:127], v[154:157], v[170:173], v[124:127]
	v_mfma_f32_16x16x32_bf16 v[120:123], v[162:165], v[170:173], v[120:123]
	v_mfma_f32_16x16x32_bf16 v[116:119], v[154:157], v[178:181], v[116:119]
	v_mfma_f32_16x16x32_bf16 v[112:115], v[162:165], v[178:181], v[112:115]
	v_mfma_f32_16x16x32_bf16 v[104:107], v[154:157], v[196:199], v[104:107]
	v_mfma_f32_16x16x32_bf16 v[96:99], v[162:165], v[196:199], v[96:99]
	v_mfma_f32_16x16x32_bf16 v[88:91], v[154:157], v[204:207], v[88:91]
	v_mfma_f32_16x16x32_bf16 v[80:83], v[162:165], v[204:207], v[80:83]
	v_mfma_f32_16x16x32_bf16 v[124:127], v[158:161], v[174:177], v[124:127]
	v_mfma_f32_16x16x32_bf16 v[120:123], v[166:169], v[174:177], v[120:123]
	v_mfma_f32_16x16x32_bf16 v[116:119], v[158:161], v[192:195], v[116:119]
	v_mfma_f32_16x16x32_bf16 v[112:115], v[166:169], v[192:195], v[112:115]
	v_mfma_f32_16x16x32_bf16 v[104:107], v[158:161], v[200:203], v[104:107]
	v_mfma_f32_16x16x32_bf16 v[96:99], v[166:169], v[200:203], v[96:99]
	v_mfma_f32_16x16x32_bf16 v[88:91], v[158:161], v[208:211], v[88:91]
	v_mfma_f32_16x16x32_bf16 v[80:83], v[166:169], v[208:211], v[80:83]
	s_barrier
	s_mov_b32 m0, s16
	v_lshl_add_u64 v[182:183], v[182:183], 0, s[18:19]
	ds_read_b128 v[212:215], v251
	ds_read_b128 v[216:219], v251 offset:1024
	ds_read_b128 v[220:223], v251 offset:2048
	ds_read_b128 v[224:227], v251 offset:3072
	global_load_lds_dwordx4 v244, s[30:31]
	v_lshl_add_u64 v[182:183], v[228:229], 0, s[18:19]
	s_mov_b32 m0, s14
	s_nop 0
	global_load_lds_dwordx4 v245, s[30:31]
	s_barrier
	s_waitcnt lgkmcnt(0)
	v_mfma_f32_16x16x32_bf16 v[108:111], v[212:215], v[170:173], v[108:111]
	v_mfma_f32_16x16x32_bf16 v[100:103], v[220:223], v[170:173], v[100:103]
	v_mfma_f32_16x16x32_bf16 v[92:95], v[212:215], v[178:181], v[92:95]
	v_mfma_f32_16x16x32_bf16 v[84:87], v[220:223], v[178:181], v[84:87]
	v_mfma_f32_16x16x32_bf16 v[76:79], v[212:215], v[196:199], v[76:79]
	v_mfma_f32_16x16x32_bf16 v[72:75], v[220:223], v[196:199], v[72:75]
	v_mfma_f32_16x16x32_bf16 v[68:71], v[212:215], v[204:207], v[68:71]
	v_mfma_f32_16x16x32_bf16 v[64:67], v[220:223], v[204:207], v[64:67]
	v_mfma_f32_16x16x32_bf16 v[108:111], v[216:219], v[174:177], v[108:111]
	v_mfma_f32_16x16x32_bf16 v[100:103], v[224:227], v[174:177], v[100:103]
	v_mfma_f32_16x16x32_bf16 v[92:95], v[216:219], v[192:195], v[92:95]
	v_mfma_f32_16x16x32_bf16 v[84:87], v[224:227], v[192:195], v[84:87]
	v_mfma_f32_16x16x32_bf16 v[76:79], v[216:219], v[200:203], v[76:79]
	v_mfma_f32_16x16x32_bf16 v[72:75], v[224:227], v[200:203], v[72:75]
	v_mfma_f32_16x16x32_bf16 v[68:71], v[216:219], v[208:211], v[68:71]
	v_mfma_f32_16x16x32_bf16 v[64:67], v[224:227], v[208:211], v[64:67]
	s_mov_b32 m0, s57
	v_lshl_add_u64 v[182:183], v[230:231], 0, s[18:19]
	s_barrier
	ds_read_b128 v[170:173], v152 offset:49152
	ds_read_b128 v[174:177], v152 offset:50176
	ds_read_b128 v[178:181], v152 offset:51200
	ds_read_b128 v[192:195], v152 offset:52224
	ds_read_b128 v[196:199], v152 offset:53248
	ds_read_b128 v[200:203], v152 offset:54272
	ds_read_b128 v[204:207], v152 offset:55296
	ds_read_b128 v[208:211], v152 offset:56320
	global_load_lds_dwordx4 v244, s[26:27]
	v_lshl_add_u64 v[182:183], v[232:233], 0, s[18:19]
	s_mov_b32 m0, s58
	s_nop 0
	global_load_lds_dwordx4 v245, s[26:27]
	s_barrier
; #define PG8_STAGE(bufoff, gbase, voff) do { _Pragma("unroll") for (int _i = 0; _i < 2; ++_i) \
;         __builtin_amdgcn_global_load_lds((const unsigned*)((const char*)(gbase) + (voff)[_i]), (PG8_LAS unsigned*)(lds + (bufoff) + ldsw + _i * 8192), 16, 0, 0); } while (0)
; #define PG8_MMA(ai, bj, At, Bt) do { __builtin_amdgcn_s_setprio(1); _Pragma("unroll") for (int m = 0; m < 4; ++m) _Pragma("unroll") for (int n = 0; n < 2; ++n) _Pragma("unroll") for (int k = 0; k < 2; ++k) \
;         acc[ai][bj][m][n] = __builtin_amdgcn_mfma_f32_16x16x32_bf16(Bt[n][k], At[m][k], acc[ai][bj][m][n], 0, 0, 0); __builtin_amdgcn_s_setprio(0); } while (0)
; #define PG8_WAIT_V(n) asm volatile("s_waitcnt vmcnt(" #n ")" ::: "memory")
; #define PG8_WAIT_L(n) asm volatile("s_waitcnt lgkmcnt(" #n ")" ::: "memory")
; #define PG8_BAR __builtin_amdgcn_s_barrier()
; #define PG8_SCHED __builtin_amdgcn_sched_barrier(0)
; template <class Epi, class Sched, bool STAMP = false>
; __device__ __forceinline__ void gemm_phase(PG8_LAS unsigned char* lds, const Gemm g, const Sched& S, const Epi& E, unsigned long long* stamps) {
;     ...
;             PG8_BAR; PG8_WAIT_L(0); PG8_MMA(1, 0, At, B0); PG8_BAR; PG8_SCHED;
;             PG8_STAGE(PG8_SB(1, 1), b3 + hstep, voffB);
;             PG8_WAIT_V(6); PG8_BAR; PG8_MMA(1, 1, At, B1); PG8_BAR;
;     __device__ __forceinline__ void operator()(const f32x4 (&acc)[2][2][4][2], const pg8::Unit& u, int wr, int wc, int fr, int fq) const {
;         const int row0 = (u.pm - 64) * 256 + wr * 64 + fr, col0 = u.pn * 256 + wc * 32 + 4 * fq;
; #pragma unroll
;         for (int ai = 0; ai < 2; ++ai)
; #pragma unroll
;             for (int m = 0; m < 4; ++m) { float* xp = PART + (size_t)(row0 + ai * 128 + m * 16) * ldp + col0;
; #pragma unroll
;                 for (int bj = 0; bj < 2; ++bj)
; #pragma unroll
;                     for (int n = 0; n < 2; ++n) *(f32x4*)(xp + bj * 128 + n * 16) = acc[ai][bj][m][n]; }
	s_waitcnt lgkmcnt(0)
	v_mfma_f32_16x16x32_bf16 v[60:63], v[154:157], v[170:173], v[60:63]
	v_mfma_f32_16x16x32_bf16 v[56:59], v[162:165], v[170:173], v[56:59]
	v_mfma_f32_16x16x32_bf16 v[52:55], v[154:157], v[178:181], v[52:55]
	v_mfma_f32_16x16x32_bf16 v[48:51], v[162:165], v[178:181], v[48:51]
	v_mfma_f32_16x16x32_bf16 v[36:39], v[154:157], v[196:199], v[36:39]
	v_mfma_f32_16x16x32_bf16 v[32:35], v[162:165], v[196:199], v[32:35]
	v_mfma_f32_16x16x32_bf16 v[20:23], v[154:157], v[204:207], v[20:23]
	v_mfma_f32_16x16x32_bf16 v[16:19], v[162:165], v[204:207], v[16:19]
	v_mfma_f32_16x16x32_bf16 v[60:63], v[158:161], v[174:177], v[60:63]
	v_mfma_f32_16x16x32_bf16 v[56:59], v[166:169], v[174:177], v[56:59]
	v_mfma_f32_16x16x32_bf16 v[52:55], v[158:161], v[192:195], v[52:55]
	v_mfma_f32_16x16x32_bf16 v[48:51], v[166:169], v[192:195], v[48:51]
	v_mfma_f32_16x16x32_bf16 v[36:39], v[158:161], v[200:203], v[36:39]
	v_mfma_f32_16x16x32_bf16 v[32:35], v[166:169], v[200:203], v[32:35]
	v_mfma_f32_16x16x32_bf16 v[20:23], v[158:161], v[208:211], v[20:23]
	v_mfma_f32_16x16x32_bf16 v[16:19], v[166:169], v[208:211], v[16:19]
	s_barrier
	s_mov_b32 m0, s52
	s_nop 0
	global_load_lds_dwordx4 v128, s[20:21]
	s_mov_b32 m0, s39
	s_nop 0
	global_load_lds_dwordx4 v148, s[20:21]
	s_waitcnt vmcnt(6)
	s_barrier
	v_mfma_f32_16x16x32_bf16 v[44:47], v[212:215], v[170:173], v[44:47]
	v_mfma_f32_16x16x32_bf16 v[40:43], v[220:223], v[170:173], v[40:43]
	v_mfma_f32_16x16x32_bf16 v[28:31], v[212:215], v[178:181], v[28:31]
	v_mfma_f32_16x16x32_bf16 v[24:27], v[220:223], v[178:181], v[24:27]
	v_mfma_f32_16x16x32_bf16 v[12:15], v[212:215], v[196:199], v[12:15]
	v_mfma_f32_16x16x32_bf16 v[8:11], v[220:223], v[196:199], v[8:11]
	v_mfma_f32_16x16x32_bf16 v[4:7], v[212:215], v[204:207], v[4:7]
	v_mfma_f32_16x16x32_bf16 v[0:3], v[220:223], v[204:207], v[0:3]
	v_mfma_f32_16x16x32_bf16 v[44:47], v[216:219], v[174:177], v[44:47]
	v_mfma_f32_16x16x32_bf16 v[40:43], v[224:227], v[174:177], v[40:43]
	v_mfma_f32_16x16x32_bf16 v[28:31], v[216:219], v[192:195], v[28:31]
	v_mfma_f32_16x16x32_bf16 v[24:27], v[224:227], v[192:195], v[24:27]
	v_mfma_f32_16x16x32_bf16 v[12:15], v[216:219], v[200:203], v[12:15]
	v_mfma_f32_16x16x32_bf16 v[8:11], v[224:227], v[200:203], v[8:11]
	v_mfma_f32_16x16x32_bf16 v[4:7], v[216:219], v[208:211], v[4:7]
	v_mfma_f32_16x16x32_bf16 v[0:3], v[224:227], v[208:211], v[0:3]
	s_andn2_b64 vcc, exec, s[12:13]
	s_mov_b64 s[20:21], -1
	s_mov_b64 s[12:13], 0
	s_movk_i32 s14, 0x100
	s_barrier
	s_cbranch_vccz .LBB0_213
	s_lshl_b32 s0, s43, 22
	s_add_u32 s0, s10, s0
	s_addc_u32 s1, s46, 0
	s_add_u32 s0, s0, 0xbb00000
	s_addc_u32 s1, s1, 0
	s_lshl_b32 s4, s42, 8
	s_add_i32 s4, s4, s53
	v_add_u32_e32 v150, s4, v150
	v_add_u32_e32 v148, 0xffffc000, v150
	s_lshl_b32 s4, s41, 8
	v_lshl_or_b32 v128, v139, 2, s4
	v_ashrrev_i32_e32 v149, 31, v148
	v_or_b32_e32 v128, s56, v128
	v_lshlrev_b64 v[148:149], 12, v[148:149]
	v_lshl_add_u64 v[148:149], s[0:1], 0, v[148:149]
	v_lshlrev_b32_e32 v128, 2, v128
	v_lshl_add_u64 v[148:149], v[148:149], 0, v[128:129]
	global_store_dwordx4 v[148:149], v[124:127], off
	global_store_dwordx4 v[148:149], v[120:123], off offset:64
	global_store_dwordx4 v[148:149], v[108:111], off offset:512
	global_store_dwordx4 v[148:149], v[100:103], off offset:576
	s_cmpk_lt_u32 s40, 0x100
	s_movk_i32 s58, 0xff60
	v_add_u32_e32 v100, 0xffffc010, v150
	v_ashrrev_i32_e32 v101, 31, v100
	v_lshlrev_b64 v[100:101], 12, v[100:101]
	v_lshl_add_u64 v[100:101], s[0:1], 0, v[100:101]
	v_lshl_add_u64 v[100:101], v[100:101], 0, v[128:129]
	global_store_dwordx4 v[100:101], v[116:119], off
	global_store_dwordx4 v[100:101], v[112:115], off offset:64
	global_store_dwordx4 v[100:101], v[92:95], off offset:512
	global_store_dwordx4 v[100:101], v[84:87], off offset:576
	s_nop 1
	v_add_u32_e32 v84, 0xffffc020, v150
	v_ashrrev_i32_e32 v85, 31, v84
	v_lshlrev_b64 v[84:85], 12, v[84:85]
	v_lshl_add_u64 v[84:85], s[0:1], 0, v[84:85]
	v_lshl_add_u64 v[84:85], v[84:85], 0, v[128:129]
	global_store_dwordx4 v[84:85], v[104:107], off
	global_store_dwordx4 v[84:85], v[96:99], off offset:64
	global_store_dwordx4 v[84:85], v[76:79], off offset:512
	global_store_dwordx4 v[84:85], v[72:75], off offset:576
	s_nop 1
	v_add_u32_e32 v72, 0xffffc030, v150
	v_ashrrev_i32_e32 v73, 31, v72
	v_lshlrev_b64 v[72:73], 12, v[72:73]
	v_lshl_add_u64 v[72:73], s[0:1], 0, v[72:73]
	v_lshl_add_u64 v[72:73], v[72:73], 0, v[128:129]
	s_mov_b64 s[0:1], 0x80000
	global_store_dwordx4 v[72:73], v[88:91], off
	global_store_dwordx4 v[72:73], v[80:83], off offset:64
	global_store_dwordx4 v[72:73], v[68:71], off offset:512
	global_store_dwordx4 v[72:73], v[64:67], off offset:576
	s_nop 1
	v_lshl_add_u64 v[64:65], v[148:149], 0, s[0:1]
	s_mov_b32 s0, 0x80000
	v_add_co_u32_e32 v66, vcc, s0, v148
	s_mov_b64 s[0:1], 0x90000
	s_nop 0
	v_addc_co_u32_e32 v67, vcc, 0, v149, vcc
	global_store_dwordx4 v[66:67], v[60:63], off
	global_store_dwordx4 v[64:65], v[56:59], off offset:64
	global_store_dwordx4 v[64:65], v[44:47], off offset:512
	global_store_dwordx4 v[64:65], v[40:43], off offset:576
	s_nop 1
	v_lshl_add_u64 v[40:41], v[148:149], 0, s[0:1]
	s_mov_b32 s0, 0x90000
	v_add_co_u32_e32 v42, vcc, s0, v148
	s_mov_b64 s[0:1], 0xa0000
	s_nop 0
	v_addc_co_u32_e32 v43, vcc, 0, v149, vcc
	global_store_dwordx4 v[42:43], v[52:55], off
	global_store_dwordx4 v[40:41], v[48:51], off offset:64
	global_store_dwordx4 v[40:41], v[28:31], off offset:512
	global_store_dwordx4 v[40:41], v[24:27], off offset:576
	s_nop 1
	v_lshl_add_u64 v[24:25], v[148:149], 0, s[0:1]
	s_mov_b32 s0, 0xa0000
	v_add_co_u32_e32 v26, vcc, s0, v148
	s_mov_b64 s[0:1], 0xb0000
	s_nop 0
	v_addc_co_u32_e32 v27, vcc, 0, v149, vcc
	global_store_dwordx4 v[26:27], v[36:39], off
	global_store_dwordx4 v[24:25], v[32:35], off offset:64
	global_store_dwordx4 v[24:25], v[12:15], off offset:512
	global_store_dwordx4 v[24:25], v[8:11], off offset:576
	s_nop 1
	v_add_co_u32_e32 v10, vcc, 0xb0000, v148
	v_lshl_add_u64 v[8:9], v[148:149], 0, s[0:1]
	s_nop 0
	v_addc_co_u32_e32 v11, vcc, 0, v149, vcc
	global_store_dwordx4 v[10:11], v[20:23], off
	global_store_dwordx4 v[8:9], v[16:19], off offset:64
	global_store_dwordx4 v[8:9], v[4:7], off offset:512
	global_store_dwordx4 v[8:9], v[0:3], off offset:576
	s_waitcnt vmcnt(0)
	s_cbranch_scc0 .LBB0_216
	s_barrier

; #define PG8_STAGE(bufoff, gbase, voff) do { _Pragma("unroll") for (int _i = 0; _i < 2; ++_i) \
;         __builtin_amdgcn_global_load_lds((const unsigned*)((const char*)(gbase) + (voff)[_i]), (PG8_LAS unsigned*)(lds + (bufoff) + ldsw + _i * 8192), 16, 0, 0); } while (0)
; #define PG8_LDA(dst, b, h) do { _Pragma("unroll") for (int m = 0; m < 4; ++m) _Pragma("unroll") for (int k = 0; k < 2; ++k) dst[m][k] = *(const PG8_LAS bf16x8*)(lds + PG8_SA(b, h) + aoff + m * 2048 + k * 1024); } while (0)
; #define PG8_LDB(dst, b, h) do { _Pragma("unroll") for (int n = 0; n < 2; ++n) _Pragma("unroll") for (int k = 0; k < 2; ++k) dst[n][k] = *(const PG8_LAS bf16x8*)(lds + PG8_SB(b, h) + boff + n * 2048 + k * 1024); } while (0)
; #define PG8_MMA(ai, bj, At, Bt) do { __builtin_amdgcn_s_setprio(1); _Pragma("unroll") for (int m = 0; m < 4; ++m) _Pragma("unroll") for (int n = 0; n < 2; ++n) _Pragma("unroll") for (int k = 0; k < 2; ++k) \
;         acc[ai][bj][m][n] = __builtin_amdgcn_mfma_f32_16x16x32_bf16(Bt[n][k], At[m][k], acc[ai][bj][m][n], 0, 0, 0); __builtin_amdgcn_s_setprio(0); } while (0)
; #define PG8_WAIT_V(n) asm volatile("s_waitcnt vmcnt(" #n ")" ::: "memory")
; #define PG8_WAIT_L(n) asm volatile("s_waitcnt lgkmcnt(" #n ")" ::: "memory")
; #define PG8_BAR __builtin_amdgcn_s_barrier()
; #define PG8_SCHED __builtin_amdgcn_sched_barrier(0)
; template <class Epi, class Sched, bool STAMP = false>
; __device__ __forceinline__ void gemm_phase(PG8_LAS unsigned char* lds, const Gemm g, const Sched& S, const Epi& E, unsigned long long* stamps) {
;     ...
;             PG8_LDB(B0, 0, 0); PG8_SCHED; PG8_LDA(At, 0, 0); PG8_STAGE(PG8_SA(1, 1), a1 + hstep, voffA);
;             PG8_WAIT_L(8); PG8_BAR; PG8_WAIT_L(0); PG8_MMA(0, 0, At, B0); PG8_BAR; PG8_SCHED;
;             PG8_LDB(B1, 0, 1); PG8_STAGE(PG8_SB(0, 0), b2, voffB);
;             PG8_BAR; PG8_WAIT_L(0); PG8_MMA(0, 1, At, B1); PG8_BAR;
;             PG8_LDA(At, 0, 1); PG8_STAGE(PG8_SA(0, 0), a2, voffA);
;             PG8_BAR; PG8_WAIT_L(0); PG8_MMA(1, 0, At, B0); PG8_BAR; PG8_SCHED;
;             PG8_STAGE(PG8_SB(0, 1), b2 + hstep, voffB);
;             PG8_WAIT_V(6); PG8_BAR; PG8_MMA(1, 1, At, B1); PG8_BAR;
.LBB0_293:
	s_add_u32 s14, s24, 0xfffe0080
	s_addc_u32 s15, s25, -1
	s_add_i32 s16, 0, 0x10000
	ds_read_b128 v[162:165], v248
	ds_read_b128 v[166:169], v248 offset:1024
	ds_read_b128 v[170:173], v248 offset:2048
	ds_read_b128 v[174:177], v248 offset:3072
	s_cmp_eq_u32 s59, 4
	s_cselect_b32 s31, s7, s15
	s_cselect_b32 s30, s53, s14
	s_cselect_b32 s27, s5, s58
	s_cselect_b32 s26, s56, s57
	s_add_i32 m0, s3, 0xc000
	ds_read_b128 v[178:181], v160
	ds_read_b128 v[192:195], v160 offset:1024
	ds_read_b128 v[196:199], v160 offset:2048
	ds_read_b128 v[200:203], v160 offset:3072
	ds_read_b128 v[204:207], v160 offset:4096
	ds_read_b128 v[208:211], v160 offset:5120
	ds_read_b128 v[212:215], v160 offset:6144
	global_load_lds_dwordx4 v154, s[24:25]
	s_add_i32 m0, s3, 0xe000
	ds_read_b128 v[216:219], v160 offset:7168
	global_load_lds_dwordx4 v156, s[24:25]
	s_waitcnt lgkmcnt(8)
	s_barrier
	s_waitcnt lgkmcnt(0)
	v_mfma_f32_16x16x32_bf16 v[124:127], v[162:165], v[178:181], v[124:127]
	v_mfma_f32_16x16x32_bf16 v[120:123], v[170:173], v[178:181], v[120:123]
	v_mfma_f32_16x16x32_bf16 v[116:119], v[162:165], v[196:199], v[116:119]
	v_mfma_f32_16x16x32_bf16 v[112:115], v[170:173], v[196:199], v[112:115]
	v_mfma_f32_16x16x32_bf16 v[100:103], v[162:165], v[204:207], v[100:103]
	v_mfma_f32_16x16x32_bf16 v[96:99], v[170:173], v[204:207], v[96:99]
	v_mfma_f32_16x16x32_bf16 v[84:87], v[162:165], v[212:215], v[84:87]
	v_mfma_f32_16x16x32_bf16 v[80:83], v[170:173], v[212:215], v[80:83]
	v_mfma_f32_16x16x32_bf16 v[124:127], v[166:169], v[192:195], v[124:127]
	v_mfma_f32_16x16x32_bf16 v[120:123], v[174:177], v[192:195], v[120:123]
	v_mfma_f32_16x16x32_bf16 v[116:119], v[166:169], v[200:203], v[116:119]
	v_mfma_f32_16x16x32_bf16 v[112:115], v[174:177], v[200:203], v[112:115]
	v_mfma_f32_16x16x32_bf16 v[100:103], v[166:169], v[208:211], v[100:103]
	v_mfma_f32_16x16x32_bf16 v[96:99], v[174:177], v[208:211], v[96:99]
	v_mfma_f32_16x16x32_bf16 v[84:87], v[166:169], v[216:219], v[84:87]
	v_mfma_f32_16x16x32_bf16 v[80:83], v[174:177], v[216:219], v[80:83]
	s_barrier
	s_add_i32 s17, 0, 0x14000
	s_add_i32 s14, s16, s40
	s_mov_b32 m0, s14
	ds_read_b128 v[220:223], v249
	ds_read_b128 v[224:227], v249 offset:1024
	ds_read_b128 v[228:231], v249 offset:2048
	global_load_lds_dwordx4 v128, s[26:27]
	s_add_i32 m0, s14, 0x2000
	ds_read_b128 v[232:235], v249 offset:3072
	global_load_lds_dwordx4 v152, s[26:27]
	s_barrier
	s_waitcnt lgkmcnt(0)
	v_mfma_f32_16x16x32_bf16 v[108:111], v[220:223], v[178:181], v[108:111]
	v_mfma_f32_16x16x32_bf16 v[104:107], v[228:231], v[178:181], v[104:107]
	v_mfma_f32_16x16x32_bf16 v[92:95], v[220:223], v[196:199], v[92:95]
	v_mfma_f32_16x16x32_bf16 v[88:91], v[228:231], v[196:199], v[88:91]
	v_mfma_f32_16x16x32_bf16 v[76:79], v[220:223], v[204:207], v[76:79]
	v_mfma_f32_16x16x32_bf16 v[72:75], v[228:231], v[204:207], v[72:75]
	v_mfma_f32_16x16x32_bf16 v[68:71], v[220:223], v[212:215], v[68:71]
	v_mfma_f32_16x16x32_bf16 v[64:67], v[228:231], v[212:215], v[64:67]
	v_mfma_f32_16x16x32_bf16 v[108:111], v[224:227], v[192:195], v[108:111]
	v_mfma_f32_16x16x32_bf16 v[104:107], v[232:235], v[192:195], v[104:107]
	v_mfma_f32_16x16x32_bf16 v[92:95], v[224:227], v[200:203], v[92:95]
	v_mfma_f32_16x16x32_bf16 v[88:91], v[232:235], v[200:203], v[88:91]
	v_mfma_f32_16x16x32_bf16 v[76:79], v[224:227], v[208:211], v[76:79]
	v_mfma_f32_16x16x32_bf16 v[72:75], v[232:235], v[208:211], v[72:75]
	v_mfma_f32_16x16x32_bf16 v[68:71], v[224:227], v[216:219], v[68:71]
	v_mfma_f32_16x16x32_bf16 v[64:67], v[232:235], v[216:219], v[64:67]
	s_mov_b32 m0, s3
	s_barrier
	ds_read_b128 v[178:181], v160 offset:16384
	ds_read_b128 v[192:195], v160 offset:17408
	ds_read_b128 v[196:199], v160 offset:18432
	ds_read_b128 v[200:203], v160 offset:19456
	ds_read_b128 v[204:207], v160 offset:20480
	ds_read_b128 v[208:211], v160 offset:21504
	ds_read_b128 v[212:215], v160 offset:22528
	global_load_lds_dwordx4 v148, s[30:31]
	s_mov_b32 m0, s41
	ds_read_b128 v[216:219], v160 offset:23552
	global_load_lds_dwordx4 v150, s[30:31]
	s_barrier
	s_waitcnt lgkmcnt(0)
	v_mfma_f32_16x16x32_bf16 v[60:63], v[162:165], v[178:181], v[60:63]
	v_mfma_f32_16x16x32_bf16 v[56:59], v[170:173], v[178:181], v[56:59]
	v_mfma_f32_16x16x32_bf16 v[52:55], v[162:165], v[196:199], v[52:55]
	v_mfma_f32_16x16x32_bf16 v[48:51], v[170:173], v[196:199], v[48:51]
	v_mfma_f32_16x16x32_bf16 v[36:39], v[162:165], v[204:207], v[36:39]
	v_mfma_f32_16x16x32_bf16 v[32:35], v[170:173], v[204:207], v[32:35]
	v_mfma_f32_16x16x32_bf16 v[20:23], v[162:165], v[212:215], v[20:23]
	v_mfma_f32_16x16x32_bf16 v[16:19], v[170:173], v[212:215], v[16:19]
	v_mfma_f32_16x16x32_bf16 v[60:63], v[166:169], v[192:195], v[60:63]
	v_mfma_f32_16x16x32_bf16 v[56:59], v[174:177], v[192:195], v[56:59]
	v_mfma_f32_16x16x32_bf16 v[52:55], v[166:169], v[200:203], v[52:55]
	v_mfma_f32_16x16x32_bf16 v[48:51], v[174:177], v[200:203], v[48:51]
	v_mfma_f32_16x16x32_bf16 v[36:39], v[166:169], v[208:211], v[36:39]
	v_mfma_f32_16x16x32_bf16 v[32:35], v[174:177], v[208:211], v[32:35]
	v_mfma_f32_16x16x32_bf16 v[20:23], v[166:169], v[216:219], v[20:23]
	v_mfma_f32_16x16x32_bf16 v[16:19], v[174:177], v[216:219], v[16:19]
	s_barrier
	s_add_u32 s14, s26, 0x20000
	s_addc_u32 s15, s27, 0
	s_add_i32 s16, s17, s40
	s_mov_b32 m0, s16
	s_nop 0
	global_load_lds_dwordx4 v128, s[14:15]
	s_add_i32 m0, s16, 0x2000
	s_nop 0
	global_load_lds_dwordx4 v152, s[14:15]
	s_waitcnt vmcnt(6)
	s_barrier
; #define PG8_STAGE(bufoff, gbase, voff) do { _Pragma("unroll") for (int _i = 0; _i < 2; ++_i) \
;         __builtin_amdgcn_global_load_lds((const unsigned*)((const char*)(gbase) + (voff)[_i]), (PG8_LAS unsigned*)(lds + (bufoff) + ldsw + _i * 8192), 16, 0, 0); } while (0)
; #define PG8_LDA(dst, b, h) do { _Pragma("unroll") for (int m = 0; m < 4; ++m) _Pragma("unroll") for (int k = 0; k < 2; ++k) dst[m][k] = *(const PG8_LAS bf16x8*)(lds + PG8_SA(b, h) + aoff + m * 2048 + k * 1024); } while (0)
; #define PG8_LDB(dst, b, h) do { _Pragma("unroll") for (int n = 0; n < 2; ++n) _Pragma("unroll") for (int k = 0; k < 2; ++k) dst[n][k] = *(const PG8_LAS bf16x8*)(lds + PG8_SB(b, h) + boff + n * 2048 + k * 1024); } while (0)
; #define PG8_MMA(ai, bj, At, Bt) do { __builtin_amdgcn_s_setprio(1); _Pragma("unroll") for (int m = 0; m < 4; ++m) _Pragma("unroll") for (int n = 0; n < 2; ++n) _Pragma("unroll") for (int k = 0; k < 2; ++k) \
;         acc[ai][bj][m][n] = __builtin_amdgcn_mfma_f32_16x16x32_bf16(Bt[n][k], At[m][k], acc[ai][bj][m][n], 0, 0, 0); __builtin_amdgcn_s_setprio(0); } while (0)
; #define PG8_WAIT_V(n) asm volatile("s_waitcnt vmcnt(" #n ")" ::: "memory")
; #define PG8_WAIT_L(n) asm volatile("s_waitcnt lgkmcnt(" #n ")" ::: "memory")
; #define PG8_BAR __builtin_amdgcn_s_barrier()
; #define PG8_SCHED __builtin_amdgcn_sched_barrier(0)
; template <class Epi, class Sched, bool STAMP = false>
; __device__ __forceinline__ void gemm_phase(PG8_LAS unsigned char* lds, const Gemm g, const Sched& S, const Epi& E, unsigned long long* stamps) {
;     ...
;             PG8_WAIT_V(6); PG8_BAR; PG8_MMA(1, 1, At, B1); PG8_BAR;
;             PG8_LDB(B0, 1, 0); PG8_SCHED; PG8_LDA(At, 1, 0); PG8_STAGE(PG8_SA(0, 1), a2 + hstep, voffA);
;             PG8_WAIT_L(8); PG8_BAR; PG8_WAIT_L(0); PG8_MMA(0, 0, At, B0); PG8_BAR; PG8_SCHED;
;             PG8_LDB(B1, 1, 1); PG8_STAGE(PG8_SB(1, 0), b3, voffB);
;             PG8_BAR; PG8_WAIT_L(0); PG8_MMA(0, 1, At, B1); PG8_BAR;
;             PG8_LDA(At, 1, 1); PG8_STAGE(PG8_SA(1, 0), a3, voffA);
	v_mfma_f32_16x16x32_bf16 v[44:47], v[220:223], v[178:181], v[44:47]
	v_mfma_f32_16x16x32_bf16 v[40:43], v[228:231], v[178:181], v[40:43]
	v_mfma_f32_16x16x32_bf16 v[28:31], v[220:223], v[196:199], v[28:31]
	v_mfma_f32_16x16x32_bf16 v[24:27], v[228:231], v[196:199], v[24:27]
	v_mfma_f32_16x16x32_bf16 v[12:15], v[220:223], v[204:207], v[12:15]
	v_mfma_f32_16x16x32_bf16 v[8:11], v[228:231], v[204:207], v[8:11]
	v_mfma_f32_16x16x32_bf16 v[4:7], v[220:223], v[212:215], v[4:7]
	v_mfma_f32_16x16x32_bf16 v[0:3], v[228:231], v[212:215], v[0:3]
	v_mfma_f32_16x16x32_bf16 v[44:47], v[224:227], v[192:195], v[44:47]
	v_mfma_f32_16x16x32_bf16 v[40:43], v[232:235], v[192:195], v[40:43]
	v_mfma_f32_16x16x32_bf16 v[28:31], v[224:227], v[200:203], v[28:31]
	v_mfma_f32_16x16x32_bf16 v[24:27], v[232:235], v[200:203], v[24:27]
	v_mfma_f32_16x16x32_bf16 v[12:15], v[224:227], v[208:211], v[12:15]
	v_mfma_f32_16x16x32_bf16 v[8:11], v[232:235], v[208:211], v[8:11]
	v_mfma_f32_16x16x32_bf16 v[4:7], v[224:227], v[216:219], v[4:7]
	v_mfma_f32_16x16x32_bf16 v[0:3], v[232:235], v[216:219], v[0:3]
	s_add_i32 s16, 0, 0x18000
	s_barrier
	ds_read_b128 v[162:165], v250
	ds_read_b128 v[166:169], v250 offset:1024
	ds_read_b128 v[170:173], v250 offset:2048
	ds_read_b128 v[174:177], v250 offset:3072
	s_add_u32 s14, s30, 0x20000
	s_addc_u32 s15, s31, 0
	s_mov_b32 m0, s42
	ds_read_b128 v[178:181], v160 offset:32768
	ds_read_b128 v[192:195], v160 offset:33792
	ds_read_b128 v[196:199], v160 offset:34816
	ds_read_b128 v[200:203], v160 offset:35840
	ds_read_b128 v[204:207], v160 offset:36864
	ds_read_b128 v[208:211], v160 offset:37888
	ds_read_b128 v[212:215], v160 offset:38912
	global_load_lds_dwordx4 v148, s[14:15]
	s_mov_b32 m0, s43
	ds_read_b128 v[216:219], v160 offset:39936
	global_load_lds_dwordx4 v150, s[14:15]
	s_waitcnt lgkmcnt(8)
	s_barrier
	s_waitcnt lgkmcnt(0)
	v_mfma_f32_16x16x32_bf16 v[124:127], v[162:165], v[178:181], v[124:127]
	v_mfma_f32_16x16x32_bf16 v[120:123], v[170:173], v[178:181], v[120:123]
	v_mfma_f32_16x16x32_bf16 v[116:119], v[162:165], v[196:199], v[116:119]
	v_mfma_f32_16x16x32_bf16 v[112:115], v[170:173], v[196:199], v[112:115]
	v_mfma_f32_16x16x32_bf16 v[100:103], v[162:165], v[204:207], v[100:103]
	v_mfma_f32_16x16x32_bf16 v[96:99], v[170:173], v[204:207], v[96:99]
	v_mfma_f32_16x16x32_bf16 v[84:87], v[162:165], v[212:215], v[84:87]
	v_mfma_f32_16x16x32_bf16 v[80:83], v[170:173], v[212:215], v[80:83]
	v_mfma_f32_16x16x32_bf16 v[124:127], v[166:169], v[192:195], v[124:127]
	v_mfma_f32_16x16x32_bf16 v[120:123], v[174:177], v[192:195], v[120:123]
	v_mfma_f32_16x16x32_bf16 v[116:119], v[166:169], v[200:203], v[116:119]
	v_mfma_f32_16x16x32_bf16 v[112:115], v[174:177], v[200:203], v[112:115]
	v_mfma_f32_16x16x32_bf16 v[100:103], v[166:169], v[208:211], v[100:103]
	v_mfma_f32_16x16x32_bf16 v[96:99], v[174:177], v[208:211], v[96:99]
	v_mfma_f32_16x16x32_bf16 v[84:87], v[166:169], v[216:219], v[84:87]
	v_mfma_f32_16x16x32_bf16 v[80:83], v[174:177], v[216:219], v[80:83]
	s_barrier
	s_add_i32 s17, 0, 0x1c000
	s_add_i32 s14, s16, s40
	s_mov_b32 m0, s14
	ds_read_b128 v[220:223], v251
	ds_read_b128 v[224:227], v251 offset:1024
	ds_read_b128 v[228:231], v251 offset:2048
	global_load_lds_dwordx4 v244, s[26:27]
	s_add_i32 m0, s14, 0x2000
	ds_read_b128 v[232:235], v251 offset:3072
	global_load_lds_dwordx4 v245, s[26:27]
	s_barrier
	s_waitcnt lgkmcnt(0)
	v_mfma_f32_16x16x32_bf16 v[108:111], v[220:223], v[178:181], v[108:111]
	v_mfma_f32_16x16x32_bf16 v[104:107], v[228:231], v[178:181], v[104:107]
	v_mfma_f32_16x16x32_bf16 v[92:95], v[220:223], v[196:199], v[92:95]
	v_mfma_f32_16x16x32_bf16 v[88:91], v[228:231], v[196:199], v[88:91]
	v_mfma_f32_16x16x32_bf16 v[76:79], v[220:223], v[204:207], v[76:79]
	v_mfma_f32_16x16x32_bf16 v[72:75], v[228:231], v[204:207], v[72:75]
	v_mfma_f32_16x16x32_bf16 v[68:71], v[220:223], v[212:215], v[68:71]
	v_mfma_f32_16x16x32_bf16 v[64:67], v[228:231], v[212:215], v[64:67]
	v_mfma_f32_16x16x32_bf16 v[108:111], v[224:227], v[192:195], v[108:111]
	v_mfma_f32_16x16x32_bf16 v[104:107], v[232:235], v[192:195], v[104:107]
	v_mfma_f32_16x16x32_bf16 v[92:95], v[224:227], v[200:203], v[92:95]
	v_mfma_f32_16x16x32_bf16 v[88:91], v[232:235], v[200:203], v[88:91]
	v_mfma_f32_16x16x32_bf16 v[76:79], v[224:227], v[208:211], v[76:79]
	v_mfma_f32_16x16x32_bf16 v[72:75], v[232:235], v[208:211], v[72:75]
	v_mfma_f32_16x16x32_bf16 v[68:71], v[224:227], v[216:219], v[68:71]
	v_mfma_f32_16x16x32_bf16 v[64:67], v[232:235], v[216:219], v[64:67]
	s_mov_b32 m0, s46
	s_barrier
	ds_read_b128 v[178:181], v160 offset:49152
	ds_read_b128 v[192:195], v160 offset:50176
	ds_read_b128 v[196:199], v160 offset:51200
	ds_read_b128 v[200:203], v160 offset:52224
	ds_read_b128 v[204:207], v160 offset:53248
	ds_read_b128 v[208:211], v160 offset:54272
	ds_read_b128 v[212:215], v160 offset:55296
	global_load_lds_dwordx4 v246, s[30:31]
	s_mov_b32 m0, s47
	ds_read_b128 v[216:219], v160 offset:56320
	global_load_lds_dwordx4 v247, s[30:31]
	s_barrier
	s_waitcnt lgkmcnt(0)
	v_mfma_f32_16x16x32_bf16 v[60:63], v[162:165], v[178:181], v[60:63]
	v_mfma_f32_16x16x32_bf16 v[56:59], v[170:173], v[178:181], v[56:59]
	v_mfma_f32_16x16x32_bf16 v[52:55], v[162:165], v[196:199], v[52:55]
	v_mfma_f32_16x16x32_bf16 v[48:51], v[170:173], v[196:199], v[48:51]
	v_mfma_f32_16x16x32_bf16 v[36:39], v[162:165], v[204:207], v[36:39]
	v_mfma_f32_16x16x32_bf16 v[32:35], v[170:173], v[204:207], v[32:35]
	v_mfma_f32_16x16x32_bf16 v[20:23], v[162:165], v[212:215], v[20:23]
	v_mfma_f32_16x16x32_bf16 v[16:19], v[170:173], v[212:215], v[16:19]
	v_mfma_f32_16x16x32_bf16 v[60:63], v[166:169], v[192:195], v[60:63]
	v_mfma_f32_16x16x32_bf16 v[56:59], v[174:177], v[192:195], v[56:59]
	v_mfma_f32_16x16x32_bf16 v[52:55], v[166:169], v[200:203], v[52:55]
	v_mfma_f32_16x16x32_bf16 v[48:51], v[174:177], v[200:203], v[48:51]
	v_mfma_f32_16x16x32_bf16 v[36:39], v[166:169], v[208:211], v[36:39]
	v_mfma_f32_16x16x32_bf16 v[32:35], v[174:177], v[208:211], v[32:35]
	v_mfma_f32_16x16x32_bf16 v[20:23], v[166:169], v[216:219], v[20:23]
	v_mfma_f32_16x16x32_bf16 v[16:19], v[174:177], v[216:219], v[16:19]
	s_barrier
; __device__ __forceinline__ unsigned cvt_pk_bf16(float lo, float hi) { const f32x2_cv v = {lo, hi}; const bf16x2_cv b = __builtin_convertvector(v, bf16x2_cv); return __builtin_bit_cast(unsigned, b); }
; #define PG8_STAGE(bufoff, gbase, voff) do { _Pragma("unroll") for (int _i = 0; _i < 2; ++_i) \
;         __builtin_amdgcn_global_load_lds((const unsigned*)((const char*)(gbase) + (voff)[_i]), (PG8_LAS unsigned*)(lds + (bufoff) + ldsw + _i * 8192), 16, 0, 0); } while (0)
; #define PG8_MMA(ai, bj, At, Bt) do { __builtin_amdgcn_s_setprio(1); _Pragma("unroll") for (int m = 0; m < 4; ++m) _Pragma("unroll") for (int n = 0; n < 2; ++n) _Pragma("unroll") for (int k = 0; k < 2; ++k) \
;         acc[ai][bj][m][n] = __builtin_amdgcn_mfma_f32_16x16x32_bf16(Bt[n][k], At[m][k], acc[ai][bj][m][n], 0, 0, 0); __builtin_amdgcn_s_setprio(0); } while (0)
; #define PG8_WAIT_V(n) asm volatile("s_waitcnt vmcnt(" #n ")" ::: "memory")
; template <class Epi, class Sched, bool STAMP = false>
; __device__ __forceinline__ void gemm_phase(PG8_LAS unsigned char* lds, const Gemm g, const Sched& S, const Epi& E, unsigned long long* stamps) {
;     ...
;             PG8_STAGE(PG8_SB(1, 1), b3 + hstep, voffB);
;             PG8_WAIT_V(6); PG8_BAR; PG8_MMA(1, 1, At, B1); PG8_BAR;
;     __device__ __forceinline__ void operator()(const f32x4 (&acc)[2][2][4][2], const pg8::Unit& u, int wr, int wc, int fr, int fq) const {
;         const int row0 = u.pm * 256 + wr * 64 + fr, col0 = u.pn * 256 + wc * 32 + 8 * fq;
; #pragma unroll
;         for (int ai = 0; ai < 2; ++ai)
; #pragma unroll
;             for (int m = 0; m < 4; ++m) {
;                 const int row = row0 + ai * 128 + m * 16;
;                 const float s = (MODE == 2) ? 1.0f : rstd_of(rowss, row);
;                 bf16_t* rowp = O + (size_t)row * ldc + col0;
; #pragma unroll
;                 for (int bj = 0; bj < 2; ++bj) {
;                     f32x4 v0 = acc[ai][bj][m][0] * s, v1 = acc[ai][bj][m][1] * s;
;                     if (MODE == 1) {
; #pragma unroll
;                         for (int j = 0; j < 4; ++j) { const float a = fmaxf(v0[j], 0.f), b = fmaxf(v1[j], 0.f); v0[j] = a * a; v1[j] = b * b; } }
;                     u32x4 w; w.x = cvt_pk_bf16(v0[0], v0[1]); w.y = cvt_pk_bf16(v0[2], v0[3]); w.z = cvt_pk_bf16(v1[0], v1[1]); w.w = cvt_pk_bf16(v1[2], v1[3]);
;                     *(u32x4*)(rowp + bj * 128) = w; } }
	s_add_u32 s14, s26, 0x20080
	s_addc_u32 s15, s27, 0
	s_add_i32 s16, s17, s40
	s_mov_b32 m0, s16
	s_nop 0
	global_load_lds_dwordx4 v128, s[14:15]
	s_add_i32 m0, s16, 0x2000
	s_nop 0
	global_load_lds_dwordx4 v152, s[14:15]
	s_waitcnt vmcnt(6)
	s_barrier
	v_mfma_f32_16x16x32_bf16 v[44:47], v[220:223], v[178:181], v[44:47]
	v_mfma_f32_16x16x32_bf16 v[40:43], v[228:231], v[178:181], v[40:43]
	v_mfma_f32_16x16x32_bf16 v[28:31], v[220:223], v[196:199], v[28:31]
	v_mfma_f32_16x16x32_bf16 v[24:27], v[228:231], v[196:199], v[24:27]
	v_mfma_f32_16x16x32_bf16 v[12:15], v[220:223], v[204:207], v[12:15]
	v_mfma_f32_16x16x32_bf16 v[8:11], v[228:231], v[204:207], v[8:11]
	v_mfma_f32_16x16x32_bf16 v[4:7], v[220:223], v[212:215], v[4:7]
	v_mfma_f32_16x16x32_bf16 v[0:3], v[228:231], v[212:215], v[0:3]
	v_mfma_f32_16x16x32_bf16 v[44:47], v[224:227], v[192:195], v[44:47]
	v_mfma_f32_16x16x32_bf16 v[40:43], v[232:235], v[192:195], v[40:43]
	v_mfma_f32_16x16x32_bf16 v[28:31], v[224:227], v[200:203], v[28:31]
	v_mfma_f32_16x16x32_bf16 v[24:27], v[232:235], v[200:203], v[24:27]
	v_mfma_f32_16x16x32_bf16 v[12:15], v[224:227], v[208:211], v[12:15]
	v_mfma_f32_16x16x32_bf16 v[8:11], v[232:235], v[208:211], v[8:11]
	v_mfma_f32_16x16x32_bf16 v[4:7], v[224:227], v[216:219], v[4:7]
	v_mfma_f32_16x16x32_bf16 v[0:3], v[232:235], v[216:219], v[0:3]
	s_add_i32 s59, s59, 2
	s_add_u32 s24, s24, 0x100
	s_addc_u32 s25, s25, 0
	s_add_u32 s57, s57, 0x100
	s_addc_u32 s58, s58, 0
	s_cmp_gt_u32 s59, 5
	s_barrier
	s_cbranch_scc0 .LBB0_293
	v_lshl_add_u32 v162, s2, 8, v139
	v_lshl_or_b32 v164, s49, 8, v159
	v_ashrrev_i32_e32 v163, 31, v162
	v_ashrrev_i32_e32 v165, 31, v164
	v_lshlrev_b64 v[166:167], 11, v[162:163]
	v_lshl_add_u64 v[166:167], s[0:1], 0, v[166:167]
	v_lshlrev_b64 v[164:165], 1, v[164:165]
	v_lshl_add_u64 v[166:167], v[166:167], 0, v[164:165]
	s_mov_b32 s2, 0x40000
	s_mov_b64 s[14:15], 0x40000
	v_cvt_pk_bf16_f32 v60, v60, v61
	v_cvt_pk_bf16_f32 v61, v62, v63
	v_cvt_pk_bf16_f32 v62, v56, v57
	v_add_co_u32_e32 v56, vcc, s2, v166
	v_cvt_pk_bf16_f32 v68, v68, v69
	v_cvt_pk_bf16_f32 v69, v70, v71
	v_cvt_pk_bf16_f32 v70, v64, v65
	v_lshl_add_u64 v[64:65], v[166:167], 0, s[14:15]
	v_addc_co_u32_e32 v57, vcc, 0, v167, vcc
	v_cvt_pk_bf16_f32 v44, v44, v45
	v_cvt_pk_bf16_f32 v45, v46, v47
	v_cvt_pk_bf16_f32 v46, v40, v41
	v_cvt_pk_bf16_f32 v47, v42, v43
	s_mov_b32 s2, 0x48000
	v_cvt_pk_bf16_f32 v108, v108, v109
	v_cvt_pk_bf16_f32 v109, v110, v111
	v_cvt_pk_bf16_f32 v110, v104, v105
	v_or_b32_e32 v104, 16, v162
	global_store_dwordx4 v[64:65], v[44:47], off offset:256
	s_mov_b64 s[14:15], 0x48000
	v_ashrrev_i32_e32 v105, 31, v104
	v_add_co_u32_e32 v46, vcc, s2, v166
	v_cvt_pk_bf16_f32 v92, v92, v93
	v_cvt_pk_bf16_f32 v93, v94, v95
	v_cvt_pk_bf16_f32 v94, v88, v89
	v_or_b32_e32 v88, 32, v162
	v_lshl_add_u64 v[44:45], v[166:167], 0, s[14:15]
	v_addc_co_u32_e32 v47, vcc, 0, v167, vcc
	v_cvt_pk_bf16_f32 v28, v28, v29
	v_cvt_pk_bf16_f32 v29, v30, v31
	v_cvt_pk_bf16_f32 v30, v24, v25
	v_cvt_pk_bf16_f32 v31, v26, v27
	s_mov_b32 s2, 0x50000
	v_lshlrev_b64 v[104:105], 11, v[104:105]
	v_ashrrev_i32_e32 v89, 31, v88
	v_cvt_pk_bf16_f32 v76, v76, v77
	v_cvt_pk_bf16_f32 v77, v78, v79
	v_cvt_pk_bf16_f32 v78, v72, v73
	v_or_b32_e32 v72, 48, v162
	global_store_dwordx4 v[44:45], v[28:31], off offset:256
	s_mov_b64 s[14:15], 0x50000
	v_cvt_pk_bf16_f32 v111, v106, v107
	v_add_co_u32_e32 v30, vcc, s2, v166
	v_lshl_add_u64 v[104:105], s[0:1], 0, v[104:105]
	v_lshlrev_b64 v[88:89], 11, v[88:89]
	v_ashrrev_i32_e32 v73, 31, v72
	v_lshl_add_u64 v[28:29], v[166:167], 0, s[14:15]
	v_addc_co_u32_e32 v31, vcc, 0, v167, vcc
	v_cvt_pk_bf16_f32 v12, v12, v13
	v_cvt_pk_bf16_f32 v13, v14, v15
	v_cvt_pk_bf16_f32 v14, v8, v9
	v_cvt_pk_bf16_f32 v15, v10, v11
	s_mov_b32 s2, 0x58000
	global_store_dwordx4 v[166:167], v[108:111], off offset:256
	v_cvt_pk_bf16_f32 v95, v90, v91
	v_lshl_add_u64 v[88:89], s[0:1], 0, v[88:89]
	v_lshl_add_u64 v[108:109], v[104:105], 0, v[164:165]
	v_lshlrev_b64 v[72:73], 11, v[72:73]
	global_store_dwordx4 v[28:29], v[12:15], off offset:256
	global_store_dwordx4 v[108:109], v[92:95], off offset:256
	v_cvt_pk_bf16_f32 v79, v74, v75
	v_add_co_u32_e32 v14, vcc, s2, v166
	v_lshl_add_u64 v[92:93], v[88:89], 0, v[164:165]
	v_lshl_add_u64 v[72:73], s[0:1], 0, v[72:73]
	s_mov_b64 s[14:15], 0x58000
	v_addc_co_u32_e32 v15, vcc, 0, v167, vcc
	v_cvt_pk_bf16_f32 v124, v124, v125
	v_cvt_pk_bf16_f32 v125, v126, v127
	v_cvt_pk_bf16_f32 v126, v120, v121
	v_cvt_pk_bf16_f32 v127, v122, v123
	v_cvt_pk_bf16_f32 v104, v116, v117
	v_cvt_pk_bf16_f32 v105, v118, v119
	v_cvt_pk_bf16_f32 v106, v112, v113
	v_cvt_pk_bf16_f32 v107, v114, v115
	v_cvt_pk_bf16_f32 v88, v100, v101
	v_cvt_pk_bf16_f32 v89, v102, v103
	v_cvt_pk_bf16_f32 v90, v96, v97
	v_cvt_pk_bf16_f32 v91, v98, v99
	global_store_dwordx4 v[92:93], v[76:79], off offset:256
	v_cvt_pk_bf16_f32 v74, v80, v81
	v_cvt_pk_bf16_f32 v75, v82, v83
	v_lshl_add_u64 v[76:77], v[72:73], 0, v[164:165]
	v_cvt_pk_bf16_f32 v72, v84, v85
	v_cvt_pk_bf16_f32 v73, v86, v87
	v_cvt_pk_bf16_f32 v71, v66, v67
	v_cvt_pk_bf16_f32 v63, v58, v59
	v_cvt_pk_bf16_f32 v40, v52, v53
	v_cvt_pk_bf16_f32 v41, v54, v55
	v_cvt_pk_bf16_f32 v42, v48, v49
	v_cvt_pk_bf16_f32 v43, v50, v51
	v_cvt_pk_bf16_f32 v24, v36, v37
	v_cvt_pk_bf16_f32 v25, v38, v39
	v_cvt_pk_bf16_f32 v26, v32, v33
	v_cvt_pk_bf16_f32 v27, v34, v35
	v_lshl_add_u64 v[12:13], v[166:167], 0, s[14:15]
	v_cvt_pk_bf16_f32 v8, v20, v21
	v_cvt_pk_bf16_f32 v9, v22, v23
	v_cvt_pk_bf16_f32 v10, v16, v17
	v_cvt_pk_bf16_f32 v11, v18, v19
	v_cvt_pk_bf16_f32 v4, v4, v5
	v_cvt_pk_bf16_f32 v5, v6, v7
	v_cvt_pk_bf16_f32 v6, v0, v1
	v_cvt_pk_bf16_f32 v7, v2, v3
	s_and_b64 vcc, exec, s[38:39]
	s_mov_b32 s49, s4
	s_mov_b32 s2, s6
	s_mov_b64 s[26:27], s[22:23]
	s_mov_b64 s[24:25], s[12:13]
	s_movk_i32 s58, 0xff60
	global_store_dwordx4 v[166:167], v[124:127], off
	global_store_dwordx4 v[108:109], v[104:107], off
	global_store_dwordx4 v[92:93], v[88:91], off
	global_store_dwordx4 v[76:77], v[72:75], off
	global_store_dwordx4 v[76:77], v[68:71], off offset:256
	global_store_dwordx4 v[56:57], v[60:63], off
	global_store_dwordx4 v[46:47], v[40:43], off
	global_store_dwordx4 v[30:31], v[24:27], off
	global_store_dwordx4 v[14:15], v[8:11], off
	global_store_dwordx4 v[12:13], v[4:7], off offset:256
	s_cbranch_vccz .LBB0_286
	s_cmpk_gt_u32 s36, 0xff
	s_cbranch_scc1 .LBB0_297
	s_barrier

; #define PG8_STAGE(bufoff, gbase, voff) do { _Pragma("unroll") for (int _i = 0; _i < 2; ++_i) \
;         __builtin_amdgcn_global_load_lds((const unsigned*)((const char*)(gbase) + (voff)[_i]), (PG8_LAS unsigned*)(lds + (bufoff) + ldsw + _i * 8192), 16, 0, 0); } while (0)
; #define PG8_LDA(dst, b, h) do { _Pragma("unroll") for (int m = 0; m < 4; ++m) _Pragma("unroll") for (int k = 0; k < 2; ++k) dst[m][k] = *(const PG8_LAS bf16x8*)(lds + PG8_SA(b, h) + aoff + m * 2048 + k * 1024); } while (0)
; #define PG8_LDB(dst, b, h) do { _Pragma("unroll") for (int n = 0; n < 2; ++n) _Pragma("unroll") for (int k = 0; k < 2; ++k) dst[n][k] = *(const PG8_LAS bf16x8*)(lds + PG8_SB(b, h) + boff + n * 2048 + k * 1024); } while (0)
; #define PG8_MMA(ai, bj, At, Bt) do { __builtin_amdgcn_s_setprio(1); _Pragma("unroll") for (int m = 0; m < 4; ++m) _Pragma("unroll") for (int n = 0; n < 2; ++n) _Pragma("unroll") for (int k = 0; k < 2; ++k) \
;         acc[ai][bj][m][n] = __builtin_amdgcn_mfma_f32_16x16x32_bf16(Bt[n][k], At[m][k], acc[ai][bj][m][n], 0, 0, 0); __builtin_amdgcn_s_setprio(0); } while (0)
; #define PG8_WAIT_V(n) asm volatile("s_waitcnt vmcnt(" #n ")" ::: "memory")
; #define PG8_WAIT_L(n) asm volatile("s_waitcnt lgkmcnt(" #n ")" ::: "memory")
; #define PG8_BAR __builtin_amdgcn_s_barrier()
; #define PG8_SCHED __builtin_amdgcn_sched_barrier(0)
; template <class Epi, class Sched, bool STAMP = false>
; __device__ __forceinline__ void gemm_phase(PG8_LAS unsigned char* lds, const Gemm g, const Sched& S, const Epi& E, unsigned long long* stamps) {
;     ...
;             PG8_LDB(B0, 0, 0); PG8_SCHED; PG8_LDA(At, 0, 0); PG8_STAGE(PG8_SA(1, 1), a1 + hstep, voffA);
;             PG8_WAIT_L(8); PG8_BAR; PG8_WAIT_L(0); PG8_MMA(0, 0, At, B0); PG8_BAR; PG8_SCHED;
;             PG8_LDB(B1, 0, 1); PG8_STAGE(PG8_SB(0, 0), b2, voffB);
;             PG8_BAR; PG8_WAIT_L(0); PG8_MMA(0, 1, At, B1); PG8_BAR;
;             PG8_LDA(At, 0, 1); PG8_STAGE(PG8_SA(0, 0), a2, voffA);
;             PG8_BAR; PG8_WAIT_L(0); PG8_MMA(1, 0, At, B0); PG8_BAR; PG8_SCHED;
;             PG8_STAGE(PG8_SB(0, 1), b2 + hstep, voffB);
;             PG8_WAIT_V(6); PG8_BAR; PG8_MMA(1, 1, At, B1); PG8_BAR;
.LBB0_313:
	s_add_u32 s12, s4, 0xfffc0080
	s_addc_u32 s13, s5, -1
	s_add_i32 s14, 0, 0x10000
	ds_read_b128 v[158:161], v248
	ds_read_b128 v[162:165], v248 offset:1024
	ds_read_b128 v[170:173], v248 offset:2048
	ds_read_b128 v[174:177], v248 offset:3072
	s_cmp_eq_u32 s65, 12
	s_cselect_b32 s27, s31, s13
	s_cselect_b32 s26, s47, s12
	s_cselect_b32 s13, s7, s63
	s_cselect_b32 s12, s53, s62
	s_add_i32 m0, s3, 0xc000
	ds_read_b128 v[178:181], v169
	ds_read_b128 v[192:195], v169 offset:1024
	ds_read_b128 v[196:199], v169 offset:2048
	ds_read_b128 v[200:203], v169 offset:3072
	ds_read_b128 v[204:207], v169 offset:4096
	ds_read_b128 v[208:211], v169 offset:5120
	ds_read_b128 v[212:215], v169 offset:6144
	global_load_lds_dwordx4 v154, s[4:5]
	s_add_i32 m0, s3, 0xe000
	ds_read_b128 v[216:219], v169 offset:7168
	global_load_lds_dwordx4 v156, s[4:5]
	s_waitcnt lgkmcnt(8)
	s_barrier
	s_waitcnt lgkmcnt(0)
	v_mfma_f32_16x16x32_bf16 v[124:127], v[158:161], v[178:181], v[124:127]
	v_mfma_f32_16x16x32_bf16 v[120:123], v[170:173], v[178:181], v[120:123]
	v_mfma_f32_16x16x32_bf16 v[108:111], v[158:161], v[196:199], v[108:111]
	v_mfma_f32_16x16x32_bf16 v[104:107], v[170:173], v[196:199], v[104:107]
	v_mfma_f32_16x16x32_bf16 v[92:95], v[158:161], v[204:207], v[92:95]
	v_mfma_f32_16x16x32_bf16 v[88:91], v[170:173], v[204:207], v[88:91]
	v_mfma_f32_16x16x32_bf16 v[76:79], v[158:161], v[212:215], v[76:79]
	v_mfma_f32_16x16x32_bf16 v[72:75], v[170:173], v[212:215], v[72:75]
	v_mfma_f32_16x16x32_bf16 v[124:127], v[162:165], v[192:195], v[124:127]
	v_mfma_f32_16x16x32_bf16 v[120:123], v[174:177], v[192:195], v[120:123]
	v_mfma_f32_16x16x32_bf16 v[108:111], v[162:165], v[200:203], v[108:111]
	v_mfma_f32_16x16x32_bf16 v[104:107], v[174:177], v[200:203], v[104:107]
	v_mfma_f32_16x16x32_bf16 v[92:95], v[162:165], v[208:211], v[92:95]
	v_mfma_f32_16x16x32_bf16 v[88:91], v[174:177], v[208:211], v[88:91]
	v_mfma_f32_16x16x32_bf16 v[76:79], v[162:165], v[216:219], v[76:79]
	v_mfma_f32_16x16x32_bf16 v[72:75], v[174:177], v[216:219], v[72:75]
	s_barrier
	s_add_i32 s16, 0, 0x14000
	s_add_i32 s14, s14, s56
	s_mov_b32 m0, s14
	ds_read_b128 v[220:223], v249
	ds_read_b128 v[224:227], v249 offset:1024
	ds_read_b128 v[228:231], v249 offset:2048
	global_load_lds_dwordx4 v128, s[12:13]
	s_add_i32 m0, s14, 0x2000
	ds_read_b128 v[232:235], v249 offset:3072
	global_load_lds_dwordx4 v152, s[12:13]
	s_barrier
	s_waitcnt lgkmcnt(0)
	v_mfma_f32_16x16x32_bf16 v[116:119], v[220:223], v[178:181], v[116:119]
	v_mfma_f32_16x16x32_bf16 v[112:115], v[228:231], v[178:181], v[112:115]
	v_mfma_f32_16x16x32_bf16 v[100:103], v[220:223], v[196:199], v[100:103]
	v_mfma_f32_16x16x32_bf16 v[96:99], v[228:231], v[196:199], v[96:99]
	v_mfma_f32_16x16x32_bf16 v[84:87], v[220:223], v[204:207], v[84:87]
	v_mfma_f32_16x16x32_bf16 v[80:83], v[228:231], v[204:207], v[80:83]
	v_mfma_f32_16x16x32_bf16 v[68:71], v[220:223], v[212:215], v[68:71]
	v_mfma_f32_16x16x32_bf16 v[64:67], v[228:231], v[212:215], v[64:67]
	v_mfma_f32_16x16x32_bf16 v[116:119], v[224:227], v[192:195], v[116:119]
	v_mfma_f32_16x16x32_bf16 v[112:115], v[232:235], v[192:195], v[112:115]
	v_mfma_f32_16x16x32_bf16 v[100:103], v[224:227], v[200:203], v[100:103]
	v_mfma_f32_16x16x32_bf16 v[96:99], v[232:235], v[200:203], v[96:99]
	v_mfma_f32_16x16x32_bf16 v[84:87], v[224:227], v[208:211], v[84:87]
	v_mfma_f32_16x16x32_bf16 v[80:83], v[232:235], v[208:211], v[80:83]
	v_mfma_f32_16x16x32_bf16 v[68:71], v[224:227], v[216:219], v[68:71]
	v_mfma_f32_16x16x32_bf16 v[64:67], v[232:235], v[216:219], v[64:67]
	s_mov_b32 m0, s3
	s_barrier
	ds_read_b128 v[178:181], v169 offset:16384
	ds_read_b128 v[192:195], v169 offset:17408
	ds_read_b128 v[196:199], v169 offset:18432
	ds_read_b128 v[200:203], v169 offset:19456
	ds_read_b128 v[204:207], v169 offset:20480
	ds_read_b128 v[208:211], v169 offset:21504
	ds_read_b128 v[212:215], v169 offset:22528
	global_load_lds_dwordx4 v148, s[26:27]
	s_mov_b32 m0, s57
	ds_read_b128 v[216:219], v169 offset:23552
	global_load_lds_dwordx4 v150, s[26:27]
	s_barrier
	s_waitcnt lgkmcnt(0)
	v_mfma_f32_16x16x32_bf16 v[60:63], v[158:161], v[178:181], v[60:63]
	v_mfma_f32_16x16x32_bf16 v[56:59], v[170:173], v[178:181], v[56:59]
	v_mfma_f32_16x16x32_bf16 v[44:47], v[158:161], v[196:199], v[44:47]
	v_mfma_f32_16x16x32_bf16 v[40:43], v[170:173], v[196:199], v[40:43]
	v_mfma_f32_16x16x32_bf16 v[28:31], v[158:161], v[204:207], v[28:31]
	v_mfma_f32_16x16x32_bf16 v[24:27], v[170:173], v[204:207], v[24:27]
	v_mfma_f32_16x16x32_bf16 v[12:15], v[158:161], v[212:215], v[12:15]
	v_mfma_f32_16x16x32_bf16 v[8:11], v[170:173], v[212:215], v[8:11]
	v_mfma_f32_16x16x32_bf16 v[60:63], v[162:165], v[192:195], v[60:63]
	v_mfma_f32_16x16x32_bf16 v[56:59], v[174:177], v[192:195], v[56:59]
	v_mfma_f32_16x16x32_bf16 v[44:47], v[162:165], v[200:203], v[44:47]
	v_mfma_f32_16x16x32_bf16 v[40:43], v[174:177], v[200:203], v[40:43]
	v_mfma_f32_16x16x32_bf16 v[28:31], v[162:165], v[208:211], v[28:31]
	v_mfma_f32_16x16x32_bf16 v[24:27], v[174:177], v[208:211], v[24:27]
	v_mfma_f32_16x16x32_bf16 v[12:15], v[162:165], v[216:219], v[12:15]
	v_mfma_f32_16x16x32_bf16 v[8:11], v[174:177], v[216:219], v[8:11]
	s_barrier
	s_add_u32 s14, s12, 0x40000
	s_addc_u32 s15, s13, 0
	s_add_i32 s16, s16, s56
	s_mov_b32 m0, s16
	s_nop 0
	global_load_lds_dwordx4 v128, s[14:15]
	s_add_i32 m0, s16, 0x2000
	s_nop 0
	global_load_lds_dwordx4 v152, s[14:15]
	s_waitcnt vmcnt(6)
	s_barrier
; #define PG8_STAGE(bufoff, gbase, voff) do { _Pragma("unroll") for (int _i = 0; _i < 2; ++_i) \
;         __builtin_amdgcn_global_load_lds((const unsigned*)((const char*)(gbase) + (voff)[_i]), (PG8_LAS unsigned*)(lds + (bufoff) + ldsw + _i * 8192), 16, 0, 0); } while (0)
; #define PG8_LDA(dst, b, h) do { _Pragma("unroll") for (int m = 0; m < 4; ++m) _Pragma("unroll") for (int k = 0; k < 2; ++k) dst[m][k] = *(const PG8_LAS bf16x8*)(lds + PG8_SA(b, h) + aoff + m * 2048 + k * 1024); } while (0)
; #define PG8_LDB(dst, b, h) do { _Pragma("unroll") for (int n = 0; n < 2; ++n) _Pragma("unroll") for (int k = 0; k < 2; ++k) dst[n][k] = *(const PG8_LAS bf16x8*)(lds + PG8_SB(b, h) + boff + n * 2048 + k * 1024); } while (0)
; #define PG8_MMA(ai, bj, At, Bt) do { __builtin_amdgcn_s_setprio(1); _Pragma("unroll") for (int m = 0; m < 4; ++m) _Pragma("unroll") for (int n = 0; n < 2; ++n) _Pragma("unroll") for (int k = 0; k < 2; ++k) \
;         acc[ai][bj][m][n] = __builtin_amdgcn_mfma_f32_16x16x32_bf16(Bt[n][k], At[m][k], acc[ai][bj][m][n], 0, 0, 0); __builtin_amdgcn_s_setprio(0); } while (0)
; #define PG8_WAIT_V(n) asm volatile("s_waitcnt vmcnt(" #n ")" ::: "memory")
; #define PG8_WAIT_L(n) asm volatile("s_waitcnt lgkmcnt(" #n ")" ::: "memory")
; #define PG8_BAR __builtin_amdgcn_s_barrier()
; #define PG8_SCHED __builtin_amdgcn_sched_barrier(0)
; template <class Epi, class Sched, bool STAMP = false>
; __device__ __forceinline__ void gemm_phase(PG8_LAS unsigned char* lds, const Gemm g, const Sched& S, const Epi& E, unsigned long long* stamps) {
;     ...
;             PG8_WAIT_V(6); PG8_BAR; PG8_MMA(1, 1, At, B1); PG8_BAR;
;             PG8_LDB(B0, 1, 0); PG8_SCHED; PG8_LDA(At, 1, 0); PG8_STAGE(PG8_SA(0, 1), a2 + hstep, voffA);
;             PG8_WAIT_L(8); PG8_BAR; PG8_WAIT_L(0); PG8_MMA(0, 0, At, B0); PG8_BAR; PG8_SCHED;
;             PG8_LDB(B1, 1, 1); PG8_STAGE(PG8_SB(1, 0), b3, voffB);
;             PG8_BAR; PG8_WAIT_L(0); PG8_MMA(0, 1, At, B1); PG8_BAR;
;             PG8_LDA(At, 1, 1); PG8_STAGE(PG8_SA(1, 0), a3, voffA);
	v_mfma_f32_16x16x32_bf16 v[52:55], v[220:223], v[178:181], v[52:55]
	v_mfma_f32_16x16x32_bf16 v[48:51], v[228:231], v[178:181], v[48:51]
	v_mfma_f32_16x16x32_bf16 v[36:39], v[220:223], v[196:199], v[36:39]
	v_mfma_f32_16x16x32_bf16 v[32:35], v[228:231], v[196:199], v[32:35]
	v_mfma_f32_16x16x32_bf16 v[20:23], v[220:223], v[204:207], v[20:23]
	v_mfma_f32_16x16x32_bf16 v[16:19], v[228:231], v[204:207], v[16:19]
	v_mfma_f32_16x16x32_bf16 v[4:7], v[220:223], v[212:215], v[4:7]
	v_mfma_f32_16x16x32_bf16 v[0:3], v[228:231], v[212:215], v[0:3]
	v_mfma_f32_16x16x32_bf16 v[52:55], v[224:227], v[192:195], v[52:55]
	v_mfma_f32_16x16x32_bf16 v[48:51], v[232:235], v[192:195], v[48:51]
	v_mfma_f32_16x16x32_bf16 v[36:39], v[224:227], v[200:203], v[36:39]
	v_mfma_f32_16x16x32_bf16 v[32:35], v[232:235], v[200:203], v[32:35]
	v_mfma_f32_16x16x32_bf16 v[20:23], v[224:227], v[208:211], v[20:23]
	v_mfma_f32_16x16x32_bf16 v[16:19], v[232:235], v[208:211], v[16:19]
	v_mfma_f32_16x16x32_bf16 v[4:7], v[224:227], v[216:219], v[4:7]
	v_mfma_f32_16x16x32_bf16 v[0:3], v[232:235], v[216:219], v[0:3]
	s_add_i32 s16, 0, 0x18000
	s_barrier
	ds_read_b128 v[158:161], v250
	ds_read_b128 v[162:165], v250 offset:1024
	ds_read_b128 v[170:173], v250 offset:2048
	ds_read_b128 v[174:177], v250 offset:3072
	s_add_u32 s14, s26, 0x40000
	s_addc_u32 s15, s27, 0
	s_mov_b32 m0, s58
	ds_read_b128 v[178:181], v169 offset:32768
	ds_read_b128 v[192:195], v169 offset:33792
	ds_read_b128 v[196:199], v169 offset:34816
	ds_read_b128 v[200:203], v169 offset:35840
	ds_read_b128 v[204:207], v169 offset:36864
	ds_read_b128 v[208:211], v169 offset:37888
	ds_read_b128 v[212:215], v169 offset:38912
	global_load_lds_dwordx4 v148, s[14:15]
	s_mov_b32 m0, s59
	ds_read_b128 v[216:219], v169 offset:39936
	global_load_lds_dwordx4 v150, s[14:15]
	s_waitcnt lgkmcnt(8)
	s_barrier
	s_waitcnt lgkmcnt(0)
	v_mfma_f32_16x16x32_bf16 v[124:127], v[158:161], v[178:181], v[124:127]
	v_mfma_f32_16x16x32_bf16 v[120:123], v[170:173], v[178:181], v[120:123]
	v_mfma_f32_16x16x32_bf16 v[108:111], v[158:161], v[196:199], v[108:111]
	v_mfma_f32_16x16x32_bf16 v[104:107], v[170:173], v[196:199], v[104:107]
	v_mfma_f32_16x16x32_bf16 v[92:95], v[158:161], v[204:207], v[92:95]
	v_mfma_f32_16x16x32_bf16 v[88:91], v[170:173], v[204:207], v[88:91]
	v_mfma_f32_16x16x32_bf16 v[76:79], v[158:161], v[212:215], v[76:79]
	v_mfma_f32_16x16x32_bf16 v[72:75], v[170:173], v[212:215], v[72:75]
	v_mfma_f32_16x16x32_bf16 v[124:127], v[162:165], v[192:195], v[124:127]
	v_mfma_f32_16x16x32_bf16 v[120:123], v[174:177], v[192:195], v[120:123]
	v_mfma_f32_16x16x32_bf16 v[108:111], v[162:165], v[200:203], v[108:111]
	v_mfma_f32_16x16x32_bf16 v[104:107], v[174:177], v[200:203], v[104:107]
	v_mfma_f32_16x16x32_bf16 v[92:95], v[162:165], v[208:211], v[92:95]
	v_mfma_f32_16x16x32_bf16 v[88:91], v[174:177], v[208:211], v[88:91]
	v_mfma_f32_16x16x32_bf16 v[76:79], v[162:165], v[216:219], v[76:79]
	v_mfma_f32_16x16x32_bf16 v[72:75], v[174:177], v[216:219], v[72:75]
	s_barrier
	s_add_i32 s14, 0, 0x1c000
	s_add_i32 s15, s16, s56
	s_mov_b32 m0, s15
	ds_read_b128 v[220:223], v251
	ds_read_b128 v[224:227], v251 offset:1024
	ds_read_b128 v[228:231], v251 offset:2048
	global_load_lds_dwordx4 v244, s[12:13]
	s_add_i32 m0, s15, 0x2000
	ds_read_b128 v[232:235], v251 offset:3072
	global_load_lds_dwordx4 v245, s[12:13]
	s_barrier
	s_waitcnt lgkmcnt(0)
	v_mfma_f32_16x16x32_bf16 v[116:119], v[220:223], v[178:181], v[116:119]
	v_mfma_f32_16x16x32_bf16 v[112:115], v[228:231], v[178:181], v[112:115]
	v_mfma_f32_16x16x32_bf16 v[100:103], v[220:223], v[196:199], v[100:103]
	v_mfma_f32_16x16x32_bf16 v[96:99], v[228:231], v[196:199], v[96:99]
	v_mfma_f32_16x16x32_bf16 v[84:87], v[220:223], v[204:207], v[84:87]
	v_mfma_f32_16x16x32_bf16 v[80:83], v[228:231], v[204:207], v[80:83]
	v_mfma_f32_16x16x32_bf16 v[68:71], v[220:223], v[212:215], v[68:71]
	v_mfma_f32_16x16x32_bf16 v[64:67], v[228:231], v[212:215], v[64:67]
	v_mfma_f32_16x16x32_bf16 v[116:119], v[224:227], v[192:195], v[116:119]
	v_mfma_f32_16x16x32_bf16 v[112:115], v[232:235], v[192:195], v[112:115]
	v_mfma_f32_16x16x32_bf16 v[100:103], v[224:227], v[200:203], v[100:103]
	v_mfma_f32_16x16x32_bf16 v[96:99], v[232:235], v[200:203], v[96:99]
	v_mfma_f32_16x16x32_bf16 v[84:87], v[224:227], v[208:211], v[84:87]
	v_mfma_f32_16x16x32_bf16 v[80:83], v[232:235], v[208:211], v[80:83]
	v_mfma_f32_16x16x32_bf16 v[68:71], v[224:227], v[216:219], v[68:71]
	v_mfma_f32_16x16x32_bf16 v[64:67], v[232:235], v[216:219], v[64:67]
	s_mov_b32 m0, s60
	s_barrier
	ds_read_b128 v[178:181], v169 offset:49152
	ds_read_b128 v[192:195], v169 offset:50176
	ds_read_b128 v[196:199], v169 offset:51200
	ds_read_b128 v[200:203], v169 offset:52224
	ds_read_b128 v[204:207], v169 offset:53248
	ds_read_b128 v[208:211], v169 offset:54272
	ds_read_b128 v[212:215], v169 offset:55296
	global_load_lds_dwordx4 v246, s[26:27]
	s_mov_b32 m0, s61
	ds_read_b128 v[216:219], v169 offset:56320
	global_load_lds_dwordx4 v247, s[26:27]
	s_barrier
	s_waitcnt lgkmcnt(0)
	v_mfma_f32_16x16x32_bf16 v[60:63], v[158:161], v[178:181], v[60:63]
	v_mfma_f32_16x16x32_bf16 v[56:59], v[170:173], v[178:181], v[56:59]
	v_mfma_f32_16x16x32_bf16 v[44:47], v[158:161], v[196:199], v[44:47]
	v_mfma_f32_16x16x32_bf16 v[40:43], v[170:173], v[196:199], v[40:43]
	v_mfma_f32_16x16x32_bf16 v[28:31], v[158:161], v[204:207], v[28:31]
	v_mfma_f32_16x16x32_bf16 v[24:27], v[170:173], v[204:207], v[24:27]
	v_mfma_f32_16x16x32_bf16 v[12:15], v[158:161], v[212:215], v[12:15]
	v_mfma_f32_16x16x32_bf16 v[8:11], v[170:173], v[212:215], v[8:11]
	v_mfma_f32_16x16x32_bf16 v[60:63], v[162:165], v[192:195], v[60:63]
	v_mfma_f32_16x16x32_bf16 v[56:59], v[174:177], v[192:195], v[56:59]
	v_mfma_f32_16x16x32_bf16 v[44:47], v[162:165], v[200:203], v[44:47]
	v_mfma_f32_16x16x32_bf16 v[40:43], v[174:177], v[200:203], v[40:43]
	v_mfma_f32_16x16x32_bf16 v[28:31], v[162:165], v[208:211], v[28:31]
	v_mfma_f32_16x16x32_bf16 v[24:27], v[174:177], v[208:211], v[24:27]
	v_mfma_f32_16x16x32_bf16 v[12:15], v[162:165], v[216:219], v[12:15]
	v_mfma_f32_16x16x32_bf16 v[8:11], v[174:177], v[216:219], v[8:11]
	s_barrier
; #define PG8_STAGE(bufoff, gbase, voff) do { _Pragma("unroll") for (int _i = 0; _i < 2; ++_i) \
;         __builtin_amdgcn_global_load_lds((const unsigned*)((const char*)(gbase) + (voff)[_i]), (PG8_LAS unsigned*)(lds + (bufoff) + ldsw + _i * 8192), 16, 0, 0); } while (0)
; #define PG8_MMA(ai, bj, At, Bt) do { __builtin_amdgcn_s_setprio(1); _Pragma("unroll") for (int m = 0; m < 4; ++m) _Pragma("unroll") for (int n = 0; n < 2; ++n) _Pragma("unroll") for (int k = 0; k < 2; ++k) \
;         acc[ai][bj][m][n] = __builtin_amdgcn_mfma_f32_16x16x32_bf16(Bt[n][k], At[m][k], acc[ai][bj][m][n], 0, 0, 0); __builtin_amdgcn_s_setprio(0); } while (0)
; #define PG8_WAIT_V(n) asm volatile("s_waitcnt vmcnt(" #n ")" ::: "memory")
; #define PG8_BAR __builtin_amdgcn_s_barrier()
; template <class Epi, class Sched, bool STAMP = false>
; __device__ __forceinline__ void gemm_phase(PG8_LAS unsigned char* lds, const Gemm g, const Sched& S, const Epi& E, unsigned long long* stamps) {
;     ...
;             PG8_STAGE(PG8_SB(1, 1), b3 + hstep, voffB);
;             PG8_WAIT_V(6); PG8_BAR; PG8_MMA(1, 1, At, B1); PG8_BAR;
;     __device__ __forceinline__ void operator()(const f32x4 (&acc)[2][2][4][2], const pg8::Unit& u, int wr, int wc, int fr, int fq) const {
;         const int row0 = u.pm * 256 + wr * 64 + fr, col0 = u.pn * 256 + wc * 32 + 8 * fq;
; #pragma unroll
;         for (int ai = 0; ai < 2; ++ai)
; #pragma unroll
;             for (int m = 0; m < 4; ++m) {
;                 const int row = row0 + ai * 128 + m * 16;
;                 const float s = rstd_of(rowss, row);
; #pragma unroll
;                 for (int bj = 0; bj < 2; ++bj) {
;                     const size_t off = (size_t)row * 1024 + col0 + bj * 128;
;                     const u32x4 tv = *(const u32x4*)(Tm + off);
;                     u32x4 pv = (u32x4){0u, 0u, 0u, 0u};
;                     if (ACC) pv = *(const u32x4*)(M + off);
;                     const f32x4 a0 = acc[ai][bj][m][0] * s, a1 = acc[ai][bj][m][1] * s;
;                     float o[8];
;                     o[0] = sigm(a0[0]) * lo16(tv.x); o[1] = sigm(a0[1]) * hi16(tv.x); o[2] = sigm(a0[2]) * lo16(tv.y); o[3] = sigm(a0[3]) * hi16(tv.y);
;                     o[4] = sigm(a1[0]) * lo16(tv.z); o[5] = sigm(a1[1]) * hi16(tv.z); o[6] = sigm(a1[2]) * lo16(tv.w); o[7] = sigm(a1[3]) * hi16(tv.w);
	s_add_u32 s12, s12, 0x40080
	s_addc_u32 s13, s13, 0
	s_add_i32 s14, s14, s56
	s_mov_b32 m0, s14
	s_nop 0
	global_load_lds_dwordx4 v128, s[12:13]
	s_add_i32 m0, s14, 0x2000
	s_nop 0
	global_load_lds_dwordx4 v152, s[12:13]
	s_waitcnt vmcnt(6)
	s_barrier
	v_mfma_f32_16x16x32_bf16 v[52:55], v[220:223], v[178:181], v[52:55]
	v_mfma_f32_16x16x32_bf16 v[48:51], v[228:231], v[178:181], v[48:51]
	v_mfma_f32_16x16x32_bf16 v[36:39], v[220:223], v[196:199], v[36:39]
	v_mfma_f32_16x16x32_bf16 v[32:35], v[228:231], v[196:199], v[32:35]
	v_mfma_f32_16x16x32_bf16 v[20:23], v[220:223], v[204:207], v[20:23]
	v_mfma_f32_16x16x32_bf16 v[16:19], v[228:231], v[204:207], v[16:19]
	v_mfma_f32_16x16x32_bf16 v[4:7], v[220:223], v[212:215], v[4:7]
	v_mfma_f32_16x16x32_bf16 v[0:3], v[228:231], v[212:215], v[0:3]
	v_mfma_f32_16x16x32_bf16 v[52:55], v[224:227], v[192:195], v[52:55]
	v_mfma_f32_16x16x32_bf16 v[48:51], v[232:235], v[192:195], v[48:51]
	v_mfma_f32_16x16x32_bf16 v[36:39], v[224:227], v[200:203], v[36:39]
	v_mfma_f32_16x16x32_bf16 v[32:35], v[232:235], v[200:203], v[32:35]
	v_mfma_f32_16x16x32_bf16 v[20:23], v[224:227], v[208:211], v[20:23]
	v_mfma_f32_16x16x32_bf16 v[16:19], v[232:235], v[208:211], v[16:19]
	v_mfma_f32_16x16x32_bf16 v[4:7], v[224:227], v[216:219], v[4:7]
	v_mfma_f32_16x16x32_bf16 v[0:3], v[232:235], v[216:219], v[0:3]
	s_add_i32 s65, s65, 2
	s_add_u32 s4, s4, 0x100
	s_addc_u32 s5, s5, 0
	s_add_u32 s62, s62, 0x100
	s_addc_u32 s63, s63, 0
	s_cmp_gt_u32 s65, 13
	s_barrier
	s_cbranch_scc0 .LBB0_313
	v_lshl_add_u32 v162, s2, 8, v139
	v_ashrrev_i32_e32 v163, 31, v162
	v_lshl_add_u64 v[160:161], v[162:163], 2, s[40:41]
	global_load_dword v164, v[160:161], off
	v_lshl_or_b32 v158, s46, 8, v168
	v_ashrrev_i32_e32 v159, 31, v158
	s_mov_b32 s2, 0x40000
	s_mov_b64 s[4:5], 0x40000
	s_mov_b32 s46, s6
	s_mov_b64 s[12:13], s[24:25]
	s_mov_b32 s62, 0x1800000
	s_waitcnt vmcnt(0)
	v_fmamk_f32 v164, v164, 0x3a800000, v187
	v_cmp_gt_f32_e32 vcc, s67, v164
	v_mul_f32_e32 v165, 0x4b800000, v164
	s_nop 0
	v_cndmask_b32_e32 v164, v164, v165, vcc
	v_rsq_f32_e32 v164, v164
	s_nop 0
	v_mul_f32_e32 v165, 0x45800000, v164
	v_cndmask_b32_e32 v166, v164, v165, vcc
	v_lshlrev_b64 v[164:165], 11, v[162:163]
	v_lshl_add_u64 v[170:171], s[0:1], 0, v[164:165]
	v_lshlrev_b64 v[164:165], 1, v[158:159]
	v_lshl_add_u64 v[158:159], v[170:171], 0, v[164:165]
	v_mov_b32_e32 v170, v158
	v_mov_b32_e32 v171, v159
	global_load_dwordx4 v[192:195], v[170:171], off
	global_load_dwordx4 v[196:199], v[170:171], off offset:256
	v_add_co_u32_e32 v170, vcc, 0x8000, v170
	s_nop 1
	v_addc_co_u32_e32 v171, vcc, 0, v171, vcc
	global_load_dwordx4 v[200:203], v[170:171], off
	global_load_dwordx4 v[204:207], v[170:171], off offset:256
	v_add_co_u32_e32 v170, vcc, 0x8000, v170
	s_nop 1
	v_addc_co_u32_e32 v171, vcc, 0, v171, vcc
	global_load_dwordx4 v[208:211], v[170:171], off
	global_load_dwordx4 v[212:215], v[170:171], off offset:256
	v_add_co_u32_e32 v170, vcc, 0x8000, v170
	s_nop 1
	v_addc_co_u32_e32 v171, vcc, 0, v171, vcc
	global_load_dwordx4 v[216:219], v[170:171], off
	global_load_dwordx4 v[220:223], v[170:171], off offset:256
	v_lshl_add_u64 v[170:171], v[158:159], 0, s[4:5]
	global_load_dwordx4 v[224:227], v[170:171], off
	global_load_dwordx4 v[228:231], v[170:171], off offset:256
	v_add_co_u32_e32 v170, vcc, 0x8000, v170
	s_nop 1
	v_addc_co_u32_e32 v171, vcc, 0, v171, vcc
	global_load_dwordx4 v[232:235], v[170:171], off
	global_load_dwordx4 v[236:239], v[170:171], off offset:256
	v_add_co_u32_e32 v170, vcc, 0x8000, v170
	s_nop 1
	v_addc_co_u32_e32 v171, vcc, 0, v171, vcc
	global_load_dwordx4 v[244:247], v[170:171], off
	global_load_dwordx4 v[248:251], v[170:171], off offset:256
	v_add_co_u32_e32 v170, vcc, 0x8000, v170
	s_nop 1
	v_addc_co_u32_e32 v171, vcc, 0, v171, vcc
	global_load_dwordx4 v[176:179], v[170:171], off
	global_load_dwordx4 v[252:255], v[170:171], off offset:256
	global_load_dword v180, v[160:161], off offset:64
	global_load_dword v181, v[160:161], off offset:128
	global_load_dword v182, v[160:161], off offset:192
	global_load_dword v183, v[160:161], off offset:512
	global_load_dword v240, v[160:161], off offset:576
	global_load_dword v241, v[160:161], off offset:640
	global_load_dword v169, v[160:161], off offset:704
	v_pk_mul_f32 v[126:127], v[126:127], v[166:167] op_sel_hi:[1,0]
	v_pk_mul_f32 v[120:121], v[120:121], v[166:167] op_sel_hi:[1,0]
	v_mul_f32_e32 v126, 0xbfb8aa3b, v126
	v_mul_f32_e32 v127, 0xbfb8aa3b, v127
	v_exp_f32_e32 v126, v126
	v_exp_f32_e32 v127, v127
	v_mul_f32_e32 v120, 0xbfb8aa3b, v120
	v_mul_f32_e32 v121, 0xbfb8aa3b, v121
	v_exp_f32_e32 v120, v120
	v_exp_f32_e32 v121, v121
	v_add_f32_e32 v126, 1.0, v126
	v_add_f32_e32 v127, 1.0, v127
	v_rcp_f32_e32 v126, v126
	v_rcp_f32_e32 v127, v127
	v_add_f32_e32 v120, 1.0, v120
	v_add_f32_e32 v121, 1.0, v121
	v_rcp_f32_e32 v120, v120
	v_rcp_f32_e32 v121, v121
	v_pk_mul_f32 v[124:125], v[124:125], v[166:167] op_sel_hi:[1,0]
	v_pk_mul_f32 v[122:123], v[122:123], v[166:167] op_sel_hi:[1,0]
	v_mul_f32_e32 v124, 0xbfb8aa3b, v124
	v_mul_f32_e32 v125, 0xbfb8aa3b, v125
	v_exp_f32_e32 v124, v124
	v_exp_f32_e32 v125, v125
	v_pk_mul_f32 v[118:119], v[118:119], v[166:167] op_sel_hi:[1,0]
	v_pk_mul_f32 v[112:113], v[112:113], v[166:167] op_sel_hi:[1,0]
	v_add_f32_e32 v124, 1.0, v124
	v_add_f32_e32 v125, 1.0, v125
	v_rcp_f32_e32 v124, v124
	v_rcp_f32_e32 v125, v125
	v_mul_f32_e32 v118, 0xbfb8aa3b, v118
	v_mul_f32_e32 v119, 0xbfb8aa3b, v119
	v_exp_f32_e32 v118, v118
	v_exp_f32_e32 v119, v119
	v_mul_f32_e32 v112, 0xbfb8aa3b, v112
	v_mul_f32_e32 v113, 0xbfb8aa3b, v113
	v_exp_f32_e32 v112, v112
	v_exp_f32_e32 v113, v113
	v_add_f32_e32 v118, 1.0, v118
	v_add_f32_e32 v119, 1.0, v119
	v_rcp_f32_e32 v118, v118
	v_rcp_f32_e32 v119, v119
	v_add_f32_e32 v112, 1.0, v112
	v_add_f32_e32 v113, 1.0, v113
	v_rcp_f32_e32 v112, v112
	v_rcp_f32_e32 v113, v113
	v_pk_mul_f32 v[116:117], v[116:117], v[166:167] op_sel_hi:[1,0]
	v_pk_mul_f32 v[114:115], v[114:115], v[166:167] op_sel_hi:[1,0]
	v_mul_f32_e32 v116, 0xbfb8aa3b, v116
	v_mul_f32_e32 v117, 0xbfb8aa3b, v117
	v_exp_f32_e32 v116, v116
	v_exp_f32_e32 v117, v117
	v_add_f32_e32 v116, 1.0, v116
	v_add_f32_e32 v117, 1.0, v117
	v_rcp_f32_e32 v116, v116
	v_rcp_f32_e32 v117, v117
	s_waitcnt vmcnt(0)
; __device__ __forceinline__ unsigned cvt_pk_bf16(float lo, float hi) { const f32x2_cv v = {lo, hi}; const bf16x2_cv b = __builtin_convertvector(v, bf16x2_cv); return __builtin_bit_cast(unsigned, b); }
; __device__ __forceinline__ float sigm(float x) { return __builtin_amdgcn_rcpf(1.0f + __expf(-x)); }
; __device__ __forceinline__ float lo16(unsigned w) { return __uint_as_float(w << 16); }
; __device__ __forceinline__ float hi16(unsigned w) { return __uint_as_float(w & 0xffff0000u); }
; __device__ __forceinline__ float rstd_of(const float* rowss, int row) { return rsqrtf(rowss[row] * (1.0f / 1024.0f) + 1e-6f); }
;     __device__ __forceinline__ void operator()(const f32x4 (&acc)[2][2][4][2], const pg8::Unit& u, int wr, int wc, int fr, int fq) const {
;     ...
;                 const int row = row0 + ai * 128 + m * 16;
;                 const float s = rstd_of(rowss, row);
; #pragma unroll
;                 for (int bj = 0; bj < 2; ++bj) {
;                     const size_t off = (size_t)row * 1024 + col0 + bj * 128;
;                     const u32x4 tv = *(const u32x4*)(Tm + off);
;                     u32x4 pv = (u32x4){0u, 0u, 0u, 0u};
;                     if (ACC) pv = *(const u32x4*)(M + off);
;                     const f32x4 a0 = acc[ai][bj][m][0] * s, a1 = acc[ai][bj][m][1] * s;
;                     float o[8];
;                     o[0] = sigm(a0[0]) * lo16(tv.x); o[1] = sigm(a0[1]) * hi16(tv.x); o[2] = sigm(a0[2]) * lo16(tv.y); o[3] = sigm(a0[3]) * hi16(tv.y);
;                     o[4] = sigm(a1[0]) * lo16(tv.z); o[5] = sigm(a1[1]) * hi16(tv.z); o[6] = sigm(a1[2]) * lo16(tv.w); o[7] = sigm(a1[3]) * hi16(tv.w);
;                     if (ACC) { o[0] += lo16(pv.x); o[1] += hi16(pv.x); o[2] += lo16(pv.y); o[3] += hi16(pv.y); o[4] += lo16(pv.z); o[5] += hi16(pv.z); o[6] += lo16(pv.w); o[7] += hi16(pv.w); }
;                     u32x4 w; w.x = cvt_pk_bf16(o[0], o[1]); w.y = cvt_pk_bf16(o[2], o[3]); w.z = cvt_pk_bf16(o[4], o[5]); w.w = cvt_pk_bf16(o[6], o[7]);
;                     *(u32x4*)(M + off) = w; } }
	v_mov_b32_e32 v170, v192
	v_mov_b32_e32 v171, v193
	v_mov_b32_e32 v172, v194
	v_mov_b32_e32 v173, v195
	v_lshlrev_b32_e32 v174, 16, v170
	v_and_b32_e32 v175, 0xffff0000, v170
	v_lshlrev_b32_e32 v170, 16, v171
	v_and_b32_e32 v171, 0xffff0000, v171
	v_pk_mul_f32 v[126:127], v[126:127], v[170:171]
	v_lshlrev_b32_e32 v170, 16, v172
	v_and_b32_e32 v171, 0xffff0000, v172
	v_pk_mul_f32 v[170:171], v[120:121], v[170:171]
	v_mul_f32_e32 v120, 0xbfb8aa3b, v122
	v_mul_f32_e32 v121, 0xbfb8aa3b, v123
	v_exp_f32_e32 v120, v120
	v_exp_f32_e32 v121, v121
	v_lshlrev_b32_e32 v122, 16, v173
	v_and_b32_e32 v123, 0xffff0000, v173
	v_add_f32_e32 v120, 1.0, v120
	v_add_f32_e32 v121, 1.0, v121
	v_rcp_f32_e32 v120, v120
	v_rcp_f32_e32 v121, v121
	v_pk_mul_f32 v[124:125], v[124:125], v[174:175]
	v_pk_mul_f32 v[172:173], v[120:121], v[122:123]
	v_cvt_pk_bf16_f32 v120, v124, v125
	v_cvt_pk_bf16_f32 v121, v126, v127
	v_cvt_pk_bf16_f32 v122, v170, v171
	v_cvt_pk_bf16_f32 v123, v172, v173
	global_store_dwordx4 v[158:159], v[120:123], off
	s_nop 1
	v_mov_b32_e32 v120, v196
	v_mov_b32_e32 v121, v197
	v_mov_b32_e32 v122, v198
	v_mov_b32_e32 v123, v199
	v_lshlrev_b32_e32 v124, 16, v120
	v_and_b32_e32 v125, 0xffff0000, v120
	v_lshlrev_b32_e32 v120, 16, v121
	v_and_b32_e32 v121, 0xffff0000, v121
	v_pk_mul_f32 v[118:119], v[118:119], v[120:121]
	v_lshlrev_b32_e32 v120, 16, v122
	v_and_b32_e32 v121, 0xffff0000, v122
	v_pk_mul_f32 v[120:121], v[112:113], v[120:121]
	v_mul_f32_e32 v112, 0xbfb8aa3b, v114
	v_mul_f32_e32 v113, 0xbfb8aa3b, v115
	v_exp_f32_e32 v112, v112
	v_exp_f32_e32 v113, v113
	v_lshlrev_b32_e32 v114, 16, v123
	v_and_b32_e32 v115, 0xffff0000, v123
	v_add_f32_e32 v112, 1.0, v112
	v_add_f32_e32 v113, 1.0, v113
	v_rcp_f32_e32 v112, v112
	v_rcp_f32_e32 v113, v113
	v_pk_mul_f32 v[116:117], v[116:117], v[124:125]
	v_pk_mul_f32 v[122:123], v[112:113], v[114:115]
	v_cvt_pk_bf16_f32 v112, v116, v117
	v_cvt_pk_bf16_f32 v113, v118, v119
	v_cvt_pk_bf16_f32 v114, v120, v121
	v_cvt_pk_bf16_f32 v115, v122, v123
	global_store_dwordx4 v[158:159], v[112:115], off offset:256
	s_nop 1
	v_mov_b32_e32 v114, v180
	s_nop 0
	v_or_b32_e32 v112, 16, v162
	v_ashrrev_i32_e32 v113, 31, v112
	v_lshlrev_b64 v[112:113], 11, v[112:113]
	v_lshl_add_u64 v[112:113], s[0:1], 0, v[112:113]
	v_lshl_add_u64 v[112:113], v[112:113], 0, v[164:165]
	s_nop 1
	v_mov_b32_e32 v116, v200
	v_mov_b32_e32 v117, v201
	v_mov_b32_e32 v118, v202
	v_mov_b32_e32 v119, v203
	v_fmamk_f32 v114, v114, 0x3a800000, v187
	v_cmp_gt_f32_e32 vcc, s67, v114
	v_mul_f32_e32 v115, 0x4b800000, v114
	v_lshlrev_b32_e32 v120, 16, v116
	v_cndmask_b32_e32 v114, v114, v115, vcc
	v_rsq_f32_e32 v114, v114
	v_and_b32_e32 v121, 0xffff0000, v116
	v_lshlrev_b32_e32 v116, 16, v117
	v_and_b32_e32 v117, 0xffff0000, v117
	v_mul_f32_e32 v115, 0x45800000, v114
	v_cndmask_b32_e32 v114, v114, v115, vcc
	v_pk_mul_f32 v[110:111], v[110:111], v[114:115] op_sel_hi:[1,0]
	v_pk_mul_f32 v[104:105], v[104:105], v[114:115] op_sel_hi:[1,0]
	v_mul_f32_e32 v110, 0xbfb8aa3b, v110
	v_mul_f32_e32 v111, 0xbfb8aa3b, v111
	v_exp_f32_e32 v110, v110
	v_exp_f32_e32 v111, v111
	v_mul_f32_e32 v104, 0xbfb8aa3b, v104
	v_mul_f32_e32 v105, 0xbfb8aa3b, v105
	v_exp_f32_e32 v104, v104
	v_exp_f32_e32 v105, v105
	v_add_f32_e32 v110, 1.0, v110
	v_add_f32_e32 v111, 1.0, v111
	v_rcp_f32_e32 v110, v110
	v_rcp_f32_e32 v111, v111
	v_add_f32_e32 v104, 1.0, v104
	v_add_f32_e32 v105, 1.0, v105
	v_rcp_f32_e32 v104, v104
	v_rcp_f32_e32 v105, v105
	v_pk_mul_f32 v[108:109], v[108:109], v[114:115] op_sel_hi:[1,0]
	v_pk_mul_f32 v[106:107], v[106:107], v[114:115] op_sel_hi:[1,0]
	v_pk_mul_f32 v[110:111], v[110:111], v[116:117]
	v_lshlrev_b32_e32 v116, 16, v118
	v_and_b32_e32 v117, 0xffff0000, v118
	v_mul_f32_e32 v108, 0xbfb8aa3b, v108
	v_mul_f32_e32 v109, 0xbfb8aa3b, v109
	v_pk_mul_f32 v[116:117], v[104:105], v[116:117]
	v_mul_f32_e32 v104, 0xbfb8aa3b, v106
	v_mul_f32_e32 v105, 0xbfb8aa3b, v107
	v_exp_f32_e32 v108, v108
	v_exp_f32_e32 v109, v109
	v_exp_f32_e32 v104, v104
	v_exp_f32_e32 v105, v105
	v_add_f32_e32 v108, 1.0, v108
	v_add_f32_e32 v109, 1.0, v109
	v_add_f32_e32 v104, 1.0, v104
	v_add_f32_e32 v105, 1.0, v105
	v_rcp_f32_e32 v108, v108
	v_rcp_f32_e32 v109, v109
	v_rcp_f32_e32 v104, v104
	v_rcp_f32_e32 v105, v105
	v_lshlrev_b32_e32 v106, 16, v119
	v_and_b32_e32 v107, 0xffff0000, v119
	v_pk_mul_f32 v[108:109], v[108:109], v[120:121]
	v_pk_mul_f32 v[118:119], v[104:105], v[106:107]
	v_cvt_pk_bf16_f32 v104, v108, v109
	v_cvt_pk_bf16_f32 v105, v110, v111
	v_cvt_pk_bf16_f32 v106, v116, v117
	v_cvt_pk_bf16_f32 v107, v118, v119
	global_store_dwordx4 v[112:113], v[104:107], off
	s_nop 1
	v_mov_b32_e32 v104, v204
	v_mov_b32_e32 v105, v205
	v_mov_b32_e32 v106, v206
	v_mov_b32_e32 v107, v207
	v_pk_mul_f32 v[102:103], v[102:103], v[114:115] op_sel_hi:[1,0]
	v_pk_mul_f32 v[96:97], v[96:97], v[114:115] op_sel_hi:[1,0]
	v_mul_f32_e32 v102, 0xbfb8aa3b, v102
	v_mul_f32_e32 v103, 0xbfb8aa3b, v103
	v_exp_f32_e32 v102, v102
	v_exp_f32_e32 v103, v103
	v_mul_f32_e32 v96, 0xbfb8aa3b, v96
	v_mul_f32_e32 v97, 0xbfb8aa3b, v97
	v_exp_f32_e32 v96, v96
	v_exp_f32_e32 v97, v97
	v_add_f32_e32 v102, 1.0, v102
	v_add_f32_e32 v103, 1.0, v103
	v_rcp_f32_e32 v102, v102
	v_rcp_f32_e32 v103, v103
	v_add_f32_e32 v96, 1.0, v96
	v_add_f32_e32 v97, 1.0, v97
	v_rcp_f32_e32 v96, v96
	v_rcp_f32_e32 v97, v97
	v_pk_mul_f32 v[100:101], v[100:101], v[114:115] op_sel_hi:[1,0]
	v_pk_mul_f32 v[98:99], v[98:99], v[114:115] op_sel_hi:[1,0]
	v_mul_f32_e32 v100, 0xbfb8aa3b, v100
	v_mul_f32_e32 v101, 0xbfb8aa3b, v101
	v_exp_f32_e32 v100, v100
	v_exp_f32_e32 v101, v101
	v_add_f32_e32 v100, 1.0, v100
	v_add_f32_e32 v101, 1.0, v101
	v_rcp_f32_e32 v100, v100
; __device__ __forceinline__ unsigned cvt_pk_bf16(float lo, float hi) { const f32x2_cv v = {lo, hi}; const bf16x2_cv b = __builtin_convertvector(v, bf16x2_cv); return __builtin_bit_cast(unsigned, b); }
; __device__ __forceinline__ float sigm(float x) { return __builtin_amdgcn_rcpf(1.0f + __expf(-x)); }
; __device__ __forceinline__ float lo16(unsigned w) { return __uint_as_float(w << 16); }
; __device__ __forceinline__ float hi16(unsigned w) { return __uint_as_float(w & 0xffff0000u); }
; __device__ __forceinline__ float rstd_of(const float* rowss, int row) { return rsqrtf(rowss[row] * (1.0f / 1024.0f) + 1e-6f); }
;     __device__ __forceinline__ void operator()(const f32x4 (&acc)[2][2][4][2], const pg8::Unit& u, int wr, int wc, int fr, int fq) const {
;     ...
;                 const int row = row0 + ai * 128 + m * 16;
;                 const float s = rstd_of(rowss, row);
; #pragma unroll
;                 for (int bj = 0; bj < 2; ++bj) {
;                     const size_t off = (size_t)row * 1024 + col0 + bj * 128;
;                     const u32x4 tv = *(const u32x4*)(Tm + off);
;                     u32x4 pv = (u32x4){0u, 0u, 0u, 0u};
;                     if (ACC) pv = *(const u32x4*)(M + off);
;                     const f32x4 a0 = acc[ai][bj][m][0] * s, a1 = acc[ai][bj][m][1] * s;
;                     float o[8];
;                     o[0] = sigm(a0[0]) * lo16(tv.x); o[1] = sigm(a0[1]) * hi16(tv.x); o[2] = sigm(a0[2]) * lo16(tv.y); o[3] = sigm(a0[3]) * hi16(tv.y);
;                     o[4] = sigm(a1[0]) * lo16(tv.z); o[5] = sigm(a1[1]) * hi16(tv.z); o[6] = sigm(a1[2]) * lo16(tv.w); o[7] = sigm(a1[3]) * hi16(tv.w);
;                     if (ACC) { o[0] += lo16(pv.x); o[1] += hi16(pv.x); o[2] += lo16(pv.y); o[3] += hi16(pv.y); o[4] += lo16(pv.z); o[5] += hi16(pv.z); o[6] += lo16(pv.w); o[7] += hi16(pv.w); }
;                     u32x4 w; w.x = cvt_pk_bf16(o[0], o[1]); w.y = cvt_pk_bf16(o[2], o[3]); w.z = cvt_pk_bf16(o[4], o[5]); w.w = cvt_pk_bf16(o[6], o[7]);
;                     *(u32x4*)(M + off) = w; } }
	v_rcp_f32_e32 v101, v101
	v_lshlrev_b32_e32 v108, 16, v104
	v_and_b32_e32 v109, 0xffff0000, v104
	v_lshlrev_b32_e32 v104, 16, v105
	v_and_b32_e32 v105, 0xffff0000, v105
	v_pk_mul_f32 v[102:103], v[102:103], v[104:105]
	v_lshlrev_b32_e32 v104, 16, v106
	v_and_b32_e32 v105, 0xffff0000, v106
	v_pk_mul_f32 v[104:105], v[96:97], v[104:105]
	v_mul_f32_e32 v96, 0xbfb8aa3b, v98
	v_mul_f32_e32 v97, 0xbfb8aa3b, v99
	v_exp_f32_e32 v96, v96
	v_exp_f32_e32 v97, v97
	v_lshlrev_b32_e32 v98, 16, v107
	v_and_b32_e32 v99, 0xffff0000, v107
	v_add_f32_e32 v96, 1.0, v96
	v_add_f32_e32 v97, 1.0, v97
	v_rcp_f32_e32 v96, v96
	v_rcp_f32_e32 v97, v97
	v_pk_mul_f32 v[100:101], v[100:101], v[108:109]
	v_pk_mul_f32 v[106:107], v[96:97], v[98:99]
	v_cvt_pk_bf16_f32 v96, v100, v101
	v_cvt_pk_bf16_f32 v97, v102, v103
	v_cvt_pk_bf16_f32 v98, v104, v105
	v_cvt_pk_bf16_f32 v99, v106, v107
	global_store_dwordx4 v[112:113], v[96:99], off offset:256
	s_nop 1
	v_mov_b32_e32 v98, v181
	s_nop 0
	v_or_b32_e32 v96, 32, v162
	v_ashrrev_i32_e32 v97, 31, v96
	v_lshlrev_b64 v[96:97], 11, v[96:97]
	v_lshl_add_u64 v[96:97], s[0:1], 0, v[96:97]
	v_lshl_add_u64 v[96:97], v[96:97], 0, v[164:165]
	s_nop 1
	v_mov_b32_e32 v100, v208
	v_mov_b32_e32 v101, v209
	v_mov_b32_e32 v102, v210
	v_mov_b32_e32 v103, v211
	v_fmamk_f32 v98, v98, 0x3a800000, v187
	v_cmp_gt_f32_e32 vcc, s67, v98
	v_mul_f32_e32 v99, 0x4b800000, v98
	v_lshlrev_b32_e32 v104, 16, v100
	v_cndmask_b32_e32 v98, v98, v99, vcc
	v_rsq_f32_e32 v98, v98
	v_and_b32_e32 v105, 0xffff0000, v100
	v_lshlrev_b32_e32 v100, 16, v101
	v_and_b32_e32 v101, 0xffff0000, v101
	v_mul_f32_e32 v99, 0x45800000, v98
	v_cndmask_b32_e32 v98, v98, v99, vcc
	v_pk_mul_f32 v[94:95], v[94:95], v[98:99] op_sel_hi:[1,0]
	v_pk_mul_f32 v[88:89], v[88:89], v[98:99] op_sel_hi:[1,0]
	v_mul_f32_e32 v94, 0xbfb8aa3b, v94
	v_mul_f32_e32 v95, 0xbfb8aa3b, v95
	v_exp_f32_e32 v94, v94
	v_exp_f32_e32 v95, v95
	v_mul_f32_e32 v88, 0xbfb8aa3b, v88
	v_mul_f32_e32 v89, 0xbfb8aa3b, v89
	v_exp_f32_e32 v88, v88
	v_exp_f32_e32 v89, v89
	v_add_f32_e32 v94, 1.0, v94
	v_add_f32_e32 v95, 1.0, v95
	v_rcp_f32_e32 v94, v94
	v_rcp_f32_e32 v95, v95
	v_add_f32_e32 v88, 1.0, v88
	v_add_f32_e32 v89, 1.0, v89
	v_rcp_f32_e32 v88, v88
	v_rcp_f32_e32 v89, v89
	v_pk_mul_f32 v[92:93], v[92:93], v[98:99] op_sel_hi:[1,0]
	v_pk_mul_f32 v[90:91], v[90:91], v[98:99] op_sel_hi:[1,0]
	v_pk_mul_f32 v[94:95], v[94:95], v[100:101]
	v_lshlrev_b32_e32 v100, 16, v102
	v_and_b32_e32 v101, 0xffff0000, v102
	v_mul_f32_e32 v92, 0xbfb8aa3b, v92
	v_mul_f32_e32 v93, 0xbfb8aa3b, v93
	v_pk_mul_f32 v[100:101], v[88:89], v[100:101]
	v_mul_f32_e32 v88, 0xbfb8aa3b, v90
	v_mul_f32_e32 v89, 0xbfb8aa3b, v91
	v_exp_f32_e32 v92, v92
	v_exp_f32_e32 v93, v93
	v_exp_f32_e32 v88, v88
	v_exp_f32_e32 v89, v89
	v_add_f32_e32 v92, 1.0, v92
	v_add_f32_e32 v93, 1.0, v93
	v_add_f32_e32 v88, 1.0, v88
	v_add_f32_e32 v89, 1.0, v89
	v_rcp_f32_e32 v92, v92
	v_rcp_f32_e32 v93, v93
	v_rcp_f32_e32 v88, v88
	v_rcp_f32_e32 v89, v89
	v_lshlrev_b32_e32 v90, 16, v103
	v_and_b32_e32 v91, 0xffff0000, v103
	v_pk_mul_f32 v[92:93], v[92:93], v[104:105]
	v_pk_mul_f32 v[102:103], v[88:89], v[90:91]
	v_cvt_pk_bf16_f32 v88, v92, v93
	v_cvt_pk_bf16_f32 v89, v94, v95
	v_cvt_pk_bf16_f32 v90, v100, v101
	v_cvt_pk_bf16_f32 v91, v102, v103
	global_store_dwordx4 v[96:97], v[88:91], off
	s_nop 1
	v_mov_b32_e32 v88, v212
	v_mov_b32_e32 v89, v213
	v_mov_b32_e32 v90, v214
	v_mov_b32_e32 v91, v215
	v_pk_mul_f32 v[86:87], v[86:87], v[98:99] op_sel_hi:[1,0]
	v_pk_mul_f32 v[80:81], v[80:81], v[98:99] op_sel_hi:[1,0]
	v_mul_f32_e32 v86, 0xbfb8aa3b, v86
	v_mul_f32_e32 v87, 0xbfb8aa3b, v87
	v_exp_f32_e32 v86, v86
	v_exp_f32_e32 v87, v87
	v_mul_f32_e32 v80, 0xbfb8aa3b, v80
	v_mul_f32_e32 v81, 0xbfb8aa3b, v81
	v_exp_f32_e32 v80, v80
	v_exp_f32_e32 v81, v81
	v_add_f32_e32 v86, 1.0, v86
	v_add_f32_e32 v87, 1.0, v87
	v_rcp_f32_e32 v86, v86
	v_rcp_f32_e32 v87, v87
	v_add_f32_e32 v80, 1.0, v80
	v_add_f32_e32 v81, 1.0, v81
	v_rcp_f32_e32 v80, v80
	v_rcp_f32_e32 v81, v81
	v_pk_mul_f32 v[84:85], v[84:85], v[98:99] op_sel_hi:[1,0]
	v_pk_mul_f32 v[82:83], v[82:83], v[98:99] op_sel_hi:[1,0]
	v_mul_f32_e32 v84, 0xbfb8aa3b, v84
	v_mul_f32_e32 v85, 0xbfb8aa3b, v85
	v_exp_f32_e32 v84, v84
	v_exp_f32_e32 v85, v85
	v_add_f32_e32 v84, 1.0, v84
	v_add_f32_e32 v85, 1.0, v85
	v_rcp_f32_e32 v84, v84
	v_rcp_f32_e32 v85, v85
	v_lshlrev_b32_e32 v92, 16, v88
	v_and_b32_e32 v93, 0xffff0000, v88
	v_lshlrev_b32_e32 v88, 16, v89
	v_and_b32_e32 v89, 0xffff0000, v89
	v_pk_mul_f32 v[86:87], v[86:87], v[88:89]
	v_lshlrev_b32_e32 v88, 16, v90
	v_and_b32_e32 v89, 0xffff0000, v90
	v_pk_mul_f32 v[88:89], v[80:81], v[88:89]
	v_mul_f32_e32 v80, 0xbfb8aa3b, v82
	v_mul_f32_e32 v81, 0xbfb8aa3b, v83
	v_exp_f32_e32 v80, v80
	v_exp_f32_e32 v81, v81
	v_lshlrev_b32_e32 v82, 16, v91
	v_and_b32_e32 v83, 0xffff0000, v91
	v_add_f32_e32 v80, 1.0, v80
	v_add_f32_e32 v81, 1.0, v81
	v_rcp_f32_e32 v80, v80
	v_rcp_f32_e32 v81, v81
	v_pk_mul_f32 v[84:85], v[84:85], v[92:93]
	v_pk_mul_f32 v[90:91], v[80:81], v[82:83]
	v_cvt_pk_bf16_f32 v80, v84, v85
	v_cvt_pk_bf16_f32 v81, v86, v87
	v_cvt_pk_bf16_f32 v82, v88, v89
	v_cvt_pk_bf16_f32 v83, v90, v91
	global_store_dwordx4 v[96:97], v[80:83], off offset:256
	s_nop 1
	v_mov_b32_e32 v82, v182
	s_nop 0
	v_or_b32_e32 v80, 48, v162
	v_ashrrev_i32_e32 v81, 31, v80
	v_lshlrev_b64 v[80:81], 11, v[80:81]
	v_lshl_add_u64 v[80:81], s[0:1], 0, v[80:81]
	v_lshl_add_u64 v[80:81], v[80:81], 0, v[164:165]
	s_nop 1
	v_mov_b32_e32 v84, v216
	v_mov_b32_e32 v85, v217
	v_mov_b32_e32 v86, v218
	v_mov_b32_e32 v87, v219
	v_fmamk_f32 v82, v82, 0x3a800000, v187
	v_cmp_gt_f32_e32 vcc, s67, v82
	v_mul_f32_e32 v83, 0x4b800000, v82
; __device__ __forceinline__ unsigned cvt_pk_bf16(float lo, float hi) { const f32x2_cv v = {lo, hi}; const bf16x2_cv b = __builtin_convertvector(v, bf16x2_cv); return __builtin_bit_cast(unsigned, b); }
; __device__ __forceinline__ float sigm(float x) { return __builtin_amdgcn_rcpf(1.0f + __expf(-x)); }
; __device__ __forceinline__ float lo16(unsigned w) { return __uint_as_float(w << 16); }
; __device__ __forceinline__ float hi16(unsigned w) { return __uint_as_float(w & 0xffff0000u); }
; __device__ __forceinline__ float rstd_of(const float* rowss, int row) { return rsqrtf(rowss[row] * (1.0f / 1024.0f) + 1e-6f); }
;     __device__ __forceinline__ void operator()(const f32x4 (&acc)[2][2][4][2], const pg8::Unit& u, int wr, int wc, int fr, int fq) const {
;     ...
;                 const int row = row0 + ai * 128 + m * 16;
;                 const float s = rstd_of(rowss, row);
; #pragma unroll
;                 for (int bj = 0; bj < 2; ++bj) {
;                     const size_t off = (size_t)row * 1024 + col0 + bj * 128;
;                     const u32x4 tv = *(const u32x4*)(Tm + off);
;                     u32x4 pv = (u32x4){0u, 0u, 0u, 0u};
;                     if (ACC) pv = *(const u32x4*)(M + off);
;                     const f32x4 a0 = acc[ai][bj][m][0] * s, a1 = acc[ai][bj][m][1] * s;
;                     float o[8];
;                     o[0] = sigm(a0[0]) * lo16(tv.x); o[1] = sigm(a0[1]) * hi16(tv.x); o[2] = sigm(a0[2]) * lo16(tv.y); o[3] = sigm(a0[3]) * hi16(tv.y);
;                     o[4] = sigm(a1[0]) * lo16(tv.z); o[5] = sigm(a1[1]) * hi16(tv.z); o[6] = sigm(a1[2]) * lo16(tv.w); o[7] = sigm(a1[3]) * hi16(tv.w);
;                     if (ACC) { o[0] += lo16(pv.x); o[1] += hi16(pv.x); o[2] += lo16(pv.y); o[3] += hi16(pv.y); o[4] += lo16(pv.z); o[5] += hi16(pv.z); o[6] += lo16(pv.w); o[7] += hi16(pv.w); }
;                     u32x4 w; w.x = cvt_pk_bf16(o[0], o[1]); w.y = cvt_pk_bf16(o[2], o[3]); w.z = cvt_pk_bf16(o[4], o[5]); w.w = cvt_pk_bf16(o[6], o[7]);
;                     *(u32x4*)(M + off) = w; } }
	v_lshlrev_b32_e32 v88, 16, v84
	v_cndmask_b32_e32 v82, v82, v83, vcc
	v_rsq_f32_e32 v82, v82
	v_and_b32_e32 v89, 0xffff0000, v84
	v_lshlrev_b32_e32 v84, 16, v85
	v_and_b32_e32 v85, 0xffff0000, v85
	v_mul_f32_e32 v83, 0x45800000, v82
	v_cndmask_b32_e32 v82, v82, v83, vcc
	v_pk_mul_f32 v[78:79], v[78:79], v[82:83] op_sel_hi:[1,0]
	v_pk_mul_f32 v[72:73], v[72:73], v[82:83] op_sel_hi:[1,0]
	v_mul_f32_e32 v78, 0xbfb8aa3b, v78
	v_mul_f32_e32 v79, 0xbfb8aa3b, v79
	v_exp_f32_e32 v78, v78
	v_exp_f32_e32 v79, v79
	v_mul_f32_e32 v72, 0xbfb8aa3b, v72
	v_mul_f32_e32 v73, 0xbfb8aa3b, v73
	v_exp_f32_e32 v72, v72
	v_exp_f32_e32 v73, v73
	v_add_f32_e32 v78, 1.0, v78
	v_add_f32_e32 v79, 1.0, v79
	v_rcp_f32_e32 v78, v78
	v_rcp_f32_e32 v79, v79
	v_add_f32_e32 v72, 1.0, v72
	v_add_f32_e32 v73, 1.0, v73
	v_rcp_f32_e32 v72, v72
	v_rcp_f32_e32 v73, v73
	v_pk_mul_f32 v[76:77], v[76:77], v[82:83] op_sel_hi:[1,0]
	v_pk_mul_f32 v[74:75], v[74:75], v[82:83] op_sel_hi:[1,0]
	v_pk_mul_f32 v[78:79], v[78:79], v[84:85]
	v_lshlrev_b32_e32 v84, 16, v86
	v_and_b32_e32 v85, 0xffff0000, v86
	v_mul_f32_e32 v76, 0xbfb8aa3b, v76
	v_mul_f32_e32 v77, 0xbfb8aa3b, v77
	v_pk_mul_f32 v[84:85], v[72:73], v[84:85]
	v_mul_f32_e32 v72, 0xbfb8aa3b, v74
	v_mul_f32_e32 v73, 0xbfb8aa3b, v75
	v_exp_f32_e32 v76, v76
	v_exp_f32_e32 v77, v77
	v_exp_f32_e32 v72, v72
	v_exp_f32_e32 v73, v73
	v_add_f32_e32 v76, 1.0, v76
	v_add_f32_e32 v77, 1.0, v77
	v_add_f32_e32 v72, 1.0, v72
	v_add_f32_e32 v73, 1.0, v73
	v_rcp_f32_e32 v76, v76
	v_rcp_f32_e32 v77, v77
	v_rcp_f32_e32 v72, v72
	v_rcp_f32_e32 v73, v73
	v_lshlrev_b32_e32 v74, 16, v87
	v_and_b32_e32 v75, 0xffff0000, v87
	v_pk_mul_f32 v[76:77], v[76:77], v[88:89]
	v_pk_mul_f32 v[86:87], v[72:73], v[74:75]
	v_cvt_pk_bf16_f32 v72, v76, v77
	v_cvt_pk_bf16_f32 v73, v78, v79
	v_cvt_pk_bf16_f32 v74, v84, v85
	v_cvt_pk_bf16_f32 v75, v86, v87
	global_store_dwordx4 v[80:81], v[72:75], off
	s_nop 1
	v_mov_b32_e32 v72, v220
	v_mov_b32_e32 v73, v221
	v_mov_b32_e32 v74, v222
	v_mov_b32_e32 v75, v223
	v_pk_mul_f32 v[70:71], v[70:71], v[82:83] op_sel_hi:[1,0]
	v_pk_mul_f32 v[64:65], v[64:65], v[82:83] op_sel_hi:[1,0]
	v_mul_f32_e32 v70, 0xbfb8aa3b, v70
	v_mul_f32_e32 v71, 0xbfb8aa3b, v71
	v_exp_f32_e32 v70, v70
	v_exp_f32_e32 v71, v71
	v_mul_f32_e32 v64, 0xbfb8aa3b, v64
	v_mul_f32_e32 v65, 0xbfb8aa3b, v65
	v_exp_f32_e32 v64, v64
	v_exp_f32_e32 v65, v65
	v_add_f32_e32 v70, 1.0, v70
	v_add_f32_e32 v71, 1.0, v71
	v_rcp_f32_e32 v70, v70
	v_rcp_f32_e32 v71, v71
	v_add_f32_e32 v64, 1.0, v64
	v_add_f32_e32 v65, 1.0, v65
	v_rcp_f32_e32 v64, v64
	v_rcp_f32_e32 v65, v65
	v_pk_mul_f32 v[68:69], v[68:69], v[82:83] op_sel_hi:[1,0]
	v_pk_mul_f32 v[66:67], v[66:67], v[82:83] op_sel_hi:[1,0]
	v_mul_f32_e32 v68, 0xbfb8aa3b, v68
	v_mul_f32_e32 v69, 0xbfb8aa3b, v69
	v_exp_f32_e32 v68, v68
	v_exp_f32_e32 v69, v69
	v_add_f32_e32 v68, 1.0, v68
	v_add_f32_e32 v69, 1.0, v69
	v_rcp_f32_e32 v68, v68
	v_rcp_f32_e32 v69, v69
	v_lshlrev_b32_e32 v76, 16, v72
	v_and_b32_e32 v77, 0xffff0000, v72
	v_lshlrev_b32_e32 v72, 16, v73
	v_and_b32_e32 v73, 0xffff0000, v73
	v_pk_mul_f32 v[70:71], v[70:71], v[72:73]
	v_lshlrev_b32_e32 v72, 16, v74
	v_and_b32_e32 v73, 0xffff0000, v74
	v_pk_mul_f32 v[72:73], v[64:65], v[72:73]
	v_mul_f32_e32 v64, 0xbfb8aa3b, v66
	v_mul_f32_e32 v65, 0xbfb8aa3b, v67
	v_exp_f32_e32 v64, v64
	v_exp_f32_e32 v65, v65
	v_lshlrev_b32_e32 v66, 16, v75
	v_and_b32_e32 v67, 0xffff0000, v75
	v_add_f32_e32 v64, 1.0, v64
	v_add_f32_e32 v65, 1.0, v65
	v_rcp_f32_e32 v64, v64
	v_rcp_f32_e32 v65, v65
	v_pk_mul_f32 v[68:69], v[68:69], v[76:77]
	v_pk_mul_f32 v[74:75], v[64:65], v[66:67]
	v_cvt_pk_bf16_f32 v64, v68, v69
	v_cvt_pk_bf16_f32 v65, v70, v71
	v_cvt_pk_bf16_f32 v66, v72, v73
	v_cvt_pk_bf16_f32 v67, v74, v75
	global_store_dwordx4 v[80:81], v[64:67], off offset:256
	s_nop 1
	v_mov_b32_e32 v64, v183
	v_fmamk_f32 v64, v64, 0x3a800000, v187
	v_cmp_gt_f32_e32 vcc, s67, v64
	v_mul_f32_e32 v65, 0x4b800000, v64
	s_nop 0
	v_cndmask_b32_e32 v64, v64, v65, vcc
	v_rsq_f32_e32 v64, v64
	s_nop 0
	v_mul_f32_e32 v65, 0x45800000, v64
	v_cndmask_b32_e32 v66, v64, v65, vcc
	v_add_co_u32_e32 v72, vcc, s2, v158
	v_pk_mul_f32 v[62:63], v[62:63], v[66:67] op_sel_hi:[1,0]
	s_nop 0
	v_addc_co_u32_e32 v73, vcc, 0, v159, vcc
	s_nop 1
	v_mov_b32_e32 v68, v224
	v_mov_b32_e32 v69, v225
	v_mov_b32_e32 v70, v226
	v_mov_b32_e32 v71, v227
	v_pk_mul_f32 v[56:57], v[56:57], v[66:67] op_sel_hi:[1,0]
	v_mul_f32_e32 v62, 0xbfb8aa3b, v62
	v_mul_f32_e32 v63, 0xbfb8aa3b, v63
	v_exp_f32_e32 v62, v62
	v_exp_f32_e32 v63, v63
	v_mul_f32_e32 v56, 0xbfb8aa3b, v56
	v_mul_f32_e32 v57, 0xbfb8aa3b, v57
	v_exp_f32_e32 v56, v56
	v_exp_f32_e32 v57, v57
	v_add_f32_e32 v62, 1.0, v62
	v_add_f32_e32 v63, 1.0, v63
	v_rcp_f32_e32 v62, v62
	v_rcp_f32_e32 v63, v63
	v_add_f32_e32 v56, 1.0, v56
	v_add_f32_e32 v57, 1.0, v57
	v_rcp_f32_e32 v56, v56
	v_rcp_f32_e32 v57, v57
	v_pk_mul_f32 v[60:61], v[60:61], v[66:67] op_sel_hi:[1,0]
	v_pk_mul_f32 v[58:59], v[58:59], v[66:67] op_sel_hi:[1,0]
	v_mul_f32_e32 v60, 0xbfb8aa3b, v60
	v_mul_f32_e32 v61, 0xbfb8aa3b, v61
	v_exp_f32_e32 v60, v60
	v_exp_f32_e32 v61, v61
	v_lshl_add_u64 v[64:65], v[158:159], 0, s[4:5]
	v_pk_mul_f32 v[54:55], v[54:55], v[66:67] op_sel_hi:[1,0]
	v_add_f32_e32 v60, 1.0, v60
	v_add_f32_e32 v61, 1.0, v61
	v_rcp_f32_e32 v60, v60
	v_rcp_f32_e32 v61, v61
	v_pk_mul_f32 v[48:49], v[48:49], v[66:67] op_sel_hi:[1,0]
	v_mul_f32_e32 v54, 0xbfb8aa3b, v54
	v_mul_f32_e32 v55, 0xbfb8aa3b, v55
	v_exp_f32_e32 v54, v54
	v_exp_f32_e32 v55, v55
	v_mul_f32_e32 v48, 0xbfb8aa3b, v48
	v_mul_f32_e32 v49, 0xbfb8aa3b, v49
	v_exp_f32_e32 v48, v48
	v_exp_f32_e32 v49, v49
	v_add_f32_e32 v54, 1.0, v54
	v_add_f32_e32 v55, 1.0, v55
; __device__ __forceinline__ unsigned cvt_pk_bf16(float lo, float hi) { const f32x2_cv v = {lo, hi}; const bf16x2_cv b = __builtin_convertvector(v, bf16x2_cv); return __builtin_bit_cast(unsigned, b); }
; __device__ __forceinline__ float sigm(float x) { return __builtin_amdgcn_rcpf(1.0f + __expf(-x)); }
; __device__ __forceinline__ float lo16(unsigned w) { return __uint_as_float(w << 16); }
; __device__ __forceinline__ float hi16(unsigned w) { return __uint_as_float(w & 0xffff0000u); }
; __device__ __forceinline__ float rstd_of(const float* rowss, int row) { return rsqrtf(rowss[row] * (1.0f / 1024.0f) + 1e-6f); }
;     __device__ __forceinline__ void operator()(const f32x4 (&acc)[2][2][4][2], const pg8::Unit& u, int wr, int wc, int fr, int fq) const {
;     ...
;                 const int row = row0 + ai * 128 + m * 16;
;                 const float s = rstd_of(rowss, row);
; #pragma unroll
;                 for (int bj = 0; bj < 2; ++bj) {
;                     const size_t off = (size_t)row * 1024 + col0 + bj * 128;
;                     const u32x4 tv = *(const u32x4*)(Tm + off);
;                     u32x4 pv = (u32x4){0u, 0u, 0u, 0u};
;                     if (ACC) pv = *(const u32x4*)(M + off);
;                     const f32x4 a0 = acc[ai][bj][m][0] * s, a1 = acc[ai][bj][m][1] * s;
;                     float o[8];
;                     o[0] = sigm(a0[0]) * lo16(tv.x); o[1] = sigm(a0[1]) * hi16(tv.x); o[2] = sigm(a0[2]) * lo16(tv.y); o[3] = sigm(a0[3]) * hi16(tv.y);
;                     o[4] = sigm(a1[0]) * lo16(tv.z); o[5] = sigm(a1[1]) * hi16(tv.z); o[6] = sigm(a1[2]) * lo16(tv.w); o[7] = sigm(a1[3]) * hi16(tv.w);
;                     if (ACC) { o[0] += lo16(pv.x); o[1] += hi16(pv.x); o[2] += lo16(pv.y); o[3] += hi16(pv.y); o[4] += lo16(pv.z); o[5] += hi16(pv.z); o[6] += lo16(pv.w); o[7] += hi16(pv.w); }
;                     u32x4 w; w.x = cvt_pk_bf16(o[0], o[1]); w.y = cvt_pk_bf16(o[2], o[3]); w.z = cvt_pk_bf16(o[4], o[5]); w.w = cvt_pk_bf16(o[6], o[7]);
;                     *(u32x4*)(M + off) = w; } }
	v_rcp_f32_e32 v54, v54
	v_rcp_f32_e32 v55, v55
	v_add_f32_e32 v48, 1.0, v48
	v_add_f32_e32 v49, 1.0, v49
	v_rcp_f32_e32 v48, v48
	v_rcp_f32_e32 v49, v49
	v_pk_mul_f32 v[52:53], v[52:53], v[66:67] op_sel_hi:[1,0]
	v_pk_mul_f32 v[50:51], v[50:51], v[66:67] op_sel_hi:[1,0]
	v_mul_f32_e32 v52, 0xbfb8aa3b, v52
	v_mul_f32_e32 v53, 0xbfb8aa3b, v53
	v_exp_f32_e32 v52, v52
	v_exp_f32_e32 v53, v53
	s_mov_b32 s2, 0x48000
	s_mov_b64 s[4:5], 0x48000
	v_add_f32_e32 v52, 1.0, v52
	v_add_f32_e32 v53, 1.0, v53
	v_rcp_f32_e32 v52, v52
	v_rcp_f32_e32 v53, v53
	v_lshlrev_b32_e32 v74, 16, v68
	v_and_b32_e32 v75, 0xffff0000, v68
	v_lshlrev_b32_e32 v68, 16, v69
	v_and_b32_e32 v69, 0xffff0000, v69
	v_pk_mul_f32 v[62:63], v[62:63], v[68:69]
	v_lshlrev_b32_e32 v68, 16, v70
	v_and_b32_e32 v69, 0xffff0000, v70
	v_pk_mul_f32 v[68:69], v[56:57], v[68:69]
	v_mul_f32_e32 v56, 0xbfb8aa3b, v58
	v_mul_f32_e32 v57, 0xbfb8aa3b, v59
	v_exp_f32_e32 v56, v56
	v_exp_f32_e32 v57, v57
	v_lshlrev_b32_e32 v58, 16, v71
	v_and_b32_e32 v59, 0xffff0000, v71
	v_add_f32_e32 v56, 1.0, v56
	v_add_f32_e32 v57, 1.0, v57
	v_rcp_f32_e32 v56, v56
	v_rcp_f32_e32 v57, v57
	v_pk_mul_f32 v[60:61], v[60:61], v[74:75]
	v_pk_mul_f32 v[70:71], v[56:57], v[58:59]
	v_cvt_pk_bf16_f32 v56, v60, v61
	v_cvt_pk_bf16_f32 v57, v62, v63
	v_cvt_pk_bf16_f32 v58, v68, v69
	v_cvt_pk_bf16_f32 v59, v70, v71
	global_store_dwordx4 v[72:73], v[56:59], off
	s_nop 1
	v_mov_b32_e32 v56, v228
	v_mov_b32_e32 v57, v229
	v_mov_b32_e32 v58, v230
	v_mov_b32_e32 v59, v231
	v_lshlrev_b32_e32 v60, 16, v56
	v_and_b32_e32 v61, 0xffff0000, v56
	v_lshlrev_b32_e32 v56, 16, v57
	v_and_b32_e32 v57, 0xffff0000, v57
	v_pk_mul_f32 v[54:55], v[54:55], v[56:57]
	v_lshlrev_b32_e32 v56, 16, v58
	v_and_b32_e32 v57, 0xffff0000, v58
	v_pk_mul_f32 v[56:57], v[48:49], v[56:57]
	v_mul_f32_e32 v48, 0xbfb8aa3b, v50
	v_mul_f32_e32 v49, 0xbfb8aa3b, v51
	v_exp_f32_e32 v48, v48
	v_exp_f32_e32 v49, v49
	v_lshlrev_b32_e32 v50, 16, v59
	v_and_b32_e32 v51, 0xffff0000, v59
	v_add_f32_e32 v48, 1.0, v48
	v_add_f32_e32 v49, 1.0, v49
	v_rcp_f32_e32 v48, v48
	v_rcp_f32_e32 v49, v49
	v_pk_mul_f32 v[52:53], v[52:53], v[60:61]
	v_pk_mul_f32 v[58:59], v[48:49], v[50:51]
	v_cvt_pk_bf16_f32 v48, v52, v53
	v_cvt_pk_bf16_f32 v49, v54, v55
	v_cvt_pk_bf16_f32 v50, v56, v57
	v_cvt_pk_bf16_f32 v51, v58, v59
	global_store_dwordx4 v[64:65], v[48:51], off offset:256
	s_nop 1
	v_mov_b32_e32 v48, v240
	v_fmamk_f32 v48, v48, 0x3a800000, v187
	v_cmp_gt_f32_e32 vcc, s67, v48
	v_mul_f32_e32 v49, 0x4b800000, v48
	s_nop 0
	v_cndmask_b32_e32 v48, v48, v49, vcc
	v_rsq_f32_e32 v48, v48
	s_nop 0
	v_mul_f32_e32 v49, 0x45800000, v48
	v_cndmask_b32_e32 v50, v48, v49, vcc
	v_add_co_u32_e32 v56, vcc, s2, v158
	v_pk_mul_f32 v[46:47], v[46:47], v[50:51] op_sel_hi:[1,0]
	s_nop 0
	v_addc_co_u32_e32 v57, vcc, 0, v159, vcc
	s_nop 1
	v_mov_b32_e32 v52, v232
	v_mov_b32_e32 v53, v233
	v_mov_b32_e32 v54, v234
	v_mov_b32_e32 v55, v235
	v_pk_mul_f32 v[40:41], v[40:41], v[50:51] op_sel_hi:[1,0]
	v_mul_f32_e32 v46, 0xbfb8aa3b, v46
	v_mul_f32_e32 v47, 0xbfb8aa3b, v47
	v_exp_f32_e32 v46, v46
	v_exp_f32_e32 v47, v47
	v_mul_f32_e32 v40, 0xbfb8aa3b, v40
	v_mul_f32_e32 v41, 0xbfb8aa3b, v41
	v_exp_f32_e32 v40, v40
	v_exp_f32_e32 v41, v41
	v_add_f32_e32 v46, 1.0, v46
	v_add_f32_e32 v47, 1.0, v47
	v_rcp_f32_e32 v46, v46
	v_rcp_f32_e32 v47, v47
	v_add_f32_e32 v40, 1.0, v40
	v_add_f32_e32 v41, 1.0, v41
	v_rcp_f32_e32 v40, v40
	v_rcp_f32_e32 v41, v41
	v_pk_mul_f32 v[44:45], v[44:45], v[50:51] op_sel_hi:[1,0]
	v_pk_mul_f32 v[42:43], v[42:43], v[50:51] op_sel_hi:[1,0]
	v_mul_f32_e32 v44, 0xbfb8aa3b, v44
	v_mul_f32_e32 v45, 0xbfb8aa3b, v45
	v_exp_f32_e32 v44, v44
	v_exp_f32_e32 v45, v45
	v_lshl_add_u64 v[48:49], v[158:159], 0, s[4:5]
	v_pk_mul_f32 v[38:39], v[38:39], v[50:51] op_sel_hi:[1,0]
	v_add_f32_e32 v44, 1.0, v44
	v_add_f32_e32 v45, 1.0, v45
	v_rcp_f32_e32 v44, v44
	v_rcp_f32_e32 v45, v45
	v_pk_mul_f32 v[32:33], v[32:33], v[50:51] op_sel_hi:[1,0]
	v_mul_f32_e32 v38, 0xbfb8aa3b, v38
	v_mul_f32_e32 v39, 0xbfb8aa3b, v39
	v_exp_f32_e32 v38, v38
	v_exp_f32_e32 v39, v39
	v_mul_f32_e32 v32, 0xbfb8aa3b, v32
	v_mul_f32_e32 v33, 0xbfb8aa3b, v33
	v_exp_f32_e32 v32, v32
	v_exp_f32_e32 v33, v33
	v_add_f32_e32 v38, 1.0, v38
	v_add_f32_e32 v39, 1.0, v39
	v_rcp_f32_e32 v38, v38
	v_rcp_f32_e32 v39, v39
	v_add_f32_e32 v32, 1.0, v32
	v_add_f32_e32 v33, 1.0, v33
	v_rcp_f32_e32 v32, v32
	v_rcp_f32_e32 v33, v33
	v_pk_mul_f32 v[36:37], v[36:37], v[50:51] op_sel_hi:[1,0]
	v_pk_mul_f32 v[34:35], v[34:35], v[50:51] op_sel_hi:[1,0]
	v_mul_f32_e32 v36, 0xbfb8aa3b, v36
	v_mul_f32_e32 v37, 0xbfb8aa3b, v37
	v_exp_f32_e32 v36, v36
	v_exp_f32_e32 v37, v37
	s_mov_b32 s2, 0x50000
	s_mov_b64 s[4:5], 0x50000
	v_add_f32_e32 v36, 1.0, v36
	v_add_f32_e32 v37, 1.0, v37
	v_rcp_f32_e32 v36, v36
	v_rcp_f32_e32 v37, v37
	v_lshlrev_b32_e32 v58, 16, v52
	v_and_b32_e32 v59, 0xffff0000, v52
	v_lshlrev_b32_e32 v52, 16, v53
	v_and_b32_e32 v53, 0xffff0000, v53
	v_pk_mul_f32 v[46:47], v[46:47], v[52:53]
	v_lshlrev_b32_e32 v52, 16, v54
	v_and_b32_e32 v53, 0xffff0000, v54
	v_pk_mul_f32 v[52:53], v[40:41], v[52:53]
	v_mul_f32_e32 v40, 0xbfb8aa3b, v42
	v_mul_f32_e32 v41, 0xbfb8aa3b, v43
	v_exp_f32_e32 v40, v40
	v_exp_f32_e32 v41, v41
	v_lshlrev_b32_e32 v42, 16, v55
	v_and_b32_e32 v43, 0xffff0000, v55
	v_add_f32_e32 v40, 1.0, v40
	v_add_f32_e32 v41, 1.0, v41
	v_rcp_f32_e32 v40, v40
	v_rcp_f32_e32 v41, v41
	v_pk_mul_f32 v[44:45], v[44:45], v[58:59]
	v_pk_mul_f32 v[54:55], v[40:41], v[42:43]
	v_cvt_pk_bf16_f32 v40, v44, v45
	v_cvt_pk_bf16_f32 v41, v46, v47
	v_cvt_pk_bf16_f32 v42, v52, v53
	v_cvt_pk_bf16_f32 v43, v54, v55
	global_store_dwordx4 v[56:57], v[40:43], off
	s_nop 1
; __device__ __forceinline__ unsigned cvt_pk_bf16(float lo, float hi) { const f32x2_cv v = {lo, hi}; const bf16x2_cv b = __builtin_convertvector(v, bf16x2_cv); return __builtin_bit_cast(unsigned, b); }
; __device__ __forceinline__ float sigm(float x) { return __builtin_amdgcn_rcpf(1.0f + __expf(-x)); }
; __device__ __forceinline__ float lo16(unsigned w) { return __uint_as_float(w << 16); }
; __device__ __forceinline__ float hi16(unsigned w) { return __uint_as_float(w & 0xffff0000u); }
; __device__ __forceinline__ float rstd_of(const float* rowss, int row) { return rsqrtf(rowss[row] * (1.0f / 1024.0f) + 1e-6f); }
;     __device__ __forceinline__ void operator()(const f32x4 (&acc)[2][2][4][2], const pg8::Unit& u, int wr, int wc, int fr, int fq) const {
;     ...
;                 const int row = row0 + ai * 128 + m * 16;
;                 const float s = rstd_of(rowss, row);
; #pragma unroll
;                 for (int bj = 0; bj < 2; ++bj) {
;                     const size_t off = (size_t)row * 1024 + col0 + bj * 128;
;                     const u32x4 tv = *(const u32x4*)(Tm + off);
;                     u32x4 pv = (u32x4){0u, 0u, 0u, 0u};
;                     if (ACC) pv = *(const u32x4*)(M + off);
;                     const f32x4 a0 = acc[ai][bj][m][0] * s, a1 = acc[ai][bj][m][1] * s;
;                     float o[8];
;                     o[0] = sigm(a0[0]) * lo16(tv.x); o[1] = sigm(a0[1]) * hi16(tv.x); o[2] = sigm(a0[2]) * lo16(tv.y); o[3] = sigm(a0[3]) * hi16(tv.y);
;                     o[4] = sigm(a1[0]) * lo16(tv.z); o[5] = sigm(a1[1]) * hi16(tv.z); o[6] = sigm(a1[2]) * lo16(tv.w); o[7] = sigm(a1[3]) * hi16(tv.w);
;                     if (ACC) { o[0] += lo16(pv.x); o[1] += hi16(pv.x); o[2] += lo16(pv.y); o[3] += hi16(pv.y); o[4] += lo16(pv.z); o[5] += hi16(pv.z); o[6] += lo16(pv.w); o[7] += hi16(pv.w); }
;                     u32x4 w; w.x = cvt_pk_bf16(o[0], o[1]); w.y = cvt_pk_bf16(o[2], o[3]); w.z = cvt_pk_bf16(o[4], o[5]); w.w = cvt_pk_bf16(o[6], o[7]);
;                     *(u32x4*)(M + off) = w; } }
	v_mov_b32_e32 v40, v236
	v_mov_b32_e32 v41, v237
	v_mov_b32_e32 v42, v238
	v_mov_b32_e32 v43, v239
	v_lshlrev_b32_e32 v44, 16, v40
	v_and_b32_e32 v45, 0xffff0000, v40
	v_lshlrev_b32_e32 v40, 16, v41
	v_and_b32_e32 v41, 0xffff0000, v41
	v_pk_mul_f32 v[38:39], v[38:39], v[40:41]
	v_lshlrev_b32_e32 v40, 16, v42
	v_and_b32_e32 v41, 0xffff0000, v42
	v_pk_mul_f32 v[40:41], v[32:33], v[40:41]
	v_mul_f32_e32 v32, 0xbfb8aa3b, v34
	v_mul_f32_e32 v33, 0xbfb8aa3b, v35
	v_exp_f32_e32 v32, v32
	v_exp_f32_e32 v33, v33
	v_lshlrev_b32_e32 v34, 16, v43
	v_and_b32_e32 v35, 0xffff0000, v43
	v_add_f32_e32 v32, 1.0, v32
	v_add_f32_e32 v33, 1.0, v33
	v_rcp_f32_e32 v32, v32
	v_rcp_f32_e32 v33, v33
	v_pk_mul_f32 v[36:37], v[36:37], v[44:45]
	v_pk_mul_f32 v[42:43], v[32:33], v[34:35]
	v_cvt_pk_bf16_f32 v32, v36, v37
	v_cvt_pk_bf16_f32 v33, v38, v39
	v_cvt_pk_bf16_f32 v34, v40, v41
	v_cvt_pk_bf16_f32 v35, v42, v43
	global_store_dwordx4 v[48:49], v[32:35], off offset:256
	s_nop 1
	v_mov_b32_e32 v32, v241
	v_fmamk_f32 v32, v32, 0x3a800000, v187
	v_cmp_gt_f32_e32 vcc, s67, v32
	v_mul_f32_e32 v33, 0x4b800000, v32
	s_nop 0
	v_cndmask_b32_e32 v32, v32, v33, vcc
	v_rsq_f32_e32 v32, v32
	s_nop 0
	v_mul_f32_e32 v33, 0x45800000, v32
	v_cndmask_b32_e32 v34, v32, v33, vcc
	v_add_co_u32_e32 v40, vcc, s2, v158
	v_pk_mul_f32 v[30:31], v[30:31], v[34:35] op_sel_hi:[1,0]
	s_nop 0
	v_addc_co_u32_e32 v41, vcc, 0, v159, vcc
	s_nop 1
	v_mov_b32_e32 v36, v244
	v_mov_b32_e32 v37, v245
	v_mov_b32_e32 v38, v246
	v_mov_b32_e32 v39, v247
	v_pk_mul_f32 v[24:25], v[24:25], v[34:35] op_sel_hi:[1,0]
	v_mul_f32_e32 v30, 0xbfb8aa3b, v30
	v_mul_f32_e32 v31, 0xbfb8aa3b, v31
	v_exp_f32_e32 v30, v30
	v_exp_f32_e32 v31, v31
	v_mul_f32_e32 v24, 0xbfb8aa3b, v24
	v_mul_f32_e32 v25, 0xbfb8aa3b, v25
	v_exp_f32_e32 v24, v24
	v_exp_f32_e32 v25, v25
	v_add_f32_e32 v30, 1.0, v30
	v_add_f32_e32 v31, 1.0, v31
	v_rcp_f32_e32 v30, v30
	v_rcp_f32_e32 v31, v31
	v_add_f32_e32 v24, 1.0, v24
	v_add_f32_e32 v25, 1.0, v25
	v_rcp_f32_e32 v24, v24
	v_rcp_f32_e32 v25, v25
	v_pk_mul_f32 v[28:29], v[28:29], v[34:35] op_sel_hi:[1,0]
	v_pk_mul_f32 v[26:27], v[26:27], v[34:35] op_sel_hi:[1,0]
	v_mul_f32_e32 v28, 0xbfb8aa3b, v28
	v_mul_f32_e32 v29, 0xbfb8aa3b, v29
	v_exp_f32_e32 v28, v28
	v_exp_f32_e32 v29, v29
	v_lshl_add_u64 v[32:33], v[158:159], 0, s[4:5]
	v_pk_mul_f32 v[22:23], v[22:23], v[34:35] op_sel_hi:[1,0]
	v_add_f32_e32 v28, 1.0, v28
	v_add_f32_e32 v29, 1.0, v29
	v_rcp_f32_e32 v28, v28
	v_rcp_f32_e32 v29, v29
	v_pk_mul_f32 v[16:17], v[16:17], v[34:35] op_sel_hi:[1,0]
	v_mul_f32_e32 v22, 0xbfb8aa3b, v22
	v_mul_f32_e32 v23, 0xbfb8aa3b, v23
	v_exp_f32_e32 v22, v22
	v_exp_f32_e32 v23, v23
	v_mul_f32_e32 v16, 0xbfb8aa3b, v16
	v_mul_f32_e32 v17, 0xbfb8aa3b, v17
	v_exp_f32_e32 v16, v16
	v_exp_f32_e32 v17, v17
	v_add_f32_e32 v22, 1.0, v22
	v_add_f32_e32 v23, 1.0, v23
	v_rcp_f32_e32 v22, v22
	v_rcp_f32_e32 v23, v23
	v_add_f32_e32 v16, 1.0, v16
	v_add_f32_e32 v17, 1.0, v17
	v_rcp_f32_e32 v16, v16
	v_rcp_f32_e32 v17, v17
	v_pk_mul_f32 v[20:21], v[20:21], v[34:35] op_sel_hi:[1,0]
	v_pk_mul_f32 v[18:19], v[18:19], v[34:35] op_sel_hi:[1,0]
	v_mul_f32_e32 v20, 0xbfb8aa3b, v20
	v_mul_f32_e32 v21, 0xbfb8aa3b, v21
	v_exp_f32_e32 v20, v20
	v_exp_f32_e32 v21, v21
	s_mov_b32 s2, 0x58000
	s_mov_b64 s[4:5], 0x58000
	v_add_f32_e32 v20, 1.0, v20
	v_add_f32_e32 v21, 1.0, v21
	v_rcp_f32_e32 v20, v20
	v_rcp_f32_e32 v21, v21
	v_lshlrev_b32_e32 v42, 16, v36
	v_and_b32_e32 v43, 0xffff0000, v36
	v_lshlrev_b32_e32 v36, 16, v37
	v_and_b32_e32 v37, 0xffff0000, v37
	v_pk_mul_f32 v[30:31], v[30:31], v[36:37]
	v_lshlrev_b32_e32 v36, 16, v38
	v_and_b32_e32 v37, 0xffff0000, v38
	v_pk_mul_f32 v[36:37], v[24:25], v[36:37]
	v_mul_f32_e32 v24, 0xbfb8aa3b, v26
	v_mul_f32_e32 v25, 0xbfb8aa3b, v27
	v_exp_f32_e32 v24, v24
	v_exp_f32_e32 v25, v25
	v_lshlrev_b32_e32 v26, 16, v39
	v_and_b32_e32 v27, 0xffff0000, v39
	v_add_f32_e32 v24, 1.0, v24
	v_add_f32_e32 v25, 1.0, v25
	v_rcp_f32_e32 v24, v24
	v_rcp_f32_e32 v25, v25
	v_pk_mul_f32 v[28:29], v[28:29], v[42:43]
	v_pk_mul_f32 v[38:39], v[24:25], v[26:27]
	v_cvt_pk_bf16_f32 v24, v28, v29
	v_cvt_pk_bf16_f32 v25, v30, v31
	v_cvt_pk_bf16_f32 v26, v36, v37
	v_cvt_pk_bf16_f32 v27, v38, v39
	global_store_dwordx4 v[40:41], v[24:27], off
	s_nop 1
	v_mov_b32_e32 v24, v248
	v_mov_b32_e32 v25, v249
	v_mov_b32_e32 v26, v250
	v_mov_b32_e32 v27, v251
	v_lshlrev_b32_e32 v28, 16, v24
	v_and_b32_e32 v29, 0xffff0000, v24
	v_lshlrev_b32_e32 v24, 16, v25
	v_and_b32_e32 v25, 0xffff0000, v25
	v_pk_mul_f32 v[22:23], v[22:23], v[24:25]
	v_lshlrev_b32_e32 v24, 16, v26
	v_and_b32_e32 v25, 0xffff0000, v26
	v_pk_mul_f32 v[24:25], v[16:17], v[24:25]
	v_mul_f32_e32 v16, 0xbfb8aa3b, v18
	v_mul_f32_e32 v17, 0xbfb8aa3b, v19
; __device__ __forceinline__ unsigned cvt_pk_bf16(float lo, float hi) { const f32x2_cv v = {lo, hi}; const bf16x2_cv b = __builtin_convertvector(v, bf16x2_cv); return __builtin_bit_cast(unsigned, b); }
; __device__ __forceinline__ float sigm(float x) { return __builtin_amdgcn_rcpf(1.0f + __expf(-x)); }
; __device__ __forceinline__ float lo16(unsigned w) { return __uint_as_float(w << 16); }
; __device__ __forceinline__ float hi16(unsigned w) { return __uint_as_float(w & 0xffff0000u); }
; __device__ __forceinline__ float rstd_of(const float* rowss, int row) { return rsqrtf(rowss[row] * (1.0f / 1024.0f) + 1e-6f); }
;     __device__ __forceinline__ void operator()(const f32x4 (&acc)[2][2][4][2], const pg8::Unit& u, int wr, int wc, int fr, int fq) const {
;     ...
;                 const int row = row0 + ai * 128 + m * 16;
;                 const float s = rstd_of(rowss, row);
; #pragma unroll
;                 for (int bj = 0; bj < 2; ++bj) {
;                     const size_t off = (size_t)row * 1024 + col0 + bj * 128;
;                     const u32x4 tv = *(const u32x4*)(Tm + off);
;                     u32x4 pv = (u32x4){0u, 0u, 0u, 0u};
;                     if (ACC) pv = *(const u32x4*)(M + off);
;                     const f32x4 a0 = acc[ai][bj][m][0] * s, a1 = acc[ai][bj][m][1] * s;
;                     float o[8];
;                     o[0] = sigm(a0[0]) * lo16(tv.x); o[1] = sigm(a0[1]) * hi16(tv.x); o[2] = sigm(a0[2]) * lo16(tv.y); o[3] = sigm(a0[3]) * hi16(tv.y);
;                     o[4] = sigm(a1[0]) * lo16(tv.z); o[5] = sigm(a1[1]) * hi16(tv.z); o[6] = sigm(a1[2]) * lo16(tv.w); o[7] = sigm(a1[3]) * hi16(tv.w);
;                     if (ACC) { o[0] += lo16(pv.x); o[1] += hi16(pv.x); o[2] += lo16(pv.y); o[3] += hi16(pv.y); o[4] += lo16(pv.z); o[5] += hi16(pv.z); o[6] += lo16(pv.w); o[7] += hi16(pv.w); }
;                     u32x4 w; w.x = cvt_pk_bf16(o[0], o[1]); w.y = cvt_pk_bf16(o[2], o[3]); w.z = cvt_pk_bf16(o[4], o[5]); w.w = cvt_pk_bf16(o[6], o[7]);
;                     *(u32x4*)(M + off) = w; } }
	v_exp_f32_e32 v16, v16
	v_exp_f32_e32 v17, v17
	v_lshlrev_b32_e32 v18, 16, v27
	v_and_b32_e32 v19, 0xffff0000, v27
	v_add_f32_e32 v16, 1.0, v16
	v_add_f32_e32 v17, 1.0, v17
	v_rcp_f32_e32 v16, v16
	v_rcp_f32_e32 v17, v17
	v_pk_mul_f32 v[20:21], v[20:21], v[28:29]
	v_pk_mul_f32 v[26:27], v[16:17], v[18:19]
	v_cvt_pk_bf16_f32 v16, v20, v21
	v_cvt_pk_bf16_f32 v17, v22, v23
	v_cvt_pk_bf16_f32 v18, v24, v25
	v_cvt_pk_bf16_f32 v19, v26, v27
	global_store_dwordx4 v[32:33], v[16:19], off offset:256
	s_nop 1
	v_mov_b32_e32 v16, v169
	v_fmamk_f32 v16, v16, 0x3a800000, v187
	v_cmp_gt_f32_e32 vcc, s67, v16
	v_mul_f32_e32 v17, 0x4b800000, v16
	s_nop 0
	v_cndmask_b32_e32 v16, v16, v17, vcc
	v_rsq_f32_e32 v16, v16
	s_nop 0
	v_mul_f32_e32 v17, 0x45800000, v16
	v_cndmask_b32_e32 v18, v16, v17, vcc
	v_add_co_u32_e32 v24, vcc, s2, v158
	v_pk_mul_f32 v[14:15], v[14:15], v[18:19] op_sel_hi:[1,0]
	s_nop 0
	v_addc_co_u32_e32 v25, vcc, 0, v159, vcc
	s_nop 1
	v_mov_b32_e32 v20, v176
	v_mov_b32_e32 v21, v177
	v_mov_b32_e32 v22, v178
	v_mov_b32_e32 v23, v179
	v_pk_mul_f32 v[8:9], v[8:9], v[18:19] op_sel_hi:[1,0]
	v_mul_f32_e32 v14, 0xbfb8aa3b, v14
	v_mul_f32_e32 v15, 0xbfb8aa3b, v15
	v_exp_f32_e32 v14, v14
	v_exp_f32_e32 v15, v15
	v_mul_f32_e32 v8, 0xbfb8aa3b, v8
	v_mul_f32_e32 v9, 0xbfb8aa3b, v9
	v_exp_f32_e32 v8, v8
	v_exp_f32_e32 v9, v9
	v_add_f32_e32 v14, 1.0, v14
	v_add_f32_e32 v15, 1.0, v15
	v_rcp_f32_e32 v14, v14
	v_rcp_f32_e32 v15, v15
	v_add_f32_e32 v8, 1.0, v8
	v_add_f32_e32 v9, 1.0, v9
	v_rcp_f32_e32 v8, v8
	v_rcp_f32_e32 v9, v9
	v_pk_mul_f32 v[12:13], v[12:13], v[18:19] op_sel_hi:[1,0]
	v_pk_mul_f32 v[10:11], v[10:11], v[18:19] op_sel_hi:[1,0]
	v_mul_f32_e32 v12, 0xbfb8aa3b, v12
	v_mul_f32_e32 v13, 0xbfb8aa3b, v13
	v_exp_f32_e32 v12, v12
	v_exp_f32_e32 v13, v13
	v_lshl_add_u64 v[16:17], v[158:159], 0, s[4:5]
	v_pk_mul_f32 v[6:7], v[6:7], v[18:19] op_sel_hi:[1,0]
	v_add_f32_e32 v12, 1.0, v12
	v_add_f32_e32 v13, 1.0, v13
	v_rcp_f32_e32 v12, v12
	v_rcp_f32_e32 v13, v13
	v_pk_mul_f32 v[0:1], v[0:1], v[18:19] op_sel_hi:[1,0]
	v_mul_f32_e32 v6, 0xbfb8aa3b, v6
	v_mul_f32_e32 v7, 0xbfb8aa3b, v7
	v_exp_f32_e32 v6, v6
	v_exp_f32_e32 v7, v7
	v_mul_f32_e32 v0, 0xbfb8aa3b, v0
	v_mul_f32_e32 v1, 0xbfb8aa3b, v1
	v_exp_f32_e32 v0, v0
	v_exp_f32_e32 v1, v1
	v_add_f32_e32 v6, 1.0, v6
	v_add_f32_e32 v7, 1.0, v7
	v_rcp_f32_e32 v6, v6
	v_rcp_f32_e32 v7, v7
	v_add_f32_e32 v0, 1.0, v0
	v_add_f32_e32 v1, 1.0, v1
	v_rcp_f32_e32 v0, v0
	v_rcp_f32_e32 v1, v1
	v_pk_mul_f32 v[4:5], v[4:5], v[18:19] op_sel_hi:[1,0]
	v_pk_mul_f32 v[2:3], v[2:3], v[18:19] op_sel_hi:[1,0]
	v_mul_f32_e32 v4, 0xbfb8aa3b, v4
	v_mul_f32_e32 v5, 0xbfb8aa3b, v5
	v_exp_f32_e32 v4, v4
	v_exp_f32_e32 v5, v5
	s_and_b64 vcc, exec, s[38:39]
	s_mov_b32 s2, s30
	v_add_f32_e32 v4, 1.0, v4
	v_add_f32_e32 v5, 1.0, v5
	v_rcp_f32_e32 v4, v4
	v_rcp_f32_e32 v5, v5
	s_mov_b64 s[4:5], s[48:49]
	v_lshlrev_b32_e32 v26, 16, v20
	v_and_b32_e32 v27, 0xffff0000, v20
	v_lshlrev_b32_e32 v20, 16, v21
	v_and_b32_e32 v21, 0xffff0000, v21
	v_pk_mul_f32 v[14:15], v[14:15], v[20:21]
	v_lshlrev_b32_e32 v20, 16, v22
	v_and_b32_e32 v21, 0xffff0000, v22
	v_pk_mul_f32 v[20:21], v[8:9], v[20:21]
	v_mul_f32_e32 v8, 0xbfb8aa3b, v10
	v_mul_f32_e32 v9, 0xbfb8aa3b, v11
	v_exp_f32_e32 v8, v8
	v_exp_f32_e32 v9, v9
	v_lshlrev_b32_e32 v10, 16, v23
	v_and_b32_e32 v11, 0xffff0000, v23
	v_add_f32_e32 v8, 1.0, v8
	v_add_f32_e32 v9, 1.0, v9
	v_rcp_f32_e32 v8, v8
	v_rcp_f32_e32 v9, v9
	v_pk_mul_f32 v[12:13], v[12:13], v[26:27]
	v_pk_mul_f32 v[22:23], v[8:9], v[10:11]
	v_cvt_pk_bf16_f32 v8, v12, v13
	v_cvt_pk_bf16_f32 v9, v14, v15
	v_cvt_pk_bf16_f32 v10, v20, v21
	v_cvt_pk_bf16_f32 v11, v22, v23
	global_store_dwordx4 v[24:25], v[8:11], off
	s_nop 1
	v_mov_b32_e32 v8, v252
	v_mov_b32_e32 v9, v253
	v_mov_b32_e32 v10, v254
	v_mov_b32_e32 v11, v255
	v_lshlrev_b32_e32 v12, 16, v8
	v_and_b32_e32 v13, 0xffff0000, v8
	v_lshlrev_b32_e32 v8, 16, v9
	v_and_b32_e32 v9, 0xffff0000, v9
	v_pk_mul_f32 v[6:7], v[6:7], v[8:9]
	v_lshlrev_b32_e32 v8, 16, v10
	v_and_b32_e32 v9, 0xffff0000, v10
	v_pk_mul_f32 v[8:9], v[0:1], v[8:9]
	v_mul_f32_e32 v0, 0xbfb8aa3b, v2
	v_mul_f32_e32 v1, 0xbfb8aa3b, v3
	v_exp_f32_e32 v0, v0
	v_exp_f32_e32 v1, v1
	v_lshlrev_b32_e32 v2, 16, v11
	v_and_b32_e32 v3, 0xffff0000, v11
	v_add_f32_e32 v0, 1.0, v0
	v_add_f32_e32 v1, 1.0, v1
	v_rcp_f32_e32 v0, v0
	v_rcp_f32_e32 v1, v1
	v_pk_mul_f32 v[4:5], v[4:5], v[12:13]
	v_pk_mul_f32 v[10:11], v[0:1], v[2:3]
	v_cvt_pk_bf16_f32 v0, v4, v5
	v_cvt_pk_bf16_f32 v1, v6, v7
	v_cvt_pk_bf16_f32 v2, v8, v9
	v_cvt_pk_bf16_f32 v3, v10, v11
	global_store_dwordx4 v[16:17], v[0:3], off offset:256
	s_cbranch_vccz .LBB0_306
	s_cmpk_gt_u32 s36, 0xff
	s_cbranch_scc1 .LBB0_317
	s_barrier

; #define PG8_STAGE(bufoff, gbase, voff) do { _Pragma("unroll") for (int _i = 0; _i < 2; ++_i) \
;         __builtin_amdgcn_global_load_lds((const unsigned*)((const char*)(gbase) + (voff)[_i]), (PG8_LAS unsigned*)(lds + (bufoff) + ldsw + _i * 8192), 16, 0, 0); } while (0)
; #define PG8_LDA(dst, b, h) do { _Pragma("unroll") for (int m = 0; m < 4; ++m) _Pragma("unroll") for (int k = 0; k < 2; ++k) dst[m][k] = *(const PG8_LAS bf16x8*)(lds + PG8_SA(b, h) + aoff + m * 2048 + k * 1024); } while (0)
; #define PG8_LDB(dst, b, h) do { _Pragma("unroll") for (int n = 0; n < 2; ++n) _Pragma("unroll") for (int k = 0; k < 2; ++k) dst[n][k] = *(const PG8_LAS bf16x8*)(lds + PG8_SB(b, h) + boff + n * 2048 + k * 1024); } while (0)
; #define PG8_MMA(ai, bj, At, Bt) do { __builtin_amdgcn_s_setprio(1); _Pragma("unroll") for (int m = 0; m < 4; ++m) _Pragma("unroll") for (int n = 0; n < 2; ++n) _Pragma("unroll") for (int k = 0; k < 2; ++k) \
;         acc[ai][bj][m][n] = __builtin_amdgcn_mfma_f32_16x16x32_bf16(Bt[n][k], At[m][k], acc[ai][bj][m][n], 0, 0, 0); __builtin_amdgcn_s_setprio(0); } while (0)
; #define PG8_WAIT_V(n) asm volatile("s_waitcnt vmcnt(" #n ")" ::: "memory")
; template <class Epi, class Sched, bool STAMP = false>
; __device__ __forceinline__ void gemm_phase(PG8_LAS unsigned char* lds, const Gemm g, const Sched& S, const Epi& E, unsigned long long* stamps) {
;     ...
;             const bool last = (t == nt - 2);
;             const char* a1 = cA + (size_t)(t + 1) * kstep;
;             const char* a2 = last ? nA : cA + (size_t)(t + 2) * kstep; const char* b2 = last ? nB : cB + (size_t)(t + 2) * kstep;
;             const char* a3 = a2 + kstep; const char* b3 = b2 + kstep;
;             if (last && has_next) S.a_ready(nxt);
;             PG8_LDB(B0, 0, 0); PG8_SCHED; PG8_LDA(At, 0, 0); PG8_STAGE(PG8_SA(1, 1), a1 + hstep, voffA);
;             PG8_WAIT_L(8); PG8_BAR; PG8_WAIT_L(0); PG8_MMA(0, 0, At, B0); PG8_BAR; PG8_SCHED;
;             PG8_LDB(B1, 0, 1); PG8_STAGE(PG8_SB(0, 0), b2, voffB);
;             PG8_BAR; PG8_WAIT_L(0); PG8_MMA(0, 1, At, B1); PG8_BAR;
;             PG8_LDA(At, 0, 1); PG8_STAGE(PG8_SA(0, 0), a2, voffA);
;             PG8_BAR; PG8_WAIT_L(0); PG8_MMA(1, 0, At, B0); PG8_BAR; PG8_SCHED;
;             PG8_STAGE(PG8_SB(0, 1), b2 + hstep, voffB);
;             PG8_WAIT_V(6); PG8_BAR; PG8_MMA(1, 1, At, B1); PG8_BAR;
.LBB0_333:
	s_add_u32 s14, s36, 0xfffe0080
	s_addc_u32 s15, s37, -1
	s_add_i32 s16, 0, 0x10000
	ds_read_b128 v[162:165], v248
	ds_read_b128 v[166:169], v248 offset:1024
	ds_read_b128 v[170:173], v248 offset:2048
	ds_read_b128 v[174:177], v248 offset:3072
	s_cmp_eq_u32 s97, 4
	s_cselect_b32 s59, s13, s15
	s_cselect_b32 s58, s77, s14
	s_cselect_b32 s57, s5, s96
	s_cselect_b32 s56, s88, s89
	s_add_i32 m0, s3, 0xc000
	ds_read_b128 v[178:181], v160
	ds_read_b128 v[192:195], v160 offset:1024
	ds_read_b128 v[196:199], v160 offset:2048
	ds_read_b128 v[200:203], v160 offset:3072
	ds_read_b128 v[204:207], v160 offset:4096
	ds_read_b128 v[208:211], v160 offset:5120
	ds_read_b128 v[212:215], v160 offset:6144
	global_load_lds_dwordx4 v154, s[36:37]
	s_add_i32 m0, s3, 0xe000
	ds_read_b128 v[216:219], v160 offset:7168
	global_load_lds_dwordx4 v156, s[36:37]
	s_waitcnt lgkmcnt(8)
	s_barrier
	s_waitcnt lgkmcnt(0)
	v_mfma_f32_16x16x32_bf16 v[124:127], v[162:165], v[178:181], v[124:127]
	v_mfma_f32_16x16x32_bf16 v[120:123], v[170:173], v[178:181], v[120:123]
	v_mfma_f32_16x16x32_bf16 v[116:119], v[162:165], v[196:199], v[116:119]
	v_mfma_f32_16x16x32_bf16 v[112:115], v[170:173], v[196:199], v[112:115]
	v_mfma_f32_16x16x32_bf16 v[100:103], v[162:165], v[204:207], v[100:103]
	v_mfma_f32_16x16x32_bf16 v[96:99], v[170:173], v[204:207], v[96:99]
	v_mfma_f32_16x16x32_bf16 v[84:87], v[162:165], v[212:215], v[84:87]
	v_mfma_f32_16x16x32_bf16 v[80:83], v[170:173], v[212:215], v[80:83]
	v_mfma_f32_16x16x32_bf16 v[124:127], v[166:169], v[192:195], v[124:127]
	v_mfma_f32_16x16x32_bf16 v[120:123], v[174:177], v[192:195], v[120:123]
	v_mfma_f32_16x16x32_bf16 v[116:119], v[166:169], v[200:203], v[116:119]
	v_mfma_f32_16x16x32_bf16 v[112:115], v[174:177], v[200:203], v[112:115]
	v_mfma_f32_16x16x32_bf16 v[100:103], v[166:169], v[208:211], v[100:103]
	v_mfma_f32_16x16x32_bf16 v[96:99], v[174:177], v[208:211], v[96:99]
	v_mfma_f32_16x16x32_bf16 v[84:87], v[166:169], v[216:219], v[84:87]
	v_mfma_f32_16x16x32_bf16 v[80:83], v[174:177], v[216:219], v[80:83]
	s_barrier
	s_add_i32 s17, 0, 0x14000
	s_add_i32 s14, s16, s53
	s_mov_b32 m0, s14
	ds_read_b128 v[220:223], v249
	ds_read_b128 v[224:227], v249 offset:1024
	ds_read_b128 v[228:231], v249 offset:2048
	global_load_lds_dwordx4 v128, s[56:57]
	s_add_i32 m0, s14, 0x2000
	ds_read_b128 v[232:235], v249 offset:3072
	global_load_lds_dwordx4 v152, s[56:57]
	s_barrier
	s_waitcnt lgkmcnt(0)
	v_mfma_f32_16x16x32_bf16 v[108:111], v[220:223], v[178:181], v[108:111]
	v_mfma_f32_16x16x32_bf16 v[104:107], v[228:231], v[178:181], v[104:107]
	v_mfma_f32_16x16x32_bf16 v[92:95], v[220:223], v[196:199], v[92:95]
	v_mfma_f32_16x16x32_bf16 v[88:91], v[228:231], v[196:199], v[88:91]
	v_mfma_f32_16x16x32_bf16 v[76:79], v[220:223], v[204:207], v[76:79]
	v_mfma_f32_16x16x32_bf16 v[72:75], v[228:231], v[204:207], v[72:75]
	v_mfma_f32_16x16x32_bf16 v[68:71], v[220:223], v[212:215], v[68:71]
	v_mfma_f32_16x16x32_bf16 v[64:67], v[228:231], v[212:215], v[64:67]
	v_mfma_f32_16x16x32_bf16 v[108:111], v[224:227], v[192:195], v[108:111]
	v_mfma_f32_16x16x32_bf16 v[104:107], v[232:235], v[192:195], v[104:107]
	v_mfma_f32_16x16x32_bf16 v[92:95], v[224:227], v[200:203], v[92:95]
	v_mfma_f32_16x16x32_bf16 v[88:91], v[232:235], v[200:203], v[88:91]
	v_mfma_f32_16x16x32_bf16 v[76:79], v[224:227], v[208:211], v[76:79]
	v_mfma_f32_16x16x32_bf16 v[72:75], v[232:235], v[208:211], v[72:75]
	v_mfma_f32_16x16x32_bf16 v[68:71], v[224:227], v[216:219], v[68:71]
	v_mfma_f32_16x16x32_bf16 v[64:67], v[232:235], v[216:219], v[64:67]
	s_mov_b32 m0, s3
	s_barrier
	ds_read_b128 v[178:181], v160 offset:16384
	ds_read_b128 v[192:195], v160 offset:17408
	ds_read_b128 v[196:199], v160 offset:18432
	ds_read_b128 v[200:203], v160 offset:19456
	ds_read_b128 v[204:207], v160 offset:20480
	ds_read_b128 v[208:211], v160 offset:21504
	ds_read_b128 v[212:215], v160 offset:22528
	global_load_lds_dwordx4 v148, s[58:59]
	s_mov_b32 m0, s60
	ds_read_b128 v[216:219], v160 offset:23552
	global_load_lds_dwordx4 v150, s[58:59]
	s_barrier
	s_waitcnt lgkmcnt(0)
	v_mfma_f32_16x16x32_bf16 v[60:63], v[162:165], v[178:181], v[60:63]
	v_mfma_f32_16x16x32_bf16 v[56:59], v[170:173], v[178:181], v[56:59]
	v_mfma_f32_16x16x32_bf16 v[52:55], v[162:165], v[196:199], v[52:55]
	v_mfma_f32_16x16x32_bf16 v[48:51], v[170:173], v[196:199], v[48:51]
	v_mfma_f32_16x16x32_bf16 v[36:39], v[162:165], v[204:207], v[36:39]
	v_mfma_f32_16x16x32_bf16 v[32:35], v[170:173], v[204:207], v[32:35]
	v_mfma_f32_16x16x32_bf16 v[20:23], v[162:165], v[212:215], v[20:23]
	v_mfma_f32_16x16x32_bf16 v[16:19], v[170:173], v[212:215], v[16:19]
	v_mfma_f32_16x16x32_bf16 v[60:63], v[166:169], v[192:195], v[60:63]
	v_mfma_f32_16x16x32_bf16 v[56:59], v[174:177], v[192:195], v[56:59]
	v_mfma_f32_16x16x32_bf16 v[52:55], v[166:169], v[200:203], v[52:55]
	v_mfma_f32_16x16x32_bf16 v[48:51], v[174:177], v[200:203], v[48:51]
	v_mfma_f32_16x16x32_bf16 v[36:39], v[166:169], v[208:211], v[36:39]
	v_mfma_f32_16x16x32_bf16 v[32:35], v[174:177], v[208:211], v[32:35]
	v_mfma_f32_16x16x32_bf16 v[20:23], v[166:169], v[216:219], v[20:23]
	v_mfma_f32_16x16x32_bf16 v[16:19], v[174:177], v[216:219], v[16:19]
	s_barrier
	s_add_u32 s14, s56, 0x20000
	s_addc_u32 s15, s57, 0
	s_add_i32 s16, s17, s53
	s_mov_b32 m0, s16
	s_nop 0
	global_load_lds_dwordx4 v128, s[14:15]
	s_add_i32 m0, s16, 0x2000
	s_nop 0
	global_load_lds_dwordx4 v152, s[14:15]
	s_waitcnt vmcnt(6)
	s_barrier
; #define PG8_STAGE(bufoff, gbase, voff) do { _Pragma("unroll") for (int _i = 0; _i < 2; ++_i) \
;         __builtin_amdgcn_global_load_lds((const unsigned*)((const char*)(gbase) + (voff)[_i]), (PG8_LAS unsigned*)(lds + (bufoff) + ldsw + _i * 8192), 16, 0, 0); } while (0)
; #define PG8_LDA(dst, b, h) do { _Pragma("unroll") for (int m = 0; m < 4; ++m) _Pragma("unroll") for (int k = 0; k < 2; ++k) dst[m][k] = *(const PG8_LAS bf16x8*)(lds + PG8_SA(b, h) + aoff + m * 2048 + k * 1024); } while (0)
; #define PG8_LDB(dst, b, h) do { _Pragma("unroll") for (int n = 0; n < 2; ++n) _Pragma("unroll") for (int k = 0; k < 2; ++k) dst[n][k] = *(const PG8_LAS bf16x8*)(lds + PG8_SB(b, h) + boff + n * 2048 + k * 1024); } while (0)
; #define PG8_MMA(ai, bj, At, Bt) do { __builtin_amdgcn_s_setprio(1); _Pragma("unroll") for (int m = 0; m < 4; ++m) _Pragma("unroll") for (int n = 0; n < 2; ++n) _Pragma("unroll") for (int k = 0; k < 2; ++k) \
;         acc[ai][bj][m][n] = __builtin_amdgcn_mfma_f32_16x16x32_bf16(Bt[n][k], At[m][k], acc[ai][bj][m][n], 0, 0, 0); __builtin_amdgcn_s_setprio(0); } while (0)
; #define PG8_WAIT_V(n) asm volatile("s_waitcnt vmcnt(" #n ")" ::: "memory")
; #define PG8_WAIT_L(n) asm volatile("s_waitcnt lgkmcnt(" #n ")" ::: "memory")
; #define PG8_BAR __builtin_amdgcn_s_barrier()
; #define PG8_SCHED __builtin_amdgcn_sched_barrier(0)
; template <class Epi, class Sched, bool STAMP = false>
; __device__ __forceinline__ void gemm_phase(PG8_LAS unsigned char* lds, const Gemm g, const Sched& S, const Epi& E, unsigned long long* stamps) {
;     ...
;             PG8_WAIT_V(6); PG8_BAR; PG8_MMA(1, 1, At, B1); PG8_BAR;
;             PG8_LDB(B0, 1, 0); PG8_SCHED; PG8_LDA(At, 1, 0); PG8_STAGE(PG8_SA(0, 1), a2 + hstep, voffA);
;             PG8_WAIT_L(8); PG8_BAR; PG8_WAIT_L(0); PG8_MMA(0, 0, At, B0); PG8_BAR; PG8_SCHED;
;             PG8_LDB(B1, 1, 1); PG8_STAGE(PG8_SB(1, 0), b3, voffB);
;             PG8_BAR; PG8_WAIT_L(0); PG8_MMA(0, 1, At, B1); PG8_BAR;
;             PG8_LDA(At, 1, 1); PG8_STAGE(PG8_SA(1, 0), a3, voffA);
;             PG8_BAR; PG8_WAIT_L(0); PG8_MMA(1, 0, At, B0); PG8_BAR; PG8_SCHED;
	v_mfma_f32_16x16x32_bf16 v[44:47], v[220:223], v[178:181], v[44:47]
	v_mfma_f32_16x16x32_bf16 v[40:43], v[228:231], v[178:181], v[40:43]
	v_mfma_f32_16x16x32_bf16 v[28:31], v[220:223], v[196:199], v[28:31]
	v_mfma_f32_16x16x32_bf16 v[24:27], v[228:231], v[196:199], v[24:27]
	v_mfma_f32_16x16x32_bf16 v[12:15], v[220:223], v[204:207], v[12:15]
	v_mfma_f32_16x16x32_bf16 v[8:11], v[228:231], v[204:207], v[8:11]
	v_mfma_f32_16x16x32_bf16 v[4:7], v[220:223], v[212:215], v[4:7]
	v_mfma_f32_16x16x32_bf16 v[0:3], v[228:231], v[212:215], v[0:3]
	v_mfma_f32_16x16x32_bf16 v[44:47], v[224:227], v[192:195], v[44:47]
	v_mfma_f32_16x16x32_bf16 v[40:43], v[232:235], v[192:195], v[40:43]
	v_mfma_f32_16x16x32_bf16 v[28:31], v[224:227], v[200:203], v[28:31]
	v_mfma_f32_16x16x32_bf16 v[24:27], v[232:235], v[200:203], v[24:27]
	v_mfma_f32_16x16x32_bf16 v[12:15], v[224:227], v[208:211], v[12:15]
	v_mfma_f32_16x16x32_bf16 v[8:11], v[232:235], v[208:211], v[8:11]
	v_mfma_f32_16x16x32_bf16 v[4:7], v[224:227], v[216:219], v[4:7]
	v_mfma_f32_16x16x32_bf16 v[0:3], v[232:235], v[216:219], v[0:3]
	s_add_i32 s16, 0, 0x18000
	s_barrier
	ds_read_b128 v[162:165], v250
	ds_read_b128 v[166:169], v250 offset:1024
	ds_read_b128 v[170:173], v250 offset:2048
	ds_read_b128 v[174:177], v250 offset:3072
	s_add_u32 s14, s58, 0x20000
	s_addc_u32 s15, s59, 0
	s_mov_b32 m0, s61
	ds_read_b128 v[178:181], v160 offset:32768
	ds_read_b128 v[192:195], v160 offset:33792
	ds_read_b128 v[196:199], v160 offset:34816
	ds_read_b128 v[200:203], v160 offset:35840
	ds_read_b128 v[204:207], v160 offset:36864
	ds_read_b128 v[208:211], v160 offset:37888
	ds_read_b128 v[212:215], v160 offset:38912
	global_load_lds_dwordx4 v148, s[14:15]
	s_mov_b32 m0, s62
	ds_read_b128 v[216:219], v160 offset:39936
	global_load_lds_dwordx4 v150, s[14:15]
	s_waitcnt lgkmcnt(8)
	s_barrier
	s_waitcnt lgkmcnt(0)
	v_mfma_f32_16x16x32_bf16 v[124:127], v[162:165], v[178:181], v[124:127]
	v_mfma_f32_16x16x32_bf16 v[120:123], v[170:173], v[178:181], v[120:123]
	v_mfma_f32_16x16x32_bf16 v[116:119], v[162:165], v[196:199], v[116:119]
	v_mfma_f32_16x16x32_bf16 v[112:115], v[170:173], v[196:199], v[112:115]
	v_mfma_f32_16x16x32_bf16 v[100:103], v[162:165], v[204:207], v[100:103]
	v_mfma_f32_16x16x32_bf16 v[96:99], v[170:173], v[204:207], v[96:99]
	v_mfma_f32_16x16x32_bf16 v[84:87], v[162:165], v[212:215], v[84:87]
	v_mfma_f32_16x16x32_bf16 v[80:83], v[170:173], v[212:215], v[80:83]
	v_mfma_f32_16x16x32_bf16 v[124:127], v[166:169], v[192:195], v[124:127]
	v_mfma_f32_16x16x32_bf16 v[120:123], v[174:177], v[192:195], v[120:123]
	v_mfma_f32_16x16x32_bf16 v[116:119], v[166:169], v[200:203], v[116:119]
	v_mfma_f32_16x16x32_bf16 v[112:115], v[174:177], v[200:203], v[112:115]
	v_mfma_f32_16x16x32_bf16 v[100:103], v[166:169], v[208:211], v[100:103]
	v_mfma_f32_16x16x32_bf16 v[96:99], v[174:177], v[208:211], v[96:99]
	v_mfma_f32_16x16x32_bf16 v[84:87], v[166:169], v[216:219], v[84:87]
	v_mfma_f32_16x16x32_bf16 v[80:83], v[174:177], v[216:219], v[80:83]
	s_barrier
	s_add_i32 s17, 0, 0x1c000
	s_add_i32 s14, s16, s53
	s_mov_b32 m0, s14
	ds_read_b128 v[220:223], v251
	ds_read_b128 v[224:227], v251 offset:1024
	ds_read_b128 v[228:231], v251 offset:2048
	global_load_lds_dwordx4 v244, s[56:57]
	s_add_i32 m0, s14, 0x2000
	ds_read_b128 v[232:235], v251 offset:3072
	global_load_lds_dwordx4 v245, s[56:57]
	s_barrier
	s_waitcnt lgkmcnt(0)
	v_mfma_f32_16x16x32_bf16 v[108:111], v[220:223], v[178:181], v[108:111]
	v_mfma_f32_16x16x32_bf16 v[104:107], v[228:231], v[178:181], v[104:107]
	v_mfma_f32_16x16x32_bf16 v[92:95], v[220:223], v[196:199], v[92:95]
	v_mfma_f32_16x16x32_bf16 v[88:91], v[228:231], v[196:199], v[88:91]
	v_mfma_f32_16x16x32_bf16 v[76:79], v[220:223], v[204:207], v[76:79]
	v_mfma_f32_16x16x32_bf16 v[72:75], v[228:231], v[204:207], v[72:75]
	v_mfma_f32_16x16x32_bf16 v[68:71], v[220:223], v[212:215], v[68:71]
	v_mfma_f32_16x16x32_bf16 v[64:67], v[228:231], v[212:215], v[64:67]
	v_mfma_f32_16x16x32_bf16 v[108:111], v[224:227], v[192:195], v[108:111]
	v_mfma_f32_16x16x32_bf16 v[104:107], v[232:235], v[192:195], v[104:107]
	v_mfma_f32_16x16x32_bf16 v[92:95], v[224:227], v[200:203], v[92:95]
	v_mfma_f32_16x16x32_bf16 v[88:91], v[232:235], v[200:203], v[88:91]
	v_mfma_f32_16x16x32_bf16 v[76:79], v[224:227], v[208:211], v[76:79]
	v_mfma_f32_16x16x32_bf16 v[72:75], v[232:235], v[208:211], v[72:75]
	v_mfma_f32_16x16x32_bf16 v[68:71], v[224:227], v[216:219], v[68:71]
	v_mfma_f32_16x16x32_bf16 v[64:67], v[232:235], v[216:219], v[64:67]
	s_mov_b32 m0, s63
	s_barrier
	ds_read_b128 v[178:181], v160 offset:49152
	ds_read_b128 v[192:195], v160 offset:50176
	ds_read_b128 v[196:199], v160 offset:51200
	ds_read_b128 v[200:203], v160 offset:52224
	ds_read_b128 v[204:207], v160 offset:53248
	ds_read_b128 v[208:211], v160 offset:54272
	ds_read_b128 v[212:215], v160 offset:55296
	global_load_lds_dwordx4 v246, s[58:59]
	s_mov_b32 m0, s64
	ds_read_b128 v[216:219], v160 offset:56320
	global_load_lds_dwordx4 v247, s[58:59]
	s_barrier
	s_waitcnt lgkmcnt(0)
	v_mfma_f32_16x16x32_bf16 v[60:63], v[162:165], v[178:181], v[60:63]
	v_mfma_f32_16x16x32_bf16 v[56:59], v[170:173], v[178:181], v[56:59]
	v_mfma_f32_16x16x32_bf16 v[52:55], v[162:165], v[196:199], v[52:55]
	v_mfma_f32_16x16x32_bf16 v[48:51], v[170:173], v[196:199], v[48:51]
	v_mfma_f32_16x16x32_bf16 v[36:39], v[162:165], v[204:207], v[36:39]
	v_mfma_f32_16x16x32_bf16 v[32:35], v[170:173], v[204:207], v[32:35]
	v_mfma_f32_16x16x32_bf16 v[20:23], v[162:165], v[212:215], v[20:23]
	v_mfma_f32_16x16x32_bf16 v[16:19], v[170:173], v[212:215], v[16:19]
	v_mfma_f32_16x16x32_bf16 v[60:63], v[166:169], v[192:195], v[60:63]
	v_mfma_f32_16x16x32_bf16 v[56:59], v[174:177], v[192:195], v[56:59]
	v_mfma_f32_16x16x32_bf16 v[52:55], v[166:169], v[200:203], v[52:55]
	v_mfma_f32_16x16x32_bf16 v[48:51], v[174:177], v[200:203], v[48:51]
	v_mfma_f32_16x16x32_bf16 v[36:39], v[166:169], v[208:211], v[36:39]
	v_mfma_f32_16x16x32_bf16 v[32:35], v[174:177], v[208:211], v[32:35]
	v_mfma_f32_16x16x32_bf16 v[20:23], v[166:169], v[216:219], v[20:23]
	v_mfma_f32_16x16x32_bf16 v[16:19], v[174:177], v[216:219], v[16:19]
	s_barrier
; __device__ __forceinline__ unsigned cvt_pk_bf16(float lo, float hi) { const f32x2_cv v = {lo, hi}; const bf16x2_cv b = __builtin_convertvector(v, bf16x2_cv); return __builtin_bit_cast(unsigned, b); }
; #define PG8_STAGE(bufoff, gbase, voff) do { _Pragma("unroll") for (int _i = 0; _i < 2; ++_i) \
;         __builtin_amdgcn_global_load_lds((const unsigned*)((const char*)(gbase) + (voff)[_i]), (PG8_LAS unsigned*)(lds + (bufoff) + ldsw + _i * 8192), 16, 0, 0); } while (0)
; #define PG8_MMA(ai, bj, At, Bt) do { __builtin_amdgcn_s_setprio(1); _Pragma("unroll") for (int m = 0; m < 4; ++m) _Pragma("unroll") for (int n = 0; n < 2; ++n) _Pragma("unroll") for (int k = 0; k < 2; ++k) \
;         acc[ai][bj][m][n] = __builtin_amdgcn_mfma_f32_16x16x32_bf16(Bt[n][k], At[m][k], acc[ai][bj][m][n], 0, 0, 0); __builtin_amdgcn_s_setprio(0); } while (0)
; #define PG8_WAIT_V(n) asm volatile("s_waitcnt vmcnt(" #n ")" ::: "memory")
; template <class Epi, class Sched, bool STAMP = false>
; __device__ __forceinline__ void gemm_phase(PG8_LAS unsigned char* lds, const Gemm g, const Sched& S, const Epi& E, unsigned long long* stamps) {
;     ...
;             PG8_STAGE(PG8_SB(1, 1), b3 + hstep, voffB);
;             PG8_WAIT_V(6); PG8_BAR; PG8_MMA(1, 1, At, B1); PG8_BAR;
;     __device__ __forceinline__ void operator()(const f32x4 (&acc)[2][2][4][2], const pg8::Unit& u, int wr, int wc, int fr, int fq) const {
;         const int row0 = u.pm * 256 + wr * 64 + fr, col0 = u.pn * 256 + wc * 32 + 8 * fq;
; #pragma unroll
;         for (int ai = 0; ai < 2; ++ai)
; #pragma unroll
;             for (int m = 0; m < 4; ++m) {
;                 const int row = row0 + ai * 128 + m * 16;
;                 const float s = (MODE == 2) ? 1.0f : rstd_of(rowss, row);
;                 bf16_t* rowp = O + (size_t)row * ldc + col0;
; #pragma unroll
;                 for (int bj = 0; bj < 2; ++bj) {
;                     f32x4 v0 = acc[ai][bj][m][0] * s, v1 = acc[ai][bj][m][1] * s;
;                     if (MODE == 1) {
; #pragma unroll
;                         for (int j = 0; j < 4; ++j) { const float a = fmaxf(v0[j], 0.f), b = fmaxf(v1[j], 0.f); v0[j] = a * a; v1[j] = b * b; } }
;                     u32x4 w; w.x = cvt_pk_bf16(v0[0], v0[1]); w.y = cvt_pk_bf16(v0[2], v0[3]); w.z = cvt_pk_bf16(v1[0], v1[1]); w.w = cvt_pk_bf16(v1[2], v1[3]);
;                     *(u32x4*)(rowp + bj * 128) = w; } }
	s_add_u32 s14, s56, 0x20080
	s_addc_u32 s15, s57, 0
	s_add_i32 s16, s17, s53
	s_mov_b32 m0, s16
	s_nop 0
	global_load_lds_dwordx4 v128, s[14:15]
	s_add_i32 m0, s16, 0x2000
	s_nop 0
	global_load_lds_dwordx4 v152, s[14:15]
	s_waitcnt vmcnt(6)
	s_barrier
	v_mfma_f32_16x16x32_bf16 v[44:47], v[220:223], v[178:181], v[44:47]
	v_mfma_f32_16x16x32_bf16 v[40:43], v[228:231], v[178:181], v[40:43]
	v_mfma_f32_16x16x32_bf16 v[28:31], v[220:223], v[196:199], v[28:31]
	v_mfma_f32_16x16x32_bf16 v[24:27], v[228:231], v[196:199], v[24:27]
	v_mfma_f32_16x16x32_bf16 v[12:15], v[220:223], v[204:207], v[12:15]
	v_mfma_f32_16x16x32_bf16 v[8:11], v[228:231], v[204:207], v[8:11]
	v_mfma_f32_16x16x32_bf16 v[4:7], v[220:223], v[212:215], v[4:7]
	v_mfma_f32_16x16x32_bf16 v[0:3], v[228:231], v[212:215], v[0:3]
	v_mfma_f32_16x16x32_bf16 v[44:47], v[224:227], v[192:195], v[44:47]
	v_mfma_f32_16x16x32_bf16 v[40:43], v[232:235], v[192:195], v[40:43]
	v_mfma_f32_16x16x32_bf16 v[28:31], v[224:227], v[200:203], v[28:31]
	v_mfma_f32_16x16x32_bf16 v[24:27], v[232:235], v[200:203], v[24:27]
	v_mfma_f32_16x16x32_bf16 v[12:15], v[224:227], v[208:211], v[12:15]
	v_mfma_f32_16x16x32_bf16 v[8:11], v[232:235], v[208:211], v[8:11]
	v_mfma_f32_16x16x32_bf16 v[4:7], v[224:227], v[216:219], v[4:7]
	v_mfma_f32_16x16x32_bf16 v[0:3], v[232:235], v[216:219], v[0:3]
	s_add_i32 s97, s97, 2
	s_add_u32 s36, s36, 0x100
	s_addc_u32 s37, s37, 0
	s_add_u32 s89, s89, 0x100
	s_addc_u32 s96, s96, 0
	s_cmp_gt_u32 s97, 5
	s_barrier
	s_cbranch_scc0 .LBB0_333
	v_lshl_add_u32 v162, s2, 8, v139
	v_lshl_or_b32 v164, s76, 8, v159
	v_ashrrev_i32_e32 v163, 31, v162
	v_ashrrev_i32_e32 v165, 31, v164
	v_lshlrev_b64 v[166:167], 11, v[162:163]
	v_lshl_add_u64 v[166:167], s[30:31], 0, v[166:167]
	v_lshlrev_b64 v[164:165], 1, v[164:165]
	v_lshl_add_u64 v[166:167], v[166:167], 0, v[164:165]
	s_mov_b32 s2, 0x40000
	s_mov_b64 s[14:15], 0x40000
	v_cvt_pk_bf16_f32 v60, v60, v61
	v_cvt_pk_bf16_f32 v61, v62, v63
	v_cvt_pk_bf16_f32 v62, v56, v57
	v_add_co_u32_e32 v56, vcc, s2, v166
	v_cvt_pk_bf16_f32 v68, v68, v69
	v_cvt_pk_bf16_f32 v69, v70, v71
	v_cvt_pk_bf16_f32 v70, v64, v65
	v_lshl_add_u64 v[64:65], v[166:167], 0, s[14:15]
	v_addc_co_u32_e32 v57, vcc, 0, v167, vcc
	v_cvt_pk_bf16_f32 v44, v44, v45
	v_cvt_pk_bf16_f32 v45, v46, v47
	v_cvt_pk_bf16_f32 v46, v40, v41
	v_cvt_pk_bf16_f32 v47, v42, v43
	s_mov_b32 s2, 0x48000
	v_cvt_pk_bf16_f32 v108, v108, v109
	v_cvt_pk_bf16_f32 v109, v110, v111
	v_cvt_pk_bf16_f32 v110, v104, v105
	v_or_b32_e32 v104, 16, v162
	global_store_dwordx4 v[64:65], v[44:47], off offset:256
	s_mov_b64 s[14:15], 0x48000
	v_ashrrev_i32_e32 v105, 31, v104
	v_add_co_u32_e32 v46, vcc, s2, v166
	v_cvt_pk_bf16_f32 v92, v92, v93
	v_cvt_pk_bf16_f32 v93, v94, v95
	v_cvt_pk_bf16_f32 v94, v88, v89
	v_or_b32_e32 v88, 32, v162
	v_lshl_add_u64 v[44:45], v[166:167], 0, s[14:15]
	v_addc_co_u32_e32 v47, vcc, 0, v167, vcc
	v_cvt_pk_bf16_f32 v28, v28, v29
	v_cvt_pk_bf16_f32 v29, v30, v31
	v_cvt_pk_bf16_f32 v30, v24, v25
	v_cvt_pk_bf16_f32 v31, v26, v27
	s_mov_b32 s2, 0x50000
	v_lshlrev_b64 v[104:105], 11, v[104:105]
	v_ashrrev_i32_e32 v89, 31, v88
	v_cvt_pk_bf16_f32 v76, v76, v77
	v_cvt_pk_bf16_f32 v77, v78, v79
	v_cvt_pk_bf16_f32 v78, v72, v73
	v_or_b32_e32 v72, 48, v162
	global_store_dwordx4 v[44:45], v[28:31], off offset:256
	s_mov_b64 s[14:15], 0x50000
	v_cvt_pk_bf16_f32 v111, v106, v107
	v_add_co_u32_e32 v30, vcc, s2, v166
	v_lshl_add_u64 v[104:105], s[30:31], 0, v[104:105]
	v_lshlrev_b64 v[88:89], 11, v[88:89]
	v_ashrrev_i32_e32 v73, 31, v72
	v_lshl_add_u64 v[28:29], v[166:167], 0, s[14:15]
	v_addc_co_u32_e32 v31, vcc, 0, v167, vcc
	v_cvt_pk_bf16_f32 v12, v12, v13
	v_cvt_pk_bf16_f32 v13, v14, v15
	v_cvt_pk_bf16_f32 v14, v8, v9
	v_cvt_pk_bf16_f32 v15, v10, v11
	s_mov_b32 s2, 0x58000
	global_store_dwordx4 v[166:167], v[108:111], off offset:256
	v_cvt_pk_bf16_f32 v95, v90, v91
	v_lshl_add_u64 v[88:89], s[30:31], 0, v[88:89]
	v_lshl_add_u64 v[108:109], v[104:105], 0, v[164:165]
	v_lshlrev_b64 v[72:73], 11, v[72:73]
	global_store_dwordx4 v[28:29], v[12:15], off offset:256
	global_store_dwordx4 v[108:109], v[92:95], off offset:256
	v_cvt_pk_bf16_f32 v79, v74, v75
	v_add_co_u32_e32 v14, vcc, s2, v166
	v_lshl_add_u64 v[92:93], v[88:89], 0, v[164:165]
	v_lshl_add_u64 v[72:73], s[30:31], 0, v[72:73]
	s_mov_b64 s[14:15], 0x58000
	v_addc_co_u32_e32 v15, vcc, 0, v167, vcc
	v_readlane_b32 s88, v242, 39
	v_cvt_pk_bf16_f32 v124, v124, v125
	v_cvt_pk_bf16_f32 v125, v126, v127
	v_cvt_pk_bf16_f32 v126, v120, v121
	v_cvt_pk_bf16_f32 v127, v122, v123
	v_cvt_pk_bf16_f32 v104, v116, v117
	v_cvt_pk_bf16_f32 v105, v118, v119
	v_cvt_pk_bf16_f32 v106, v112, v113
	v_cvt_pk_bf16_f32 v107, v114, v115
	v_cvt_pk_bf16_f32 v88, v100, v101
	v_cvt_pk_bf16_f32 v89, v102, v103
	v_cvt_pk_bf16_f32 v90, v96, v97
	v_cvt_pk_bf16_f32 v91, v98, v99
	global_store_dwordx4 v[92:93], v[76:79], off offset:256
	v_cvt_pk_bf16_f32 v74, v80, v81
	v_cvt_pk_bf16_f32 v75, v82, v83
	v_lshl_add_u64 v[76:77], v[72:73], 0, v[164:165]
	v_cvt_pk_bf16_f32 v72, v84, v85
	v_cvt_pk_bf16_f32 v73, v86, v87
	v_cvt_pk_bf16_f32 v71, v66, v67
	v_cvt_pk_bf16_f32 v63, v58, v59
	v_cvt_pk_bf16_f32 v40, v52, v53
	v_cvt_pk_bf16_f32 v41, v54, v55
	v_cvt_pk_bf16_f32 v42, v48, v49
	v_cvt_pk_bf16_f32 v43, v50, v51
	v_cvt_pk_bf16_f32 v24, v36, v37
	v_cvt_pk_bf16_f32 v25, v38, v39
	v_cvt_pk_bf16_f32 v26, v32, v33
	v_cvt_pk_bf16_f32 v27, v34, v35
	v_lshl_add_u64 v[12:13], v[166:167], 0, s[14:15]
	v_cvt_pk_bf16_f32 v8, v20, v21
	v_cvt_pk_bf16_f32 v9, v22, v23
	v_cvt_pk_bf16_f32 v10, v16, v17
	v_cvt_pk_bf16_f32 v11, v18, v19
	v_cvt_pk_bf16_f32 v4, v4, v5
	v_cvt_pk_bf16_f32 v5, v6, v7
	v_cvt_pk_bf16_f32 v6, v0, v1
	v_cvt_pk_bf16_f32 v7, v2, v3
	s_and_b64 vcc, exec, s[38:39]
	s_mov_b32 s76, s4
	s_mov_b32 s2, s12
	s_mov_b64 s[56:57], s[26:27]
	s_mov_b64 s[36:37], s[24:25]
	s_movk_i32 s77, 0xa0
	s_movk_i32 s58, 0xff60
	v_readlane_b32 s89, v242, 40
	global_store_dwordx4 v[166:167], v[124:127], off
	global_store_dwordx4 v[108:109], v[104:107], off
	global_store_dwordx4 v[92:93], v[88:91], off
	global_store_dwordx4 v[76:77], v[72:75], off
	global_store_dwordx4 v[76:77], v[68:71], off offset:256
	global_store_dwordx4 v[56:57], v[60:63], off
	global_store_dwordx4 v[46:47], v[40:43], off
	global_store_dwordx4 v[30:31], v[24:27], off
	global_store_dwordx4 v[14:15], v[8:11], off
	global_store_dwordx4 v[12:13], v[4:7], off offset:256
	s_cbranch_vccz .LBB0_326
	s_cmpk_gt_u32 s46, 0xff
	s_cbranch_scc1 .LBB0_337
	s_barrier

; #define PG8_STAGE(bufoff, gbase, voff) do { _Pragma("unroll") for (int _i = 0; _i < 2; ++_i) \
;         __builtin_amdgcn_global_load_lds((const unsigned*)((const char*)(gbase) + (voff)[_i]), (PG8_LAS unsigned*)(lds + (bufoff) + ldsw + _i * 8192), 16, 0, 0); } while (0)
; #define PG8_LDA(dst, b, h) do { _Pragma("unroll") for (int m = 0; m < 4; ++m) _Pragma("unroll") for (int k = 0; k < 2; ++k) dst[m][k] = *(const PG8_LAS bf16x8*)(lds + PG8_SA(b, h) + aoff + m * 2048 + k * 1024); } while (0)
; #define PG8_LDB(dst, b, h) do { _Pragma("unroll") for (int n = 0; n < 2; ++n) _Pragma("unroll") for (int k = 0; k < 2; ++k) dst[n][k] = *(const PG8_LAS bf16x8*)(lds + PG8_SB(b, h) + boff + n * 2048 + k * 1024); } while (0)
; #define PG8_MMA(ai, bj, At, Bt) do { __builtin_amdgcn_s_setprio(1); _Pragma("unroll") for (int m = 0; m < 4; ++m) _Pragma("unroll") for (int n = 0; n < 2; ++n) _Pragma("unroll") for (int k = 0; k < 2; ++k) \
;         acc[ai][bj][m][n] = __builtin_amdgcn_mfma_f32_16x16x32_bf16(Bt[n][k], At[m][k], acc[ai][bj][m][n], 0, 0, 0); __builtin_amdgcn_s_setprio(0); } while (0)
; #define PG8_WAIT_V(n) asm volatile("s_waitcnt vmcnt(" #n ")" ::: "memory")
; template <class Epi, class Sched, bool STAMP = false>
; __device__ __forceinline__ void gemm_phase(PG8_LAS unsigned char* lds, const Gemm g, const Sched& S, const Epi& E, unsigned long long* stamps) {
;     ...
;             const bool last = (t == nt - 2);
;             const char* a1 = cA + (size_t)(t + 1) * kstep;
;             const char* a2 = last ? nA : cA + (size_t)(t + 2) * kstep; const char* b2 = last ? nB : cB + (size_t)(t + 2) * kstep;
;             const char* a3 = a2 + kstep; const char* b3 = b2 + kstep;
;             if (last && has_next) S.a_ready(nxt);
;             PG8_LDB(B0, 0, 0); PG8_SCHED; PG8_LDA(At, 0, 0); PG8_STAGE(PG8_SA(1, 1), a1 + hstep, voffA);
;             PG8_WAIT_L(8); PG8_BAR; PG8_WAIT_L(0); PG8_MMA(0, 0, At, B0); PG8_BAR; PG8_SCHED;
;             PG8_LDB(B1, 0, 1); PG8_STAGE(PG8_SB(0, 0), b2, voffB);
;             PG8_BAR; PG8_WAIT_L(0); PG8_MMA(0, 1, At, B1); PG8_BAR;
;             PG8_LDA(At, 0, 1); PG8_STAGE(PG8_SA(0, 0), a2, voffA);
;             PG8_BAR; PG8_WAIT_L(0); PG8_MMA(1, 0, At, B0); PG8_BAR; PG8_SCHED;
;             PG8_STAGE(PG8_SB(0, 1), b2 + hstep, voffB);
;             PG8_WAIT_V(6); PG8_BAR; PG8_MMA(1, 1, At, B1); PG8_BAR;
.LBB0_353:
	s_add_u32 s14, s56, 0xfffc0080
	s_addc_u32 s15, s57, -1
	s_add_i32 s16, 0, 0x10000
	ds_read_b128 v[158:161], v248
	ds_read_b128 v[162:165], v248 offset:1024
	ds_read_b128 v[172:175], v248 offset:2048
	ds_read_b128 v[176:179], v248 offset:3072
	s_cmp_eq_u32 vcc_lo, 12
	s_cselect_b32 s61, s13, s15
	s_cselect_b32 s60, s47, s14
	s_cselect_b32 s59, s27, s77
	s_cselect_b32 s58, s53, s76
	s_add_i32 m0, s89, 0xc000
	ds_read_b128 v[180:183], v171
	ds_read_b128 v[192:195], v171 offset:1024
	ds_read_b128 v[196:199], v171 offset:2048
	ds_read_b128 v[200:203], v171 offset:3072
	ds_read_b128 v[204:207], v171 offset:4096
	ds_read_b128 v[208:211], v171 offset:5120
	ds_read_b128 v[212:215], v171 offset:6144
	global_load_lds_dwordx4 v154, s[56:57]
	s_add_i32 m0, s89, 0xe000
	ds_read_b128 v[216:219], v171 offset:7168
	global_load_lds_dwordx4 v156, s[56:57]
	s_waitcnt lgkmcnt(8)
	s_barrier
	s_waitcnt lgkmcnt(0)
	v_mfma_f32_16x16x32_bf16 v[124:127], v[158:161], v[180:183], v[124:127]
	v_mfma_f32_16x16x32_bf16 v[120:123], v[172:175], v[180:183], v[120:123]
	v_mfma_f32_16x16x32_bf16 v[108:111], v[158:161], v[196:199], v[108:111]
	v_mfma_f32_16x16x32_bf16 v[104:107], v[172:175], v[196:199], v[104:107]
	v_mfma_f32_16x16x32_bf16 v[92:95], v[158:161], v[204:207], v[92:95]
	v_mfma_f32_16x16x32_bf16 v[88:91], v[172:175], v[204:207], v[88:91]
	v_mfma_f32_16x16x32_bf16 v[76:79], v[158:161], v[212:215], v[76:79]
	v_mfma_f32_16x16x32_bf16 v[72:75], v[172:175], v[212:215], v[72:75]
	v_mfma_f32_16x16x32_bf16 v[124:127], v[162:165], v[192:195], v[124:127]
	v_mfma_f32_16x16x32_bf16 v[120:123], v[176:179], v[192:195], v[120:123]
	v_mfma_f32_16x16x32_bf16 v[108:111], v[162:165], v[200:203], v[108:111]
	v_mfma_f32_16x16x32_bf16 v[104:107], v[176:179], v[200:203], v[104:107]
	v_mfma_f32_16x16x32_bf16 v[92:95], v[162:165], v[208:211], v[92:95]
	v_mfma_f32_16x16x32_bf16 v[88:91], v[176:179], v[208:211], v[88:91]
	v_mfma_f32_16x16x32_bf16 v[76:79], v[162:165], v[216:219], v[76:79]
	v_mfma_f32_16x16x32_bf16 v[72:75], v[176:179], v[216:219], v[72:75]
	s_barrier
	s_add_i32 s17, 0, 0x14000
	s_add_i32 s14, s16, s88
	s_mov_b32 m0, s14
	ds_read_b128 v[220:223], v249
	ds_read_b128 v[224:227], v249 offset:1024
	ds_read_b128 v[228:231], v249 offset:2048
	global_load_lds_dwordx4 v128, s[58:59]
	s_add_i32 m0, s14, 0x2000
	ds_read_b128 v[232:235], v249 offset:3072
	global_load_lds_dwordx4 v152, s[58:59]
	s_barrier
	s_waitcnt lgkmcnt(0)
	v_mfma_f32_16x16x32_bf16 v[116:119], v[220:223], v[180:183], v[116:119]
	v_mfma_f32_16x16x32_bf16 v[112:115], v[228:231], v[180:183], v[112:115]
	v_mfma_f32_16x16x32_bf16 v[100:103], v[220:223], v[196:199], v[100:103]
	v_mfma_f32_16x16x32_bf16 v[96:99], v[228:231], v[196:199], v[96:99]
	v_mfma_f32_16x16x32_bf16 v[84:87], v[220:223], v[204:207], v[84:87]
	v_mfma_f32_16x16x32_bf16 v[80:83], v[228:231], v[204:207], v[80:83]
	v_mfma_f32_16x16x32_bf16 v[68:71], v[220:223], v[212:215], v[68:71]
	v_mfma_f32_16x16x32_bf16 v[64:67], v[228:231], v[212:215], v[64:67]
	v_mfma_f32_16x16x32_bf16 v[116:119], v[224:227], v[192:195], v[116:119]
	v_mfma_f32_16x16x32_bf16 v[112:115], v[232:235], v[192:195], v[112:115]
	v_mfma_f32_16x16x32_bf16 v[100:103], v[224:227], v[200:203], v[100:103]
	v_mfma_f32_16x16x32_bf16 v[96:99], v[232:235], v[200:203], v[96:99]
	v_mfma_f32_16x16x32_bf16 v[84:87], v[224:227], v[208:211], v[84:87]
	v_mfma_f32_16x16x32_bf16 v[80:83], v[232:235], v[208:211], v[80:83]
	v_mfma_f32_16x16x32_bf16 v[68:71], v[224:227], v[216:219], v[68:71]
	v_mfma_f32_16x16x32_bf16 v[64:67], v[232:235], v[216:219], v[64:67]
	s_mov_b32 m0, s89
	s_barrier
	ds_read_b128 v[180:183], v171 offset:16384
	ds_read_b128 v[192:195], v171 offset:17408
	ds_read_b128 v[196:199], v171 offset:18432
	ds_read_b128 v[200:203], v171 offset:19456
	ds_read_b128 v[204:207], v171 offset:20480
	ds_read_b128 v[208:211], v171 offset:21504
	ds_read_b128 v[212:215], v171 offset:22528
	global_load_lds_dwordx4 v148, s[60:61]
	s_mov_b32 m0, s96
	ds_read_b128 v[216:219], v171 offset:23552
	global_load_lds_dwordx4 v150, s[60:61]
	s_barrier
	s_waitcnt lgkmcnt(0)
	v_mfma_f32_16x16x32_bf16 v[60:63], v[158:161], v[180:183], v[60:63]
	v_mfma_f32_16x16x32_bf16 v[56:59], v[172:175], v[180:183], v[56:59]
	v_mfma_f32_16x16x32_bf16 v[44:47], v[158:161], v[196:199], v[44:47]
	v_mfma_f32_16x16x32_bf16 v[40:43], v[172:175], v[196:199], v[40:43]
	v_mfma_f32_16x16x32_bf16 v[28:31], v[158:161], v[204:207], v[28:31]
	v_mfma_f32_16x16x32_bf16 v[24:27], v[172:175], v[204:207], v[24:27]
	v_mfma_f32_16x16x32_bf16 v[12:15], v[158:161], v[212:215], v[12:15]
	v_mfma_f32_16x16x32_bf16 v[8:11], v[172:175], v[212:215], v[8:11]
	v_mfma_f32_16x16x32_bf16 v[60:63], v[162:165], v[192:195], v[60:63]
	v_mfma_f32_16x16x32_bf16 v[56:59], v[176:179], v[192:195], v[56:59]
	v_mfma_f32_16x16x32_bf16 v[44:47], v[162:165], v[200:203], v[44:47]
	v_mfma_f32_16x16x32_bf16 v[40:43], v[176:179], v[200:203], v[40:43]
	v_mfma_f32_16x16x32_bf16 v[28:31], v[162:165], v[208:211], v[28:31]
	v_mfma_f32_16x16x32_bf16 v[24:27], v[176:179], v[208:211], v[24:27]
	v_mfma_f32_16x16x32_bf16 v[12:15], v[162:165], v[216:219], v[12:15]
	v_mfma_f32_16x16x32_bf16 v[8:11], v[176:179], v[216:219], v[8:11]
	s_barrier
	s_add_u32 s14, s58, 0x40000
	s_addc_u32 s15, s59, 0
	s_add_i32 s16, s17, s88
	s_mov_b32 m0, s16
	s_nop 0
	global_load_lds_dwordx4 v128, s[14:15]
	s_add_i32 m0, s16, 0x2000
	s_nop 0
	global_load_lds_dwordx4 v152, s[14:15]
	s_waitcnt vmcnt(6)
	s_barrier
; #define PG8_STAGE(bufoff, gbase, voff) do { _Pragma("unroll") for (int _i = 0; _i < 2; ++_i) \
;         __builtin_amdgcn_global_load_lds((const unsigned*)((const char*)(gbase) + (voff)[_i]), (PG8_LAS unsigned*)(lds + (bufoff) + ldsw + _i * 8192), 16, 0, 0); } while (0)
; #define PG8_LDA(dst, b, h) do { _Pragma("unroll") for (int m = 0; m < 4; ++m) _Pragma("unroll") for (int k = 0; k < 2; ++k) dst[m][k] = *(const PG8_LAS bf16x8*)(lds + PG8_SA(b, h) + aoff + m * 2048 + k * 1024); } while (0)
; #define PG8_LDB(dst, b, h) do { _Pragma("unroll") for (int n = 0; n < 2; ++n) _Pragma("unroll") for (int k = 0; k < 2; ++k) dst[n][k] = *(const PG8_LAS bf16x8*)(lds + PG8_SB(b, h) + boff + n * 2048 + k * 1024); } while (0)
; #define PG8_MMA(ai, bj, At, Bt) do { __builtin_amdgcn_s_setprio(1); _Pragma("unroll") for (int m = 0; m < 4; ++m) _Pragma("unroll") for (int n = 0; n < 2; ++n) _Pragma("unroll") for (int k = 0; k < 2; ++k) \
;         acc[ai][bj][m][n] = __builtin_amdgcn_mfma_f32_16x16x32_bf16(Bt[n][k], At[m][k], acc[ai][bj][m][n], 0, 0, 0); __builtin_amdgcn_s_setprio(0); } while (0)
; #define PG8_WAIT_V(n) asm volatile("s_waitcnt vmcnt(" #n ")" ::: "memory")
; #define PG8_WAIT_L(n) asm volatile("s_waitcnt lgkmcnt(" #n ")" ::: "memory")
; #define PG8_BAR __builtin_amdgcn_s_barrier()
; #define PG8_SCHED __builtin_amdgcn_sched_barrier(0)
; template <class Epi, class Sched, bool STAMP = false>
; __device__ __forceinline__ void gemm_phase(PG8_LAS unsigned char* lds, const Gemm g, const Sched& S, const Epi& E, unsigned long long* stamps) {
;     ...
;             PG8_WAIT_V(6); PG8_BAR; PG8_MMA(1, 1, At, B1); PG8_BAR;
;             PG8_LDB(B0, 1, 0); PG8_SCHED; PG8_LDA(At, 1, 0); PG8_STAGE(PG8_SA(0, 1), a2 + hstep, voffA);
;             PG8_WAIT_L(8); PG8_BAR; PG8_WAIT_L(0); PG8_MMA(0, 0, At, B0); PG8_BAR; PG8_SCHED;
;             PG8_LDB(B1, 1, 1); PG8_STAGE(PG8_SB(1, 0), b3, voffB);
;             PG8_BAR; PG8_WAIT_L(0); PG8_MMA(0, 1, At, B1); PG8_BAR;
;             PG8_LDA(At, 1, 1); PG8_STAGE(PG8_SA(1, 0), a3, voffA);
;             PG8_BAR; PG8_WAIT_L(0); PG8_MMA(1, 0, At, B0); PG8_BAR; PG8_SCHED;
	v_mfma_f32_16x16x32_bf16 v[52:55], v[220:223], v[180:183], v[52:55]
	v_mfma_f32_16x16x32_bf16 v[48:51], v[228:231], v[180:183], v[48:51]
	v_mfma_f32_16x16x32_bf16 v[36:39], v[220:223], v[196:199], v[36:39]
	v_mfma_f32_16x16x32_bf16 v[32:35], v[228:231], v[196:199], v[32:35]
	v_mfma_f32_16x16x32_bf16 v[20:23], v[220:223], v[204:207], v[20:23]
	v_mfma_f32_16x16x32_bf16 v[16:19], v[228:231], v[204:207], v[16:19]
	v_mfma_f32_16x16x32_bf16 v[4:7], v[220:223], v[212:215], v[4:7]
	v_mfma_f32_16x16x32_bf16 v[0:3], v[228:231], v[212:215], v[0:3]
	v_mfma_f32_16x16x32_bf16 v[52:55], v[224:227], v[192:195], v[52:55]
	v_mfma_f32_16x16x32_bf16 v[48:51], v[232:235], v[192:195], v[48:51]
	v_mfma_f32_16x16x32_bf16 v[36:39], v[224:227], v[200:203], v[36:39]
	v_mfma_f32_16x16x32_bf16 v[32:35], v[232:235], v[200:203], v[32:35]
	v_mfma_f32_16x16x32_bf16 v[20:23], v[224:227], v[208:211], v[20:23]
	v_mfma_f32_16x16x32_bf16 v[16:19], v[232:235], v[208:211], v[16:19]
	v_mfma_f32_16x16x32_bf16 v[4:7], v[224:227], v[216:219], v[4:7]
	v_mfma_f32_16x16x32_bf16 v[0:3], v[232:235], v[216:219], v[0:3]
	s_add_i32 s16, 0, 0x18000
	s_barrier
	ds_read_b128 v[158:161], v250
	ds_read_b128 v[162:165], v250 offset:1024
	ds_read_b128 v[172:175], v250 offset:2048
	ds_read_b128 v[176:179], v250 offset:3072
	s_add_u32 s14, s60, 0x40000
	s_addc_u32 s15, s61, 0
	s_mov_b32 m0, s97
	ds_read_b128 v[180:183], v171 offset:32768
	ds_read_b128 v[192:195], v171 offset:33792
	ds_read_b128 v[196:199], v171 offset:34816
	ds_read_b128 v[200:203], v171 offset:35840
	ds_read_b128 v[204:207], v171 offset:36864
	ds_read_b128 v[208:211], v171 offset:37888
	ds_read_b128 v[212:215], v171 offset:38912
	global_load_lds_dwordx4 v148, s[14:15]
	s_mov_b32 m0, s64
	ds_read_b128 v[216:219], v171 offset:39936
	global_load_lds_dwordx4 v150, s[14:15]
	s_waitcnt lgkmcnt(8)
	s_barrier
	s_waitcnt lgkmcnt(0)
	v_mfma_f32_16x16x32_bf16 v[124:127], v[158:161], v[180:183], v[124:127]
	v_mfma_f32_16x16x32_bf16 v[120:123], v[172:175], v[180:183], v[120:123]
	v_mfma_f32_16x16x32_bf16 v[108:111], v[158:161], v[196:199], v[108:111]
	v_mfma_f32_16x16x32_bf16 v[104:107], v[172:175], v[196:199], v[104:107]
	v_mfma_f32_16x16x32_bf16 v[92:95], v[158:161], v[204:207], v[92:95]
	v_mfma_f32_16x16x32_bf16 v[88:91], v[172:175], v[204:207], v[88:91]
	v_mfma_f32_16x16x32_bf16 v[76:79], v[158:161], v[212:215], v[76:79]
	v_mfma_f32_16x16x32_bf16 v[72:75], v[172:175], v[212:215], v[72:75]
	v_mfma_f32_16x16x32_bf16 v[124:127], v[162:165], v[192:195], v[124:127]
	v_mfma_f32_16x16x32_bf16 v[120:123], v[176:179], v[192:195], v[120:123]
	v_mfma_f32_16x16x32_bf16 v[108:111], v[162:165], v[200:203], v[108:111]
	v_mfma_f32_16x16x32_bf16 v[104:107], v[176:179], v[200:203], v[104:107]
	v_mfma_f32_16x16x32_bf16 v[92:95], v[162:165], v[208:211], v[92:95]
	v_mfma_f32_16x16x32_bf16 v[88:91], v[176:179], v[208:211], v[88:91]
	v_mfma_f32_16x16x32_bf16 v[76:79], v[162:165], v[216:219], v[76:79]
	v_mfma_f32_16x16x32_bf16 v[72:75], v[176:179], v[216:219], v[72:75]
	s_barrier
	s_add_i32 s17, 0, 0x1c000
	s_add_i32 s14, s16, s88
	s_mov_b32 m0, s14
	ds_read_b128 v[220:223], v251
	ds_read_b128 v[224:227], v251 offset:1024
	ds_read_b128 v[228:231], v251 offset:2048
	global_load_lds_dwordx4 v244, s[58:59]
	s_add_i32 m0, s14, 0x2000
	ds_read_b128 v[232:235], v251 offset:3072
	global_load_lds_dwordx4 v245, s[58:59]
	s_barrier
	s_waitcnt lgkmcnt(0)
	v_mfma_f32_16x16x32_bf16 v[116:119], v[220:223], v[180:183], v[116:119]
	v_mfma_f32_16x16x32_bf16 v[112:115], v[228:231], v[180:183], v[112:115]
	v_mfma_f32_16x16x32_bf16 v[100:103], v[220:223], v[196:199], v[100:103]
	v_mfma_f32_16x16x32_bf16 v[96:99], v[228:231], v[196:199], v[96:99]
	v_mfma_f32_16x16x32_bf16 v[84:87], v[220:223], v[204:207], v[84:87]
	v_mfma_f32_16x16x32_bf16 v[80:83], v[228:231], v[204:207], v[80:83]
	v_mfma_f32_16x16x32_bf16 v[68:71], v[220:223], v[212:215], v[68:71]
	v_mfma_f32_16x16x32_bf16 v[64:67], v[228:231], v[212:215], v[64:67]
	v_mfma_f32_16x16x32_bf16 v[116:119], v[224:227], v[192:195], v[116:119]
	v_mfma_f32_16x16x32_bf16 v[112:115], v[232:235], v[192:195], v[112:115]
	v_mfma_f32_16x16x32_bf16 v[100:103], v[224:227], v[200:203], v[100:103]
	v_mfma_f32_16x16x32_bf16 v[96:99], v[232:235], v[200:203], v[96:99]
	v_mfma_f32_16x16x32_bf16 v[84:87], v[224:227], v[208:211], v[84:87]
	v_mfma_f32_16x16x32_bf16 v[80:83], v[232:235], v[208:211], v[80:83]
	v_mfma_f32_16x16x32_bf16 v[68:71], v[224:227], v[216:219], v[68:71]
	v_mfma_f32_16x16x32_bf16 v[64:67], v[232:235], v[216:219], v[64:67]
	s_mov_b32 m0, s62
	s_barrier
	ds_read_b128 v[180:183], v171 offset:49152
	ds_read_b128 v[192:195], v171 offset:50176
	ds_read_b128 v[196:199], v171 offset:51200
	ds_read_b128 v[200:203], v171 offset:52224
	ds_read_b128 v[204:207], v171 offset:53248
	ds_read_b128 v[208:211], v171 offset:54272
	ds_read_b128 v[212:215], v171 offset:55296
	global_load_lds_dwordx4 v246, s[60:61]
	s_mov_b32 m0, s63
	ds_read_b128 v[216:219], v171 offset:56320
	global_load_lds_dwordx4 v247, s[60:61]
	s_barrier
	s_waitcnt lgkmcnt(0)
	v_mfma_f32_16x16x32_bf16 v[60:63], v[158:161], v[180:183], v[60:63]
	v_mfma_f32_16x16x32_bf16 v[56:59], v[172:175], v[180:183], v[56:59]
	v_mfma_f32_16x16x32_bf16 v[44:47], v[158:161], v[196:199], v[44:47]
	v_mfma_f32_16x16x32_bf16 v[40:43], v[172:175], v[196:199], v[40:43]
	v_mfma_f32_16x16x32_bf16 v[28:31], v[158:161], v[204:207], v[28:31]
	v_mfma_f32_16x16x32_bf16 v[24:27], v[172:175], v[204:207], v[24:27]
	v_mfma_f32_16x16x32_bf16 v[12:15], v[158:161], v[212:215], v[12:15]
	v_mfma_f32_16x16x32_bf16 v[8:11], v[172:175], v[212:215], v[8:11]
	v_mfma_f32_16x16x32_bf16 v[60:63], v[162:165], v[192:195], v[60:63]
	v_mfma_f32_16x16x32_bf16 v[56:59], v[176:179], v[192:195], v[56:59]
	v_mfma_f32_16x16x32_bf16 v[44:47], v[162:165], v[200:203], v[44:47]
	v_mfma_f32_16x16x32_bf16 v[40:43], v[176:179], v[200:203], v[40:43]
	v_mfma_f32_16x16x32_bf16 v[28:31], v[162:165], v[208:211], v[28:31]
	v_mfma_f32_16x16x32_bf16 v[24:27], v[176:179], v[208:211], v[24:27]
	v_mfma_f32_16x16x32_bf16 v[12:15], v[162:165], v[216:219], v[12:15]
	v_mfma_f32_16x16x32_bf16 v[8:11], v[176:179], v[216:219], v[8:11]
	s_barrier
; __device__ __forceinline__ unsigned cvt_pk_bf16(float lo, float hi) { const f32x2_cv v = {lo, hi}; const bf16x2_cv b = __builtin_convertvector(v, bf16x2_cv); return __builtin_bit_cast(unsigned, b); }
; #define PG8_WAIT_V(n) asm volatile("s_waitcnt vmcnt(" #n ")" ::: "memory")
; #define PG8_BAR __builtin_amdgcn_s_barrier()
; __device__ __forceinline__ float sigm(float x) { return __builtin_amdgcn_rcpf(1.0f + __expf(-x)); }
; template <class Epi, class Sched, bool STAMP = false>
; __device__ __forceinline__ void gemm_phase(PG8_LAS unsigned char* lds, const Gemm g, const Sched& S, const Epi& E, unsigned long long* stamps) {
;     ...
;             PG8_STAGE(PG8_SB(1, 1), b3 + hstep, voffB);
;             PG8_WAIT_V(6); PG8_BAR; PG8_MMA(1, 1, At, B1); PG8_BAR;
;     __device__ __forceinline__ void operator()(const f32x4 (&acc)[2][2][4][2], const pg8::Unit& u, int wr, int wc, int fr, int fq) const {
;         const int row0 = u.pm * 256 + wr * 64 + fr, col0 = u.pn * 256 + wc * 32 + 8 * fq;
; #pragma unroll
;         for (int ai = 0; ai < 2; ++ai)
; #pragma unroll
;             for (int m = 0; m < 4; ++m) {
;                 const int row = row0 + ai * 128 + m * 16;
;                 const float s = rstd_of(rowss, row);
; #pragma unroll
;                 for (int bj = 0; bj < 2; ++bj) {
;                     const size_t off = (size_t)row * 1024 + col0 + bj * 128;
;                     const u32x4 tv = *(const u32x4*)(Tm + off);
;                     u32x4 pv = (u32x4){0u, 0u, 0u, 0u};
;                     if (ACC) pv = *(const u32x4*)(M + off);
;                     const f32x4 a0 = acc[ai][bj][m][0] * s, a1 = acc[ai][bj][m][1] * s;
;                     float o[8];
;                     o[0] = sigm(a0[0]) * lo16(tv.x); o[1] = sigm(a0[1]) * hi16(tv.x); o[2] = sigm(a0[2]) * lo16(tv.y); o[3] = sigm(a0[3]) * hi16(tv.y);
;                     o[4] = sigm(a1[0]) * lo16(tv.z); o[5] = sigm(a1[1]) * hi16(tv.z); o[6] = sigm(a1[2]) * lo16(tv.w); o[7] = sigm(a1[3]) * hi16(tv.w);
;                     if (ACC) { o[0] += lo16(pv.x); o[1] += hi16(pv.x); o[2] += lo16(pv.y); o[3] += hi16(pv.y); o[4] += lo16(pv.z); o[5] += hi16(pv.z); o[6] += lo16(pv.w); o[7] += hi16(pv.w); }
;                     u32x4 w; w.x = cvt_pk_bf16(o[0], o[1]); w.y = cvt_pk_bf16(o[2], o[3]); w.z = cvt_pk_bf16(o[4], o[5]); w.w = cvt_pk_bf16(o[6], o[7]);
;                     *(u32x4*)(M + off) = w; } }
	s_add_u32 s14, s58, 0x40080
	s_addc_u32 s15, s59, 0
	s_add_i32 s16, s17, s88
	s_mov_b32 m0, s16
	s_nop 0
	global_load_lds_dwordx4 v128, s[14:15]
	s_add_i32 m0, s16, 0x2000
	s_nop 0
	global_load_lds_dwordx4 v152, s[14:15]
	s_waitcnt vmcnt(6)
	s_barrier
	v_mfma_f32_16x16x32_bf16 v[52:55], v[220:223], v[180:183], v[52:55]
	v_mfma_f32_16x16x32_bf16 v[48:51], v[228:231], v[180:183], v[48:51]
	v_mfma_f32_16x16x32_bf16 v[36:39], v[220:223], v[196:199], v[36:39]
	v_mfma_f32_16x16x32_bf16 v[32:35], v[228:231], v[196:199], v[32:35]
	v_mfma_f32_16x16x32_bf16 v[20:23], v[220:223], v[204:207], v[20:23]
	v_mfma_f32_16x16x32_bf16 v[16:19], v[228:231], v[204:207], v[16:19]
	v_mfma_f32_16x16x32_bf16 v[4:7], v[220:223], v[212:215], v[4:7]
	v_mfma_f32_16x16x32_bf16 v[0:3], v[228:231], v[212:215], v[0:3]
	v_mfma_f32_16x16x32_bf16 v[52:55], v[224:227], v[192:195], v[52:55]
	v_mfma_f32_16x16x32_bf16 v[48:51], v[232:235], v[192:195], v[48:51]
	v_mfma_f32_16x16x32_bf16 v[36:39], v[224:227], v[200:203], v[36:39]
	v_mfma_f32_16x16x32_bf16 v[32:35], v[232:235], v[200:203], v[32:35]
	v_mfma_f32_16x16x32_bf16 v[20:23], v[224:227], v[208:211], v[20:23]
	v_mfma_f32_16x16x32_bf16 v[16:19], v[232:235], v[208:211], v[16:19]
	v_mfma_f32_16x16x32_bf16 v[4:7], v[224:227], v[216:219], v[4:7]
	v_mfma_f32_16x16x32_bf16 v[0:3], v[232:235], v[216:219], v[0:3]
	s_add_i32 vcc_lo, vcc_lo, 2
	s_add_u32 s56, s56, 0x100
	s_addc_u32 s57, s57, 0
	s_add_u32 s76, s76, 0x100
	s_addc_u32 s77, s77, 0
	s_cmp_gt_u32 vcc_lo, 13
	s_barrier
	s_cbranch_scc0 .LBB0_353
	v_lshl_add_u32 v164, s2, 8, v139
	v_ashrrev_i32_e32 v165, 31, v164
	v_lshl_add_u64 v[160:161], v[164:165], 2, s[40:41]
	global_load_dword v158, v[160:161], off
	v_lshl_or_b32 v162, s3, 8, v170
	v_ashrrev_i32_e32 v163, 31, v162
	s_mov_b64 s[2:3], 0x40000
	s_mov_b64 s[58:59], s[36:37]
	s_mov_b64 s[56:57], s[4:5]
	s_waitcnt vmcnt(0)
	v_fmamk_f32 v158, v158, 0x3a800000, v187
	v_cmp_gt_f32_e32 vcc, s67, v158
	v_mul_f32_e32 v159, 0x4b800000, v158
	s_nop 0
	v_cndmask_b32_e32 v158, v158, v159, vcc
	v_rsq_f32_e32 v158, v158
	s_nop 0
	v_mul_f32_e32 v159, 0x45800000, v158
	v_cndmask_b32_e32 v166, v158, v159, vcc
	v_lshlrev_b64 v[158:159], 10, v[164:165]
	v_lshl_add_u64 v[158:159], v[158:159], 0, v[162:163]
	v_lshlrev_b64 v[158:159], 1, v[158:159]
	v_lshl_add_u64 v[168:169], s[30:31], 0, v[158:159]
	v_mov_b32_e32 v249, v158
	v_mov_b32_e32 v250, v249
	global_load_dwordx4 v[192:195], v250, s[30:31]
	global_load_dwordx4 v[196:199], v250, s[0:1]
	global_load_dwordx4 v[200:203], v250, s[30:31] offset:256
	global_load_dwordx4 v[204:207], v250, s[0:1] offset:256
	v_add_u32_e32 v250, 0x8000, v249
	global_load_dwordx4 v[208:211], v250, s[30:31]
	global_load_dwordx4 v[212:215], v250, s[0:1]
	global_load_dwordx4 v[216:219], v250, s[30:31] offset:256
	global_load_dwordx4 v[220:223], v250, s[0:1] offset:256
	v_add_u32_e32 v250, 0x10000, v249
	global_load_dwordx4 v[224:227], v250, s[30:31]
	global_load_dwordx4 v[228:231], v250, s[0:1]
	global_load_dwordx4 v[232:235], v250, s[30:31] offset:256
	global_load_dwordx4 v[236:239], v250, s[0:1] offset:256
	global_load_dword v240, v[160:161], off offset:64
	global_load_dword v241, v[160:161], off offset:128
	global_load_dword v244, v[160:161], off offset:192
	global_load_dword v245, v[160:161], off offset:512
	global_load_dword v246, v[160:161], off offset:576
	global_load_dword v247, v[160:161], off offset:640
	global_load_dword v248, v[160:161], off offset:704
	v_lshl_add_u64 v[168:169], s[0:1], 0, v[158:159]
	v_pk_mul_f32 v[126:127], v[126:127], v[166:167] op_sel_hi:[1,0]
	v_pk_mul_f32 v[120:121], v[120:121], v[166:167] op_sel_hi:[1,0]
	v_mul_f32_e32 v126, 0xbfb8aa3b, v126
	v_mul_f32_e32 v127, 0xbfb8aa3b, v127
	v_pk_mul_f32 v[124:125], v[124:125], v[166:167] op_sel_hi:[1,0]
	v_pk_mul_f32 v[122:123], v[122:123], v[166:167] op_sel_hi:[1,0]
	v_exp_f32_e32 v126, v126
	v_exp_f32_e32 v127, v127
	v_mul_f32_e32 v120, 0xbfb8aa3b, v120
	v_mul_f32_e32 v121, 0xbfb8aa3b, v121
	v_mul_f32_e32 v124, 0xbfb8aa3b, v124
	v_mul_f32_e32 v125, 0xbfb8aa3b, v125
	v_exp_f32_e32 v120, v120
	v_exp_f32_e32 v121, v121
	v_mul_f32_e32 v122, 0xbfb8aa3b, v122
	v_mul_f32_e32 v123, 0xbfb8aa3b, v123
	v_exp_f32_e32 v124, v124
	v_exp_f32_e32 v125, v125
	v_exp_f32_e32 v122, v122
	v_exp_f32_e32 v123, v123
	v_add_f32_e32 v126, 1.0, v126
	v_add_f32_e32 v127, 1.0, v127
	v_rcp_f32_e32 v126, v126
	v_rcp_f32_e32 v127, v127
	v_add_f32_e32 v120, 1.0, v120
	v_add_f32_e32 v121, 1.0, v121
	v_add_f32_e32 v124, 1.0, v124
	v_add_f32_e32 v125, 1.0, v125
	v_rcp_f32_e32 v120, v120
	v_rcp_f32_e32 v121, v121
	v_add_f32_e32 v122, 1.0, v122
	v_add_f32_e32 v123, 1.0, v123
	v_rcp_f32_e32 v124, v124
	v_rcp_f32_e32 v125, v125
	v_rcp_f32_e32 v122, v122
	v_rcp_f32_e32 v123, v123
	v_pk_mul_f32 v[116:117], v[116:117], v[166:167] op_sel_hi:[1,0]
	v_pk_mul_f32 v[114:115], v[114:115], v[166:167] op_sel_hi:[1,0]
	s_waitcnt vmcnt(0)
; __device__ __forceinline__ unsigned cvt_pk_bf16(float lo, float hi) { const f32x2_cv v = {lo, hi}; const bf16x2_cv b = __builtin_convertvector(v, bf16x2_cv); return __builtin_bit_cast(unsigned, b); }
; __device__ __forceinline__ float sigm(float x) { return __builtin_amdgcn_rcpf(1.0f + __expf(-x)); }
; __device__ __forceinline__ float lo16(unsigned w) { return __uint_as_float(w << 16); }
; __device__ __forceinline__ float hi16(unsigned w) { return __uint_as_float(w & 0xffff0000u); }
; __device__ __forceinline__ float rstd_of(const float* rowss, int row) { return rsqrtf(rowss[row] * (1.0f / 1024.0f) + 1e-6f); }
;     __device__ __forceinline__ void operator()(const f32x4 (&acc)[2][2][4][2], const pg8::Unit& u, int wr, int wc, int fr, int fq) const {
;     ...
;                 const int row = row0 + ai * 128 + m * 16;
;                 const float s = rstd_of(rowss, row);
; #pragma unroll
;                 for (int bj = 0; bj < 2; ++bj) {
;                     const size_t off = (size_t)row * 1024 + col0 + bj * 128;
;                     const u32x4 tv = *(const u32x4*)(Tm + off);
;                     u32x4 pv = (u32x4){0u, 0u, 0u, 0u};
;                     if (ACC) pv = *(const u32x4*)(M + off);
;                     const f32x4 a0 = acc[ai][bj][m][0] * s, a1 = acc[ai][bj][m][1] * s;
;                     float o[8];
;                     o[0] = sigm(a0[0]) * lo16(tv.x); o[1] = sigm(a0[1]) * hi16(tv.x); o[2] = sigm(a0[2]) * lo16(tv.y); o[3] = sigm(a0[3]) * hi16(tv.y);
;                     o[4] = sigm(a1[0]) * lo16(tv.z); o[5] = sigm(a1[1]) * hi16(tv.z); o[6] = sigm(a1[2]) * lo16(tv.w); o[7] = sigm(a1[3]) * hi16(tv.w);
;                     if (ACC) { o[0] += lo16(pv.x); o[1] += hi16(pv.x); o[2] += lo16(pv.y); o[3] += hi16(pv.y); o[4] += lo16(pv.z); o[5] += hi16(pv.z); o[6] += lo16(pv.w); o[7] += hi16(pv.w); }
;                     u32x4 w; w.x = cvt_pk_bf16(o[0], o[1]); w.y = cvt_pk_bf16(o[2], o[3]); w.z = cvt_pk_bf16(o[4], o[5]); w.w = cvt_pk_bf16(o[6], o[7]);
;                     *(u32x4*)(M + off) = w; } }
	v_mov_b32_e32 v172, v192
	v_mov_b32_e32 v173, v193
	v_mov_b32_e32 v174, v194
	v_mov_b32_e32 v175, v195
	v_mov_b32_e32 v176, v196
	v_mov_b32_e32 v177, v197
	v_mov_b32_e32 v178, v198
	v_mov_b32_e32 v179, v199
	v_lshlrev_b32_e32 v180, 16, v172
	v_and_b32_e32 v181, 0xffff0000, v172
	v_lshlrev_b32_e32 v182, 16, v176
	v_and_b32_e32 v183, 0xffff0000, v176
	v_lshlrev_b32_e32 v172, 16, v173
	v_and_b32_e32 v173, 0xffff0000, v173
	v_lshlrev_b32_e32 v176, 16, v177
	v_and_b32_e32 v177, 0xffff0000, v177
	v_pk_fma_f32 v[126:127], v[126:127], v[172:173], v[176:177]
	v_lshlrev_b32_e32 v172, 16, v174
	v_and_b32_e32 v173, 0xffff0000, v174
	v_lshlrev_b32_e32 v176, 16, v178
	v_and_b32_e32 v177, 0xffff0000, v178
	v_pk_fma_f32 v[172:173], v[120:121], v[172:173], v[176:177]
	v_lshlrev_b32_e32 v120, 16, v175
	v_and_b32_e32 v121, 0xffff0000, v175
	v_lshlrev_b32_e32 v174, 16, v179
	v_and_b32_e32 v175, 0xffff0000, v179
	v_pk_fma_f32 v[124:125], v[124:125], v[180:181], v[182:183]
	v_pk_fma_f32 v[174:175], v[122:123], v[120:121], v[174:175]
	v_cvt_pk_bf16_f32 v120, v124, v125
	v_cvt_pk_bf16_f32 v121, v126, v127
	v_cvt_pk_bf16_f32 v122, v172, v173
	v_cvt_pk_bf16_f32 v123, v174, v175
	v_or_b32_e32 v124, 0x100, v158
	v_mov_b32_e32 v125, v159
	global_store_dwordx4 v[168:169], v[120:123], off
	v_lshl_add_u64 v[168:169], s[0:1], 0, v[124:125]
	v_pk_mul_f32 v[172:173], v[118:119], v[166:167] op_sel_hi:[1,0]
	v_lshl_add_u64 v[120:121], s[30:31], 0, v[124:125]
	s_nop 1
	v_mov_b32_e32 v120, v200
	v_mov_b32_e32 v121, v201
	v_mov_b32_e32 v122, v202
	v_mov_b32_e32 v123, v203
	v_pk_mul_f32 v[118:119], v[112:113], v[166:167] op_sel_hi:[1,0]
	s_nop 1
	v_mov_b32_e32 v124, v204
	v_mov_b32_e32 v125, v205
	v_mov_b32_e32 v126, v206
	v_mov_b32_e32 v127, v207
	v_add_u32_e32 v250, 0x18000, v249
	global_load_dwordx4 v[192:195], v250, s[30:31]
	global_load_dwordx4 v[196:199], v250, s[0:1]
	global_load_dwordx4 v[200:203], v250, s[30:31] offset:256
	global_load_dwordx4 v[204:207], v250, s[0:1] offset:256
	v_mul_f32_e32 v112, 0xbfb8aa3b, v116
	v_mul_f32_e32 v113, 0xbfb8aa3b, v117
	v_mul_f32_e32 v116, 0xbfb8aa3b, v172
	v_mul_f32_e32 v117, 0xbfb8aa3b, v173
	v_exp_f32_e32 v116, v116
	v_exp_f32_e32 v117, v117
	v_mul_f32_e32 v118, 0xbfb8aa3b, v118
	v_mul_f32_e32 v119, 0xbfb8aa3b, v119
	v_exp_f32_e32 v118, v118
	v_exp_f32_e32 v119, v119
	v_mul_f32_e32 v114, 0xbfb8aa3b, v114
	v_mul_f32_e32 v115, 0xbfb8aa3b, v115
	v_exp_f32_e32 v112, v112
	v_exp_f32_e32 v113, v113
	v_exp_f32_e32 v114, v114
	v_exp_f32_e32 v115, v115
	v_add_f32_e32 v116, 1.0, v116
	v_add_f32_e32 v117, 1.0, v117
	v_rcp_f32_e32 v116, v116
	v_rcp_f32_e32 v117, v117
	v_add_f32_e32 v118, 1.0, v118
	v_add_f32_e32 v119, 1.0, v119
	v_add_f32_e32 v112, 1.0, v112
	v_add_f32_e32 v113, 1.0, v113
	v_rcp_f32_e32 v118, v118
	v_rcp_f32_e32 v119, v119
	v_add_f32_e32 v114, 1.0, v114
	v_add_f32_e32 v115, 1.0, v115
	v_rcp_f32_e32 v112, v112
	v_rcp_f32_e32 v113, v113
	v_rcp_f32_e32 v114, v114
	v_rcp_f32_e32 v115, v115
	v_lshlrev_b32_e32 v172, 16, v120
	v_and_b32_e32 v173, 0xffff0000, v120
	v_lshlrev_b32_e32 v174, 16, v124
	v_and_b32_e32 v175, 0xffff0000, v124
	v_lshlrev_b32_e32 v120, 16, v121
	v_and_b32_e32 v121, 0xffff0000, v121
	v_lshlrev_b32_e32 v124, 16, v125
	v_and_b32_e32 v125, 0xffff0000, v125
	v_pk_fma_f32 v[116:117], v[116:117], v[120:121], v[124:125]
	v_lshlrev_b32_e32 v120, 16, v122
	v_and_b32_e32 v121, 0xffff0000, v122
	v_lshlrev_b32_e32 v124, 16, v126
	v_and_b32_e32 v125, 0xffff0000, v126
	v_pk_fma_f32 v[118:119], v[118:119], v[120:121], v[124:125]
	v_lshlrev_b32_e32 v120, 16, v123
	v_and_b32_e32 v121, 0xffff0000, v123
	v_lshlrev_b32_e32 v122, 16, v127
	v_and_b32_e32 v123, 0xffff0000, v127
	v_pk_fma_f32 v[112:113], v[112:113], v[172:173], v[174:175]
	v_pk_fma_f32 v[120:121], v[114:115], v[120:121], v[122:123]
	v_cvt_pk_bf16_f32 v112, v112, v113
	v_cvt_pk_bf16_f32 v113, v116, v117
	v_cvt_pk_bf16_f32 v114, v118, v119
	v_cvt_pk_bf16_f32 v115, v120, v121
	global_store_dwordx4 v[168:169], v[112:115], off
	s_nop 1
	v_mov_b32_e32 v112, v240
	s_nop 0
	v_or_b32_e32 v114, 16, v164
	v_ashrrev_i32_e32 v115, 31, v114
	v_lshlrev_b64 v[114:115], 10, v[114:115]
	v_lshl_add_u64 v[114:115], v[114:115], 0, v[162:163]
	v_lshlrev_b64 v[114:115], 1, v[114:115]
	v_lshl_add_u64 v[116:117], s[30:31], 0, v[114:115]
	v_lshl_add_u64 v[124:125], s[0:1], 0, v[114:115]
	s_nop 1
	v_mov_b32_e32 v116, v208
	v_mov_b32_e32 v117, v209
	v_mov_b32_e32 v118, v210
	v_mov_b32_e32 v119, v211
	v_or_b32_e32 v114, 0x100, v114
	s_nop 1
	v_mov_b32_e32 v120, v212
	v_mov_b32_e32 v121, v213
	v_mov_b32_e32 v122, v214
	v_mov_b32_e32 v123, v215
	v_fmamk_f32 v112, v112, 0x3a800000, v187
	v_cmp_gt_f32_e32 vcc, s67, v112
	v_mul_f32_e32 v113, 0x4b800000, v112
	v_lshlrev_b32_e32 v126, 16, v116
	v_cndmask_b32_e32 v112, v112, v113, vcc
	v_rsq_f32_e32 v112, v112
	v_and_b32_e32 v127, 0xffff0000, v116
	v_lshlrev_b32_e32 v168, 16, v120
	v_and_b32_e32 v169, 0xffff0000, v120
	v_mul_f32_e32 v113, 0x45800000, v112
	v_cndmask_b32_e32 v112, v112, v113, vcc
	v_pk_mul_f32 v[110:111], v[110:111], v[112:113] op_sel_hi:[1,0]
	v_pk_mul_f32 v[104:105], v[104:105], v[112:113] op_sel_hi:[1,0]
	v_mul_f32_e32 v110, 0xbfb8aa3b, v110
	v_mul_f32_e32 v111, 0xbfb8aa3b, v111
	v_pk_mul_f32 v[108:109], v[108:109], v[112:113] op_sel_hi:[1,0]
	v_pk_mul_f32 v[106:107], v[106:107], v[112:113] op_sel_hi:[1,0]
	v_exp_f32_e32 v110, v110
	v_exp_f32_e32 v111, v111
	v_mul_f32_e32 v104, 0xbfb8aa3b, v104
	v_mul_f32_e32 v105, 0xbfb8aa3b, v105
	v_mul_f32_e32 v108, 0xbfb8aa3b, v108
	v_mul_f32_e32 v109, 0xbfb8aa3b, v109
	v_exp_f32_e32 v104, v104
	v_exp_f32_e32 v105, v105
	v_mul_f32_e32 v106, 0xbfb8aa3b, v106
	v_mul_f32_e32 v107, 0xbfb8aa3b, v107
; __device__ __forceinline__ unsigned cvt_pk_bf16(float lo, float hi) { const f32x2_cv v = {lo, hi}; const bf16x2_cv b = __builtin_convertvector(v, bf16x2_cv); return __builtin_bit_cast(unsigned, b); }
; __device__ __forceinline__ float sigm(float x) { return __builtin_amdgcn_rcpf(1.0f + __expf(-x)); }
; __device__ __forceinline__ float lo16(unsigned w) { return __uint_as_float(w << 16); }
; __device__ __forceinline__ float hi16(unsigned w) { return __uint_as_float(w & 0xffff0000u); }
; __device__ __forceinline__ float rstd_of(const float* rowss, int row) { return rsqrtf(rowss[row] * (1.0f / 1024.0f) + 1e-6f); }
;     __device__ __forceinline__ void operator()(const f32x4 (&acc)[2][2][4][2], const pg8::Unit& u, int wr, int wc, int fr, int fq) const {
;     ...
;                 const int row = row0 + ai * 128 + m * 16;
;                 const float s = rstd_of(rowss, row);
; #pragma unroll
;                 for (int bj = 0; bj < 2; ++bj) {
;                     const size_t off = (size_t)row * 1024 + col0 + bj * 128;
;                     const u32x4 tv = *(const u32x4*)(Tm + off);
;                     u32x4 pv = (u32x4){0u, 0u, 0u, 0u};
;                     if (ACC) pv = *(const u32x4*)(M + off);
;                     const f32x4 a0 = acc[ai][bj][m][0] * s, a1 = acc[ai][bj][m][1] * s;
;                     float o[8];
;                     o[0] = sigm(a0[0]) * lo16(tv.x); o[1] = sigm(a0[1]) * hi16(tv.x); o[2] = sigm(a0[2]) * lo16(tv.y); o[3] = sigm(a0[3]) * hi16(tv.y);
;                     o[4] = sigm(a1[0]) * lo16(tv.z); o[5] = sigm(a1[1]) * hi16(tv.z); o[6] = sigm(a1[2]) * lo16(tv.w); o[7] = sigm(a1[3]) * hi16(tv.w);
;                     if (ACC) { o[0] += lo16(pv.x); o[1] += hi16(pv.x); o[2] += lo16(pv.y); o[3] += hi16(pv.y); o[4] += lo16(pv.z); o[5] += hi16(pv.z); o[6] += lo16(pv.w); o[7] += hi16(pv.w); }
;                     u32x4 w; w.x = cvt_pk_bf16(o[0], o[1]); w.y = cvt_pk_bf16(o[2], o[3]); w.z = cvt_pk_bf16(o[4], o[5]); w.w = cvt_pk_bf16(o[6], o[7]);
;                     *(u32x4*)(M + off) = w; } }
	v_exp_f32_e32 v108, v108
	v_exp_f32_e32 v109, v109
	v_exp_f32_e32 v106, v106
	v_exp_f32_e32 v107, v107
	v_add_f32_e32 v110, 1.0, v110
	v_add_f32_e32 v111, 1.0, v111
	v_rcp_f32_e32 v110, v110
	v_rcp_f32_e32 v111, v111
	v_add_f32_e32 v104, 1.0, v104
	v_add_f32_e32 v105, 1.0, v105
	v_add_f32_e32 v108, 1.0, v108
	v_add_f32_e32 v109, 1.0, v109
	v_rcp_f32_e32 v104, v104
	v_rcp_f32_e32 v105, v105
	v_add_f32_e32 v106, 1.0, v106
	v_add_f32_e32 v107, 1.0, v107
	v_rcp_f32_e32 v108, v108
	v_rcp_f32_e32 v109, v109
	v_rcp_f32_e32 v106, v106
	v_rcp_f32_e32 v107, v107
	v_lshlrev_b32_e32 v116, 16, v117
	v_and_b32_e32 v117, 0xffff0000, v117
	v_lshlrev_b32_e32 v120, 16, v121
	v_and_b32_e32 v121, 0xffff0000, v121
	v_pk_fma_f32 v[110:111], v[110:111], v[116:117], v[120:121]
	v_lshlrev_b32_e32 v116, 16, v118
	v_and_b32_e32 v117, 0xffff0000, v118
	v_lshlrev_b32_e32 v120, 16, v122
	v_and_b32_e32 v121, 0xffff0000, v122
	v_pk_fma_f32 v[116:117], v[104:105], v[116:117], v[120:121]
	v_lshlrev_b32_e32 v104, 16, v119
	v_and_b32_e32 v105, 0xffff0000, v119
	v_lshlrev_b32_e32 v118, 16, v123
	v_and_b32_e32 v119, 0xffff0000, v123
	v_pk_fma_f32 v[108:109], v[108:109], v[126:127], v[168:169]
	v_pk_fma_f32 v[118:119], v[106:107], v[104:105], v[118:119]
	v_cvt_pk_bf16_f32 v104, v108, v109
	v_cvt_pk_bf16_f32 v105, v110, v111
	v_cvt_pk_bf16_f32 v106, v116, v117
	v_cvt_pk_bf16_f32 v107, v118, v119
	global_store_dwordx4 v[124:125], v[104:107], off
	v_pk_mul_f32 v[102:103], v[102:103], v[112:113] op_sel_hi:[1,0]
	v_pk_mul_f32 v[96:97], v[96:97], v[112:113] op_sel_hi:[1,0]
	v_lshl_add_u64 v[104:105], s[30:31], 0, v[114:115]
	v_lshl_add_u64 v[114:115], s[0:1], 0, v[114:115]
	s_nop 1
	v_mov_b32_e32 v104, v216
	v_mov_b32_e32 v105, v217
	v_mov_b32_e32 v106, v218
	v_mov_b32_e32 v107, v219
	v_mul_f32_e32 v102, 0xbfb8aa3b, v102
	s_nop 1
	v_mov_b32_e32 v108, v220
	v_mov_b32_e32 v109, v221
	v_mov_b32_e32 v110, v222
	v_mov_b32_e32 v111, v223
	v_add_u32_e32 v250, 0x40000, v249
	global_load_dwordx4 v[208:211], v250, s[30:31]
	global_load_dwordx4 v[212:215], v250, s[0:1]
	global_load_dwordx4 v[216:219], v250, s[30:31] offset:256
	global_load_dwordx4 v[220:223], v250, s[0:1] offset:256
	v_mul_f32_e32 v103, 0xbfb8aa3b, v103
	v_pk_mul_f32 v[100:101], v[100:101], v[112:113] op_sel_hi:[1,0]
	v_pk_mul_f32 v[98:99], v[98:99], v[112:113] op_sel_hi:[1,0]
	v_exp_f32_e32 v102, v102
	v_exp_f32_e32 v103, v103
	v_mul_f32_e32 v96, 0xbfb8aa3b, v96
	v_mul_f32_e32 v97, 0xbfb8aa3b, v97
	v_mul_f32_e32 v100, 0xbfb8aa3b, v100
	v_mul_f32_e32 v101, 0xbfb8aa3b, v101
	v_exp_f32_e32 v96, v96
	v_exp_f32_e32 v97, v97
	v_mul_f32_e32 v98, 0xbfb8aa3b, v98
	v_mul_f32_e32 v99, 0xbfb8aa3b, v99
	v_exp_f32_e32 v100, v100
	v_exp_f32_e32 v101, v101
	v_exp_f32_e32 v98, v98
	v_exp_f32_e32 v99, v99
	v_add_f32_e32 v102, 1.0, v102
	v_add_f32_e32 v103, 1.0, v103
	v_rcp_f32_e32 v102, v102
	v_rcp_f32_e32 v103, v103
	v_add_f32_e32 v96, 1.0, v96
	v_add_f32_e32 v97, 1.0, v97
	v_add_f32_e32 v100, 1.0, v100
	v_add_f32_e32 v101, 1.0, v101
	v_rcp_f32_e32 v96, v96
	v_rcp_f32_e32 v97, v97
	v_add_f32_e32 v98, 1.0, v98
	v_add_f32_e32 v99, 1.0, v99
	v_rcp_f32_e32 v100, v100
	v_rcp_f32_e32 v101, v101
	v_rcp_f32_e32 v98, v98
	v_rcp_f32_e32 v99, v99
	v_lshlrev_b32_e32 v112, 16, v104
	v_and_b32_e32 v113, 0xffff0000, v104
	v_lshlrev_b32_e32 v116, 16, v108
	v_and_b32_e32 v117, 0xffff0000, v108
	v_lshlrev_b32_e32 v104, 16, v105
	v_and_b32_e32 v105, 0xffff0000, v105
	v_lshlrev_b32_e32 v108, 16, v109
	v_and_b32_e32 v109, 0xffff0000, v109
	v_pk_fma_f32 v[102:103], v[102:103], v[104:105], v[108:109]
	v_lshlrev_b32_e32 v104, 16, v106
	v_and_b32_e32 v105, 0xffff0000, v106
	v_lshlrev_b32_e32 v108, 16, v110
	v_and_b32_e32 v109, 0xffff0000, v110
	v_pk_fma_f32 v[104:105], v[96:97], v[104:105], v[108:109]
	v_lshlrev_b32_e32 v96, 16, v107
	v_and_b32_e32 v97, 0xffff0000, v107
	v_lshlrev_b32_e32 v106, 16, v111
	v_and_b32_e32 v107, 0xffff0000, v111
	v_pk_fma_f32 v[100:101], v[100:101], v[112:113], v[116:117]
	v_pk_fma_f32 v[106:107], v[98:99], v[96:97], v[106:107]
	v_cvt_pk_bf16_f32 v96, v100, v101
	v_cvt_pk_bf16_f32 v97, v102, v103
	v_cvt_pk_bf16_f32 v98, v104, v105
	v_cvt_pk_bf16_f32 v99, v106, v107
	global_store_dwordx4 v[114:115], v[96:99], off
	s_nop 1
	v_mov_b32_e32 v96, v241
	s_nop 0
	v_or_b32_e32 v98, 32, v164
	v_ashrrev_i32_e32 v99, 31, v98
	v_lshlrev_b64 v[98:99], 10, v[98:99]
	v_lshl_add_u64 v[98:99], v[98:99], 0, v[162:163]
	v_lshlrev_b64 v[98:99], 1, v[98:99]
	v_lshl_add_u64 v[100:101], s[30:31], 0, v[98:99]
	v_lshl_add_u64 v[108:109], s[0:1], 0, v[98:99]
	s_nop 1
	v_mov_b32_e32 v100, v224
	v_mov_b32_e32 v101, v225
	v_mov_b32_e32 v102, v226
	v_mov_b32_e32 v103, v227
	v_or_b32_e32 v98, 0x100, v98
	s_nop 1
	v_mov_b32_e32 v104, v228
	v_mov_b32_e32 v105, v229
	v_mov_b32_e32 v106, v230
	v_mov_b32_e32 v107, v231
	v_fmamk_f32 v96, v96, 0x3a800000, v187
	v_cmp_gt_f32_e32 vcc, s67, v96
	v_mul_f32_e32 v97, 0x4b800000, v96
	v_lshlrev_b32_e32 v110, 16, v100
	v_cndmask_b32_e32 v96, v96, v97, vcc
	v_rsq_f32_e32 v96, v96
	v_and_b32_e32 v111, 0xffff0000, v100
	v_lshlrev_b32_e32 v112, 16, v104
	v_and_b32_e32 v113, 0xffff0000, v104
	v_mul_f32_e32 v97, 0x45800000, v96
	v_cndmask_b32_e32 v96, v96, v97, vcc
	v_pk_mul_f32 v[94:95], v[94:95], v[96:97] op_sel_hi:[1,0]
	v_pk_mul_f32 v[88:89], v[88:89], v[96:97] op_sel_hi:[1,0]
	v_mul_f32_e32 v94, 0xbfb8aa3b, v94
	v_mul_f32_e32 v95, 0xbfb8aa3b, v95
	v_pk_mul_f32 v[92:93], v[92:93], v[96:97] op_sel_hi:[1,0]
	v_pk_mul_f32 v[90:91], v[90:91], v[96:97] op_sel_hi:[1,0]
	v_exp_f32_e32 v94, v94
	v_exp_f32_e32 v95, v95
	v_mul_f32_e32 v88, 0xbfb8aa3b, v88
	v_mul_f32_e32 v89, 0xbfb8aa3b, v89
	v_mul_f32_e32 v92, 0xbfb8aa3b, v92
; __device__ __forceinline__ unsigned cvt_pk_bf16(float lo, float hi) { const f32x2_cv v = {lo, hi}; const bf16x2_cv b = __builtin_convertvector(v, bf16x2_cv); return __builtin_bit_cast(unsigned, b); }
; __device__ __forceinline__ float sigm(float x) { return __builtin_amdgcn_rcpf(1.0f + __expf(-x)); }
; __device__ __forceinline__ float lo16(unsigned w) { return __uint_as_float(w << 16); }
; __device__ __forceinline__ float hi16(unsigned w) { return __uint_as_float(w & 0xffff0000u); }
; __device__ __forceinline__ float rstd_of(const float* rowss, int row) { return rsqrtf(rowss[row] * (1.0f / 1024.0f) + 1e-6f); }
;     __device__ __forceinline__ void operator()(const f32x4 (&acc)[2][2][4][2], const pg8::Unit& u, int wr, int wc, int fr, int fq) const {
;     ...
;                 const int row = row0 + ai * 128 + m * 16;
;                 const float s = rstd_of(rowss, row);
; #pragma unroll
;                 for (int bj = 0; bj < 2; ++bj) {
;                     const size_t off = (size_t)row * 1024 + col0 + bj * 128;
;                     const u32x4 tv = *(const u32x4*)(Tm + off);
;                     u32x4 pv = (u32x4){0u, 0u, 0u, 0u};
;                     if (ACC) pv = *(const u32x4*)(M + off);
;                     const f32x4 a0 = acc[ai][bj][m][0] * s, a1 = acc[ai][bj][m][1] * s;
;                     float o[8];
;                     o[0] = sigm(a0[0]) * lo16(tv.x); o[1] = sigm(a0[1]) * hi16(tv.x); o[2] = sigm(a0[2]) * lo16(tv.y); o[3] = sigm(a0[3]) * hi16(tv.y);
;                     o[4] = sigm(a1[0]) * lo16(tv.z); o[5] = sigm(a1[1]) * hi16(tv.z); o[6] = sigm(a1[2]) * lo16(tv.w); o[7] = sigm(a1[3]) * hi16(tv.w);
;                     if (ACC) { o[0] += lo16(pv.x); o[1] += hi16(pv.x); o[2] += lo16(pv.y); o[3] += hi16(pv.y); o[4] += lo16(pv.z); o[5] += hi16(pv.z); o[6] += lo16(pv.w); o[7] += hi16(pv.w); }
;                     u32x4 w; w.x = cvt_pk_bf16(o[0], o[1]); w.y = cvt_pk_bf16(o[2], o[3]); w.z = cvt_pk_bf16(o[4], o[5]); w.w = cvt_pk_bf16(o[6], o[7]);
;                     *(u32x4*)(M + off) = w; } }
	v_mul_f32_e32 v93, 0xbfb8aa3b, v93
	v_exp_f32_e32 v88, v88
	v_exp_f32_e32 v89, v89
	v_mul_f32_e32 v90, 0xbfb8aa3b, v90
	v_mul_f32_e32 v91, 0xbfb8aa3b, v91
	v_exp_f32_e32 v92, v92
	v_exp_f32_e32 v93, v93
	v_exp_f32_e32 v90, v90
	v_exp_f32_e32 v91, v91
	v_add_f32_e32 v94, 1.0, v94
	v_add_f32_e32 v95, 1.0, v95
	v_rcp_f32_e32 v94, v94
	v_rcp_f32_e32 v95, v95
	v_add_f32_e32 v88, 1.0, v88
	v_add_f32_e32 v89, 1.0, v89
	v_add_f32_e32 v92, 1.0, v92
	v_add_f32_e32 v93, 1.0, v93
	v_rcp_f32_e32 v88, v88
	v_rcp_f32_e32 v89, v89
	v_add_f32_e32 v90, 1.0, v90
	v_add_f32_e32 v91, 1.0, v91
	v_rcp_f32_e32 v92, v92
	v_rcp_f32_e32 v93, v93
	v_rcp_f32_e32 v90, v90
	v_rcp_f32_e32 v91, v91
	v_lshlrev_b32_e32 v100, 16, v101
	v_and_b32_e32 v101, 0xffff0000, v101
	v_lshlrev_b32_e32 v104, 16, v105
	v_and_b32_e32 v105, 0xffff0000, v105
	v_pk_fma_f32 v[94:95], v[94:95], v[100:101], v[104:105]
	v_lshlrev_b32_e32 v100, 16, v102
	v_and_b32_e32 v101, 0xffff0000, v102
	v_lshlrev_b32_e32 v104, 16, v106
	v_and_b32_e32 v105, 0xffff0000, v106
	v_pk_fma_f32 v[100:101], v[88:89], v[100:101], v[104:105]
	v_lshlrev_b32_e32 v88, 16, v103
	v_and_b32_e32 v89, 0xffff0000, v103
	v_lshlrev_b32_e32 v102, 16, v107
	v_and_b32_e32 v103, 0xffff0000, v107
	v_pk_fma_f32 v[92:93], v[92:93], v[110:111], v[112:113]
	v_pk_fma_f32 v[102:103], v[90:91], v[88:89], v[102:103]
	v_cvt_pk_bf16_f32 v88, v92, v93
	v_cvt_pk_bf16_f32 v89, v94, v95
	v_cvt_pk_bf16_f32 v90, v100, v101
	v_cvt_pk_bf16_f32 v91, v102, v103
	global_store_dwordx4 v[108:109], v[88:91], off
	v_pk_mul_f32 v[86:87], v[86:87], v[96:97] op_sel_hi:[1,0]
	v_pk_mul_f32 v[80:81], v[80:81], v[96:97] op_sel_hi:[1,0]
	v_lshl_add_u64 v[88:89], s[30:31], 0, v[98:99]
	v_lshl_add_u64 v[98:99], s[0:1], 0, v[98:99]
	s_nop 1
	v_mov_b32_e32 v92, v232
	v_mov_b32_e32 v93, v233
	v_mov_b32_e32 v94, v234
	v_mov_b32_e32 v95, v235
	v_mul_f32_e32 v86, 0xbfb8aa3b, v86
	s_nop 1
	v_mov_b32_e32 v88, v236
	v_mov_b32_e32 v89, v237
	v_mov_b32_e32 v90, v238
	v_mov_b32_e32 v91, v239
	v_add_u32_e32 v250, 0x48000, v249
	global_load_dwordx4 v[224:227], v250, s[30:31]
	global_load_dwordx4 v[228:231], v250, s[0:1]
	global_load_dwordx4 v[232:235], v250, s[30:31] offset:256
	global_load_dwordx4 v[236:239], v250, s[0:1] offset:256
	v_mul_f32_e32 v87, 0xbfb8aa3b, v87
	v_pk_mul_f32 v[84:85], v[84:85], v[96:97] op_sel_hi:[1,0]
	v_pk_mul_f32 v[82:83], v[82:83], v[96:97] op_sel_hi:[1,0]
	v_exp_f32_e32 v86, v86
	v_exp_f32_e32 v87, v87
	v_mul_f32_e32 v80, 0xbfb8aa3b, v80
	v_mul_f32_e32 v81, 0xbfb8aa3b, v81
	v_mul_f32_e32 v84, 0xbfb8aa3b, v84
	v_mul_f32_e32 v85, 0xbfb8aa3b, v85
	v_exp_f32_e32 v80, v80
	v_exp_f32_e32 v81, v81
	v_mul_f32_e32 v82, 0xbfb8aa3b, v82
	v_mul_f32_e32 v83, 0xbfb8aa3b, v83
	v_exp_f32_e32 v84, v84
	v_exp_f32_e32 v85, v85
	v_exp_f32_e32 v82, v82
	v_exp_f32_e32 v83, v83
	v_add_f32_e32 v86, 1.0, v86
	v_add_f32_e32 v87, 1.0, v87
	v_rcp_f32_e32 v86, v86
	v_rcp_f32_e32 v87, v87
	v_add_f32_e32 v80, 1.0, v80
	v_add_f32_e32 v81, 1.0, v81
	v_add_f32_e32 v84, 1.0, v84
	v_add_f32_e32 v85, 1.0, v85
	v_rcp_f32_e32 v80, v80
	v_rcp_f32_e32 v81, v81
	v_add_f32_e32 v82, 1.0, v82
	v_add_f32_e32 v83, 1.0, v83
	v_rcp_f32_e32 v84, v84
	v_rcp_f32_e32 v85, v85
	v_rcp_f32_e32 v82, v82
	v_rcp_f32_e32 v83, v83
	v_lshlrev_b32_e32 v96, 16, v92
	v_and_b32_e32 v97, 0xffff0000, v92
	v_lshlrev_b32_e32 v100, 16, v88
	v_and_b32_e32 v101, 0xffff0000, v88
	v_lshlrev_b32_e32 v92, 16, v93
	v_and_b32_e32 v93, 0xffff0000, v93
	v_lshlrev_b32_e32 v88, 16, v89
	v_and_b32_e32 v89, 0xffff0000, v89
	v_pk_fma_f32 v[86:87], v[86:87], v[92:93], v[88:89]
	v_lshlrev_b32_e32 v88, 16, v94
	v_and_b32_e32 v89, 0xffff0000, v94
	v_lshlrev_b32_e32 v92, 16, v90
	v_and_b32_e32 v93, 0xffff0000, v90
	v_pk_fma_f32 v[88:89], v[80:81], v[88:89], v[92:93]
	v_lshlrev_b32_e32 v80, 16, v95
	v_and_b32_e32 v81, 0xffff0000, v95
	v_lshlrev_b32_e32 v90, 16, v91
	v_and_b32_e32 v91, 0xffff0000, v91
	v_pk_fma_f32 v[84:85], v[84:85], v[96:97], v[100:101]
	v_pk_fma_f32 v[90:91], v[82:83], v[80:81], v[90:91]
	v_cvt_pk_bf16_f32 v80, v84, v85
	v_cvt_pk_bf16_f32 v81, v86, v87
	v_cvt_pk_bf16_f32 v82, v88, v89
	v_cvt_pk_bf16_f32 v83, v90, v91
	global_store_dwordx4 v[98:99], v[80:83], off
	s_nop 1
	v_mov_b32_e32 v80, v244
	s_nop 0
	v_or_b32_e32 v82, 48, v164
	v_ashrrev_i32_e32 v83, 31, v82
	v_lshlrev_b64 v[82:83], 10, v[82:83]
	v_lshl_add_u64 v[82:83], v[82:83], 0, v[162:163]
	v_lshlrev_b64 v[82:83], 1, v[82:83]
	v_lshl_add_u64 v[84:85], s[30:31], 0, v[82:83]
	v_lshl_add_u64 v[92:93], s[0:1], 0, v[82:83]
	s_waitcnt vmcnt(13)
; __device__ __forceinline__ unsigned cvt_pk_bf16(float lo, float hi) { const f32x2_cv v = {lo, hi}; const bf16x2_cv b = __builtin_convertvector(v, bf16x2_cv); return __builtin_bit_cast(unsigned, b); }
; __device__ __forceinline__ float sigm(float x) { return __builtin_amdgcn_rcpf(1.0f + __expf(-x)); }
; __device__ __forceinline__ float lo16(unsigned w) { return __uint_as_float(w << 16); }
; __device__ __forceinline__ float hi16(unsigned w) { return __uint_as_float(w & 0xffff0000u); }
; __device__ __forceinline__ float rstd_of(const float* rowss, int row) { return rsqrtf(rowss[row] * (1.0f / 1024.0f) + 1e-6f); }
;     __device__ __forceinline__ void operator()(const f32x4 (&acc)[2][2][4][2], const pg8::Unit& u, int wr, int wc, int fr, int fq) const {
;     ...
;                 const int row = row0 + ai * 128 + m * 16;
;                 const float s = rstd_of(rowss, row);
; #pragma unroll
;                 for (int bj = 0; bj < 2; ++bj) {
;                     const size_t off = (size_t)row * 1024 + col0 + bj * 128;
;                     const u32x4 tv = *(const u32x4*)(Tm + off);
;                     u32x4 pv = (u32x4){0u, 0u, 0u, 0u};
;                     if (ACC) pv = *(const u32x4*)(M + off);
;                     const f32x4 a0 = acc[ai][bj][m][0] * s, a1 = acc[ai][bj][m][1] * s;
;                     float o[8];
;                     o[0] = sigm(a0[0]) * lo16(tv.x); o[1] = sigm(a0[1]) * hi16(tv.x); o[2] = sigm(a0[2]) * lo16(tv.y); o[3] = sigm(a0[3]) * hi16(tv.y);
;                     o[4] = sigm(a1[0]) * lo16(tv.z); o[5] = sigm(a1[1]) * hi16(tv.z); o[6] = sigm(a1[2]) * lo16(tv.w); o[7] = sigm(a1[3]) * hi16(tv.w);
;                     if (ACC) { o[0] += lo16(pv.x); o[1] += hi16(pv.x); o[2] += lo16(pv.y); o[3] += hi16(pv.y); o[4] += lo16(pv.z); o[5] += hi16(pv.z); o[6] += lo16(pv.w); o[7] += hi16(pv.w); }
;                     u32x4 w; w.x = cvt_pk_bf16(o[0], o[1]); w.y = cvt_pk_bf16(o[2], o[3]); w.z = cvt_pk_bf16(o[4], o[5]); w.w = cvt_pk_bf16(o[6], o[7]);
;                     *(u32x4*)(M + off) = w; } }
	s_nop 1
	v_mov_b32_e32 v84, v192
	v_mov_b32_e32 v85, v193
	v_mov_b32_e32 v86, v194
	v_mov_b32_e32 v87, v195
	v_or_b32_e32 v82, 0x100, v82
	s_nop 1
	v_mov_b32_e32 v88, v196
	v_mov_b32_e32 v89, v197
	v_mov_b32_e32 v90, v198
	v_mov_b32_e32 v91, v199
	v_fmamk_f32 v80, v80, 0x3a800000, v187
	v_cmp_gt_f32_e32 vcc, s67, v80
	v_mul_f32_e32 v81, 0x4b800000, v80
	v_lshlrev_b32_e32 v94, 16, v84
	v_cndmask_b32_e32 v80, v80, v81, vcc
	v_rsq_f32_e32 v80, v80
	v_and_b32_e32 v95, 0xffff0000, v84
	v_lshlrev_b32_e32 v96, 16, v88
	v_and_b32_e32 v97, 0xffff0000, v88
	v_mul_f32_e32 v81, 0x45800000, v80
	v_cndmask_b32_e32 v80, v80, v81, vcc
	v_pk_mul_f32 v[78:79], v[78:79], v[80:81] op_sel_hi:[1,0]
	v_pk_mul_f32 v[72:73], v[72:73], v[80:81] op_sel_hi:[1,0]
	v_mul_f32_e32 v78, 0xbfb8aa3b, v78
	v_mul_f32_e32 v79, 0xbfb8aa3b, v79
	v_pk_mul_f32 v[76:77], v[76:77], v[80:81] op_sel_hi:[1,0]
	v_pk_mul_f32 v[74:75], v[74:75], v[80:81] op_sel_hi:[1,0]
	v_exp_f32_e32 v78, v78
	v_exp_f32_e32 v79, v79
	v_mul_f32_e32 v72, 0xbfb8aa3b, v72
	v_mul_f32_e32 v73, 0xbfb8aa3b, v73
	v_mul_f32_e32 v76, 0xbfb8aa3b, v76
	v_mul_f32_e32 v77, 0xbfb8aa3b, v77
	v_exp_f32_e32 v72, v72
	v_exp_f32_e32 v73, v73
	v_mul_f32_e32 v74, 0xbfb8aa3b, v74
	v_mul_f32_e32 v75, 0xbfb8aa3b, v75
	v_exp_f32_e32 v76, v76
	v_exp_f32_e32 v77, v77
	v_exp_f32_e32 v74, v74
	v_exp_f32_e32 v75, v75
	v_add_f32_e32 v78, 1.0, v78
	v_add_f32_e32 v79, 1.0, v79
	v_rcp_f32_e32 v78, v78
	v_rcp_f32_e32 v79, v79
	v_add_f32_e32 v72, 1.0, v72
	v_add_f32_e32 v73, 1.0, v73
	v_add_f32_e32 v76, 1.0, v76
	v_add_f32_e32 v77, 1.0, v77
	v_rcp_f32_e32 v72, v72
	v_rcp_f32_e32 v73, v73
	v_add_f32_e32 v74, 1.0, v74
	v_add_f32_e32 v75, 1.0, v75
	v_rcp_f32_e32 v76, v76
	v_rcp_f32_e32 v77, v77
	v_rcp_f32_e32 v74, v74
	v_rcp_f32_e32 v75, v75
	v_lshlrev_b32_e32 v84, 16, v85
	v_and_b32_e32 v85, 0xffff0000, v85
	v_lshlrev_b32_e32 v88, 16, v89
	v_and_b32_e32 v89, 0xffff0000, v89
	v_pk_fma_f32 v[78:79], v[78:79], v[84:85], v[88:89]
	v_lshlrev_b32_e32 v84, 16, v86
	v_and_b32_e32 v85, 0xffff0000, v86
	v_lshlrev_b32_e32 v88, 16, v90
	v_and_b32_e32 v89, 0xffff0000, v90
	v_pk_fma_f32 v[84:85], v[72:73], v[84:85], v[88:89]
	v_lshlrev_b32_e32 v72, 16, v87
	v_and_b32_e32 v73, 0xffff0000, v87
	v_lshlrev_b32_e32 v86, 16, v91
	v_and_b32_e32 v87, 0xffff0000, v91
	v_pk_fma_f32 v[76:77], v[76:77], v[94:95], v[96:97]
	v_pk_fma_f32 v[86:87], v[74:75], v[72:73], v[86:87]
	v_cvt_pk_bf16_f32 v72, v76, v77
	v_cvt_pk_bf16_f32 v73, v78, v79
	v_cvt_pk_bf16_f32 v74, v84, v85
	v_cvt_pk_bf16_f32 v75, v86, v87
	global_store_dwordx4 v[92:93], v[72:75], off
	v_pk_mul_f32 v[70:71], v[70:71], v[80:81] op_sel_hi:[1,0]
	v_pk_mul_f32 v[64:65], v[64:65], v[80:81] op_sel_hi:[1,0]
	v_lshl_add_u64 v[72:73], s[30:31], 0, v[82:83]
	v_lshl_add_u64 v[82:83], s[0:1], 0, v[82:83]
	s_nop 1
	v_mov_b32_e32 v76, v200
	v_mov_b32_e32 v77, v201
	v_mov_b32_e32 v78, v202
	v_mov_b32_e32 v79, v203
	v_mul_f32_e32 v70, 0xbfb8aa3b, v70
	s_nop 1
	v_mov_b32_e32 v72, v204
	v_mov_b32_e32 v73, v205
	v_mov_b32_e32 v74, v206
	v_mov_b32_e32 v75, v207
	v_add_u32_e32 v250, 0x50000, v249
	global_load_dwordx4 v[192:195], v250, s[30:31]
	global_load_dwordx4 v[196:199], v250, s[0:1]
	global_load_dwordx4 v[200:203], v250, s[30:31] offset:256
	global_load_dwordx4 v[204:207], v250, s[0:1] offset:256
	v_mul_f32_e32 v71, 0xbfb8aa3b, v71
	v_pk_mul_f32 v[68:69], v[68:69], v[80:81] op_sel_hi:[1,0]
	v_pk_mul_f32 v[66:67], v[66:67], v[80:81] op_sel_hi:[1,0]
	v_exp_f32_e32 v70, v70
	v_exp_f32_e32 v71, v71
	v_mul_f32_e32 v64, 0xbfb8aa3b, v64
	v_mul_f32_e32 v65, 0xbfb8aa3b, v65
	v_mul_f32_e32 v68, 0xbfb8aa3b, v68
	v_mul_f32_e32 v69, 0xbfb8aa3b, v69
	v_exp_f32_e32 v64, v64
	v_exp_f32_e32 v65, v65
	v_mul_f32_e32 v66, 0xbfb8aa3b, v66
	v_mul_f32_e32 v67, 0xbfb8aa3b, v67
	v_exp_f32_e32 v68, v68
	v_exp_f32_e32 v69, v69
	v_exp_f32_e32 v66, v66
	v_exp_f32_e32 v67, v67
	v_add_f32_e32 v70, 1.0, v70
	v_add_f32_e32 v71, 1.0, v71
	v_rcp_f32_e32 v70, v70
	v_rcp_f32_e32 v71, v71
	v_add_f32_e32 v64, 1.0, v64
	v_add_f32_e32 v65, 1.0, v65
	v_add_f32_e32 v68, 1.0, v68
	v_add_f32_e32 v69, 1.0, v69
	v_rcp_f32_e32 v64, v64
	v_rcp_f32_e32 v65, v65
	v_add_f32_e32 v66, 1.0, v66
	v_add_f32_e32 v67, 1.0, v67
	v_rcp_f32_e32 v68, v68
	v_rcp_f32_e32 v69, v69
	v_rcp_f32_e32 v66, v66
	v_rcp_f32_e32 v67, v67
	v_lshlrev_b32_e32 v80, 16, v76
	v_and_b32_e32 v81, 0xffff0000, v76
	v_lshlrev_b32_e32 v84, 16, v72
	v_and_b32_e32 v85, 0xffff0000, v72
	v_lshlrev_b32_e32 v76, 16, v77
	v_and_b32_e32 v77, 0xffff0000, v77
	v_lshlrev_b32_e32 v72, 16, v73
	v_and_b32_e32 v73, 0xffff0000, v73
	v_pk_fma_f32 v[70:71], v[70:71], v[76:77], v[72:73]
	v_lshlrev_b32_e32 v72, 16, v78
	v_and_b32_e32 v73, 0xffff0000, v78
	v_lshlrev_b32_e32 v76, 16, v74
	v_and_b32_e32 v77, 0xffff0000, v74
	v_pk_fma_f32 v[72:73], v[64:65], v[72:73], v[76:77]
	v_lshlrev_b32_e32 v64, 16, v79
	v_and_b32_e32 v65, 0xffff0000, v79
	v_lshlrev_b32_e32 v74, 16, v75
	v_and_b32_e32 v75, 0xffff0000, v75
	v_pk_fma_f32 v[68:69], v[68:69], v[80:81], v[84:85]
	v_pk_fma_f32 v[74:75], v[66:67], v[64:65], v[74:75]
	v_cvt_pk_bf16_f32 v64, v68, v69
	v_cvt_pk_bf16_f32 v65, v70, v71
	v_cvt_pk_bf16_f32 v66, v72, v73
	v_cvt_pk_bf16_f32 v67, v74, v75
	global_store_dwordx4 v[82:83], v[64:67], off
	s_nop 1
	v_mov_b32_e32 v64, v245
	v_lshl_add_u64 v[70:71], v[158:159], 0, s[2:3]
	v_lshl_add_u64 v[66:67], s[30:31], 0, v[70:71]
	v_lshl_add_u64 v[74:75], s[0:1], 0, v[70:71]
	s_waitcnt vmcnt(13)
; __device__ __forceinline__ unsigned cvt_pk_bf16(float lo, float hi) { const f32x2_cv v = {lo, hi}; const bf16x2_cv b = __builtin_convertvector(v, bf16x2_cv); return __builtin_bit_cast(unsigned, b); }
; __device__ __forceinline__ float sigm(float x) { return __builtin_amdgcn_rcpf(1.0f + __expf(-x)); }
; __device__ __forceinline__ float lo16(unsigned w) { return __uint_as_float(w << 16); }
; __device__ __forceinline__ float hi16(unsigned w) { return __uint_as_float(w & 0xffff0000u); }
; __device__ __forceinline__ float rstd_of(const float* rowss, int row) { return rsqrtf(rowss[row] * (1.0f / 1024.0f) + 1e-6f); }
;     __device__ __forceinline__ void operator()(const f32x4 (&acc)[2][2][4][2], const pg8::Unit& u, int wr, int wc, int fr, int fq) const {
;     ...
;                 const int row = row0 + ai * 128 + m * 16;
;                 const float s = rstd_of(rowss, row);
; #pragma unroll
;                 for (int bj = 0; bj < 2; ++bj) {
;                     const size_t off = (size_t)row * 1024 + col0 + bj * 128;
;                     const u32x4 tv = *(const u32x4*)(Tm + off);
;                     u32x4 pv = (u32x4){0u, 0u, 0u, 0u};
;                     if (ACC) pv = *(const u32x4*)(M + off);
;                     const f32x4 a0 = acc[ai][bj][m][0] * s, a1 = acc[ai][bj][m][1] * s;
;                     float o[8];
;                     o[0] = sigm(a0[0]) * lo16(tv.x); o[1] = sigm(a0[1]) * hi16(tv.x); o[2] = sigm(a0[2]) * lo16(tv.y); o[3] = sigm(a0[3]) * hi16(tv.y);
;                     o[4] = sigm(a1[0]) * lo16(tv.z); o[5] = sigm(a1[1]) * hi16(tv.z); o[6] = sigm(a1[2]) * lo16(tv.w); o[7] = sigm(a1[3]) * hi16(tv.w);
;                     if (ACC) { o[0] += lo16(pv.x); o[1] += hi16(pv.x); o[2] += lo16(pv.y); o[3] += hi16(pv.y); o[4] += lo16(pv.z); o[5] += hi16(pv.z); o[6] += lo16(pv.w); o[7] += hi16(pv.w); }
;                     u32x4 w; w.x = cvt_pk_bf16(o[0], o[1]); w.y = cvt_pk_bf16(o[2], o[3]); w.z = cvt_pk_bf16(o[4], o[5]); w.w = cvt_pk_bf16(o[6], o[7]);
;                     *(u32x4*)(M + off) = w; } }
	s_nop 1
	v_mov_b32_e32 v66, v208
	v_mov_b32_e32 v67, v209
	v_mov_b32_e32 v68, v210
	v_mov_b32_e32 v69, v211
	s_mov_b64 s[2:3], 0x40100
	s_nop 1
	v_mov_b32_e32 v70, v212
	v_mov_b32_e32 v71, v213
	v_mov_b32_e32 v72, v214
	v_mov_b32_e32 v73, v215
	v_fmamk_f32 v64, v64, 0x3a800000, v187
	v_cmp_gt_f32_e32 vcc, s67, v64
	v_mul_f32_e32 v65, 0x4b800000, v64
	v_lshlrev_b32_e32 v76, 16, v66
	v_cndmask_b32_e32 v64, v64, v65, vcc
	v_rsq_f32_e32 v64, v64
	v_and_b32_e32 v77, 0xffff0000, v66
	v_lshlrev_b32_e32 v78, 16, v70
	v_and_b32_e32 v79, 0xffff0000, v70
	v_mul_f32_e32 v65, 0x45800000, v64
	v_cndmask_b32_e32 v64, v64, v65, vcc
	v_pk_mul_f32 v[62:63], v[62:63], v[64:65] op_sel_hi:[1,0]
	v_pk_mul_f32 v[56:57], v[56:57], v[64:65] op_sel_hi:[1,0]
	v_mul_f32_e32 v62, 0xbfb8aa3b, v62
	v_mul_f32_e32 v63, 0xbfb8aa3b, v63
	v_pk_mul_f32 v[60:61], v[60:61], v[64:65] op_sel_hi:[1,0]
	v_pk_mul_f32 v[58:59], v[58:59], v[64:65] op_sel_hi:[1,0]
	v_exp_f32_e32 v62, v62
	v_exp_f32_e32 v63, v63
	v_mul_f32_e32 v56, 0xbfb8aa3b, v56
	v_mul_f32_e32 v57, 0xbfb8aa3b, v57
	v_mul_f32_e32 v60, 0xbfb8aa3b, v60
	v_mul_f32_e32 v61, 0xbfb8aa3b, v61
	v_exp_f32_e32 v56, v56
	v_exp_f32_e32 v57, v57
	v_mul_f32_e32 v58, 0xbfb8aa3b, v58
	v_mul_f32_e32 v59, 0xbfb8aa3b, v59
	v_exp_f32_e32 v60, v60
	v_exp_f32_e32 v61, v61
	v_exp_f32_e32 v58, v58
	v_exp_f32_e32 v59, v59
	v_add_f32_e32 v62, 1.0, v62
	v_add_f32_e32 v63, 1.0, v63
	v_rcp_f32_e32 v62, v62
	v_rcp_f32_e32 v63, v63
	v_add_f32_e32 v56, 1.0, v56
	v_add_f32_e32 v57, 1.0, v57
	v_add_f32_e32 v60, 1.0, v60
	v_add_f32_e32 v61, 1.0, v61
	v_rcp_f32_e32 v56, v56
	v_rcp_f32_e32 v57, v57
	v_add_f32_e32 v58, 1.0, v58
	v_add_f32_e32 v59, 1.0, v59
	v_rcp_f32_e32 v60, v60
	v_rcp_f32_e32 v61, v61
	v_rcp_f32_e32 v58, v58
	v_rcp_f32_e32 v59, v59
	v_lshlrev_b32_e32 v66, 16, v67
	v_and_b32_e32 v67, 0xffff0000, v67
	v_lshlrev_b32_e32 v70, 16, v71
	v_and_b32_e32 v71, 0xffff0000, v71
	v_pk_fma_f32 v[62:63], v[62:63], v[66:67], v[70:71]
	v_lshlrev_b32_e32 v66, 16, v68
	v_and_b32_e32 v67, 0xffff0000, v68
	v_lshlrev_b32_e32 v70, 16, v72
	v_and_b32_e32 v71, 0xffff0000, v72
	v_pk_fma_f32 v[66:67], v[56:57], v[66:67], v[70:71]
	v_lshlrev_b32_e32 v56, 16, v69
	v_and_b32_e32 v57, 0xffff0000, v69
	v_lshlrev_b32_e32 v68, 16, v73
	v_and_b32_e32 v69, 0xffff0000, v73
	v_pk_fma_f32 v[60:61], v[60:61], v[76:77], v[78:79]
	v_pk_fma_f32 v[68:69], v[58:59], v[56:57], v[68:69]
	v_cvt_pk_bf16_f32 v56, v60, v61
	v_cvt_pk_bf16_f32 v57, v62, v63
	v_cvt_pk_bf16_f32 v58, v66, v67
	v_cvt_pk_bf16_f32 v59, v68, v69
	global_store_dwordx4 v[74:75], v[56:59], off
	v_pk_mul_f32 v[54:55], v[54:55], v[64:65] op_sel_hi:[1,0]
	v_pk_mul_f32 v[48:49], v[48:49], v[64:65] op_sel_hi:[1,0]
	v_lshl_add_u64 v[56:57], v[158:159], 0, s[2:3]
	v_lshl_add_u64 v[58:59], s[30:31], 0, v[56:57]
	v_lshl_add_u64 v[66:67], s[0:1], 0, v[56:57]
	s_nop 1
	v_mov_b32_e32 v60, v216
	v_mov_b32_e32 v61, v217
	v_mov_b32_e32 v62, v218
	v_mov_b32_e32 v63, v219
	v_mul_f32_e32 v54, 0xbfb8aa3b, v54
	s_nop 1
	v_mov_b32_e32 v56, v220
	v_mov_b32_e32 v57, v221
	v_mov_b32_e32 v58, v222
	v_mov_b32_e32 v59, v223
	v_add_u32_e32 v250, 0x58000, v249
	global_load_dwordx4 v[208:211], v250, s[30:31]
	global_load_dwordx4 v[212:215], v250, s[0:1]
	global_load_dwordx4 v[216:219], v250, s[30:31] offset:256
	global_load_dwordx4 v[220:223], v250, s[0:1] offset:256
	v_mul_f32_e32 v55, 0xbfb8aa3b, v55
	v_pk_mul_f32 v[52:53], v[52:53], v[64:65] op_sel_hi:[1,0]
	v_pk_mul_f32 v[50:51], v[50:51], v[64:65] op_sel_hi:[1,0]
	v_exp_f32_e32 v54, v54
	v_exp_f32_e32 v55, v55
	v_mul_f32_e32 v48, 0xbfb8aa3b, v48
	v_mul_f32_e32 v49, 0xbfb8aa3b, v49
	v_mul_f32_e32 v52, 0xbfb8aa3b, v52
	v_mul_f32_e32 v53, 0xbfb8aa3b, v53
	v_exp_f32_e32 v48, v48
	v_exp_f32_e32 v49, v49
	v_mul_f32_e32 v50, 0xbfb8aa3b, v50
	v_mul_f32_e32 v51, 0xbfb8aa3b, v51
	v_exp_f32_e32 v52, v52
	v_exp_f32_e32 v53, v53
	v_exp_f32_e32 v50, v50
	v_exp_f32_e32 v51, v51
	v_add_f32_e32 v54, 1.0, v54
	v_add_f32_e32 v55, 1.0, v55
	v_rcp_f32_e32 v54, v54
	v_rcp_f32_e32 v55, v55
	v_add_f32_e32 v48, 1.0, v48
	v_add_f32_e32 v49, 1.0, v49
	v_add_f32_e32 v52, 1.0, v52
	v_add_f32_e32 v53, 1.0, v53
	v_rcp_f32_e32 v48, v48
	v_rcp_f32_e32 v49, v49
	v_add_f32_e32 v50, 1.0, v50
	v_add_f32_e32 v51, 1.0, v51
	v_rcp_f32_e32 v52, v52
	v_rcp_f32_e32 v53, v53
	v_rcp_f32_e32 v50, v50
	v_rcp_f32_e32 v51, v51
	s_mov_b64 s[2:3], 0x48000
	v_lshlrev_b32_e32 v64, 16, v60
	v_and_b32_e32 v65, 0xffff0000, v60
	v_lshlrev_b32_e32 v68, 16, v56
	v_and_b32_e32 v69, 0xffff0000, v56
	v_lshlrev_b32_e32 v60, 16, v61
	v_and_b32_e32 v61, 0xffff0000, v61
	v_lshlrev_b32_e32 v56, 16, v57
	v_and_b32_e32 v57, 0xffff0000, v57
	v_pk_fma_f32 v[54:55], v[54:55], v[60:61], v[56:57]
	v_lshlrev_b32_e32 v56, 16, v62
	v_and_b32_e32 v57, 0xffff0000, v62
	v_lshlrev_b32_e32 v60, 16, v58
	v_and_b32_e32 v61, 0xffff0000, v58
	v_pk_fma_f32 v[56:57], v[48:49], v[56:57], v[60:61]
	v_lshlrev_b32_e32 v48, 16, v63
	v_and_b32_e32 v49, 0xffff0000, v63
	v_lshlrev_b32_e32 v58, 16, v59
	v_and_b32_e32 v59, 0xffff0000, v59
	v_pk_fma_f32 v[52:53], v[52:53], v[64:65], v[68:69]
	v_pk_fma_f32 v[58:59], v[50:51], v[48:49], v[58:59]
	v_cvt_pk_bf16_f32 v48, v52, v53
	v_cvt_pk_bf16_f32 v49, v54, v55
	v_cvt_pk_bf16_f32 v50, v56, v57
	v_cvt_pk_bf16_f32 v51, v58, v59
	global_store_dwordx4 v[66:67], v[48:51], off
	s_nop 1
	v_mov_b32_e32 v48, v246
	v_lshl_add_u64 v[54:55], v[158:159], 0, s[2:3]
	v_lshl_add_u64 v[50:51], s[30:31], 0, v[54:55]
	v_lshl_add_u64 v[58:59], s[0:1], 0, v[54:55]
	s_waitcnt vmcnt(13)
; __device__ __forceinline__ unsigned cvt_pk_bf16(float lo, float hi) { const f32x2_cv v = {lo, hi}; const bf16x2_cv b = __builtin_convertvector(v, bf16x2_cv); return __builtin_bit_cast(unsigned, b); }
; __device__ __forceinline__ float sigm(float x) { return __builtin_amdgcn_rcpf(1.0f + __expf(-x)); }
; __device__ __forceinline__ float lo16(unsigned w) { return __uint_as_float(w << 16); }
; __device__ __forceinline__ float hi16(unsigned w) { return __uint_as_float(w & 0xffff0000u); }
; __device__ __forceinline__ float rstd_of(const float* rowss, int row) { return rsqrtf(rowss[row] * (1.0f / 1024.0f) + 1e-6f); }
;     __device__ __forceinline__ void operator()(const f32x4 (&acc)[2][2][4][2], const pg8::Unit& u, int wr, int wc, int fr, int fq) const {
;     ...
;                 const int row = row0 + ai * 128 + m * 16;
;                 const float s = rstd_of(rowss, row);
; #pragma unroll
;                 for (int bj = 0; bj < 2; ++bj) {
;                     const size_t off = (size_t)row * 1024 + col0 + bj * 128;
;                     const u32x4 tv = *(const u32x4*)(Tm + off);
;                     u32x4 pv = (u32x4){0u, 0u, 0u, 0u};
;                     if (ACC) pv = *(const u32x4*)(M + off);
;                     const f32x4 a0 = acc[ai][bj][m][0] * s, a1 = acc[ai][bj][m][1] * s;
;                     float o[8];
;                     o[0] = sigm(a0[0]) * lo16(tv.x); o[1] = sigm(a0[1]) * hi16(tv.x); o[2] = sigm(a0[2]) * lo16(tv.y); o[3] = sigm(a0[3]) * hi16(tv.y);
;                     o[4] = sigm(a1[0]) * lo16(tv.z); o[5] = sigm(a1[1]) * hi16(tv.z); o[6] = sigm(a1[2]) * lo16(tv.w); o[7] = sigm(a1[3]) * hi16(tv.w);
;                     if (ACC) { o[0] += lo16(pv.x); o[1] += hi16(pv.x); o[2] += lo16(pv.y); o[3] += hi16(pv.y); o[4] += lo16(pv.z); o[5] += hi16(pv.z); o[6] += lo16(pv.w); o[7] += hi16(pv.w); }
;                     u32x4 w; w.x = cvt_pk_bf16(o[0], o[1]); w.y = cvt_pk_bf16(o[2], o[3]); w.z = cvt_pk_bf16(o[4], o[5]); w.w = cvt_pk_bf16(o[6], o[7]);
;                     *(u32x4*)(M + off) = w; } }
	s_nop 1
	v_mov_b32_e32 v50, v224
	v_mov_b32_e32 v51, v225
	v_mov_b32_e32 v52, v226
	v_mov_b32_e32 v53, v227
	s_mov_b64 s[2:3], 0x48100
	s_nop 1
	v_mov_b32_e32 v54, v228
	v_mov_b32_e32 v55, v229
	v_mov_b32_e32 v56, v230
	v_mov_b32_e32 v57, v231
	v_fmamk_f32 v48, v48, 0x3a800000, v187
	v_cmp_gt_f32_e32 vcc, s67, v48
	v_mul_f32_e32 v49, 0x4b800000, v48
	v_lshlrev_b32_e32 v60, 16, v50
	v_cndmask_b32_e32 v48, v48, v49, vcc
	v_rsq_f32_e32 v48, v48
	v_and_b32_e32 v61, 0xffff0000, v50
	v_lshlrev_b32_e32 v62, 16, v54
	v_and_b32_e32 v63, 0xffff0000, v54
	v_mul_f32_e32 v49, 0x45800000, v48
	v_cndmask_b32_e32 v48, v48, v49, vcc
	v_pk_mul_f32 v[46:47], v[46:47], v[48:49] op_sel_hi:[1,0]
	v_pk_mul_f32 v[40:41], v[40:41], v[48:49] op_sel_hi:[1,0]
	v_mul_f32_e32 v46, 0xbfb8aa3b, v46
	v_mul_f32_e32 v47, 0xbfb8aa3b, v47
	v_pk_mul_f32 v[44:45], v[44:45], v[48:49] op_sel_hi:[1,0]
	v_pk_mul_f32 v[42:43], v[42:43], v[48:49] op_sel_hi:[1,0]
	v_exp_f32_e32 v46, v46
	v_exp_f32_e32 v47, v47
	v_mul_f32_e32 v40, 0xbfb8aa3b, v40
	v_mul_f32_e32 v41, 0xbfb8aa3b, v41
	v_mul_f32_e32 v44, 0xbfb8aa3b, v44
	v_mul_f32_e32 v45, 0xbfb8aa3b, v45
	v_exp_f32_e32 v40, v40
	v_exp_f32_e32 v41, v41
	v_mul_f32_e32 v42, 0xbfb8aa3b, v42
	v_mul_f32_e32 v43, 0xbfb8aa3b, v43
	v_exp_f32_e32 v44, v44
	v_exp_f32_e32 v45, v45
	v_exp_f32_e32 v42, v42
	v_exp_f32_e32 v43, v43
	v_add_f32_e32 v46, 1.0, v46
	v_add_f32_e32 v47, 1.0, v47
	v_rcp_f32_e32 v46, v46
	v_rcp_f32_e32 v47, v47
	v_add_f32_e32 v40, 1.0, v40
	v_add_f32_e32 v41, 1.0, v41
	v_add_f32_e32 v44, 1.0, v44
	v_add_f32_e32 v45, 1.0, v45
	v_rcp_f32_e32 v40, v40
	v_rcp_f32_e32 v41, v41
	v_add_f32_e32 v42, 1.0, v42
	v_add_f32_e32 v43, 1.0, v43
	v_rcp_f32_e32 v44, v44
	v_rcp_f32_e32 v45, v45
	v_rcp_f32_e32 v42, v42
	v_rcp_f32_e32 v43, v43
	v_lshlrev_b32_e32 v50, 16, v51
	v_and_b32_e32 v51, 0xffff0000, v51
	v_lshlrev_b32_e32 v54, 16, v55
	v_and_b32_e32 v55, 0xffff0000, v55
	v_pk_fma_f32 v[46:47], v[46:47], v[50:51], v[54:55]
	v_lshlrev_b32_e32 v50, 16, v52
	v_and_b32_e32 v51, 0xffff0000, v52
	v_lshlrev_b32_e32 v54, 16, v56
	v_and_b32_e32 v55, 0xffff0000, v56
	v_pk_fma_f32 v[50:51], v[40:41], v[50:51], v[54:55]
	v_lshlrev_b32_e32 v40, 16, v53
	v_and_b32_e32 v41, 0xffff0000, v53
	v_lshlrev_b32_e32 v52, 16, v57
	v_and_b32_e32 v53, 0xffff0000, v57
	v_pk_fma_f32 v[44:45], v[44:45], v[60:61], v[62:63]
	v_pk_fma_f32 v[52:53], v[42:43], v[40:41], v[52:53]
	v_cvt_pk_bf16_f32 v40, v44, v45
	v_cvt_pk_bf16_f32 v41, v46, v47
	v_cvt_pk_bf16_f32 v42, v50, v51
	v_cvt_pk_bf16_f32 v43, v52, v53
	global_store_dwordx4 v[58:59], v[40:43], off
	v_pk_mul_f32 v[38:39], v[38:39], v[48:49] op_sel_hi:[1,0]
	v_pk_mul_f32 v[32:33], v[32:33], v[48:49] op_sel_hi:[1,0]
	v_lshl_add_u64 v[40:41], v[158:159], 0, s[2:3]
	v_lshl_add_u64 v[42:43], s[30:31], 0, v[40:41]
	v_lshl_add_u64 v[50:51], s[0:1], 0, v[40:41]
	s_nop 1
	v_mov_b32_e32 v44, v232
	v_mov_b32_e32 v45, v233
	v_mov_b32_e32 v46, v234
	v_mov_b32_e32 v47, v235
	v_mul_f32_e32 v38, 0xbfb8aa3b, v38
	s_nop 1
	v_mov_b32_e32 v40, v236
	v_mov_b32_e32 v41, v237
	v_mov_b32_e32 v42, v238
	v_mov_b32_e32 v43, v239
	v_mul_f32_e32 v39, 0xbfb8aa3b, v39
	v_pk_mul_f32 v[36:37], v[36:37], v[48:49] op_sel_hi:[1,0]
	v_pk_mul_f32 v[34:35], v[34:35], v[48:49] op_sel_hi:[1,0]
	v_exp_f32_e32 v38, v38
	v_exp_f32_e32 v39, v39
	v_mul_f32_e32 v32, 0xbfb8aa3b, v32
	v_mul_f32_e32 v33, 0xbfb8aa3b, v33
	v_mul_f32_e32 v36, 0xbfb8aa3b, v36
	v_mul_f32_e32 v37, 0xbfb8aa3b, v37
	v_exp_f32_e32 v32, v32
	v_exp_f32_e32 v33, v33
	v_mul_f32_e32 v34, 0xbfb8aa3b, v34
	v_mul_f32_e32 v35, 0xbfb8aa3b, v35
	v_exp_f32_e32 v36, v36
	v_exp_f32_e32 v37, v37
	v_exp_f32_e32 v34, v34
	v_exp_f32_e32 v35, v35
	v_add_f32_e32 v38, 1.0, v38
	v_add_f32_e32 v39, 1.0, v39
	v_rcp_f32_e32 v38, v38
	v_rcp_f32_e32 v39, v39
	v_add_f32_e32 v32, 1.0, v32
	v_add_f32_e32 v33, 1.0, v33
	v_add_f32_e32 v36, 1.0, v36
	v_add_f32_e32 v37, 1.0, v37
	v_rcp_f32_e32 v32, v32
	v_rcp_f32_e32 v33, v33
	v_add_f32_e32 v34, 1.0, v34
	v_add_f32_e32 v35, 1.0, v35
	v_rcp_f32_e32 v36, v36
	v_rcp_f32_e32 v37, v37
	v_rcp_f32_e32 v34, v34
	v_rcp_f32_e32 v35, v35
	s_mov_b64 s[2:3], 0x50000
	v_lshlrev_b32_e32 v48, 16, v44
	v_and_b32_e32 v49, 0xffff0000, v44
	v_lshlrev_b32_e32 v52, 16, v40
	v_and_b32_e32 v53, 0xffff0000, v40
	v_lshlrev_b32_e32 v44, 16, v45
	v_and_b32_e32 v45, 0xffff0000, v45
	v_lshlrev_b32_e32 v40, 16, v41
	v_and_b32_e32 v41, 0xffff0000, v41
	v_pk_fma_f32 v[38:39], v[38:39], v[44:45], v[40:41]
	v_lshlrev_b32_e32 v40, 16, v46
	v_and_b32_e32 v41, 0xffff0000, v46
	v_lshlrev_b32_e32 v44, 16, v42
	v_and_b32_e32 v45, 0xffff0000, v42
	v_pk_fma_f32 v[40:41], v[32:33], v[40:41], v[44:45]
	v_lshlrev_b32_e32 v32, 16, v47
	v_and_b32_e32 v33, 0xffff0000, v47
	v_lshlrev_b32_e32 v42, 16, v43
	v_and_b32_e32 v43, 0xffff0000, v43
	v_pk_fma_f32 v[36:37], v[36:37], v[48:49], v[52:53]
	v_pk_fma_f32 v[42:43], v[34:35], v[32:33], v[42:43]
	v_cvt_pk_bf16_f32 v32, v36, v37
	v_cvt_pk_bf16_f32 v33, v38, v39
	v_cvt_pk_bf16_f32 v34, v40, v41
	v_cvt_pk_bf16_f32 v35, v42, v43
	global_store_dwordx4 v[50:51], v[32:35], off
	s_nop 1
	v_mov_b32_e32 v32, v247
	v_lshl_add_u64 v[38:39], v[158:159], 0, s[2:3]
	v_lshl_add_u64 v[34:35], s[30:31], 0, v[38:39]
	v_lshl_add_u64 v[42:43], s[0:1], 0, v[38:39]
	s_waitcnt vmcnt(9)
; __device__ __forceinline__ unsigned cvt_pk_bf16(float lo, float hi) { const f32x2_cv v = {lo, hi}; const bf16x2_cv b = __builtin_convertvector(v, bf16x2_cv); return __builtin_bit_cast(unsigned, b); }
; __device__ __forceinline__ float sigm(float x) { return __builtin_amdgcn_rcpf(1.0f + __expf(-x)); }
; __device__ __forceinline__ float lo16(unsigned w) { return __uint_as_float(w << 16); }
; __device__ __forceinline__ float hi16(unsigned w) { return __uint_as_float(w & 0xffff0000u); }
; __device__ __forceinline__ float rstd_of(const float* rowss, int row) { return rsqrtf(rowss[row] * (1.0f / 1024.0f) + 1e-6f); }
;     __device__ __forceinline__ void operator()(const f32x4 (&acc)[2][2][4][2], const pg8::Unit& u, int wr, int wc, int fr, int fq) const {
;     ...
;                 const int row = row0 + ai * 128 + m * 16;
;                 const float s = rstd_of(rowss, row);
; #pragma unroll
;                 for (int bj = 0; bj < 2; ++bj) {
;                     const size_t off = (size_t)row * 1024 + col0 + bj * 128;
;                     const u32x4 tv = *(const u32x4*)(Tm + off);
;                     u32x4 pv = (u32x4){0u, 0u, 0u, 0u};
;                     if (ACC) pv = *(const u32x4*)(M + off);
;                     const f32x4 a0 = acc[ai][bj][m][0] * s, a1 = acc[ai][bj][m][1] * s;
;                     float o[8];
;                     o[0] = sigm(a0[0]) * lo16(tv.x); o[1] = sigm(a0[1]) * hi16(tv.x); o[2] = sigm(a0[2]) * lo16(tv.y); o[3] = sigm(a0[3]) * hi16(tv.y);
;                     o[4] = sigm(a1[0]) * lo16(tv.z); o[5] = sigm(a1[1]) * hi16(tv.z); o[6] = sigm(a1[2]) * lo16(tv.w); o[7] = sigm(a1[3]) * hi16(tv.w);
;                     if (ACC) { o[0] += lo16(pv.x); o[1] += hi16(pv.x); o[2] += lo16(pv.y); o[3] += hi16(pv.y); o[4] += lo16(pv.z); o[5] += hi16(pv.z); o[6] += lo16(pv.w); o[7] += hi16(pv.w); }
;                     u32x4 w; w.x = cvt_pk_bf16(o[0], o[1]); w.y = cvt_pk_bf16(o[2], o[3]); w.z = cvt_pk_bf16(o[4], o[5]); w.w = cvt_pk_bf16(o[6], o[7]);
;                     *(u32x4*)(M + off) = w; } }
	s_nop 1
	v_mov_b32_e32 v34, v192
	v_mov_b32_e32 v35, v193
	v_mov_b32_e32 v36, v194
	v_mov_b32_e32 v37, v195
	s_mov_b64 s[2:3], 0x50100
	s_nop 1
	v_mov_b32_e32 v38, v196
	v_mov_b32_e32 v39, v197
	v_mov_b32_e32 v40, v198
	v_mov_b32_e32 v41, v199
	v_fmamk_f32 v32, v32, 0x3a800000, v187
	v_cmp_gt_f32_e32 vcc, s67, v32
	v_mul_f32_e32 v33, 0x4b800000, v32
	v_lshlrev_b32_e32 v44, 16, v34
	v_cndmask_b32_e32 v32, v32, v33, vcc
	v_rsq_f32_e32 v32, v32
	v_and_b32_e32 v45, 0xffff0000, v34
	v_lshlrev_b32_e32 v46, 16, v38
	v_and_b32_e32 v47, 0xffff0000, v38
	v_mul_f32_e32 v33, 0x45800000, v32
	v_cndmask_b32_e32 v32, v32, v33, vcc
	v_pk_mul_f32 v[30:31], v[30:31], v[32:33] op_sel_hi:[1,0]
	v_pk_mul_f32 v[24:25], v[24:25], v[32:33] op_sel_hi:[1,0]
	v_mul_f32_e32 v30, 0xbfb8aa3b, v30
	v_mul_f32_e32 v31, 0xbfb8aa3b, v31
	v_pk_mul_f32 v[28:29], v[28:29], v[32:33] op_sel_hi:[1,0]
	v_pk_mul_f32 v[26:27], v[26:27], v[32:33] op_sel_hi:[1,0]
	v_exp_f32_e32 v30, v30
	v_exp_f32_e32 v31, v31
	v_mul_f32_e32 v24, 0xbfb8aa3b, v24
	v_mul_f32_e32 v25, 0xbfb8aa3b, v25
	v_mul_f32_e32 v28, 0xbfb8aa3b, v28
	v_mul_f32_e32 v29, 0xbfb8aa3b, v29
	v_exp_f32_e32 v24, v24
	v_exp_f32_e32 v25, v25
	v_mul_f32_e32 v26, 0xbfb8aa3b, v26
	v_mul_f32_e32 v27, 0xbfb8aa3b, v27
	v_exp_f32_e32 v28, v28
	v_exp_f32_e32 v29, v29
	v_exp_f32_e32 v26, v26
	v_exp_f32_e32 v27, v27
	v_add_f32_e32 v30, 1.0, v30
	v_add_f32_e32 v31, 1.0, v31
	v_rcp_f32_e32 v30, v30
	v_rcp_f32_e32 v31, v31
	v_add_f32_e32 v24, 1.0, v24
	v_add_f32_e32 v25, 1.0, v25
	v_add_f32_e32 v28, 1.0, v28
	v_add_f32_e32 v29, 1.0, v29
	v_rcp_f32_e32 v24, v24
	v_rcp_f32_e32 v25, v25
	v_add_f32_e32 v26, 1.0, v26
	v_add_f32_e32 v27, 1.0, v27
	v_rcp_f32_e32 v28, v28
	v_rcp_f32_e32 v29, v29
	v_rcp_f32_e32 v26, v26
	v_rcp_f32_e32 v27, v27
	v_lshlrev_b32_e32 v34, 16, v35
	v_and_b32_e32 v35, 0xffff0000, v35
	v_lshlrev_b32_e32 v38, 16, v39
	v_and_b32_e32 v39, 0xffff0000, v39
	v_pk_fma_f32 v[30:31], v[30:31], v[34:35], v[38:39]
	v_lshlrev_b32_e32 v34, 16, v36
	v_and_b32_e32 v35, 0xffff0000, v36
	v_lshlrev_b32_e32 v38, 16, v40
	v_and_b32_e32 v39, 0xffff0000, v40
	v_pk_fma_f32 v[34:35], v[24:25], v[34:35], v[38:39]
	v_lshlrev_b32_e32 v24, 16, v37
	v_and_b32_e32 v25, 0xffff0000, v37
	v_lshlrev_b32_e32 v36, 16, v41
	v_and_b32_e32 v37, 0xffff0000, v41
	v_pk_fma_f32 v[28:29], v[28:29], v[44:45], v[46:47]
	v_pk_fma_f32 v[36:37], v[26:27], v[24:25], v[36:37]
	v_cvt_pk_bf16_f32 v24, v28, v29
	v_cvt_pk_bf16_f32 v25, v30, v31
	v_cvt_pk_bf16_f32 v26, v34, v35
	v_cvt_pk_bf16_f32 v27, v36, v37
	global_store_dwordx4 v[42:43], v[24:27], off
	v_pk_mul_f32 v[22:23], v[22:23], v[32:33] op_sel_hi:[1,0]
	v_pk_mul_f32 v[16:17], v[16:17], v[32:33] op_sel_hi:[1,0]
	v_lshl_add_u64 v[24:25], v[158:159], 0, s[2:3]
	v_lshl_add_u64 v[26:27], s[30:31], 0, v[24:25]
	v_lshl_add_u64 v[34:35], s[0:1], 0, v[24:25]
	s_nop 1
	v_mov_b32_e32 v28, v200
	v_mov_b32_e32 v29, v201
	v_mov_b32_e32 v30, v202
	v_mov_b32_e32 v31, v203
	v_mul_f32_e32 v22, 0xbfb8aa3b, v22
	s_nop 1
	v_mov_b32_e32 v24, v204
	v_mov_b32_e32 v25, v205
	v_mov_b32_e32 v26, v206
	v_mov_b32_e32 v27, v207
	v_mul_f32_e32 v23, 0xbfb8aa3b, v23
	v_pk_mul_f32 v[20:21], v[20:21], v[32:33] op_sel_hi:[1,0]
	v_pk_mul_f32 v[18:19], v[18:19], v[32:33] op_sel_hi:[1,0]
	v_exp_f32_e32 v22, v22
	v_exp_f32_e32 v23, v23
	v_mul_f32_e32 v16, 0xbfb8aa3b, v16
	v_mul_f32_e32 v17, 0xbfb8aa3b, v17
	v_mul_f32_e32 v20, 0xbfb8aa3b, v20
	v_mul_f32_e32 v21, 0xbfb8aa3b, v21
	v_exp_f32_e32 v16, v16
	v_exp_f32_e32 v17, v17
	v_mul_f32_e32 v18, 0xbfb8aa3b, v18
	v_mul_f32_e32 v19, 0xbfb8aa3b, v19
	v_exp_f32_e32 v20, v20
	v_exp_f32_e32 v21, v21
	v_exp_f32_e32 v18, v18
	v_exp_f32_e32 v19, v19
	v_add_f32_e32 v22, 1.0, v22
	v_add_f32_e32 v23, 1.0, v23
	v_rcp_f32_e32 v22, v22
	v_rcp_f32_e32 v23, v23
	v_add_f32_e32 v16, 1.0, v16
	v_add_f32_e32 v17, 1.0, v17
	v_add_f32_e32 v20, 1.0, v20
	v_add_f32_e32 v21, 1.0, v21
	v_rcp_f32_e32 v16, v16
	v_rcp_f32_e32 v17, v17
	v_add_f32_e32 v18, 1.0, v18
	v_add_f32_e32 v19, 1.0, v19
	v_rcp_f32_e32 v20, v20
	v_rcp_f32_e32 v21, v21
	v_rcp_f32_e32 v18, v18
	v_rcp_f32_e32 v19, v19
	s_mov_b64 s[2:3], 0x58000
	v_lshlrev_b32_e32 v32, 16, v28
	v_and_b32_e32 v33, 0xffff0000, v28
	v_lshlrev_b32_e32 v36, 16, v24
	v_and_b32_e32 v37, 0xffff0000, v24
	v_lshlrev_b32_e32 v28, 16, v29
	v_and_b32_e32 v29, 0xffff0000, v29
	v_lshlrev_b32_e32 v24, 16, v25
	v_and_b32_e32 v25, 0xffff0000, v25
	v_pk_fma_f32 v[22:23], v[22:23], v[28:29], v[24:25]
	v_lshlrev_b32_e32 v24, 16, v30
	v_and_b32_e32 v25, 0xffff0000, v30
	v_lshlrev_b32_e32 v28, 16, v26
	v_and_b32_e32 v29, 0xffff0000, v26
	v_pk_fma_f32 v[24:25], v[16:17], v[24:25], v[28:29]
	v_lshlrev_b32_e32 v16, 16, v31
	v_and_b32_e32 v17, 0xffff0000, v31
	v_lshlrev_b32_e32 v26, 16, v27
	v_and_b32_e32 v27, 0xffff0000, v27
	v_pk_fma_f32 v[20:21], v[20:21], v[32:33], v[36:37]
	v_pk_fma_f32 v[26:27], v[18:19], v[16:17], v[26:27]
	v_cvt_pk_bf16_f32 v16, v20, v21
	v_cvt_pk_bf16_f32 v17, v22, v23
	v_cvt_pk_bf16_f32 v18, v24, v25
	v_cvt_pk_bf16_f32 v19, v26, v27
	global_store_dwordx4 v[34:35], v[16:19], off
	s_nop 1
	v_mov_b32_e32 v16, v248
	v_lshl_add_u64 v[22:23], v[158:159], 0, s[2:3]
	v_lshl_add_u64 v[18:19], s[30:31], 0, v[22:23]
	v_lshl_add_u64 v[26:27], s[0:1], 0, v[22:23]
	s_waitcnt vmcnt(5)
; __device__ __forceinline__ unsigned cvt_pk_bf16(float lo, float hi) { const f32x2_cv v = {lo, hi}; const bf16x2_cv b = __builtin_convertvector(v, bf16x2_cv); return __builtin_bit_cast(unsigned, b); }
; __device__ __forceinline__ float sigm(float x) { return __builtin_amdgcn_rcpf(1.0f + __expf(-x)); }
; __device__ __forceinline__ float lo16(unsigned w) { return __uint_as_float(w << 16); }
; __device__ __forceinline__ float hi16(unsigned w) { return __uint_as_float(w & 0xffff0000u); }
; __device__ __forceinline__ float rstd_of(const float* rowss, int row) { return rsqrtf(rowss[row] * (1.0f / 1024.0f) + 1e-6f); }
;     __device__ __forceinline__ void operator()(const f32x4 (&acc)[2][2][4][2], const pg8::Unit& u, int wr, int wc, int fr, int fq) const {
;     ...
;                 const int row = row0 + ai * 128 + m * 16;
;                 const float s = rstd_of(rowss, row);
; #pragma unroll
;                 for (int bj = 0; bj < 2; ++bj) {
;                     const size_t off = (size_t)row * 1024 + col0 + bj * 128;
;                     const u32x4 tv = *(const u32x4*)(Tm + off);
;                     u32x4 pv = (u32x4){0u, 0u, 0u, 0u};
;                     if (ACC) pv = *(const u32x4*)(M + off);
;                     const f32x4 a0 = acc[ai][bj][m][0] * s, a1 = acc[ai][bj][m][1] * s;
;                     float o[8];
;                     o[0] = sigm(a0[0]) * lo16(tv.x); o[1] = sigm(a0[1]) * hi16(tv.x); o[2] = sigm(a0[2]) * lo16(tv.y); o[3] = sigm(a0[3]) * hi16(tv.y);
;                     o[4] = sigm(a1[0]) * lo16(tv.z); o[5] = sigm(a1[1]) * hi16(tv.z); o[6] = sigm(a1[2]) * lo16(tv.w); o[7] = sigm(a1[3]) * hi16(tv.w);
;                     if (ACC) { o[0] += lo16(pv.x); o[1] += hi16(pv.x); o[2] += lo16(pv.y); o[3] += hi16(pv.y); o[4] += lo16(pv.z); o[5] += hi16(pv.z); o[6] += lo16(pv.w); o[7] += hi16(pv.w); }
;                     u32x4 w; w.x = cvt_pk_bf16(o[0], o[1]); w.y = cvt_pk_bf16(o[2], o[3]); w.z = cvt_pk_bf16(o[4], o[5]); w.w = cvt_pk_bf16(o[6], o[7]);
;                     *(u32x4*)(M + off) = w; } }
	s_nop 1
	v_mov_b32_e32 v18, v208
	v_mov_b32_e32 v19, v209
	v_mov_b32_e32 v20, v210
	v_mov_b32_e32 v21, v211
	s_mov_b64 s[2:3], 0x58100
	s_nop 1
	v_mov_b32_e32 v22, v212
	v_mov_b32_e32 v23, v213
	v_mov_b32_e32 v24, v214
	v_mov_b32_e32 v25, v215
	v_fmamk_f32 v16, v16, 0x3a800000, v187
	v_cmp_gt_f32_e32 vcc, s67, v16
	v_mul_f32_e32 v17, 0x4b800000, v16
	v_lshlrev_b32_e32 v28, 16, v18
	v_cndmask_b32_e32 v16, v16, v17, vcc
	v_rsq_f32_e32 v16, v16
	v_and_b32_e32 v29, 0xffff0000, v18
	v_lshlrev_b32_e32 v30, 16, v22
	v_and_b32_e32 v31, 0xffff0000, v22
	v_mul_f32_e32 v17, 0x45800000, v16
	v_cndmask_b32_e32 v16, v16, v17, vcc
	v_pk_mul_f32 v[14:15], v[14:15], v[16:17] op_sel_hi:[1,0]
	v_pk_mul_f32 v[8:9], v[8:9], v[16:17] op_sel_hi:[1,0]
	v_mul_f32_e32 v14, 0xbfb8aa3b, v14
	v_mul_f32_e32 v15, 0xbfb8aa3b, v15
	v_pk_mul_f32 v[12:13], v[12:13], v[16:17] op_sel_hi:[1,0]
	v_pk_mul_f32 v[10:11], v[10:11], v[16:17] op_sel_hi:[1,0]
	v_exp_f32_e32 v14, v14
	v_exp_f32_e32 v15, v15
	v_mul_f32_e32 v8, 0xbfb8aa3b, v8
	v_mul_f32_e32 v9, 0xbfb8aa3b, v9
	v_mul_f32_e32 v12, 0xbfb8aa3b, v12
	v_mul_f32_e32 v13, 0xbfb8aa3b, v13
	v_exp_f32_e32 v8, v8
	v_exp_f32_e32 v9, v9
	v_mul_f32_e32 v10, 0xbfb8aa3b, v10
	v_mul_f32_e32 v11, 0xbfb8aa3b, v11
	v_exp_f32_e32 v12, v12
	v_exp_f32_e32 v13, v13
	v_exp_f32_e32 v10, v10
	v_exp_f32_e32 v11, v11
	v_add_f32_e32 v14, 1.0, v14
	v_add_f32_e32 v15, 1.0, v15
	v_rcp_f32_e32 v14, v14
	v_rcp_f32_e32 v15, v15
	v_add_f32_e32 v8, 1.0, v8
	v_add_f32_e32 v9, 1.0, v9
	v_add_f32_e32 v12, 1.0, v12
	v_add_f32_e32 v13, 1.0, v13
	v_rcp_f32_e32 v8, v8
	v_rcp_f32_e32 v9, v9
	v_add_f32_e32 v10, 1.0, v10
	v_add_f32_e32 v11, 1.0, v11
	v_rcp_f32_e32 v12, v12
	v_rcp_f32_e32 v13, v13
	v_rcp_f32_e32 v10, v10
	v_rcp_f32_e32 v11, v11
	v_lshlrev_b32_e32 v18, 16, v19
	v_and_b32_e32 v19, 0xffff0000, v19
	v_lshlrev_b32_e32 v22, 16, v23
	v_and_b32_e32 v23, 0xffff0000, v23
	v_pk_fma_f32 v[14:15], v[14:15], v[18:19], v[22:23]
	v_lshlrev_b32_e32 v18, 16, v20
	v_and_b32_e32 v19, 0xffff0000, v20
	v_lshlrev_b32_e32 v22, 16, v24
	v_and_b32_e32 v23, 0xffff0000, v24
	v_pk_fma_f32 v[18:19], v[8:9], v[18:19], v[22:23]
	v_lshlrev_b32_e32 v8, 16, v21
	v_and_b32_e32 v9, 0xffff0000, v21
	v_lshlrev_b32_e32 v20, 16, v25
	v_and_b32_e32 v21, 0xffff0000, v25
	v_pk_fma_f32 v[12:13], v[12:13], v[28:29], v[30:31]
	v_pk_fma_f32 v[20:21], v[10:11], v[8:9], v[20:21]
	v_cvt_pk_bf16_f32 v8, v12, v13
	v_cvt_pk_bf16_f32 v9, v14, v15
	v_cvt_pk_bf16_f32 v10, v18, v19
	v_cvt_pk_bf16_f32 v11, v20, v21
	global_store_dwordx4 v[26:27], v[8:11], off
	v_pk_mul_f32 v[6:7], v[6:7], v[16:17] op_sel_hi:[1,0]
	v_pk_mul_f32 v[0:1], v[0:1], v[16:17] op_sel_hi:[1,0]
	v_lshl_add_u64 v[8:9], v[158:159], 0, s[2:3]
	v_lshl_add_u64 v[10:11], s[30:31], 0, v[8:9]
	v_lshl_add_u64 v[18:19], s[0:1], 0, v[8:9]
	s_nop 1
	v_mov_b32_e32 v12, v216
	v_mov_b32_e32 v13, v217
	v_mov_b32_e32 v14, v218
	v_mov_b32_e32 v15, v219
	v_mul_f32_e32 v6, 0xbfb8aa3b, v6
	s_nop 1
	v_mov_b32_e32 v8, v220
	v_mov_b32_e32 v9, v221
	v_mov_b32_e32 v10, v222
	v_mov_b32_e32 v11, v223
	v_mul_f32_e32 v7, 0xbfb8aa3b, v7
	v_pk_mul_f32 v[4:5], v[4:5], v[16:17] op_sel_hi:[1,0]
	v_pk_mul_f32 v[2:3], v[2:3], v[16:17] op_sel_hi:[1,0]
	v_exp_f32_e32 v6, v6
	v_exp_f32_e32 v7, v7
	v_mul_f32_e32 v0, 0xbfb8aa3b, v0
	v_mul_f32_e32 v1, 0xbfb8aa3b, v1
	v_mul_f32_e32 v4, 0xbfb8aa3b, v4
	v_mul_f32_e32 v5, 0xbfb8aa3b, v5
	v_exp_f32_e32 v0, v0
	v_exp_f32_e32 v1, v1
	v_mul_f32_e32 v2, 0xbfb8aa3b, v2
	v_mul_f32_e32 v3, 0xbfb8aa3b, v3
	v_exp_f32_e32 v4, v4
	v_exp_f32_e32 v5, v5
	v_exp_f32_e32 v2, v2
	v_exp_f32_e32 v3, v3
	v_add_f32_e32 v6, 1.0, v6
	v_add_f32_e32 v7, 1.0, v7
	v_rcp_f32_e32 v6, v6
	v_rcp_f32_e32 v7, v7
	v_add_f32_e32 v0, 1.0, v0
	v_add_f32_e32 v1, 1.0, v1
	v_add_f32_e32 v4, 1.0, v4
	v_add_f32_e32 v5, 1.0, v5
	v_rcp_f32_e32 v0, v0
	v_rcp_f32_e32 v1, v1
	v_add_f32_e32 v2, 1.0, v2
	v_add_f32_e32 v3, 1.0, v3
	v_rcp_f32_e32 v4, v4
	v_rcp_f32_e32 v5, v5
	v_rcp_f32_e32 v2, v2
	v_rcp_f32_e32 v3, v3
	s_and_b64 vcc, exec, s[38:39]
	s_mov_b32 s3, s26
	s_mov_b32 s2, s12
	v_lshlrev_b32_e32 v16, 16, v12
	v_and_b32_e32 v17, 0xffff0000, v12
	v_lshlrev_b32_e32 v20, 16, v8
	v_and_b32_e32 v21, 0xffff0000, v8
	v_lshlrev_b32_e32 v12, 16, v13
	v_and_b32_e32 v13, 0xffff0000, v13
	v_lshlrev_b32_e32 v8, 16, v9
	v_and_b32_e32 v9, 0xffff0000, v9
	v_pk_fma_f32 v[6:7], v[6:7], v[12:13], v[8:9]
	v_lshlrev_b32_e32 v8, 16, v14
	v_and_b32_e32 v9, 0xffff0000, v14
	v_lshlrev_b32_e32 v12, 16, v10
	v_and_b32_e32 v13, 0xffff0000, v10
	v_pk_fma_f32 v[8:9], v[0:1], v[8:9], v[12:13]
	v_lshlrev_b32_e32 v0, 16, v15
	v_and_b32_e32 v1, 0xffff0000, v15
	v_lshlrev_b32_e32 v10, 16, v11
	v_and_b32_e32 v11, 0xffff0000, v11
	v_pk_fma_f32 v[4:5], v[4:5], v[16:17], v[20:21]
	v_pk_fma_f32 v[10:11], v[2:3], v[0:1], v[10:11]
	v_cvt_pk_bf16_f32 v0, v4, v5
	v_cvt_pk_bf16_f32 v1, v6, v7
	v_cvt_pk_bf16_f32 v2, v8, v9
	v_cvt_pk_bf16_f32 v3, v10, v11
	global_store_dwordx4 v[18:19], v[0:3], off
	s_cbranch_vccz .LBB0_346
	s_cmpk_gt_u32 s70, 0xff
	s_cbranch_scc1 .LBB0_357
	s_barrier

; #define PG8_STAGE(bufoff, gbase, voff) do { _Pragma("unroll") for (int _i = 0; _i < 2; ++_i) \
;         __builtin_amdgcn_global_load_lds((const unsigned*)((const char*)(gbase) + (voff)[_i]), (PG8_LAS unsigned*)(lds + (bufoff) + ldsw + _i * 8192), 16, 0, 0); } while (0)
; #define PG8_LDA(dst, b, h) do { _Pragma("unroll") for (int m = 0; m < 4; ++m) _Pragma("unroll") for (int k = 0; k < 2; ++k) dst[m][k] = *(const PG8_LAS bf16x8*)(lds + PG8_SA(b, h) + aoff + m * 2048 + k * 1024); } while (0)
; #define PG8_LDB(dst, b, h) do { _Pragma("unroll") for (int n = 0; n < 2; ++n) _Pragma("unroll") for (int k = 0; k < 2; ++k) dst[n][k] = *(const PG8_LAS bf16x8*)(lds + PG8_SB(b, h) + boff + n * 2048 + k * 1024); } while (0)
; #define PG8_MMA(ai, bj, At, Bt) do { __builtin_amdgcn_s_setprio(1); _Pragma("unroll") for (int m = 0; m < 4; ++m) _Pragma("unroll") for (int n = 0; n < 2; ++n) _Pragma("unroll") for (int k = 0; k < 2; ++k) \
;         acc[ai][bj][m][n] = __builtin_amdgcn_mfma_f32_16x16x32_bf16(Bt[n][k], At[m][k], acc[ai][bj][m][n], 0, 0, 0); __builtin_amdgcn_s_setprio(0); } while (0)
; #define PG8_WAIT_V(n) asm volatile("s_waitcnt vmcnt(" #n ")" ::: "memory")
; #define PG8_WAIT_L(n) asm volatile("s_waitcnt lgkmcnt(" #n ")" ::: "memory")
; template <class Epi, class Sched, bool STAMP = false>
; __device__ __forceinline__ void gemm_phase(PG8_LAS unsigned char* lds, const Gemm g, const Sched& S, const Epi& E, unsigned long long* stamps) {
;     ...
;             const char* a1 = cA + (size_t)(t + 1) * kstep;
;             const char* a2 = last ? nA : cA + (size_t)(t + 2) * kstep; const char* b2 = last ? nB : cB + (size_t)(t + 2) * kstep;
;             const char* a3 = a2 + kstep; const char* b3 = b2 + kstep;
;             if (last && has_next) S.a_ready(nxt);
;             PG8_LDB(B0, 0, 0); PG8_SCHED; PG8_LDA(At, 0, 0); PG8_STAGE(PG8_SA(1, 1), a1 + hstep, voffA);
;             PG8_WAIT_L(8); PG8_BAR; PG8_WAIT_L(0); PG8_MMA(0, 0, At, B0); PG8_BAR; PG8_SCHED;
;             PG8_LDB(B1, 0, 1); PG8_STAGE(PG8_SB(0, 0), b2, voffB);
;             PG8_BAR; PG8_WAIT_L(0); PG8_MMA(0, 1, At, B1); PG8_BAR;
;             PG8_LDA(At, 0, 1); PG8_STAGE(PG8_SA(0, 0), a2, voffA);
;             PG8_BAR; PG8_WAIT_L(0); PG8_MMA(1, 0, At, B0); PG8_BAR; PG8_SCHED;
;             PG8_STAGE(PG8_SB(0, 1), b2 + hstep, voffB);
;             PG8_WAIT_V(6); PG8_BAR; PG8_MMA(1, 1, At, B1); PG8_BAR;
.LBB0_374:
	s_add_i32 s15, s14, 0x100
	s_and_b64 s[16:17], s[22:23], exec
	s_cselect_b32 s15, 0, s15
	s_cselect_b32 s16, 0, 0
	s_add_u32 s26, s6, s15
	s_addc_u32 s27, s7, s16
	s_add_i32 s52, 0, 0x10000
	s_add_u32 s30, s4, s15
	s_addc_u32 s31, s5, s16
	s_add_u32 s36, s12, s14
	s_addc_u32 s37, s13, 0
	s_add_i32 s62, s52, s46
	s_add_i32 m0, s42, 0xc000
	s_add_i32 s61, s42, 0xe000
	s_add_i32 s60, 0, 0x14000
	s_add_i32 s59, s62, 0x2000
	ds_read_b128 v[154:157], v248
	ds_read_b128 v[158:161], v248 offset:1024
	ds_read_b128 v[162:165], v248 offset:2048
	ds_read_b128 v[166:169], v248 offset:3072
	s_add_u32 s24, s30, s45
	s_addc_u32 s25, s31, 0
	s_add_i32 s29, s60, s46
	s_add_i32 s17, s29, 0x2000
	s_add_i32 s16, 0, 0x18000
	s_add_u32 s22, s26, s45
	s_addc_u32 s23, s27, 0
	s_add_i32 s14, 0, 0x1c000
	s_add_i32 s15, s16, s46
	s_add_i32 s58, s14, s46
	s_add_i32 s63, s15, 0x2000
	s_add_i32 s52, s58, 0x2000
	v_lshl_add_u64 v[182:183], s[36:37], 0, v[128:129]
	v_lshl_add_u64 v[182:183], v[182:183], 0, s[18:19]
	ds_read_b128 v[170:173], v152
	ds_read_b128 v[174:177], v152 offset:1024
	ds_read_b128 v[178:181], v152 offset:2048
	ds_read_b128 v[192:195], v152 offset:3072
	ds_read_b128 v[196:199], v152 offset:4096
	ds_read_b128 v[200:203], v152 offset:5120
	ds_read_b128 v[204:207], v152 offset:6144
	ds_read_b128 v[208:211], v152 offset:7168
	global_load_lds_dwordx4 v244, s[36:37]
	v_lshl_add_u64 v[182:183], s[36:37], 0, v[148:149]
	v_lshl_add_u64 v[182:183], v[182:183], 0, s[18:19]
	s_mov_b32 m0, s61
	s_nop 0
	global_load_lds_dwordx4 v245, s[36:37]
	s_waitcnt lgkmcnt(8)
	s_barrier
	s_waitcnt lgkmcnt(0)
	v_mfma_f32_16x16x32_bf16 v[124:127], v[154:157], v[170:173], v[124:127]
	v_mfma_f32_16x16x32_bf16 v[120:123], v[162:165], v[170:173], v[120:123]
	v_mfma_f32_16x16x32_bf16 v[116:119], v[154:157], v[178:181], v[116:119]
	v_mfma_f32_16x16x32_bf16 v[112:115], v[162:165], v[178:181], v[112:115]
	v_mfma_f32_16x16x32_bf16 v[104:107], v[154:157], v[196:199], v[104:107]
	v_mfma_f32_16x16x32_bf16 v[96:99], v[162:165], v[196:199], v[96:99]
	v_mfma_f32_16x16x32_bf16 v[88:91], v[154:157], v[204:207], v[88:91]
	v_mfma_f32_16x16x32_bf16 v[80:83], v[162:165], v[204:207], v[80:83]
	v_mfma_f32_16x16x32_bf16 v[124:127], v[158:161], v[174:177], v[124:127]
	v_mfma_f32_16x16x32_bf16 v[120:123], v[166:169], v[174:177], v[120:123]
	v_mfma_f32_16x16x32_bf16 v[116:119], v[158:161], v[192:195], v[116:119]
	v_mfma_f32_16x16x32_bf16 v[112:115], v[166:169], v[192:195], v[112:115]
	v_mfma_f32_16x16x32_bf16 v[104:107], v[158:161], v[200:203], v[104:107]
	v_mfma_f32_16x16x32_bf16 v[96:99], v[166:169], v[200:203], v[96:99]
	v_mfma_f32_16x16x32_bf16 v[88:91], v[158:161], v[208:211], v[88:91]
	v_mfma_f32_16x16x32_bf16 v[80:83], v[166:169], v[208:211], v[80:83]
	s_barrier
	s_mov_b32 m0, s62
	v_lshl_add_u64 v[182:183], s[30:31], 0, v[128:129]
	ds_read_b128 v[212:215], v249
	ds_read_b128 v[216:219], v249 offset:1024
	ds_read_b128 v[220:223], v249 offset:2048
	ds_read_b128 v[224:227], v249 offset:3072
	global_load_lds_dwordx4 v128, s[30:31]
	v_lshl_add_u64 v[228:229], s[30:31], 0, v[148:149]
	s_mov_b32 m0, s59
	s_nop 0
	global_load_lds_dwordx4 v148, s[30:31]
	s_barrier
	s_waitcnt lgkmcnt(0)
	v_mfma_f32_16x16x32_bf16 v[108:111], v[212:215], v[170:173], v[108:111]
	v_mfma_f32_16x16x32_bf16 v[100:103], v[220:223], v[170:173], v[100:103]
	v_mfma_f32_16x16x32_bf16 v[92:95], v[212:215], v[178:181], v[92:95]
	v_mfma_f32_16x16x32_bf16 v[84:87], v[220:223], v[178:181], v[84:87]
	v_mfma_f32_16x16x32_bf16 v[76:79], v[212:215], v[196:199], v[76:79]
	v_mfma_f32_16x16x32_bf16 v[72:75], v[220:223], v[196:199], v[72:75]
	v_mfma_f32_16x16x32_bf16 v[68:71], v[212:215], v[204:207], v[68:71]
	v_mfma_f32_16x16x32_bf16 v[64:67], v[220:223], v[204:207], v[64:67]
	v_mfma_f32_16x16x32_bf16 v[108:111], v[216:219], v[174:177], v[108:111]
	v_mfma_f32_16x16x32_bf16 v[100:103], v[224:227], v[174:177], v[100:103]
	v_mfma_f32_16x16x32_bf16 v[92:95], v[216:219], v[192:195], v[92:95]
	v_mfma_f32_16x16x32_bf16 v[84:87], v[224:227], v[192:195], v[84:87]
	v_mfma_f32_16x16x32_bf16 v[76:79], v[216:219], v[200:203], v[76:79]
	v_mfma_f32_16x16x32_bf16 v[72:75], v[224:227], v[200:203], v[72:75]
	v_mfma_f32_16x16x32_bf16 v[68:71], v[216:219], v[208:211], v[68:71]
	v_mfma_f32_16x16x32_bf16 v[64:67], v[224:227], v[208:211], v[64:67]
	s_mov_b32 m0, s42
	v_lshl_add_u64 v[230:231], s[26:27], 0, v[128:129]
	s_barrier
	ds_read_b128 v[170:173], v152 offset:16384
	ds_read_b128 v[174:177], v152 offset:17408
	ds_read_b128 v[178:181], v152 offset:18432
	ds_read_b128 v[192:195], v152 offset:19456
	ds_read_b128 v[196:199], v152 offset:20480
	ds_read_b128 v[200:203], v152 offset:21504
	ds_read_b128 v[204:207], v152 offset:22528
	ds_read_b128 v[208:211], v152 offset:23552
	global_load_lds_dwordx4 v128, s[26:27]
	v_lshl_add_u64 v[232:233], s[26:27], 0, v[148:149]
	s_mov_b32 m0, s43
	s_nop 0
	global_load_lds_dwordx4 v148, s[26:27]
	s_barrier
	s_waitcnt lgkmcnt(0)
	v_mfma_f32_16x16x32_bf16 v[60:63], v[154:157], v[170:173], v[60:63]
	v_mfma_f32_16x16x32_bf16 v[56:59], v[162:165], v[170:173], v[56:59]
	v_mfma_f32_16x16x32_bf16 v[52:55], v[154:157], v[178:181], v[52:55]
	v_mfma_f32_16x16x32_bf16 v[48:51], v[162:165], v[178:181], v[48:51]
	v_mfma_f32_16x16x32_bf16 v[36:39], v[154:157], v[196:199], v[36:39]
	v_mfma_f32_16x16x32_bf16 v[32:35], v[162:165], v[196:199], v[32:35]
	v_mfma_f32_16x16x32_bf16 v[20:23], v[154:157], v[204:207], v[20:23]
	v_mfma_f32_16x16x32_bf16 v[16:19], v[162:165], v[204:207], v[16:19]
	v_mfma_f32_16x16x32_bf16 v[60:63], v[158:161], v[174:177], v[60:63]
	v_mfma_f32_16x16x32_bf16 v[56:59], v[166:169], v[174:177], v[56:59]
	v_mfma_f32_16x16x32_bf16 v[52:55], v[158:161], v[192:195], v[52:55]
	v_mfma_f32_16x16x32_bf16 v[48:51], v[166:169], v[192:195], v[48:51]
	v_mfma_f32_16x16x32_bf16 v[36:39], v[158:161], v[200:203], v[36:39]
	v_mfma_f32_16x16x32_bf16 v[32:35], v[166:169], v[200:203], v[32:35]
	v_mfma_f32_16x16x32_bf16 v[20:23], v[158:161], v[208:211], v[20:23]
	v_mfma_f32_16x16x32_bf16 v[16:19], v[166:169], v[208:211], v[16:19]
	s_barrier
; #define PG8_STAGE(bufoff, gbase, voff) do { _Pragma("unroll") for (int _i = 0; _i < 2; ++_i) \
;         __builtin_amdgcn_global_load_lds((const unsigned*)((const char*)(gbase) + (voff)[_i]), (PG8_LAS unsigned*)(lds + (bufoff) + ldsw + _i * 8192), 16, 0, 0); } while (0)
; #define PG8_LDA(dst, b, h) do { _Pragma("unroll") for (int m = 0; m < 4; ++m) _Pragma("unroll") for (int k = 0; k < 2; ++k) dst[m][k] = *(const PG8_LAS bf16x8*)(lds + PG8_SA(b, h) + aoff + m * 2048 + k * 1024); } while (0)
; #define PG8_LDB(dst, b, h) do { _Pragma("unroll") for (int n = 0; n < 2; ++n) _Pragma("unroll") for (int k = 0; k < 2; ++k) dst[n][k] = *(const PG8_LAS bf16x8*)(lds + PG8_SB(b, h) + boff + n * 2048 + k * 1024); } while (0)
; #define PG8_MMA(ai, bj, At, Bt) do { __builtin_amdgcn_s_setprio(1); _Pragma("unroll") for (int m = 0; m < 4; ++m) _Pragma("unroll") for (int n = 0; n < 2; ++n) _Pragma("unroll") for (int k = 0; k < 2; ++k) \
;         acc[ai][bj][m][n] = __builtin_amdgcn_mfma_f32_16x16x32_bf16(Bt[n][k], At[m][k], acc[ai][bj][m][n], 0, 0, 0); __builtin_amdgcn_s_setprio(0); } while (0)
; #define PG8_WAIT_V(n) asm volatile("s_waitcnt vmcnt(" #n ")" ::: "memory")
; #define PG8_WAIT_L(n) asm volatile("s_waitcnt lgkmcnt(" #n ")" ::: "memory")
; #define PG8_BAR __builtin_amdgcn_s_barrier()
; #define PG8_SCHED __builtin_amdgcn_sched_barrier(0)
; template <class Epi, class Sched, bool STAMP = false>
; __device__ __forceinline__ void gemm_phase(PG8_LAS unsigned char* lds, const Gemm g, const Sched& S, const Epi& E, unsigned long long* stamps) {
;     ...
;             PG8_WAIT_V(6); PG8_BAR; PG8_MMA(1, 1, At, B1); PG8_BAR;
;             PG8_LDB(B0, 1, 0); PG8_SCHED; PG8_LDA(At, 1, 0); PG8_STAGE(PG8_SA(0, 1), a2 + hstep, voffA);
;             PG8_WAIT_L(8); PG8_BAR; PG8_WAIT_L(0); PG8_MMA(0, 0, At, B0); PG8_BAR; PG8_SCHED;
;             PG8_LDB(B1, 1, 1); PG8_STAGE(PG8_SB(1, 0), b3, voffB);
;             PG8_BAR; PG8_WAIT_L(0); PG8_MMA(0, 1, At, B1); PG8_BAR;
;             PG8_LDA(At, 1, 1); PG8_STAGE(PG8_SA(1, 0), a3, voffA);
;             PG8_BAR; PG8_WAIT_L(0); PG8_MMA(1, 0, At, B0); PG8_BAR; PG8_SCHED;
	s_mov_b32 m0, s29
	s_nop 0
	global_load_lds_dwordx4 v128, s[24:25]
	s_mov_b32 m0, s17
	s_nop 0
	global_load_lds_dwordx4 v148, s[24:25]
	s_waitcnt vmcnt(6)
	s_barrier
	v_mfma_f32_16x16x32_bf16 v[44:47], v[212:215], v[170:173], v[44:47]
	v_mfma_f32_16x16x32_bf16 v[40:43], v[220:223], v[170:173], v[40:43]
	v_mfma_f32_16x16x32_bf16 v[28:31], v[212:215], v[178:181], v[28:31]
	v_mfma_f32_16x16x32_bf16 v[24:27], v[220:223], v[178:181], v[24:27]
	v_mfma_f32_16x16x32_bf16 v[12:15], v[212:215], v[196:199], v[12:15]
	v_mfma_f32_16x16x32_bf16 v[8:11], v[220:223], v[196:199], v[8:11]
	v_mfma_f32_16x16x32_bf16 v[4:7], v[212:215], v[204:207], v[4:7]
	v_mfma_f32_16x16x32_bf16 v[0:3], v[220:223], v[204:207], v[0:3]
	v_mfma_f32_16x16x32_bf16 v[44:47], v[216:219], v[174:177], v[44:47]
	v_mfma_f32_16x16x32_bf16 v[40:43], v[224:227], v[174:177], v[40:43]
	v_mfma_f32_16x16x32_bf16 v[28:31], v[216:219], v[192:195], v[28:31]
	v_mfma_f32_16x16x32_bf16 v[24:27], v[224:227], v[192:195], v[24:27]
	v_mfma_f32_16x16x32_bf16 v[12:15], v[216:219], v[200:203], v[12:15]
	v_mfma_f32_16x16x32_bf16 v[8:11], v[224:227], v[200:203], v[8:11]
	v_mfma_f32_16x16x32_bf16 v[4:7], v[216:219], v[208:211], v[4:7]
	v_mfma_f32_16x16x32_bf16 v[0:3], v[224:227], v[208:211], v[0:3]
	s_barrier
	ds_read_b128 v[154:157], v250
	ds_read_b128 v[158:161], v250 offset:1024
	ds_read_b128 v[162:165], v250 offset:2048
	ds_read_b128 v[166:169], v250 offset:3072
	s_mov_b32 m0, s47
	ds_read_b128 v[170:173], v152 offset:32768
	ds_read_b128 v[174:177], v152 offset:33792
	ds_read_b128 v[178:181], v152 offset:34816
	ds_read_b128 v[192:195], v152 offset:35840
	ds_read_b128 v[196:199], v152 offset:36864
	ds_read_b128 v[200:203], v152 offset:37888
	ds_read_b128 v[204:207], v152 offset:38912
	global_load_lds_dwordx4 v128, s[22:23]
	s_mov_b32 m0, s48
	ds_read_b128 v[208:211], v152 offset:39936
	global_load_lds_dwordx4 v148, s[22:23]
	s_waitcnt lgkmcnt(8)
	s_barrier
	s_waitcnt lgkmcnt(0)
	v_mfma_f32_16x16x32_bf16 v[124:127], v[154:157], v[170:173], v[124:127]
	v_mfma_f32_16x16x32_bf16 v[120:123], v[162:165], v[170:173], v[120:123]
	v_mfma_f32_16x16x32_bf16 v[116:119], v[154:157], v[178:181], v[116:119]
	v_mfma_f32_16x16x32_bf16 v[112:115], v[162:165], v[178:181], v[112:115]
	v_mfma_f32_16x16x32_bf16 v[104:107], v[154:157], v[196:199], v[104:107]
	v_mfma_f32_16x16x32_bf16 v[96:99], v[162:165], v[196:199], v[96:99]
	v_mfma_f32_16x16x32_bf16 v[88:91], v[154:157], v[204:207], v[88:91]
	v_mfma_f32_16x16x32_bf16 v[80:83], v[162:165], v[204:207], v[80:83]
	v_mfma_f32_16x16x32_bf16 v[124:127], v[158:161], v[174:177], v[124:127]
	v_mfma_f32_16x16x32_bf16 v[120:123], v[166:169], v[174:177], v[120:123]
	v_mfma_f32_16x16x32_bf16 v[116:119], v[158:161], v[192:195], v[116:119]
	v_mfma_f32_16x16x32_bf16 v[112:115], v[166:169], v[192:195], v[112:115]
	v_mfma_f32_16x16x32_bf16 v[104:107], v[158:161], v[200:203], v[104:107]
	v_mfma_f32_16x16x32_bf16 v[96:99], v[166:169], v[200:203], v[96:99]
	v_mfma_f32_16x16x32_bf16 v[88:91], v[158:161], v[208:211], v[88:91]
	v_mfma_f32_16x16x32_bf16 v[80:83], v[166:169], v[208:211], v[80:83]
	s_barrier
	s_mov_b32 m0, s15
	v_lshl_add_u64 v[182:183], v[182:183], 0, s[18:19]
	ds_read_b128 v[212:215], v251
	ds_read_b128 v[216:219], v251 offset:1024
	ds_read_b128 v[220:223], v251 offset:2048
	ds_read_b128 v[224:227], v251 offset:3072
	global_load_lds_dwordx4 v244, s[30:31]
	v_lshl_add_u64 v[182:183], v[228:229], 0, s[18:19]
	s_mov_b32 m0, s63
	s_nop 0
	global_load_lds_dwordx4 v245, s[30:31]
	s_barrier
	s_waitcnt lgkmcnt(0)
	v_mfma_f32_16x16x32_bf16 v[108:111], v[212:215], v[170:173], v[108:111]
	v_mfma_f32_16x16x32_bf16 v[100:103], v[220:223], v[170:173], v[100:103]
	v_mfma_f32_16x16x32_bf16 v[92:95], v[212:215], v[178:181], v[92:95]
	v_mfma_f32_16x16x32_bf16 v[84:87], v[220:223], v[178:181], v[84:87]
	v_mfma_f32_16x16x32_bf16 v[76:79], v[212:215], v[196:199], v[76:79]
	v_mfma_f32_16x16x32_bf16 v[72:75], v[220:223], v[196:199], v[72:75]
	v_mfma_f32_16x16x32_bf16 v[68:71], v[212:215], v[204:207], v[68:71]
	v_mfma_f32_16x16x32_bf16 v[64:67], v[220:223], v[204:207], v[64:67]
	v_mfma_f32_16x16x32_bf16 v[108:111], v[216:219], v[174:177], v[108:111]
	v_mfma_f32_16x16x32_bf16 v[100:103], v[224:227], v[174:177], v[100:103]
	v_mfma_f32_16x16x32_bf16 v[92:95], v[216:219], v[192:195], v[92:95]
	v_mfma_f32_16x16x32_bf16 v[84:87], v[224:227], v[192:195], v[84:87]
	v_mfma_f32_16x16x32_bf16 v[76:79], v[216:219], v[200:203], v[76:79]
	v_mfma_f32_16x16x32_bf16 v[72:75], v[224:227], v[200:203], v[72:75]
	v_mfma_f32_16x16x32_bf16 v[68:71], v[216:219], v[208:211], v[68:71]
	v_mfma_f32_16x16x32_bf16 v[64:67], v[224:227], v[208:211], v[64:67]
	s_mov_b32 m0, s56
	v_lshl_add_u64 v[182:183], v[230:231], 0, s[18:19]
	s_barrier
	ds_read_b128 v[170:173], v152 offset:49152
	ds_read_b128 v[174:177], v152 offset:50176
	ds_read_b128 v[178:181], v152 offset:51200
	ds_read_b128 v[192:195], v152 offset:52224
	ds_read_b128 v[196:199], v152 offset:53248
	ds_read_b128 v[200:203], v152 offset:54272
	ds_read_b128 v[204:207], v152 offset:55296
	ds_read_b128 v[208:211], v152 offset:56320
	global_load_lds_dwordx4 v244, s[26:27]
	v_lshl_add_u64 v[182:183], v[232:233], 0, s[18:19]
	s_mov_b32 m0, s57
	s_nop 0
	global_load_lds_dwordx4 v245, s[26:27]
	s_barrier
; #define PG8_STAGE(bufoff, gbase, voff) do { _Pragma("unroll") for (int _i = 0; _i < 2; ++_i) \
;         __builtin_amdgcn_global_load_lds((const unsigned*)((const char*)(gbase) + (voff)[_i]), (PG8_LAS unsigned*)(lds + (bufoff) + ldsw + _i * 8192), 16, 0, 0); } while (0)
; #define PG8_MMA(ai, bj, At, Bt) do { __builtin_amdgcn_s_setprio(1); _Pragma("unroll") for (int m = 0; m < 4; ++m) _Pragma("unroll") for (int n = 0; n < 2; ++n) _Pragma("unroll") for (int k = 0; k < 2; ++k) \
;         acc[ai][bj][m][n] = __builtin_amdgcn_mfma_f32_16x16x32_bf16(Bt[n][k], At[m][k], acc[ai][bj][m][n], 0, 0, 0); __builtin_amdgcn_s_setprio(0); } while (0)
; #define PG8_WAIT_V(n) asm volatile("s_waitcnt vmcnt(" #n ")" ::: "memory")
; #define PG8_BAR __builtin_amdgcn_s_barrier()
; template <class Epi, class Sched, bool STAMP = false>
; __device__ __forceinline__ void gemm_phase(PG8_LAS unsigned char* lds, const Gemm g, const Sched& S, const Epi& E, unsigned long long* stamps) {
;     ...
;             PG8_STAGE(PG8_SB(1, 1), b3 + hstep, voffB);
;             PG8_WAIT_V(6); PG8_BAR; PG8_MMA(1, 1, At, B1); PG8_BAR;
;     __device__ __forceinline__ void operator()(const f32x4 (&acc)[2][2][4][2], const pg8::Unit& u, int wr, int wc, int fr, int fq) const {
;         const int row0 = (u.pm - 64) * 256 + wr * 64 + fr, col0 = u.pn * 256 + wc * 32 + 4 * fq;
; #pragma unroll
;         for (int ai = 0; ai < 2; ++ai)
; #pragma unroll
;             for (int m = 0; m < 4; ++m) { float* xp = PART + (size_t)(row0 + ai * 128 + m * 16) * ldp + col0;
; #pragma unroll
;                 for (int bj = 0; bj < 2; ++bj)
; #pragma unroll
;                     for (int n = 0; n < 2; ++n) *(f32x4*)(xp + bj * 128 + n * 16) = acc[ai][bj][m][n]; }
	s_waitcnt lgkmcnt(0)
	v_mfma_f32_16x16x32_bf16 v[60:63], v[154:157], v[170:173], v[60:63]
	v_mfma_f32_16x16x32_bf16 v[56:59], v[162:165], v[170:173], v[56:59]
	v_mfma_f32_16x16x32_bf16 v[52:55], v[154:157], v[178:181], v[52:55]
	v_mfma_f32_16x16x32_bf16 v[48:51], v[162:165], v[178:181], v[48:51]
	v_mfma_f32_16x16x32_bf16 v[36:39], v[154:157], v[196:199], v[36:39]
	v_mfma_f32_16x16x32_bf16 v[32:35], v[162:165], v[196:199], v[32:35]
	v_mfma_f32_16x16x32_bf16 v[20:23], v[154:157], v[204:207], v[20:23]
	v_mfma_f32_16x16x32_bf16 v[16:19], v[162:165], v[204:207], v[16:19]
	v_mfma_f32_16x16x32_bf16 v[60:63], v[158:161], v[174:177], v[60:63]
	v_mfma_f32_16x16x32_bf16 v[56:59], v[166:169], v[174:177], v[56:59]
	v_mfma_f32_16x16x32_bf16 v[52:55], v[158:161], v[192:195], v[52:55]
	v_mfma_f32_16x16x32_bf16 v[48:51], v[166:169], v[192:195], v[48:51]
	v_mfma_f32_16x16x32_bf16 v[36:39], v[158:161], v[200:203], v[36:39]
	v_mfma_f32_16x16x32_bf16 v[32:35], v[166:169], v[200:203], v[32:35]
	v_mfma_f32_16x16x32_bf16 v[20:23], v[158:161], v[208:211], v[20:23]
	v_mfma_f32_16x16x32_bf16 v[16:19], v[166:169], v[208:211], v[16:19]
	s_barrier
	s_mov_b32 m0, s58
	s_nop 0
	global_load_lds_dwordx4 v244, s[24:25]
	s_mov_b32 m0, s52
	s_nop 0
	global_load_lds_dwordx4 v245, s[24:25]
	s_waitcnt vmcnt(6)
	s_barrier
	v_mfma_f32_16x16x32_bf16 v[44:47], v[212:215], v[170:173], v[44:47]
	v_mfma_f32_16x16x32_bf16 v[40:43], v[220:223], v[170:173], v[40:43]
	v_mfma_f32_16x16x32_bf16 v[28:31], v[212:215], v[178:181], v[28:31]
	v_mfma_f32_16x16x32_bf16 v[24:27], v[220:223], v[178:181], v[24:27]
	v_mfma_f32_16x16x32_bf16 v[12:15], v[212:215], v[196:199], v[12:15]
	v_mfma_f32_16x16x32_bf16 v[8:11], v[220:223], v[196:199], v[8:11]
	v_mfma_f32_16x16x32_bf16 v[4:7], v[212:215], v[204:207], v[4:7]
	v_mfma_f32_16x16x32_bf16 v[0:3], v[220:223], v[204:207], v[0:3]
	v_mfma_f32_16x16x32_bf16 v[44:47], v[216:219], v[174:177], v[44:47]
	v_mfma_f32_16x16x32_bf16 v[40:43], v[224:227], v[174:177], v[40:43]
	v_mfma_f32_16x16x32_bf16 v[28:31], v[216:219], v[192:195], v[28:31]
	v_mfma_f32_16x16x32_bf16 v[24:27], v[224:227], v[192:195], v[24:27]
	v_mfma_f32_16x16x32_bf16 v[12:15], v[216:219], v[200:203], v[12:15]
	v_mfma_f32_16x16x32_bf16 v[8:11], v[224:227], v[200:203], v[8:11]
	v_mfma_f32_16x16x32_bf16 v[4:7], v[216:219], v[208:211], v[4:7]
	v_mfma_f32_16x16x32_bf16 v[0:3], v[224:227], v[208:211], v[0:3]
	s_andn2_b64 vcc, exec, s[20:21]
	s_mov_b64 s[22:23], -1
	s_mov_b64 s[20:21], 0
	s_movk_i32 s14, 0x100
	s_barrier
	s_cbranch_vccz .LBB0_374
	s_lshl_b64 s[4:5], s[10:11], 22
	s_add_u32 s4, s2, s4
	s_addc_u32 s5, s3, s5
	s_lshl_b32 s6, s44, 8
	s_addk_i32 s6, 0xc000
	v_or_b32_e32 v128, s6, v150
	v_add_u32_e32 v148, s49, v128
	s_lshl_b32 s6, s39, 8
	v_lshl_or_b32 v128, v139, 2, s6
	v_ashrrev_i32_e32 v149, 31, v148
	v_or_b32_e32 v128, s53, v128
	v_lshlrev_b64 v[150:151], 12, v[148:149]
	v_lshl_add_u64 v[150:151], s[4:5], 0, v[150:151]
	v_lshlrev_b32_e32 v128, 2, v128
	v_lshl_add_u64 v[150:151], v[150:151], 0, v[128:129]
	global_store_dwordx4 v[150:151], v[124:127], off
	global_store_dwordx4 v[150:151], v[120:123], off offset:64
	global_store_dwordx4 v[150:151], v[108:111], off offset:512
	global_store_dwordx4 v[150:151], v[100:103], off offset:576
	s_cmpk_lt_u32 s38, 0x100
	s_nop 0
	v_or_b32_e32 v100, 16, v148
	v_ashrrev_i32_e32 v101, 31, v100
	v_lshlrev_b64 v[100:101], 12, v[100:101]
	v_lshl_add_u64 v[100:101], s[4:5], 0, v[100:101]
	v_lshl_add_u64 v[100:101], v[100:101], 0, v[128:129]
	global_store_dwordx4 v[100:101], v[116:119], off
	global_store_dwordx4 v[100:101], v[112:115], off offset:64
	global_store_dwordx4 v[100:101], v[92:95], off offset:512
	global_store_dwordx4 v[100:101], v[84:87], off offset:576
	s_nop 1
	v_or_b32_e32 v84, 32, v148
	v_ashrrev_i32_e32 v85, 31, v84
	v_lshlrev_b64 v[84:85], 12, v[84:85]
	v_lshl_add_u64 v[84:85], s[4:5], 0, v[84:85]
	v_lshl_add_u64 v[84:85], v[84:85], 0, v[128:129]
	global_store_dwordx4 v[84:85], v[104:107], off
	global_store_dwordx4 v[84:85], v[96:99], off offset:64
	global_store_dwordx4 v[84:85], v[76:79], off offset:512
	global_store_dwordx4 v[84:85], v[72:75], off offset:576
	s_nop 1
	v_or_b32_e32 v72, 48, v148
	v_ashrrev_i32_e32 v73, 31, v72
	v_lshlrev_b64 v[72:73], 12, v[72:73]
	v_lshl_add_u64 v[72:73], s[4:5], 0, v[72:73]
	v_lshl_add_u64 v[72:73], v[72:73], 0, v[128:129]
	s_mov_b64 s[4:5], 0x80000
	global_store_dwordx4 v[72:73], v[88:91], off
	global_store_dwordx4 v[72:73], v[80:83], off offset:64
	global_store_dwordx4 v[72:73], v[68:71], off offset:512
	global_store_dwordx4 v[72:73], v[64:67], off offset:576
	s_nop 1
	v_lshl_add_u64 v[64:65], v[150:151], 0, s[4:5]
	s_mov_b32 s4, 0x80000
	v_add_co_u32_e32 v66, vcc, s4, v150
	s_mov_b64 s[4:5], 0x90000
	s_nop 0
	v_addc_co_u32_e32 v67, vcc, 0, v151, vcc
	global_store_dwordx4 v[66:67], v[60:63], off
	global_store_dwordx4 v[64:65], v[56:59], off offset:64
	global_store_dwordx4 v[64:65], v[44:47], off offset:512
	global_store_dwordx4 v[64:65], v[40:43], off offset:576
	s_nop 1
	v_lshl_add_u64 v[40:41], v[150:151], 0, s[4:5]
	s_mov_b32 s4, 0x90000
	v_add_co_u32_e32 v42, vcc, s4, v150
	s_mov_b64 s[4:5], 0xa0000
	s_nop 0
	v_addc_co_u32_e32 v43, vcc, 0, v151, vcc
	global_store_dwordx4 v[42:43], v[52:55], off
	global_store_dwordx4 v[40:41], v[48:51], off offset:64
	global_store_dwordx4 v[40:41], v[28:31], off offset:512
	global_store_dwordx4 v[40:41], v[24:27], off offset:576
	s_nop 1
	v_lshl_add_u64 v[24:25], v[150:151], 0, s[4:5]
	s_mov_b32 s4, 0xa0000
	v_add_co_u32_e32 v26, vcc, s4, v150
	s_mov_b64 s[4:5], 0xb0000
	s_nop 0
	v_addc_co_u32_e32 v27, vcc, 0, v151, vcc
	global_store_dwordx4 v[26:27], v[36:39], off
	global_store_dwordx4 v[24:25], v[32:35], off offset:64
	global_store_dwordx4 v[24:25], v[12:15], off offset:512
	global_store_dwordx4 v[24:25], v[8:11], off offset:576
	s_nop 1
	v_add_co_u32_e32 v10, vcc, 0xb0000, v150
	v_lshl_add_u64 v[8:9], v[150:151], 0, s[4:5]
	s_nop 0
	v_addc_co_u32_e32 v11, vcc, 0, v151, vcc
	global_store_dwordx4 v[10:11], v[20:23], off
	global_store_dwordx4 v[8:9], v[16:19], off offset:64
	global_store_dwordx4 v[8:9], v[4:7], off offset:512
	global_store_dwordx4 v[8:9], v[0:3], off offset:576
	s_waitcnt vmcnt(0)
	s_cbranch_scc0 .LBB0_377
	s_barrier

; #define PG8_STAGE(bufoff, gbase, voff) do { _Pragma("unroll") for (int _i = 0; _i < 2; ++_i) \
;         __builtin_amdgcn_global_load_lds((const unsigned*)((const char*)(gbase) + (voff)[_i]), (PG8_LAS unsigned*)(lds + (bufoff) + ldsw + _i * 8192), 16, 0, 0); } while (0)
; #define PG8_LDA(dst, b, h) do { _Pragma("unroll") for (int m = 0; m < 4; ++m) _Pragma("unroll") for (int k = 0; k < 2; ++k) dst[m][k] = *(const PG8_LAS bf16x8*)(lds + PG8_SA(b, h) + aoff + m * 2048 + k * 1024); } while (0)
; #define PG8_LDB(dst, b, h) do { _Pragma("unroll") for (int n = 0; n < 2; ++n) _Pragma("unroll") for (int k = 0; k < 2; ++k) dst[n][k] = *(const PG8_LAS bf16x8*)(lds + PG8_SB(b, h) + boff + n * 2048 + k * 1024); } while (0)
; #define PG8_MMA(ai, bj, At, Bt) do { __builtin_amdgcn_s_setprio(1); _Pragma("unroll") for (int m = 0; m < 4; ++m) _Pragma("unroll") for (int n = 0; n < 2; ++n) _Pragma("unroll") for (int k = 0; k < 2; ++k) \
;         acc[ai][bj][m][n] = __builtin_amdgcn_mfma_f32_16x16x32_bf16(Bt[n][k], At[m][k], acc[ai][bj][m][n], 0, 0, 0); __builtin_amdgcn_s_setprio(0); } while (0)
; #define PG8_WAIT_V(n) asm volatile("s_waitcnt vmcnt(" #n ")" ::: "memory")
; template <class Epi, class Sched, bool STAMP = false>
; __device__ __forceinline__ void gemm_phase(PG8_LAS unsigned char* lds, const Gemm g, const Sched& S, const Epi& E, unsigned long long* stamps) {
;     ...
;             const bool last = (t == nt - 2);
;             const char* a1 = cA + (size_t)(t + 1) * kstep;
;             const char* a2 = last ? nA : cA + (size_t)(t + 2) * kstep; const char* b2 = last ? nB : cB + (size_t)(t + 2) * kstep;
;             const char* a3 = a2 + kstep; const char* b3 = b2 + kstep;
;             if (last && has_next) S.a_ready(nxt);
;             PG8_LDB(B0, 0, 0); PG8_SCHED; PG8_LDA(At, 0, 0); PG8_STAGE(PG8_SA(1, 1), a1 + hstep, voffA);
;             PG8_WAIT_L(8); PG8_BAR; PG8_WAIT_L(0); PG8_MMA(0, 0, At, B0); PG8_BAR; PG8_SCHED;
;             PG8_LDB(B1, 0, 1); PG8_STAGE(PG8_SB(0, 0), b2, voffB);
;             PG8_BAR; PG8_WAIT_L(0); PG8_MMA(0, 1, At, B1); PG8_BAR;
;             PG8_LDA(At, 0, 1); PG8_STAGE(PG8_SA(0, 0), a2, voffA);
;             PG8_BAR; PG8_WAIT_L(0); PG8_MMA(1, 0, At, B0); PG8_BAR; PG8_SCHED;
;             PG8_STAGE(PG8_SB(0, 1), b2 + hstep, voffB);
;             PG8_WAIT_V(6); PG8_BAR; PG8_MMA(1, 1, At, B1); PG8_BAR;
.LBB0_495:
	s_add_u32 s14, s24, 0xfffc0080
	s_addc_u32 s15, s25, -1
	s_add_i32 s16, 0, 0x10000
	ds_read_b128 v[158:161], v248
	ds_read_b128 v[162:165], v248 offset:1024
	ds_read_b128 v[170:173], v248 offset:2048
	ds_read_b128 v[174:177], v248 offset:3072
	s_cmp_eq_u32 s61, 12
	s_cselect_b32 s31, s7, s15
	s_cselect_b32 s30, s57, s14
	s_cselect_b32 s27, s5, s60
	s_cselect_b32 s26, s58, s59
	s_add_i32 m0, s23, 0xc000
	ds_read_b128 v[178:181], v168
	ds_read_b128 v[192:195], v168 offset:1024
	ds_read_b128 v[196:199], v168 offset:2048
	ds_read_b128 v[200:203], v168 offset:3072
	ds_read_b128 v[204:207], v168 offset:4096
	ds_read_b128 v[208:211], v168 offset:5120
	ds_read_b128 v[212:215], v168 offset:6144
	global_load_lds_dwordx4 v154, s[24:25]
	s_add_i32 m0, s23, 0xe000
	ds_read_b128 v[216:219], v168 offset:7168
	global_load_lds_dwordx4 v156, s[24:25]
	s_waitcnt lgkmcnt(8)
	s_barrier
	s_waitcnt lgkmcnt(0)
	v_mfma_f32_16x16x32_bf16 v[124:127], v[158:161], v[178:181], v[124:127]
	v_mfma_f32_16x16x32_bf16 v[120:123], v[170:173], v[178:181], v[120:123]
	v_mfma_f32_16x16x32_bf16 v[108:111], v[158:161], v[196:199], v[108:111]
	v_mfma_f32_16x16x32_bf16 v[104:107], v[170:173], v[196:199], v[104:107]
	v_mfma_f32_16x16x32_bf16 v[92:95], v[158:161], v[204:207], v[92:95]
	v_mfma_f32_16x16x32_bf16 v[88:91], v[170:173], v[204:207], v[88:91]
	v_mfma_f32_16x16x32_bf16 v[76:79], v[158:161], v[212:215], v[76:79]
	v_mfma_f32_16x16x32_bf16 v[72:75], v[170:173], v[212:215], v[72:75]
	v_mfma_f32_16x16x32_bf16 v[124:127], v[162:165], v[192:195], v[124:127]
	v_mfma_f32_16x16x32_bf16 v[120:123], v[174:177], v[192:195], v[120:123]
	v_mfma_f32_16x16x32_bf16 v[108:111], v[162:165], v[200:203], v[108:111]
	v_mfma_f32_16x16x32_bf16 v[104:107], v[174:177], v[200:203], v[104:107]
	v_mfma_f32_16x16x32_bf16 v[92:95], v[162:165], v[208:211], v[92:95]
	v_mfma_f32_16x16x32_bf16 v[88:91], v[174:177], v[208:211], v[88:91]
	v_mfma_f32_16x16x32_bf16 v[76:79], v[162:165], v[216:219], v[76:79]
	v_mfma_f32_16x16x32_bf16 v[72:75], v[174:177], v[216:219], v[72:75]
	s_barrier
	s_add_i32 s17, 0, 0x14000
	s_add_i32 s14, s16, s43
	s_mov_b32 m0, s14
	ds_read_b128 v[220:223], v249
	ds_read_b128 v[224:227], v249 offset:1024
	ds_read_b128 v[228:231], v249 offset:2048
	global_load_lds_dwordx4 v128, s[26:27]
	s_add_i32 m0, s14, 0x2000
	ds_read_b128 v[232:235], v249 offset:3072
	global_load_lds_dwordx4 v148, s[26:27]
	s_barrier
	s_waitcnt lgkmcnt(0)
	v_mfma_f32_16x16x32_bf16 v[116:119], v[220:223], v[178:181], v[116:119]
	v_mfma_f32_16x16x32_bf16 v[112:115], v[228:231], v[178:181], v[112:115]
	v_mfma_f32_16x16x32_bf16 v[100:103], v[220:223], v[196:199], v[100:103]
	v_mfma_f32_16x16x32_bf16 v[96:99], v[228:231], v[196:199], v[96:99]
	v_mfma_f32_16x16x32_bf16 v[84:87], v[220:223], v[204:207], v[84:87]
	v_mfma_f32_16x16x32_bf16 v[80:83], v[228:231], v[204:207], v[80:83]
	v_mfma_f32_16x16x32_bf16 v[68:71], v[220:223], v[212:215], v[68:71]
	v_mfma_f32_16x16x32_bf16 v[64:67], v[228:231], v[212:215], v[64:67]
	v_mfma_f32_16x16x32_bf16 v[116:119], v[224:227], v[192:195], v[116:119]
	v_mfma_f32_16x16x32_bf16 v[112:115], v[232:235], v[192:195], v[112:115]
	v_mfma_f32_16x16x32_bf16 v[100:103], v[224:227], v[200:203], v[100:103]
	v_mfma_f32_16x16x32_bf16 v[96:99], v[232:235], v[200:203], v[96:99]
	v_mfma_f32_16x16x32_bf16 v[84:87], v[224:227], v[208:211], v[84:87]
	v_mfma_f32_16x16x32_bf16 v[80:83], v[232:235], v[208:211], v[80:83]
	v_mfma_f32_16x16x32_bf16 v[68:71], v[224:227], v[216:219], v[68:71]
	v_mfma_f32_16x16x32_bf16 v[64:67], v[232:235], v[216:219], v[64:67]
	s_mov_b32 m0, s23
	s_barrier
	ds_read_b128 v[178:181], v168 offset:16384
	ds_read_b128 v[192:195], v168 offset:17408
	ds_read_b128 v[196:199], v168 offset:18432
	ds_read_b128 v[200:203], v168 offset:19456
	ds_read_b128 v[204:207], v168 offset:20480
	ds_read_b128 v[208:211], v168 offset:21504
	ds_read_b128 v[212:215], v168 offset:22528
	global_load_lds_dwordx4 v152, s[30:31]
	s_mov_b32 m0, s45
	ds_read_b128 v[216:219], v168 offset:23552
	global_load_lds_dwordx4 v150, s[30:31]
	s_barrier
	s_waitcnt lgkmcnt(0)
	v_mfma_f32_16x16x32_bf16 v[60:63], v[158:161], v[178:181], v[60:63]
	v_mfma_f32_16x16x32_bf16 v[56:59], v[170:173], v[178:181], v[56:59]
	v_mfma_f32_16x16x32_bf16 v[44:47], v[158:161], v[196:199], v[44:47]
	v_mfma_f32_16x16x32_bf16 v[40:43], v[170:173], v[196:199], v[40:43]
	v_mfma_f32_16x16x32_bf16 v[28:31], v[158:161], v[204:207], v[28:31]
	v_mfma_f32_16x16x32_bf16 v[24:27], v[170:173], v[204:207], v[24:27]
	v_mfma_f32_16x16x32_bf16 v[12:15], v[158:161], v[212:215], v[12:15]
	v_mfma_f32_16x16x32_bf16 v[8:11], v[170:173], v[212:215], v[8:11]
	v_mfma_f32_16x16x32_bf16 v[60:63], v[162:165], v[192:195], v[60:63]
	v_mfma_f32_16x16x32_bf16 v[56:59], v[174:177], v[192:195], v[56:59]
	v_mfma_f32_16x16x32_bf16 v[44:47], v[162:165], v[200:203], v[44:47]
	v_mfma_f32_16x16x32_bf16 v[40:43], v[174:177], v[200:203], v[40:43]
	v_mfma_f32_16x16x32_bf16 v[28:31], v[162:165], v[208:211], v[28:31]
	v_mfma_f32_16x16x32_bf16 v[24:27], v[174:177], v[208:211], v[24:27]
	v_mfma_f32_16x16x32_bf16 v[12:15], v[162:165], v[216:219], v[12:15]
	v_mfma_f32_16x16x32_bf16 v[8:11], v[174:177], v[216:219], v[8:11]
	s_barrier
	s_add_u32 s14, s26, 0x40000
	s_addc_u32 s15, s27, 0
	s_add_i32 s16, s17, s43
	s_mov_b32 m0, s16
	s_nop 0
	global_load_lds_dwordx4 v128, s[14:15]
	s_add_i32 m0, s16, 0x2000
	s_nop 0
	global_load_lds_dwordx4 v148, s[14:15]
	s_waitcnt vmcnt(6)
	s_barrier
; #define PG8_STAGE(bufoff, gbase, voff) do { _Pragma("unroll") for (int _i = 0; _i < 2; ++_i) \
;         __builtin_amdgcn_global_load_lds((const unsigned*)((const char*)(gbase) + (voff)[_i]), (PG8_LAS unsigned*)(lds + (bufoff) + ldsw + _i * 8192), 16, 0, 0); } while (0)
; #define PG8_LDA(dst, b, h) do { _Pragma("unroll") for (int m = 0; m < 4; ++m) _Pragma("unroll") for (int k = 0; k < 2; ++k) dst[m][k] = *(const PG8_LAS bf16x8*)(lds + PG8_SA(b, h) + aoff + m * 2048 + k * 1024); } while (0)
; #define PG8_LDB(dst, b, h) do { _Pragma("unroll") for (int n = 0; n < 2; ++n) _Pragma("unroll") for (int k = 0; k < 2; ++k) dst[n][k] = *(const PG8_LAS bf16x8*)(lds + PG8_SB(b, h) + boff + n * 2048 + k * 1024); } while (0)
; #define PG8_MMA(ai, bj, At, Bt) do { __builtin_amdgcn_s_setprio(1); _Pragma("unroll") for (int m = 0; m < 4; ++m) _Pragma("unroll") for (int n = 0; n < 2; ++n) _Pragma("unroll") for (int k = 0; k < 2; ++k) \
;         acc[ai][bj][m][n] = __builtin_amdgcn_mfma_f32_16x16x32_bf16(Bt[n][k], At[m][k], acc[ai][bj][m][n], 0, 0, 0); __builtin_amdgcn_s_setprio(0); } while (0)
; #define PG8_WAIT_V(n) asm volatile("s_waitcnt vmcnt(" #n ")" ::: "memory")
; #define PG8_WAIT_L(n) asm volatile("s_waitcnt lgkmcnt(" #n ")" ::: "memory")
; #define PG8_BAR __builtin_amdgcn_s_barrier()
; #define PG8_SCHED __builtin_amdgcn_sched_barrier(0)
; template <class Epi, class Sched, bool STAMP = false>
; __device__ __forceinline__ void gemm_phase(PG8_LAS unsigned char* lds, const Gemm g, const Sched& S, const Epi& E, unsigned long long* stamps) {
;     ...
;             PG8_WAIT_V(6); PG8_BAR; PG8_MMA(1, 1, At, B1); PG8_BAR;
;             PG8_LDB(B0, 1, 0); PG8_SCHED; PG8_LDA(At, 1, 0); PG8_STAGE(PG8_SA(0, 1), a2 + hstep, voffA);
;             PG8_WAIT_L(8); PG8_BAR; PG8_WAIT_L(0); PG8_MMA(0, 0, At, B0); PG8_BAR; PG8_SCHED;
;             PG8_LDB(B1, 1, 1); PG8_STAGE(PG8_SB(1, 0), b3, voffB);
;             PG8_BAR; PG8_WAIT_L(0); PG8_MMA(0, 1, At, B1); PG8_BAR;
;             PG8_LDA(At, 1, 1); PG8_STAGE(PG8_SA(1, 0), a3, voffA);
;             PG8_BAR; PG8_WAIT_L(0); PG8_MMA(1, 0, At, B0); PG8_BAR; PG8_SCHED;
	v_mfma_f32_16x16x32_bf16 v[52:55], v[220:223], v[178:181], v[52:55]
	v_mfma_f32_16x16x32_bf16 v[48:51], v[228:231], v[178:181], v[48:51]
	v_mfma_f32_16x16x32_bf16 v[36:39], v[220:223], v[196:199], v[36:39]
	v_mfma_f32_16x16x32_bf16 v[32:35], v[228:231], v[196:199], v[32:35]
	v_mfma_f32_16x16x32_bf16 v[20:23], v[220:223], v[204:207], v[20:23]
	v_mfma_f32_16x16x32_bf16 v[16:19], v[228:231], v[204:207], v[16:19]
	v_mfma_f32_16x16x32_bf16 v[4:7], v[220:223], v[212:215], v[4:7]
	v_mfma_f32_16x16x32_bf16 v[0:3], v[228:231], v[212:215], v[0:3]
	v_mfma_f32_16x16x32_bf16 v[52:55], v[224:227], v[192:195], v[52:55]
	v_mfma_f32_16x16x32_bf16 v[48:51], v[232:235], v[192:195], v[48:51]
	v_mfma_f32_16x16x32_bf16 v[36:39], v[224:227], v[200:203], v[36:39]
	v_mfma_f32_16x16x32_bf16 v[32:35], v[232:235], v[200:203], v[32:35]
	v_mfma_f32_16x16x32_bf16 v[20:23], v[224:227], v[208:211], v[20:23]
	v_mfma_f32_16x16x32_bf16 v[16:19], v[232:235], v[208:211], v[16:19]
	v_mfma_f32_16x16x32_bf16 v[4:7], v[224:227], v[216:219], v[4:7]
	v_mfma_f32_16x16x32_bf16 v[0:3], v[232:235], v[216:219], v[0:3]
	s_add_i32 s16, 0, 0x18000
	s_barrier
	ds_read_b128 v[158:161], v250
	ds_read_b128 v[162:165], v250 offset:1024
	ds_read_b128 v[170:173], v250 offset:2048
	ds_read_b128 v[174:177], v250 offset:3072
	s_add_u32 s14, s30, 0x40000
	s_addc_u32 s15, s31, 0
	s_mov_b32 m0, s46
	ds_read_b128 v[178:181], v168 offset:32768
	ds_read_b128 v[192:195], v168 offset:33792
	ds_read_b128 v[196:199], v168 offset:34816
	ds_read_b128 v[200:203], v168 offset:35840
	ds_read_b128 v[204:207], v168 offset:36864
	ds_read_b128 v[208:211], v168 offset:37888
	ds_read_b128 v[212:215], v168 offset:38912
	global_load_lds_dwordx4 v152, s[14:15]
	s_mov_b32 m0, s47
	ds_read_b128 v[216:219], v168 offset:39936
	global_load_lds_dwordx4 v150, s[14:15]
	s_waitcnt lgkmcnt(8)
	s_barrier
	s_waitcnt lgkmcnt(0)
	v_mfma_f32_16x16x32_bf16 v[124:127], v[158:161], v[178:181], v[124:127]
	v_mfma_f32_16x16x32_bf16 v[120:123], v[170:173], v[178:181], v[120:123]
	v_mfma_f32_16x16x32_bf16 v[108:111], v[158:161], v[196:199], v[108:111]
	v_mfma_f32_16x16x32_bf16 v[104:107], v[170:173], v[196:199], v[104:107]
	v_mfma_f32_16x16x32_bf16 v[92:95], v[158:161], v[204:207], v[92:95]
	v_mfma_f32_16x16x32_bf16 v[88:91], v[170:173], v[204:207], v[88:91]
	v_mfma_f32_16x16x32_bf16 v[76:79], v[158:161], v[212:215], v[76:79]
	v_mfma_f32_16x16x32_bf16 v[72:75], v[170:173], v[212:215], v[72:75]
	v_mfma_f32_16x16x32_bf16 v[124:127], v[162:165], v[192:195], v[124:127]
	v_mfma_f32_16x16x32_bf16 v[120:123], v[174:177], v[192:195], v[120:123]
	v_mfma_f32_16x16x32_bf16 v[108:111], v[162:165], v[200:203], v[108:111]
	v_mfma_f32_16x16x32_bf16 v[104:107], v[174:177], v[200:203], v[104:107]
	v_mfma_f32_16x16x32_bf16 v[92:95], v[162:165], v[208:211], v[92:95]
	v_mfma_f32_16x16x32_bf16 v[88:91], v[174:177], v[208:211], v[88:91]
	v_mfma_f32_16x16x32_bf16 v[76:79], v[162:165], v[216:219], v[76:79]
	v_mfma_f32_16x16x32_bf16 v[72:75], v[174:177], v[216:219], v[72:75]
	s_barrier
	s_add_i32 s17, 0, 0x1c000
	s_add_i32 s14, s16, s43
	s_mov_b32 m0, s14
	ds_read_b128 v[220:223], v251
	ds_read_b128 v[224:227], v251 offset:1024
	ds_read_b128 v[228:231], v251 offset:2048
	global_load_lds_dwordx4 v244, s[26:27]
	s_add_i32 m0, s14, 0x2000
	ds_read_b128 v[232:235], v251 offset:3072
	global_load_lds_dwordx4 v245, s[26:27]
	s_barrier
	s_waitcnt lgkmcnt(0)
	v_mfma_f32_16x16x32_bf16 v[116:119], v[220:223], v[178:181], v[116:119]
	v_mfma_f32_16x16x32_bf16 v[112:115], v[228:231], v[178:181], v[112:115]
	v_mfma_f32_16x16x32_bf16 v[100:103], v[220:223], v[196:199], v[100:103]
	v_mfma_f32_16x16x32_bf16 v[96:99], v[228:231], v[196:199], v[96:99]
	v_mfma_f32_16x16x32_bf16 v[84:87], v[220:223], v[204:207], v[84:87]
	v_mfma_f32_16x16x32_bf16 v[80:83], v[228:231], v[204:207], v[80:83]
	v_mfma_f32_16x16x32_bf16 v[68:71], v[220:223], v[212:215], v[68:71]
	v_mfma_f32_16x16x32_bf16 v[64:67], v[228:231], v[212:215], v[64:67]
	v_mfma_f32_16x16x32_bf16 v[116:119], v[224:227], v[192:195], v[116:119]
	v_mfma_f32_16x16x32_bf16 v[112:115], v[232:235], v[192:195], v[112:115]
	v_mfma_f32_16x16x32_bf16 v[100:103], v[224:227], v[200:203], v[100:103]
	v_mfma_f32_16x16x32_bf16 v[96:99], v[232:235], v[200:203], v[96:99]
	v_mfma_f32_16x16x32_bf16 v[84:87], v[224:227], v[208:211], v[84:87]
	v_mfma_f32_16x16x32_bf16 v[80:83], v[232:235], v[208:211], v[80:83]
	v_mfma_f32_16x16x32_bf16 v[68:71], v[224:227], v[216:219], v[68:71]
	v_mfma_f32_16x16x32_bf16 v[64:67], v[232:235], v[216:219], v[64:67]
	s_mov_b32 m0, s49
	s_barrier
	ds_read_b128 v[178:181], v168 offset:49152
	ds_read_b128 v[192:195], v168 offset:50176
	ds_read_b128 v[196:199], v168 offset:51200
	ds_read_b128 v[200:203], v168 offset:52224
	ds_read_b128 v[204:207], v168 offset:53248
	ds_read_b128 v[208:211], v168 offset:54272
	ds_read_b128 v[212:215], v168 offset:55296
	global_load_lds_dwordx4 v246, s[30:31]
	s_mov_b32 m0, s53
	ds_read_b128 v[216:219], v168 offset:56320
	global_load_lds_dwordx4 v247, s[30:31]
	s_barrier
	s_waitcnt lgkmcnt(0)
	v_mfma_f32_16x16x32_bf16 v[60:63], v[158:161], v[178:181], v[60:63]
	v_mfma_f32_16x16x32_bf16 v[56:59], v[170:173], v[178:181], v[56:59]
	v_mfma_f32_16x16x32_bf16 v[44:47], v[158:161], v[196:199], v[44:47]
	v_mfma_f32_16x16x32_bf16 v[40:43], v[170:173], v[196:199], v[40:43]
	v_mfma_f32_16x16x32_bf16 v[28:31], v[158:161], v[204:207], v[28:31]
	v_mfma_f32_16x16x32_bf16 v[24:27], v[170:173], v[204:207], v[24:27]
	v_mfma_f32_16x16x32_bf16 v[12:15], v[158:161], v[212:215], v[12:15]
	v_mfma_f32_16x16x32_bf16 v[8:11], v[170:173], v[212:215], v[8:11]
	v_mfma_f32_16x16x32_bf16 v[60:63], v[162:165], v[192:195], v[60:63]
	v_mfma_f32_16x16x32_bf16 v[56:59], v[174:177], v[192:195], v[56:59]
	v_mfma_f32_16x16x32_bf16 v[44:47], v[162:165], v[200:203], v[44:47]
	v_mfma_f32_16x16x32_bf16 v[40:43], v[174:177], v[200:203], v[40:43]
	v_mfma_f32_16x16x32_bf16 v[28:31], v[162:165], v[208:211], v[28:31]
	v_mfma_f32_16x16x32_bf16 v[24:27], v[174:177], v[208:211], v[24:27]
	v_mfma_f32_16x16x32_bf16 v[12:15], v[162:165], v[216:219], v[12:15]
	v_mfma_f32_16x16x32_bf16 v[8:11], v[174:177], v[216:219], v[8:11]
	s_barrier
; __device__ __forceinline__ unsigned cvt_pk_bf16(float lo, float hi) { const f32x2_cv v = {lo, hi}; const bf16x2_cv b = __builtin_convertvector(v, bf16x2_cv); return __builtin_bit_cast(unsigned, b); }
; #define PG8_STAGE(bufoff, gbase, voff) do { _Pragma("unroll") for (int _i = 0; _i < 2; ++_i) \
;         __builtin_amdgcn_global_load_lds((const unsigned*)((const char*)(gbase) + (voff)[_i]), (PG8_LAS unsigned*)(lds + (bufoff) + ldsw + _i * 8192), 16, 0, 0); } while (0)
; #define PG8_MMA(ai, bj, At, Bt) do { __builtin_amdgcn_s_setprio(1); _Pragma("unroll") for (int m = 0; m < 4; ++m) _Pragma("unroll") for (int n = 0; n < 2; ++n) _Pragma("unroll") for (int k = 0; k < 2; ++k) \
;         acc[ai][bj][m][n] = __builtin_amdgcn_mfma_f32_16x16x32_bf16(Bt[n][k], At[m][k], acc[ai][bj][m][n], 0, 0, 0); __builtin_amdgcn_s_setprio(0); } while (0)
; #define PG8_WAIT_V(n) asm volatile("s_waitcnt vmcnt(" #n ")" ::: "memory")
; template <class Epi, class Sched, bool STAMP = false>
; __device__ __forceinline__ void gemm_phase(PG8_LAS unsigned char* lds, const Gemm g, const Sched& S, const Epi& E, unsigned long long* stamps) {
;     ...
;             PG8_STAGE(PG8_SB(1, 1), b3 + hstep, voffB);
;             PG8_WAIT_V(6); PG8_BAR; PG8_MMA(1, 1, At, B1); PG8_BAR;
;     __device__ __forceinline__ void operator()(const f32x4 (&acc)[2][2][4][2], const pg8::Unit& u, int wr, int wc, int fr, int fq) const {
;         const int row0 = u.pm * 256 + wr * 64 + fr, col0 = u.pn * 256 + wc * 32 + 8 * fq;
; #pragma unroll
;         for (int ai = 0; ai < 2; ++ai)
; #pragma unroll
;             for (int m = 0; m < 4; ++m) {
;                 const int row = row0 + ai * 128 + m * 16;
;                 const float s = (MODE == 2) ? 1.0f : rstd_of(rowss, row);
;                 bf16_t* rowp = O + (size_t)row * ldc + col0;
; #pragma unroll
;                 for (int bj = 0; bj < 2; ++bj) {
;                     f32x4 v0 = acc[ai][bj][m][0] * s, v1 = acc[ai][bj][m][1] * s;
;                     if (MODE == 1) {
; #pragma unroll
;                         for (int j = 0; j < 4; ++j) { const float a = fmaxf(v0[j], 0.f), b = fmaxf(v1[j], 0.f); v0[j] = a * a; v1[j] = b * b; } }
;                     u32x4 w; w.x = cvt_pk_bf16(v0[0], v0[1]); w.y = cvt_pk_bf16(v0[2], v0[3]); w.z = cvt_pk_bf16(v1[0], v1[1]); w.w = cvt_pk_bf16(v1[2], v1[3]);
;                     *(u32x4*)(rowp + bj * 128) = w; } }
	s_add_u32 s14, s26, 0x40080
	s_addc_u32 s15, s27, 0
	s_add_i32 s16, s17, s43
	s_mov_b32 m0, s16
	s_nop 0
	global_load_lds_dwordx4 v128, s[14:15]
	s_add_i32 m0, s16, 0x2000
	s_nop 0
	global_load_lds_dwordx4 v148, s[14:15]
	s_waitcnt vmcnt(6)
	s_barrier
	v_mfma_f32_16x16x32_bf16 v[52:55], v[220:223], v[178:181], v[52:55]
	v_mfma_f32_16x16x32_bf16 v[48:51], v[228:231], v[178:181], v[48:51]
	v_mfma_f32_16x16x32_bf16 v[36:39], v[220:223], v[196:199], v[36:39]
	v_mfma_f32_16x16x32_bf16 v[32:35], v[228:231], v[196:199], v[32:35]
	v_mfma_f32_16x16x32_bf16 v[20:23], v[220:223], v[204:207], v[20:23]
	v_mfma_f32_16x16x32_bf16 v[16:19], v[228:231], v[204:207], v[16:19]
	v_mfma_f32_16x16x32_bf16 v[4:7], v[220:223], v[212:215], v[4:7]
	v_mfma_f32_16x16x32_bf16 v[0:3], v[228:231], v[212:215], v[0:3]
	v_mfma_f32_16x16x32_bf16 v[52:55], v[224:227], v[192:195], v[52:55]
	v_mfma_f32_16x16x32_bf16 v[48:51], v[232:235], v[192:195], v[48:51]
	v_mfma_f32_16x16x32_bf16 v[36:39], v[224:227], v[200:203], v[36:39]
	v_mfma_f32_16x16x32_bf16 v[32:35], v[232:235], v[200:203], v[32:35]
	v_mfma_f32_16x16x32_bf16 v[20:23], v[224:227], v[208:211], v[20:23]
	v_mfma_f32_16x16x32_bf16 v[16:19], v[232:235], v[208:211], v[16:19]
	v_mfma_f32_16x16x32_bf16 v[4:7], v[224:227], v[216:219], v[4:7]
	v_mfma_f32_16x16x32_bf16 v[0:3], v[232:235], v[216:219], v[0:3]
	s_add_i32 s61, s61, 2
	s_add_u32 s24, s24, 0x100
	s_addc_u32 s25, s25, 0
	s_add_u32 s59, s59, 0x100
	s_addc_u32 s60, s60, 0
	s_cmp_gt_u32 s61, 13
	s_barrier
	s_cbranch_scc0 .LBB0_495
	v_lshl_add_u32 v162, s22, 8, v139
	v_ashrrev_i32_e32 v163, 31, v162
	v_lshl_add_u64 v[158:159], v[162:163], 2, s[0:1]
	global_load_dword v164, v[158:159], off
	global_load_dword v193, v[158:159], off offset:64
	global_load_dword v194, v[158:159], off offset:128
	global_load_dword v195, v[158:159], off offset:192
	global_load_dword v196, v[158:159], off offset:512
	global_load_dword v197, v[158:159], off offset:576
	global_load_dword v198, v[158:159], off offset:640
	global_load_dword v199, v[158:159], off offset:704
	v_lshl_or_b32 v160, s56, 8, v167
	v_ashrrev_i32_e32 v161, 31, v160
	s_mov_b32 s5, 0x80000
	s_mov_b64 s[14:15], 0x80000
	s_mov_b32 s56, s4
	s_mov_b32 s22, s6
	s_mov_b64 s[26:27], s[20:21]
	s_mov_b64 s[24:25], s[12:13]
	s_waitcnt vmcnt(0)
	v_fmamk_f32 v164, v164, 0x3a800000, v187
	v_cmp_gt_f32_e32 vcc, s67, v164
	v_mul_f32_e32 v165, 0x4b800000, v164
	s_nop 0
	v_cndmask_b32_e32 v164, v164, v165, vcc
	v_rsq_f32_e32 v164, v164
	s_nop 0
	v_mul_f32_e32 v165, 0x45800000, v164
	v_cndmask_b32_e32 v170, v164, v165, vcc
	v_lshlrev_b64 v[164:165], 12, v[162:163]
	v_lshl_add_u64 v[172:173], s[2:3], 0, v[164:165]
	v_lshlrev_b64 v[164:165], 1, v[160:161]
	v_lshl_add_u64 v[160:161], v[172:173], 0, v[164:165]
	v_pk_mul_f32 v[126:127], v[126:127], v[170:171] op_sel_hi:[1,0]
	v_pk_mul_f32 v[124:125], v[124:125], v[170:171] op_sel_hi:[1,0]
	v_pk_mul_f32 v[172:173], v[122:123], v[170:171] op_sel_hi:[1,0]
	v_pk_mul_f32 v[122:123], v[120:121], v[170:171] op_sel_hi:[1,0]
	v_cvt_pk_bf16_f32 v120, v124, v125
	v_cvt_pk_bf16_f32 v121, v126, v127
	v_cvt_pk_bf16_f32 v122, v122, v123
	v_cvt_pk_bf16_f32 v123, v172, v173
	global_store_dwordx4 v[160:161], v[120:123], off
	v_pk_mul_f32 v[118:119], v[118:119], v[170:171] op_sel_hi:[1,0]
	v_pk_mul_f32 v[116:117], v[116:117], v[170:171] op_sel_hi:[1,0]
	v_pk_mul_f32 v[120:121], v[114:115], v[170:171] op_sel_hi:[1,0]
	v_pk_mul_f32 v[114:115], v[112:113], v[170:171] op_sel_hi:[1,0]
	v_cvt_pk_bf16_f32 v112, v116, v117
	v_cvt_pk_bf16_f32 v113, v118, v119
	v_cvt_pk_bf16_f32 v114, v114, v115
	v_cvt_pk_bf16_f32 v115, v120, v121
	global_store_dwordx4 v[160:161], v[112:115], off offset:256
	s_nop 1
	v_mov_b32_e32 v114, v193
	s_nop 0
	v_or_b32_e32 v112, 16, v162
	v_ashrrev_i32_e32 v113, 31, v112
	v_lshlrev_b64 v[112:113], 12, v[112:113]
	v_lshl_add_u64 v[112:113], s[2:3], 0, v[112:113]
	v_lshl_add_u64 v[112:113], v[112:113], 0, v[164:165]
	v_fmamk_f32 v114, v114, 0x3a800000, v187
	v_cmp_gt_f32_e32 vcc, s67, v114
	v_mul_f32_e32 v115, 0x4b800000, v114
	s_nop 0
	v_cndmask_b32_e32 v114, v114, v115, vcc
	v_rsq_f32_e32 v114, v114
	s_nop 0
	v_mul_f32_e32 v115, 0x45800000, v114
	v_cndmask_b32_e32 v114, v114, v115, vcc
	v_pk_mul_f32 v[110:111], v[110:111], v[114:115] op_sel_hi:[1,0]
	v_pk_mul_f32 v[108:109], v[108:109], v[114:115] op_sel_hi:[1,0]
	v_pk_mul_f32 v[116:117], v[106:107], v[114:115] op_sel_hi:[1,0]
	v_pk_mul_f32 v[106:107], v[104:105], v[114:115] op_sel_hi:[1,0]
	v_cvt_pk_bf16_f32 v104, v108, v109
	v_cvt_pk_bf16_f32 v105, v110, v111
	v_cvt_pk_bf16_f32 v106, v106, v107
	v_cvt_pk_bf16_f32 v107, v116, v117
	global_store_dwordx4 v[112:113], v[104:107], off
	v_pk_mul_f32 v[102:103], v[102:103], v[114:115] op_sel_hi:[1,0]
	v_pk_mul_f32 v[100:101], v[100:101], v[114:115] op_sel_hi:[1,0]
	v_pk_mul_f32 v[104:105], v[98:99], v[114:115] op_sel_hi:[1,0]
	v_pk_mul_f32 v[98:99], v[96:97], v[114:115] op_sel_hi:[1,0]
	v_cvt_pk_bf16_f32 v96, v100, v101
	v_cvt_pk_bf16_f32 v97, v102, v103
	v_cvt_pk_bf16_f32 v98, v98, v99
	v_cvt_pk_bf16_f32 v99, v104, v105
	global_store_dwordx4 v[112:113], v[96:99], off offset:256
	s_nop 1
	v_mov_b32_e32 v98, v194
	s_nop 0
	v_or_b32_e32 v96, 32, v162
	v_ashrrev_i32_e32 v97, 31, v96
	v_lshlrev_b64 v[96:97], 12, v[96:97]
	v_lshl_add_u64 v[96:97], s[2:3], 0, v[96:97]
	v_lshl_add_u64 v[96:97], v[96:97], 0, v[164:165]
	v_fmamk_f32 v98, v98, 0x3a800000, v187
	v_cmp_gt_f32_e32 vcc, s67, v98
	v_mul_f32_e32 v99, 0x4b800000, v98
	s_nop 0
	v_cndmask_b32_e32 v98, v98, v99, vcc
	v_rsq_f32_e32 v98, v98
	s_nop 0
	v_mul_f32_e32 v99, 0x45800000, v98
	v_cndmask_b32_e32 v98, v98, v99, vcc
	v_pk_mul_f32 v[94:95], v[94:95], v[98:99] op_sel_hi:[1,0]
; __device__ __forceinline__ unsigned cvt_pk_bf16(float lo, float hi) { const f32x2_cv v = {lo, hi}; const bf16x2_cv b = __builtin_convertvector(v, bf16x2_cv); return __builtin_bit_cast(unsigned, b); }
; __device__ __forceinline__ float rstd_of(const float* rowss, int row) { return rsqrtf(rowss[row] * (1.0f / 1024.0f) + 1e-6f); }
;     __device__ __forceinline__ void operator()(const f32x4 (&acc)[2][2][4][2], const pg8::Unit& u, int wr, int wc, int fr, int fq) const {
;     ...
;             for (int m = 0; m < 4; ++m) {
;                 const int row = row0 + ai * 128 + m * 16;
;                 const float s = (MODE == 2) ? 1.0f : rstd_of(rowss, row);
;                 bf16_t* rowp = O + (size_t)row * ldc + col0;
; #pragma unroll
;                 for (int bj = 0; bj < 2; ++bj) {
;                     f32x4 v0 = acc[ai][bj][m][0] * s, v1 = acc[ai][bj][m][1] * s;
;                     if (MODE == 1) {
; #pragma unroll
;                         for (int j = 0; j < 4; ++j) { const float a = fmaxf(v0[j], 0.f), b = fmaxf(v1[j], 0.f); v0[j] = a * a; v1[j] = b * b; } }
;                     u32x4 w; w.x = cvt_pk_bf16(v0[0], v0[1]); w.y = cvt_pk_bf16(v0[2], v0[3]); w.z = cvt_pk_bf16(v1[0], v1[1]); w.w = cvt_pk_bf16(v1[2], v1[3]);
;                     *(u32x4*)(rowp + bj * 128) = w; } }
	v_pk_mul_f32 v[92:93], v[92:93], v[98:99] op_sel_hi:[1,0]
	v_pk_mul_f32 v[100:101], v[90:91], v[98:99] op_sel_hi:[1,0]
	v_pk_mul_f32 v[90:91], v[88:89], v[98:99] op_sel_hi:[1,0]
	v_cvt_pk_bf16_f32 v88, v92, v93
	v_cvt_pk_bf16_f32 v89, v94, v95
	v_cvt_pk_bf16_f32 v90, v90, v91
	v_cvt_pk_bf16_f32 v91, v100, v101
	global_store_dwordx4 v[96:97], v[88:91], off
	v_pk_mul_f32 v[86:87], v[86:87], v[98:99] op_sel_hi:[1,0]
	v_pk_mul_f32 v[84:85], v[84:85], v[98:99] op_sel_hi:[1,0]
	v_pk_mul_f32 v[88:89], v[82:83], v[98:99] op_sel_hi:[1,0]
	v_pk_mul_f32 v[82:83], v[80:81], v[98:99] op_sel_hi:[1,0]
	v_cvt_pk_bf16_f32 v80, v84, v85
	v_cvt_pk_bf16_f32 v81, v86, v87
	v_cvt_pk_bf16_f32 v82, v82, v83
	v_cvt_pk_bf16_f32 v83, v88, v89
	global_store_dwordx4 v[96:97], v[80:83], off offset:256
	s_nop 1
	v_mov_b32_e32 v82, v195
	s_nop 0
	v_or_b32_e32 v80, 48, v162
	v_ashrrev_i32_e32 v81, 31, v80
	v_lshlrev_b64 v[80:81], 12, v[80:81]
	v_lshl_add_u64 v[80:81], s[2:3], 0, v[80:81]
	v_lshl_add_u64 v[80:81], v[80:81], 0, v[164:165]
	v_fmamk_f32 v82, v82, 0x3a800000, v187
	v_cmp_gt_f32_e32 vcc, s67, v82
	v_mul_f32_e32 v83, 0x4b800000, v82
	s_nop 0
	v_cndmask_b32_e32 v82, v82, v83, vcc
	v_rsq_f32_e32 v82, v82
	s_nop 0
	v_mul_f32_e32 v83, 0x45800000, v82
	v_cndmask_b32_e32 v82, v82, v83, vcc
	v_pk_mul_f32 v[78:79], v[78:79], v[82:83] op_sel_hi:[1,0]
	v_pk_mul_f32 v[76:77], v[76:77], v[82:83] op_sel_hi:[1,0]
	v_pk_mul_f32 v[84:85], v[74:75], v[82:83] op_sel_hi:[1,0]
	v_pk_mul_f32 v[74:75], v[72:73], v[82:83] op_sel_hi:[1,0]
	v_cvt_pk_bf16_f32 v72, v76, v77
	v_cvt_pk_bf16_f32 v73, v78, v79
	v_cvt_pk_bf16_f32 v74, v74, v75
	v_cvt_pk_bf16_f32 v75, v84, v85
	global_store_dwordx4 v[80:81], v[72:75], off
	v_pk_mul_f32 v[70:71], v[70:71], v[82:83] op_sel_hi:[1,0]
	v_pk_mul_f32 v[68:69], v[68:69], v[82:83] op_sel_hi:[1,0]
	v_pk_mul_f32 v[72:73], v[66:67], v[82:83] op_sel_hi:[1,0]
	v_pk_mul_f32 v[66:67], v[64:65], v[82:83] op_sel_hi:[1,0]
	v_cvt_pk_bf16_f32 v64, v68, v69
	v_cvt_pk_bf16_f32 v65, v70, v71
	v_cvt_pk_bf16_f32 v66, v66, v67
	v_cvt_pk_bf16_f32 v67, v72, v73
	global_store_dwordx4 v[80:81], v[64:67], off offset:256
	s_nop 1
	v_mov_b32_e32 v64, v196
	s_nop 0
	v_lshl_add_u64 v[66:67], v[160:161], 0, s[14:15]
	s_mov_b64 s[14:15], 0x90000
	v_fmamk_f32 v64, v64, 0x3a800000, v187
	v_cmp_gt_f32_e32 vcc, s67, v64
	v_mul_f32_e32 v65, 0x4b800000, v64
	s_nop 0
	v_cndmask_b32_e32 v64, v64, v65, vcc
	v_rsq_f32_e32 v64, v64
	s_nop 0
	v_mul_f32_e32 v65, 0x45800000, v64
	v_cndmask_b32_e32 v64, v64, v65, vcc
	v_pk_mul_f32 v[60:61], v[60:61], v[64:65] op_sel_hi:[1,0]
	v_pk_mul_f32 v[62:63], v[62:63], v[64:65] op_sel_hi:[1,0]
	v_pk_mul_f32 v[68:69], v[58:59], v[64:65] op_sel_hi:[1,0]
	v_pk_mul_f32 v[58:59], v[56:57], v[64:65] op_sel_hi:[1,0]
	v_cvt_pk_bf16_f32 v56, v60, v61
	v_add_co_u32_e32 v60, vcc, s5, v160
	v_cvt_pk_bf16_f32 v57, v62, v63
	v_cvt_pk_bf16_f32 v58, v58, v59
	v_cvt_pk_bf16_f32 v59, v68, v69
	v_addc_co_u32_e32 v61, vcc, 0, v161, vcc
	global_store_dwordx4 v[60:61], v[56:59], off
	v_pk_mul_f32 v[54:55], v[54:55], v[64:65] op_sel_hi:[1,0]
	v_pk_mul_f32 v[52:53], v[52:53], v[64:65] op_sel_hi:[1,0]
	v_pk_mul_f32 v[56:57], v[50:51], v[64:65] op_sel_hi:[1,0]
	v_pk_mul_f32 v[50:51], v[48:49], v[64:65] op_sel_hi:[1,0]
	v_cvt_pk_bf16_f32 v48, v52, v53
	v_cvt_pk_bf16_f32 v49, v54, v55
	v_cvt_pk_bf16_f32 v50, v50, v51
	v_cvt_pk_bf16_f32 v51, v56, v57
	global_store_dwordx4 v[66:67], v[48:51], off offset:256
	s_nop 1
	v_mov_b32_e32 v48, v197
	s_mov_b32 s5, 0x90000
	v_lshl_add_u64 v[50:51], v[160:161], 0, s[14:15]
	s_mov_b64 s[14:15], 0xa0000
	v_fmamk_f32 v48, v48, 0x3a800000, v187
	v_cmp_gt_f32_e32 vcc, s67, v48
	v_mul_f32_e32 v49, 0x4b800000, v48
	s_nop 0
	v_cndmask_b32_e32 v48, v48, v49, vcc
; __device__ __forceinline__ unsigned cvt_pk_bf16(float lo, float hi) { const f32x2_cv v = {lo, hi}; const bf16x2_cv b = __builtin_convertvector(v, bf16x2_cv); return __builtin_bit_cast(unsigned, b); }
; #define PG8_WAIT_V(n) asm volatile("s_waitcnt vmcnt(" #n ")" ::: "memory")
; #define PG8_BAR __builtin_amdgcn_s_barrier()
; __device__ __forceinline__ float rstd_of(const float* rowss, int row) { return rsqrtf(rowss[row] * (1.0f / 1024.0f) + 1e-6f); }
; template <class Epi, class Sched, bool STAMP = false>
; __device__ __forceinline__ void gemm_phase(PG8_LAS unsigned char* lds, const Gemm g, const Sched& S, const Epi& E, unsigned long long* stamps) {
;     ...
;         if constexpr (!Epi::AFTER_DRAIN) { E(acc, cur, wr, wc, fr, fq); S.done(cur); }
;         if (!has_next) break;
; #pragma unroll
;         for (int a = 0; a < 2; ++a)
; #pragma unroll
;             for (int b = 0; b < 2; ++b)
; #pragma unroll
;                 for (int m = 0; m < 4; ++m)
; #pragma unroll
;                     for (int n = 0; n < 2; ++n) acc[a][b][m][n] = (f32x4){0.f, 0.f, 0.f, 0.f};
;         cur = nxt; cA = nA; cB = nB; ++ui;
;     }
;     PG8_WAIT_V(0);
;     if (wr == 0) PG8_BAR;
;     PG8_BAR;
;     __device__ __forceinline__ void operator()(const f32x4 (&acc)[2][2][4][2], const pg8::Unit& u, int wr, int wc, int fr, int fq) const {
;         const int row0 = u.pm * 256 + wr * 64 + fr, col0 = u.pn * 256 + wc * 32 + 8 * fq;
; #pragma unroll
;         for (int ai = 0; ai < 2; ++ai)
; #pragma unroll
;             for (int m = 0; m < 4; ++m) {
;                 const int row = row0 + ai * 128 + m * 16;
;                 const float s = (MODE == 2) ? 1.0f : rstd_of(rowss, row);
;                 bf16_t* rowp = O + (size_t)row * ldc + col0;
; #pragma unroll
;                 for (int bj = 0; bj < 2; ++bj) {
;                     f32x4 v0 = acc[ai][bj][m][0] * s, v1 = acc[ai][bj][m][1] * s;
;                     if (MODE == 1) {
; #pragma unroll
;                         for (int j = 0; j < 4; ++j) { const float a = fmaxf(v0[j], 0.f), b = fmaxf(v1[j], 0.f); v0[j] = a * a; v1[j] = b * b; } }
;                     u32x4 w; w.x = cvt_pk_bf16(v0[0], v0[1]); w.y = cvt_pk_bf16(v0[2], v0[3]); w.z = cvt_pk_bf16(v1[0], v1[1]); w.w = cvt_pk_bf16(v1[2], v1[3]);
;                     *(u32x4*)(rowp + bj * 128) = w; } }
	v_rsq_f32_e32 v48, v48
	s_nop 0
	v_mul_f32_e32 v49, 0x45800000, v48
	v_cndmask_b32_e32 v48, v48, v49, vcc
	v_pk_mul_f32 v[44:45], v[44:45], v[48:49] op_sel_hi:[1,0]
	v_pk_mul_f32 v[46:47], v[46:47], v[48:49] op_sel_hi:[1,0]
	v_pk_mul_f32 v[52:53], v[42:43], v[48:49] op_sel_hi:[1,0]
	v_pk_mul_f32 v[42:43], v[40:41], v[48:49] op_sel_hi:[1,0]
	v_cvt_pk_bf16_f32 v40, v44, v45
	v_add_co_u32_e32 v44, vcc, s5, v160
	v_cvt_pk_bf16_f32 v41, v46, v47
	v_cvt_pk_bf16_f32 v42, v42, v43
	v_cvt_pk_bf16_f32 v43, v52, v53
	v_addc_co_u32_e32 v45, vcc, 0, v161, vcc
	global_store_dwordx4 v[44:45], v[40:43], off
	v_pk_mul_f32 v[38:39], v[38:39], v[48:49] op_sel_hi:[1,0]
	v_pk_mul_f32 v[36:37], v[36:37], v[48:49] op_sel_hi:[1,0]
	v_pk_mul_f32 v[40:41], v[34:35], v[48:49] op_sel_hi:[1,0]
	v_pk_mul_f32 v[34:35], v[32:33], v[48:49] op_sel_hi:[1,0]
	v_cvt_pk_bf16_f32 v32, v36, v37
	v_cvt_pk_bf16_f32 v33, v38, v39
	v_cvt_pk_bf16_f32 v34, v34, v35
	v_cvt_pk_bf16_f32 v35, v40, v41
	global_store_dwordx4 v[50:51], v[32:35], off offset:256
	s_nop 1
	v_mov_b32_e32 v32, v198
	s_mov_b32 s5, 0xa0000
	v_lshl_add_u64 v[34:35], v[160:161], 0, s[14:15]
	s_mov_b64 s[14:15], 0xb0000
	v_fmamk_f32 v32, v32, 0x3a800000, v187
	v_cmp_gt_f32_e32 vcc, s67, v32
	v_mul_f32_e32 v33, 0x4b800000, v32
	s_nop 0
	v_cndmask_b32_e32 v32, v32, v33, vcc
	v_rsq_f32_e32 v32, v32
	s_nop 0
	v_mul_f32_e32 v33, 0x45800000, v32
	v_cndmask_b32_e32 v32, v32, v33, vcc
	v_pk_mul_f32 v[28:29], v[28:29], v[32:33] op_sel_hi:[1,0]
	v_pk_mul_f32 v[30:31], v[30:31], v[32:33] op_sel_hi:[1,0]
	v_pk_mul_f32 v[36:37], v[26:27], v[32:33] op_sel_hi:[1,0]
	v_pk_mul_f32 v[26:27], v[24:25], v[32:33] op_sel_hi:[1,0]
	v_cvt_pk_bf16_f32 v24, v28, v29
	v_add_co_u32_e32 v28, vcc, s5, v160
	v_cvt_pk_bf16_f32 v25, v30, v31
	v_cvt_pk_bf16_f32 v26, v26, v27
	v_cvt_pk_bf16_f32 v27, v36, v37
	v_addc_co_u32_e32 v29, vcc, 0, v161, vcc
	global_store_dwordx4 v[28:29], v[24:27], off
	v_pk_mul_f32 v[22:23], v[22:23], v[32:33] op_sel_hi:[1,0]
	v_pk_mul_f32 v[20:21], v[20:21], v[32:33] op_sel_hi:[1,0]
	v_pk_mul_f32 v[24:25], v[18:19], v[32:33] op_sel_hi:[1,0]
	v_pk_mul_f32 v[18:19], v[16:17], v[32:33] op_sel_hi:[1,0]
	v_cvt_pk_bf16_f32 v16, v20, v21
	v_cvt_pk_bf16_f32 v17, v22, v23
	v_cvt_pk_bf16_f32 v18, v18, v19
	v_cvt_pk_bf16_f32 v19, v24, v25
	global_store_dwordx4 v[34:35], v[16:19], off offset:256
	s_nop 1
	v_mov_b32_e32 v16, v199
	s_mov_b32 s5, 0xb0000
	v_lshl_add_u64 v[18:19], v[160:161], 0, s[14:15]
	v_fmamk_f32 v16, v16, 0x3a800000, v187
	v_cmp_gt_f32_e32 vcc, s67, v16
	v_mul_f32_e32 v17, 0x4b800000, v16
	s_nop 0
	v_cndmask_b32_e32 v16, v16, v17, vcc
	v_rsq_f32_e32 v16, v16
	s_nop 0
	v_mul_f32_e32 v17, 0x45800000, v16
	v_cndmask_b32_e32 v16, v16, v17, vcc
	v_pk_mul_f32 v[12:13], v[12:13], v[16:17] op_sel_hi:[1,0]
	v_pk_mul_f32 v[14:15], v[14:15], v[16:17] op_sel_hi:[1,0]
	v_pk_mul_f32 v[20:21], v[10:11], v[16:17] op_sel_hi:[1,0]
	v_pk_mul_f32 v[10:11], v[8:9], v[16:17] op_sel_hi:[1,0]
	v_cvt_pk_bf16_f32 v8, v12, v13
	v_add_co_u32_e32 v12, vcc, s5, v160
	v_cvt_pk_bf16_f32 v9, v14, v15
	v_cvt_pk_bf16_f32 v10, v10, v11
	v_cvt_pk_bf16_f32 v11, v20, v21
	v_addc_co_u32_e32 v13, vcc, 0, v161, vcc
	global_store_dwordx4 v[12:13], v[8:11], off
	v_pk_mul_f32 v[6:7], v[6:7], v[16:17] op_sel_hi:[1,0]
	v_pk_mul_f32 v[4:5], v[4:5], v[16:17] op_sel_hi:[1,0]
	v_pk_mul_f32 v[8:9], v[2:3], v[16:17] op_sel_hi:[1,0]
	v_pk_mul_f32 v[2:3], v[0:1], v[16:17] op_sel_hi:[1,0]
	v_cvt_pk_bf16_f32 v0, v4, v5
	v_cvt_pk_bf16_f32 v1, v6, v7
	v_cvt_pk_bf16_f32 v2, v2, v3
	v_cvt_pk_bf16_f32 v3, v8, v9
	s_and_b64 vcc, exec, s[38:39]
	global_store_dwordx4 v[18:19], v[0:3], off offset:256
	s_cbranch_vccz .LBB0_492
	s_waitcnt vmcnt(0)
	s_cmpk_gt_u32 s36, 0xff
	s_cbranch_scc1 .LBB0_499
	s_barrier

; #define PG8_STAGE(bufoff, gbase, voff) do { _Pragma("unroll") for (int _i = 0; _i < 2; ++_i) \
;         __builtin_amdgcn_global_load_lds((const unsigned*)((const char*)(gbase) + (voff)[_i]), (PG8_LAS unsigned*)(lds + (bufoff) + ldsw + _i * 8192), 16, 0, 0); } while (0)
; #define PG8_LDA(dst, b, h) do { _Pragma("unroll") for (int m = 0; m < 4; ++m) _Pragma("unroll") for (int k = 0; k < 2; ++k) dst[m][k] = *(const PG8_LAS bf16x8*)(lds + PG8_SA(b, h) + aoff + m * 2048 + k * 1024); } while (0)
; #define PG8_LDB(dst, b, h) do { _Pragma("unroll") for (int n = 0; n < 2; ++n) _Pragma("unroll") for (int k = 0; k < 2; ++k) dst[n][k] = *(const PG8_LAS bf16x8*)(lds + PG8_SB(b, h) + boff + n * 2048 + k * 1024); } while (0)
; #define PG8_MMA(ai, bj, At, Bt) do { __builtin_amdgcn_s_setprio(1); _Pragma("unroll") for (int m = 0; m < 4; ++m) _Pragma("unroll") for (int n = 0; n < 2; ++n) _Pragma("unroll") for (int k = 0; k < 2; ++k) \
;         acc[ai][bj][m][n] = __builtin_amdgcn_mfma_f32_16x16x32_bf16(Bt[n][k], At[m][k], acc[ai][bj][m][n], 0, 0, 0); __builtin_amdgcn_s_setprio(0); } while (0)
; #define PG8_WAIT_V(n) asm volatile("s_waitcnt vmcnt(" #n ")" ::: "memory")
; #define PG8_WAIT_L(n) asm volatile("s_waitcnt lgkmcnt(" #n ")" ::: "memory")
; #define PG8_BAR __builtin_amdgcn_s_barrier()
; #define PG8_SCHED __builtin_amdgcn_sched_barrier(0)
; template <class Epi, class Sched, bool STAMP = false>
; __device__ __forceinline__ void gemm_phase(PG8_LAS unsigned char* lds, const Gemm g, const Sched& S, const Epi& E, unsigned long long* stamps) {
;     ...
;             PG8_LDB(B0, 0, 0); PG8_SCHED; PG8_LDA(At, 0, 0); PG8_STAGE(PG8_SA(1, 1), a1 + hstep, voffA);
;             PG8_WAIT_L(8); PG8_BAR; PG8_WAIT_L(0); PG8_MMA(0, 0, At, B0); PG8_BAR; PG8_SCHED;
;             PG8_LDB(B1, 0, 1); PG8_STAGE(PG8_SB(0, 0), b2, voffB);
;             PG8_BAR; PG8_WAIT_L(0); PG8_MMA(0, 1, At, B1); PG8_BAR;
;             PG8_LDA(At, 0, 1); PG8_STAGE(PG8_SA(0, 0), a2, voffA);
;             PG8_BAR; PG8_WAIT_L(0); PG8_MMA(1, 0, At, B0); PG8_BAR; PG8_SCHED;
;             PG8_STAGE(PG8_SB(0, 1), b2 + hstep, voffB);
;             PG8_WAIT_V(6); PG8_BAR; PG8_MMA(1, 1, At, B1); PG8_BAR;
.LBB0_1183:
	s_add_u32 s30, s26, 0x100
	s_addc_u32 s31, s27, 0
	s_add_i32 s14, 0, 0x10000
	ds_read_b128 v[154:157], v248
	ds_read_b128 v[162:165], v248 offset:1024
	ds_read_b128 v[166:169], v248 offset:2048
	ds_read_b128 v[170:173], v248 offset:3072
	s_cmp_eq_u32 s65, 60
	s_cselect_b32 s37, s7, s31
	s_cselect_b32 s36, s23, s30
	s_cselect_b32 s35, s5, s64
	s_cselect_b32 s34, s62, s63
	s_add_i32 m0, s25, 0xc000
	ds_read_b128 v[174:177], v160
	ds_read_b128 v[178:181], v160 offset:1024
	ds_read_b128 v[192:195], v160 offset:2048
	ds_read_b128 v[196:199], v160 offset:3072
	ds_read_b128 v[200:203], v160 offset:4096
	ds_read_b128 v[204:207], v160 offset:5120
	ds_read_b128 v[208:211], v160 offset:6144
	global_load_lds_dwordx4 v150, s[26:27]
	s_add_i32 m0, s25, 0xe000
	ds_read_b128 v[212:215], v160 offset:7168
	global_load_lds_dwordx4 v152, s[26:27]
	s_waitcnt lgkmcnt(8)
	s_barrier
	s_waitcnt lgkmcnt(0)
	v_mfma_f32_16x16x32_bf16 v[124:127], v[154:157], v[174:177], v[124:127]
	v_mfma_f32_16x16x32_bf16 v[120:123], v[166:169], v[174:177], v[120:123]
	v_mfma_f32_16x16x32_bf16 v[108:111], v[154:157], v[192:195], v[108:111]
	v_mfma_f32_16x16x32_bf16 v[104:107], v[166:169], v[192:195], v[104:107]
	v_mfma_f32_16x16x32_bf16 v[92:95], v[154:157], v[200:203], v[92:95]
	v_mfma_f32_16x16x32_bf16 v[88:91], v[166:169], v[200:203], v[88:91]
	v_mfma_f32_16x16x32_bf16 v[76:79], v[154:157], v[208:211], v[76:79]
	v_mfma_f32_16x16x32_bf16 v[72:75], v[166:169], v[208:211], v[72:75]
	v_mfma_f32_16x16x32_bf16 v[124:127], v[162:165], v[178:181], v[124:127]
	v_mfma_f32_16x16x32_bf16 v[120:123], v[170:173], v[178:181], v[120:123]
	v_mfma_f32_16x16x32_bf16 v[108:111], v[162:165], v[196:199], v[108:111]
	v_mfma_f32_16x16x32_bf16 v[104:107], v[170:173], v[196:199], v[104:107]
	v_mfma_f32_16x16x32_bf16 v[92:95], v[162:165], v[204:207], v[92:95]
	v_mfma_f32_16x16x32_bf16 v[88:91], v[170:173], v[204:207], v[88:91]
	v_mfma_f32_16x16x32_bf16 v[76:79], v[162:165], v[212:215], v[76:79]
	v_mfma_f32_16x16x32_bf16 v[72:75], v[170:173], v[212:215], v[72:75]
	s_barrier
	s_add_i32 s16, 0, 0x14000
	s_add_i32 s14, s14, s49
	s_mov_b32 m0, s14
	ds_read_b128 v[216:219], v249
	ds_read_b128 v[220:223], v249 offset:1024
	ds_read_b128 v[224:227], v249 offset:2048
	global_load_lds_dwordx4 v128, s[34:35]
	s_add_i32 m0, s14, 0x2000
	ds_read_b128 v[228:231], v249 offset:3072
	global_load_lds_dwordx4 v148, s[34:35]
	s_barrier
	s_waitcnt lgkmcnt(0)
	v_mfma_f32_16x16x32_bf16 v[116:119], v[216:219], v[174:177], v[116:119]
	v_mfma_f32_16x16x32_bf16 v[112:115], v[224:227], v[174:177], v[112:115]
	v_mfma_f32_16x16x32_bf16 v[100:103], v[216:219], v[192:195], v[100:103]
	v_mfma_f32_16x16x32_bf16 v[96:99], v[224:227], v[192:195], v[96:99]
	v_mfma_f32_16x16x32_bf16 v[84:87], v[216:219], v[200:203], v[84:87]
	v_mfma_f32_16x16x32_bf16 v[80:83], v[224:227], v[200:203], v[80:83]
	v_mfma_f32_16x16x32_bf16 v[68:71], v[216:219], v[208:211], v[68:71]
	v_mfma_f32_16x16x32_bf16 v[64:67], v[224:227], v[208:211], v[64:67]
	v_mfma_f32_16x16x32_bf16 v[116:119], v[220:223], v[178:181], v[116:119]
	v_mfma_f32_16x16x32_bf16 v[112:115], v[228:231], v[178:181], v[112:115]
	v_mfma_f32_16x16x32_bf16 v[100:103], v[220:223], v[196:199], v[100:103]
	v_mfma_f32_16x16x32_bf16 v[96:99], v[228:231], v[196:199], v[96:99]
	v_mfma_f32_16x16x32_bf16 v[84:87], v[220:223], v[204:207], v[84:87]
	v_mfma_f32_16x16x32_bf16 v[80:83], v[228:231], v[204:207], v[80:83]
	v_mfma_f32_16x16x32_bf16 v[68:71], v[220:223], v[212:215], v[68:71]
	v_mfma_f32_16x16x32_bf16 v[64:67], v[228:231], v[212:215], v[64:67]
	s_mov_b32 m0, s25
	s_barrier
	ds_read_b128 v[174:177], v160 offset:16384
	ds_read_b128 v[178:181], v160 offset:17408
	ds_read_b128 v[192:195], v160 offset:18432
	ds_read_b128 v[196:199], v160 offset:19456
	ds_read_b128 v[200:203], v160 offset:20480
	ds_read_b128 v[204:207], v160 offset:21504
	ds_read_b128 v[208:211], v160 offset:22528
	global_load_lds_dwordx4 v128, s[36:37]
	s_mov_b32 m0, s53
	ds_read_b128 v[212:215], v160 offset:23552
	global_load_lds_dwordx4 v148, s[36:37]
	s_barrier
	s_waitcnt lgkmcnt(0)
	v_mfma_f32_16x16x32_bf16 v[60:63], v[154:157], v[174:177], v[60:63]
	v_mfma_f32_16x16x32_bf16 v[56:59], v[166:169], v[174:177], v[56:59]
	v_mfma_f32_16x16x32_bf16 v[44:47], v[154:157], v[192:195], v[44:47]
	v_mfma_f32_16x16x32_bf16 v[40:43], v[166:169], v[192:195], v[40:43]
	v_mfma_f32_16x16x32_bf16 v[28:31], v[154:157], v[200:203], v[28:31]
	v_mfma_f32_16x16x32_bf16 v[24:27], v[166:169], v[200:203], v[24:27]
	v_mfma_f32_16x16x32_bf16 v[12:15], v[154:157], v[208:211], v[12:15]
	v_mfma_f32_16x16x32_bf16 v[8:11], v[166:169], v[208:211], v[8:11]
	v_mfma_f32_16x16x32_bf16 v[60:63], v[162:165], v[178:181], v[60:63]
	v_mfma_f32_16x16x32_bf16 v[56:59], v[170:173], v[178:181], v[56:59]
	v_mfma_f32_16x16x32_bf16 v[44:47], v[162:165], v[196:199], v[44:47]
	v_mfma_f32_16x16x32_bf16 v[40:43], v[170:173], v[196:199], v[40:43]
	v_mfma_f32_16x16x32_bf16 v[28:31], v[162:165], v[204:207], v[28:31]
	v_mfma_f32_16x16x32_bf16 v[24:27], v[170:173], v[204:207], v[24:27]
	v_mfma_f32_16x16x32_bf16 v[12:15], v[162:165], v[212:215], v[12:15]
	v_mfma_f32_16x16x32_bf16 v[8:11], v[170:173], v[212:215], v[8:11]
	s_barrier
	s_add_u32 s14, s34, 0x100000
	s_addc_u32 s15, s35, 0
	s_add_i32 s16, s16, s49
	s_mov_b32 m0, s16
	s_nop 0
	global_load_lds_dwordx4 v128, s[14:15]
	s_add_i32 m0, s16, 0x2000
	s_nop 0
	global_load_lds_dwordx4 v148, s[14:15]
	s_waitcnt vmcnt(6)
	s_barrier
; #define PG8_STAGE(bufoff, gbase, voff) do { _Pragma("unroll") for (int _i = 0; _i < 2; ++_i) \
;         __builtin_amdgcn_global_load_lds((const unsigned*)((const char*)(gbase) + (voff)[_i]), (PG8_LAS unsigned*)(lds + (bufoff) + ldsw + _i * 8192), 16, 0, 0); } while (0)
; #define PG8_LDA(dst, b, h) do { _Pragma("unroll") for (int m = 0; m < 4; ++m) _Pragma("unroll") for (int k = 0; k < 2; ++k) dst[m][k] = *(const PG8_LAS bf16x8*)(lds + PG8_SA(b, h) + aoff + m * 2048 + k * 1024); } while (0)
; #define PG8_LDB(dst, b, h) do { _Pragma("unroll") for (int n = 0; n < 2; ++n) _Pragma("unroll") for (int k = 0; k < 2; ++k) dst[n][k] = *(const PG8_LAS bf16x8*)(lds + PG8_SB(b, h) + boff + n * 2048 + k * 1024); } while (0)
; #define PG8_MMA(ai, bj, At, Bt) do { __builtin_amdgcn_s_setprio(1); _Pragma("unroll") for (int m = 0; m < 4; ++m) _Pragma("unroll") for (int n = 0; n < 2; ++n) _Pragma("unroll") for (int k = 0; k < 2; ++k) \
;         acc[ai][bj][m][n] = __builtin_amdgcn_mfma_f32_16x16x32_bf16(Bt[n][k], At[m][k], acc[ai][bj][m][n], 0, 0, 0); __builtin_amdgcn_s_setprio(0); } while (0)
; #define PG8_WAIT_V(n) asm volatile("s_waitcnt vmcnt(" #n ")" ::: "memory")
; #define PG8_WAIT_L(n) asm volatile("s_waitcnt lgkmcnt(" #n ")" ::: "memory")
; #define PG8_BAR __builtin_amdgcn_s_barrier()
; #define PG8_SCHED __builtin_amdgcn_sched_barrier(0)
; template <class Epi, class Sched, bool STAMP = false>
; __device__ __forceinline__ void gemm_phase(PG8_LAS unsigned char* lds, const Gemm g, const Sched& S, const Epi& E, unsigned long long* stamps) {
;     ...
;             PG8_WAIT_V(6); PG8_BAR; PG8_MMA(1, 1, At, B1); PG8_BAR;
;             PG8_LDB(B0, 1, 0); PG8_SCHED; PG8_LDA(At, 1, 0); PG8_STAGE(PG8_SA(0, 1), a2 + hstep, voffA);
;             PG8_WAIT_L(8); PG8_BAR; PG8_WAIT_L(0); PG8_MMA(0, 0, At, B0); PG8_BAR; PG8_SCHED;
;             PG8_LDB(B1, 1, 1); PG8_STAGE(PG8_SB(1, 0), b3, voffB);
;             PG8_BAR; PG8_WAIT_L(0); PG8_MMA(0, 1, At, B1); PG8_BAR;
;             PG8_LDA(At, 1, 1); PG8_STAGE(PG8_SA(1, 0), a3, voffA);
;             PG8_BAR; PG8_WAIT_L(0); PG8_MMA(1, 0, At, B0); PG8_BAR; PG8_SCHED;
	v_mfma_f32_16x16x32_bf16 v[52:55], v[216:219], v[174:177], v[52:55]
	v_mfma_f32_16x16x32_bf16 v[48:51], v[224:227], v[174:177], v[48:51]
	v_mfma_f32_16x16x32_bf16 v[36:39], v[216:219], v[192:195], v[36:39]
	v_mfma_f32_16x16x32_bf16 v[32:35], v[224:227], v[192:195], v[32:35]
	v_mfma_f32_16x16x32_bf16 v[20:23], v[216:219], v[200:203], v[20:23]
	v_mfma_f32_16x16x32_bf16 v[16:19], v[224:227], v[200:203], v[16:19]
	v_mfma_f32_16x16x32_bf16 v[4:7], v[216:219], v[208:211], v[4:7]
	v_mfma_f32_16x16x32_bf16 v[0:3], v[224:227], v[208:211], v[0:3]
	v_mfma_f32_16x16x32_bf16 v[52:55], v[220:223], v[178:181], v[52:55]
	v_mfma_f32_16x16x32_bf16 v[48:51], v[228:231], v[178:181], v[48:51]
	v_mfma_f32_16x16x32_bf16 v[36:39], v[220:223], v[196:199], v[36:39]
	v_mfma_f32_16x16x32_bf16 v[32:35], v[228:231], v[196:199], v[32:35]
	v_mfma_f32_16x16x32_bf16 v[20:23], v[220:223], v[204:207], v[20:23]
	v_mfma_f32_16x16x32_bf16 v[16:19], v[228:231], v[204:207], v[16:19]
	v_mfma_f32_16x16x32_bf16 v[4:7], v[220:223], v[212:215], v[4:7]
	v_mfma_f32_16x16x32_bf16 v[0:3], v[228:231], v[212:215], v[0:3]
	s_add_i32 s16, 0, 0x18000
	s_barrier
	ds_read_b128 v[154:157], v250
	ds_read_b128 v[162:165], v250 offset:1024
	ds_read_b128 v[166:169], v250 offset:2048
	ds_read_b128 v[170:173], v250 offset:3072
	s_add_u32 s14, s36, 0x100000
	s_addc_u32 s15, s37, 0
	s_mov_b32 m0, s56
	ds_read_b128 v[174:177], v160 offset:32768
	ds_read_b128 v[178:181], v160 offset:33792
	ds_read_b128 v[192:195], v160 offset:34816
	ds_read_b128 v[196:199], v160 offset:35840
	ds_read_b128 v[200:203], v160 offset:36864
	ds_read_b128 v[204:207], v160 offset:37888
	ds_read_b128 v[208:211], v160 offset:38912
	global_load_lds_dwordx4 v128, s[14:15]
	s_mov_b32 m0, s57
	ds_read_b128 v[212:215], v160 offset:39936
	global_load_lds_dwordx4 v148, s[14:15]
	s_waitcnt lgkmcnt(8)
	s_barrier
	s_waitcnt lgkmcnt(0)
	v_mfma_f32_16x16x32_bf16 v[124:127], v[154:157], v[174:177], v[124:127]
	v_mfma_f32_16x16x32_bf16 v[120:123], v[166:169], v[174:177], v[120:123]
	v_mfma_f32_16x16x32_bf16 v[108:111], v[154:157], v[192:195], v[108:111]
	v_mfma_f32_16x16x32_bf16 v[104:107], v[166:169], v[192:195], v[104:107]
	v_mfma_f32_16x16x32_bf16 v[92:95], v[154:157], v[200:203], v[92:95]
	v_mfma_f32_16x16x32_bf16 v[88:91], v[166:169], v[200:203], v[88:91]
	v_mfma_f32_16x16x32_bf16 v[76:79], v[154:157], v[208:211], v[76:79]
	v_mfma_f32_16x16x32_bf16 v[72:75], v[166:169], v[208:211], v[72:75]
	v_mfma_f32_16x16x32_bf16 v[124:127], v[162:165], v[178:181], v[124:127]
	v_mfma_f32_16x16x32_bf16 v[120:123], v[170:173], v[178:181], v[120:123]
	v_mfma_f32_16x16x32_bf16 v[108:111], v[162:165], v[196:199], v[108:111]
	v_mfma_f32_16x16x32_bf16 v[104:107], v[170:173], v[196:199], v[104:107]
	v_mfma_f32_16x16x32_bf16 v[92:95], v[162:165], v[204:207], v[92:95]
	v_mfma_f32_16x16x32_bf16 v[88:91], v[170:173], v[204:207], v[88:91]
	v_mfma_f32_16x16x32_bf16 v[76:79], v[162:165], v[212:215], v[76:79]
	v_mfma_f32_16x16x32_bf16 v[72:75], v[170:173], v[212:215], v[72:75]
	s_barrier
	s_add_i32 s17, 0, 0x1c000
	s_add_i32 s14, s16, s49
	s_mov_b32 m0, s14
	ds_read_b128 v[216:219], v251
	ds_read_b128 v[220:223], v251 offset:1024
	ds_read_b128 v[224:227], v251 offset:2048
	global_load_lds_dwordx4 v244, s[34:35]
	s_add_i32 m0, s14, 0x2000
	ds_read_b128 v[228:231], v251 offset:3072
	global_load_lds_dwordx4 v245, s[34:35]
	s_barrier
	s_waitcnt lgkmcnt(0)
	v_mfma_f32_16x16x32_bf16 v[116:119], v[216:219], v[174:177], v[116:119]
	v_mfma_f32_16x16x32_bf16 v[112:115], v[224:227], v[174:177], v[112:115]
	v_mfma_f32_16x16x32_bf16 v[100:103], v[216:219], v[192:195], v[100:103]
	v_mfma_f32_16x16x32_bf16 v[96:99], v[224:227], v[192:195], v[96:99]
	v_mfma_f32_16x16x32_bf16 v[84:87], v[216:219], v[200:203], v[84:87]
	v_mfma_f32_16x16x32_bf16 v[80:83], v[224:227], v[200:203], v[80:83]
	v_mfma_f32_16x16x32_bf16 v[68:71], v[216:219], v[208:211], v[68:71]
	v_mfma_f32_16x16x32_bf16 v[64:67], v[224:227], v[208:211], v[64:67]
	v_mfma_f32_16x16x32_bf16 v[116:119], v[220:223], v[178:181], v[116:119]
	v_mfma_f32_16x16x32_bf16 v[112:115], v[228:231], v[178:181], v[112:115]
	v_mfma_f32_16x16x32_bf16 v[100:103], v[220:223], v[196:199], v[100:103]
	v_mfma_f32_16x16x32_bf16 v[96:99], v[228:231], v[196:199], v[96:99]
	v_mfma_f32_16x16x32_bf16 v[84:87], v[220:223], v[204:207], v[84:87]
	v_mfma_f32_16x16x32_bf16 v[80:83], v[228:231], v[204:207], v[80:83]
	v_mfma_f32_16x16x32_bf16 v[68:71], v[220:223], v[212:215], v[68:71]
	v_mfma_f32_16x16x32_bf16 v[64:67], v[228:231], v[212:215], v[64:67]
	s_mov_b32 m0, s59
	s_barrier
	ds_read_b128 v[174:177], v160 offset:49152
	ds_read_b128 v[178:181], v160 offset:50176
	ds_read_b128 v[192:195], v160 offset:51200
	ds_read_b128 v[196:199], v160 offset:52224
	ds_read_b128 v[200:203], v160 offset:53248
	ds_read_b128 v[204:207], v160 offset:54272
	ds_read_b128 v[208:211], v160 offset:55296
	global_load_lds_dwordx4 v244, s[36:37]
	s_mov_b32 m0, s60
	ds_read_b128 v[212:215], v160 offset:56320
	global_load_lds_dwordx4 v245, s[36:37]
	s_barrier
	s_waitcnt lgkmcnt(0)
	v_mfma_f32_16x16x32_bf16 v[60:63], v[154:157], v[174:177], v[60:63]
	v_mfma_f32_16x16x32_bf16 v[56:59], v[166:169], v[174:177], v[56:59]
	v_mfma_f32_16x16x32_bf16 v[44:47], v[154:157], v[192:195], v[44:47]
	v_mfma_f32_16x16x32_bf16 v[40:43], v[166:169], v[192:195], v[40:43]
	v_mfma_f32_16x16x32_bf16 v[28:31], v[154:157], v[200:203], v[28:31]
	v_mfma_f32_16x16x32_bf16 v[24:27], v[166:169], v[200:203], v[24:27]
	v_mfma_f32_16x16x32_bf16 v[12:15], v[154:157], v[208:211], v[12:15]
	v_mfma_f32_16x16x32_bf16 v[8:11], v[166:169], v[208:211], v[8:11]
	v_mfma_f32_16x16x32_bf16 v[60:63], v[162:165], v[178:181], v[60:63]
	v_mfma_f32_16x16x32_bf16 v[56:59], v[170:173], v[178:181], v[56:59]
	v_mfma_f32_16x16x32_bf16 v[44:47], v[162:165], v[196:199], v[44:47]
	v_mfma_f32_16x16x32_bf16 v[40:43], v[170:173], v[196:199], v[40:43]
	v_mfma_f32_16x16x32_bf16 v[28:31], v[162:165], v[204:207], v[28:31]
	v_mfma_f32_16x16x32_bf16 v[24:27], v[170:173], v[204:207], v[24:27]
	v_mfma_f32_16x16x32_bf16 v[12:15], v[162:165], v[212:215], v[12:15]
	v_mfma_f32_16x16x32_bf16 v[8:11], v[170:173], v[212:215], v[8:11]
	s_barrier
; __device__ __forceinline__ unsigned cvt_pk_bf16(float lo, float hi) { const f32x2_cv v = {lo, hi}; const bf16x2_cv b = __builtin_convertvector(v, bf16x2_cv); return __builtin_bit_cast(unsigned, b); }
; #define PG8_STAGE(bufoff, gbase, voff) do { _Pragma("unroll") for (int _i = 0; _i < 2; ++_i) \
;         __builtin_amdgcn_global_load_lds((const unsigned*)((const char*)(gbase) + (voff)[_i]), (PG8_LAS unsigned*)(lds + (bufoff) + ldsw + _i * 8192), 16, 0, 0); } while (0)
; #define PG8_WAIT_V(n) asm volatile("s_waitcnt vmcnt(" #n ")" ::: "memory")
; #define PG8_BAR __builtin_amdgcn_s_barrier()
; template <class Epi, class Sched, bool STAMP = false>
; __device__ __forceinline__ void gemm_phase(PG8_LAS unsigned char* lds, const Gemm g, const Sched& S, const Epi& E, unsigned long long* stamps) {
;     ...
;             PG8_STAGE(PG8_SB(1, 1), b3 + hstep, voffB);
;             PG8_WAIT_V(6); PG8_BAR; PG8_MMA(1, 1, At, B1); PG8_BAR;
;     __device__ __forceinline__ void operator()(const f32x4 (&acc)[2][2][4][2], const pg8::Unit& u, int wr, int wc, int fr, int fq) const {
;         const int row0 = u.pm * 256 + wr * 64 + fr, col0 = u.pn * 256 + wc * 32 + 4 * fq;
; #pragma unroll
;         for (int ai = 0; ai < 2; ++ai)
; #pragma unroll
;             for (int m = 0; m < 4; ++m) {
;                 const int row = row0 + ai * 128 + m * 16;
;                 float* xp = X + (size_t)row * 1024 + col0; bf16_t* bp = XB + (size_t)row * 1024 + col0;
;                 const float* xi = Xp0 ? (row < T_P ? Xp0 + (size_t)row * 1024 + col0 : Xs0 + (size_t)(row - T_P) * 1024 + col0) : xp;
;                 float ss = 0.f;
; #pragma unroll
;                 for (int bj = 0; bj < 2; ++bj)
; #pragma unroll
;                     for (int n = 0; n < 2; ++n) {
;                         f32x4 xv = *(const f32x4*)(xi + bj * 128 + n * 16) + acc[ai][bj][m][n];
;                         *(f32x4*)(xp + bj * 128 + n * 16) = xv;
;                         ss += (xv[0] * xv[0] + xv[1] * xv[1]) + (xv[2] * xv[2] + xv[3] * xv[3]);
;                         u32x2 w; w.x = cvt_pk_bf16(xv[0], xv[1]); w.y = cvt_pk_bf16(xv[2], xv[3]);
;                         *(u32x2*)(bp + bj * 128 + n * 16) = w; }
;                 ss += __shfl_xor(ss, 16); ss += __shfl_xor(ss, 32);
;                 if (fq == 0) atomicAdd(rowss_out + row, ss); }
	s_add_u32 s14, s34, 0x100080
	s_addc_u32 s15, s35, 0
	s_add_i32 s16, s17, s49
	s_mov_b32 m0, s16
	s_nop 0
	global_load_lds_dwordx4 v128, s[14:15]
	s_add_i32 m0, s16, 0x2000
	s_nop 0
	global_load_lds_dwordx4 v148, s[14:15]
	s_waitcnt vmcnt(6)
	s_barrier
	v_mfma_f32_16x16x32_bf16 v[52:55], v[216:219], v[174:177], v[52:55]
	v_mfma_f32_16x16x32_bf16 v[48:51], v[224:227], v[174:177], v[48:51]
	v_mfma_f32_16x16x32_bf16 v[36:39], v[216:219], v[192:195], v[36:39]
	v_mfma_f32_16x16x32_bf16 v[32:35], v[224:227], v[192:195], v[32:35]
	v_mfma_f32_16x16x32_bf16 v[20:23], v[216:219], v[200:203], v[20:23]
	v_mfma_f32_16x16x32_bf16 v[16:19], v[224:227], v[200:203], v[16:19]
	v_mfma_f32_16x16x32_bf16 v[4:7], v[216:219], v[208:211], v[4:7]
	v_mfma_f32_16x16x32_bf16 v[0:3], v[224:227], v[208:211], v[0:3]
	v_mfma_f32_16x16x32_bf16 v[52:55], v[220:223], v[178:181], v[52:55]
	v_mfma_f32_16x16x32_bf16 v[48:51], v[228:231], v[178:181], v[48:51]
	v_mfma_f32_16x16x32_bf16 v[36:39], v[220:223], v[196:199], v[36:39]
	v_mfma_f32_16x16x32_bf16 v[32:35], v[228:231], v[196:199], v[32:35]
	v_mfma_f32_16x16x32_bf16 v[20:23], v[220:223], v[204:207], v[20:23]
	v_mfma_f32_16x16x32_bf16 v[16:19], v[228:231], v[204:207], v[16:19]
	v_mfma_f32_16x16x32_bf16 v[4:7], v[220:223], v[212:215], v[4:7]
	v_mfma_f32_16x16x32_bf16 v[0:3], v[228:231], v[212:215], v[0:3]
	s_add_i32 s65, s65, 2
	s_add_u32 s63, s63, 0x100
	s_addc_u32 s64, s64, 0
	s_cmp_gt_u32 s65, 61
	s_mov_b64 s[26:27], s[30:31]
	s_barrier
	s_cbranch_scc0 .LBB0_1183
	v_lshl_add_u32 v156, s22, 8, v139
	v_ashrrev_i32_e32 v157, 31, v156
	v_lshl_or_b32 v154, s24, 8, v159
	v_lshlrev_b64 v[162:163], 12, v[156:157]
	v_ashrrev_i32_e32 v155, 31, v154
	v_lshl_add_u64 v[162:163], s[84:85], 0, v[162:163]
	v_lshl_add_u64 v[170:171], v[154:155], 2, v[162:163]
	global_load_dwordx4 v[192:195], v[170:171], off
	global_load_dwordx4 v[196:199], v[170:171], off offset:64
	global_load_dwordx4 v[200:203], v[170:171], off offset:512
	global_load_dwordx4 v[204:207], v[170:171], off offset:576
	v_add_co_u32_e32 v224, vcc, 0x10000, v170
	s_nop 1
	v_addc_co_u32_e32 v225, vcc, 0, v171, vcc
	global_load_dwordx4 v[208:211], v[224:225], off
	global_load_dwordx4 v[212:215], v[224:225], off offset:64
	global_load_dwordx4 v[216:219], v[224:225], off offset:512
	global_load_dwordx4 v[220:223], v[224:225], off offset:576
	v_lshlrev_b64 v[166:167], 11, v[156:157]
	v_lshl_add_u64 v[166:167], s[0:1], 0, v[166:167]
	v_lshl_add_u64 v[172:173], v[154:155], 1, v[166:167]
	v_xor_b32_e32 v161, 32, v189
	s_waitcnt vmcnt(4)
	v_mov_b32_e32 v162, v192
	v_mov_b32_e32 v163, v193
	v_mov_b32_e32 v164, v194
	v_mov_b32_e32 v165, v195
	v_pk_add_f32 v[126:127], v[126:127], v[164:165]
	v_pk_add_f32 v[124:125], v[124:125], v[162:163]
	v_cvt_pk_bf16_f32 v163, v126, v127
	v_cvt_pk_bf16_f32 v162, v124, v125
	global_store_dwordx4 v[170:171], v[124:127], off
	global_store_dwordx2 v[172:173], v[162:163], off
	s_nop 1
	v_mov_b32_e32 v162, v196
	v_mov_b32_e32 v163, v197
	v_mov_b32_e32 v164, v198
	v_mov_b32_e32 v165, v199
	v_pk_add_f32 v[122:123], v[122:123], v[164:165]
	v_pk_add_f32 v[120:121], v[120:121], v[162:163]
	v_cvt_pk_bf16_f32 v163, v122, v123
	v_cvt_pk_bf16_f32 v162, v120, v121
	global_store_dwordx4 v[170:171], v[120:123], off offset:64
	global_store_dwordx2 v[172:173], v[162:163], off offset:32
	s_nop 1
	v_mov_b32_e32 v162, v200
	v_mov_b32_e32 v163, v201
	v_mov_b32_e32 v164, v202
	v_mov_b32_e32 v165, v203
	v_pk_add_f32 v[164:165], v[118:119], v[164:165]
	v_pk_add_f32 v[162:163], v[116:117], v[162:163]
	v_cvt_pk_bf16_f32 v117, v164, v165
	v_cvt_pk_bf16_f32 v116, v162, v163
	global_store_dwordx4 v[170:171], v[162:165], off offset:512
	global_store_dwordx2 v[172:173], v[116:117], off offset:256
	s_nop 1
	v_mov_b32_e32 v166, v204
	v_mov_b32_e32 v167, v205
	v_mov_b32_e32 v168, v206
	v_mov_b32_e32 v169, v207
	v_mul_f32_e32 v118, v125, v125
	v_mul_f32_e32 v119, v127, v127
	v_fmac_f32_e32 v118, v124, v124
	v_fmac_f32_e32 v119, v126, v126
	v_add_f32_e32 v118, v118, v119
	v_mul_f32_e32 v119, v121, v121
	v_mul_f32_e32 v121, v123, v123
	v_fmac_f32_e32 v119, v120, v120
	v_fmac_f32_e32 v121, v122, v122
	v_add_f32_e32 v119, v119, v121
	v_add_f32_e32 v118, v118, v119
	v_mul_f32_e32 v119, v163, v163
	v_mul_f32_e32 v120, v165, v165
	v_fmac_f32_e32 v119, v162, v162
	v_fmac_f32_e32 v120, v164, v164
	v_add_f32_e32 v119, v119, v120
	v_and_b32_e32 v117, 64, v189
	v_add_f32_e32 v122, v118, v119
	v_xor_b32_e32 v116, 16, v189
	v_add_u32_e32 v117, 64, v117
	v_cmp_lt_i32_e32 vcc, v116, v117
	v_pk_add_f32 v[120:121], v[114:115], v[168:169]
	v_pk_add_f32 v[118:119], v[112:113], v[166:167]
	v_mul_f32_e32 v113, v121, v121
	v_mul_f32_e32 v112, v119, v119
	v_fmac_f32_e32 v112, v118, v118
	v_fmac_f32_e32 v113, v120, v120
	v_cndmask_b32_e32 v116, v189, v116, vcc
	v_add_f32_e32 v112, v112, v113
	v_lshlrev_b32_e32 v116, 2, v116
	v_add_f32_e32 v112, v122, v112
	ds_bpermute_b32 v113, v116, v112
	v_cmp_lt_i32_e32 vcc, v161, v117
	global_store_dwordx4 v[170:171], v[118:121], off offset:576
	s_waitcnt lgkmcnt(0)
	v_add_f32_e32 v115, v112, v113
	v_cndmask_b32_e32 v114, v189, v161, vcc
	v_lshlrev_b32_e32 v114, 2, v114
	ds_bpermute_b32 v117, v114, v115
	v_cvt_pk_bf16_f32 v112, v118, v119
	v_cvt_pk_bf16_f32 v113, v120, v121
	global_store_dwordx2 v[172:173], v[112:113], off offset:288
	v_lshl_add_u64 v[112:113], v[156:157], 2, s[2:3]
	s_and_saveexec_b64 s[22:23], s[38:39]
	s_cbranch_execz .LBB0_1186
	s_waitcnt lgkmcnt(0)
	v_add_f32_e32 v115, v115, v117
	global_atomic_add_f32 v[112:113], v115, off

; #define PG8_STAGE(bufoff, gbase, voff) do { _Pragma("unroll") for (int _i = 0; _i < 2; ++_i) \
;         __builtin_amdgcn_global_load_lds((const unsigned*)((const char*)(gbase) + (voff)[_i]), (PG8_LAS unsigned*)(lds + (bufoff) + ldsw + _i * 8192), 16, 0, 0); } while (0)
; #define PG8_LDA(dst, b, h) do { _Pragma("unroll") for (int m = 0; m < 4; ++m) _Pragma("unroll") for (int k = 0; k < 2; ++k) dst[m][k] = *(const PG8_LAS bf16x8*)(lds + PG8_SA(b, h) + aoff + m * 2048 + k * 1024); } while (0)
; #define PG8_LDB(dst, b, h) do { _Pragma("unroll") for (int n = 0; n < 2; ++n) _Pragma("unroll") for (int k = 0; k < 2; ++k) dst[n][k] = *(const PG8_LAS bf16x8*)(lds + PG8_SB(b, h) + boff + n * 2048 + k * 1024); } while (0)
; #define PG8_WAIT_V(n) asm volatile("s_waitcnt vmcnt(" #n ")" ::: "memory")
; #define PG8_WAIT_L(n) asm volatile("s_waitcnt lgkmcnt(" #n ")" ::: "memory")
; #define PG8_BAR __builtin_amdgcn_s_barrier()
; #define PG8_SCHED __builtin_amdgcn_sched_barrier(0)
; template <class Epi, class Sched, bool STAMP = false>
; __device__ __forceinline__ void gemm_phase(PG8_LAS unsigned char* lds, const Gemm g, const Sched& S, const Epi& E, unsigned long long* stamps) {
;     ...
;             PG8_LDB(B0, 0, 0); PG8_SCHED; PG8_LDA(At, 0, 0); PG8_STAGE(PG8_SA(1, 1), a1 + hstep, voffA);
;             PG8_WAIT_L(8); PG8_BAR; PG8_WAIT_L(0); PG8_MMA(0, 0, At, B0); PG8_BAR; PG8_SCHED;
;             PG8_LDB(B1, 0, 1); PG8_STAGE(PG8_SB(0, 0), b2, voffB);
;             PG8_BAR; PG8_WAIT_L(0); PG8_MMA(0, 1, At, B1); PG8_BAR;
;             PG8_LDA(At, 0, 1); PG8_STAGE(PG8_SA(0, 0), a2, voffA);
;             PG8_BAR; PG8_WAIT_L(0); PG8_MMA(1, 0, At, B0); PG8_BAR; PG8_SCHED;
;             PG8_STAGE(PG8_SB(0, 1), b2 + hstep, voffB);
;             PG8_WAIT_V(6); PG8_BAR; PG8_MMA(1, 1, At, B1); PG8_BAR;
; __device__ __forceinline__ void run_ffn_down(LAS unsigned char* lds, const bf16_t* HID, const bf16_t* WDN, const EpiResid& E, float* PART) {
;     ...
;     { const int t = bidx(); OneUnit S; S.valid = t < 128; const int sl = t & 7, u = (t >> 3) & 15; S.pm = 64 + (u >> 2); S.pn = u & 3;
;       pg8::Gemm g; g.A = HID + sl * 512; g.Bt = WDN + sl * 512; g.M = T_ALL; g.N = 1024; g.K = 512; g.ld = 4096;
;       EpiPartial EA; EA.PART = PART + (size_t)sl * 1024 * 1024; EA.ldp = 1024;
;       pg8::gemm_phase<EpiPartial, OneUnit, false>(lds, g, S, EA, nullptr); }
.LBB0_1207:
	s_add_u32 s6, s4, 0x100
	s_addc_u32 s7, s5, 0
	s_cmp_lg_u32 s39, 4
	s_cselect_b32 s12, s6, 0
	s_cselect_b32 s13, s7, 0
	s_add_u32 s20, s2, s12
	s_addc_u32 s21, s3, s13
	s_add_i32 s14, 0, 0x10000
	ds_read_b128 v[158:161], v248
	ds_read_b128 v[162:165], v248 offset:1024
	ds_read_b128 v[166:169], v248 offset:2048
	ds_read_b128 v[170:173], v248 offset:3072
	s_add_u32 s12, s0, s12
	s_addc_u32 s13, s1, s13
	v_lshl_add_u64 v[182:183], v[150:151], 0, s[4:5]
	s_add_i32 m0, s27, 0xc000
	ds_read_b128 v[174:177], v156
	ds_read_b128 v[178:181], v156 offset:1024
	ds_read_b128 v[192:195], v156 offset:2048
	ds_read_b128 v[196:199], v156 offset:3072
	ds_read_b128 v[200:203], v156 offset:4096
	ds_read_b128 v[204:207], v156 offset:5120
	ds_read_b128 v[208:211], v156 offset:6144
	ds_read_b128 v[212:215], v156 offset:7168
	global_load_lds_dwordx4 v[182:183], off
	v_lshl_add_u64 v[182:183], v[152:153], 0, s[4:5]
	s_add_i32 m0, s27, 0xe000
	s_nop 0
	global_load_lds_dwordx4 v[182:183], off
	s_waitcnt lgkmcnt(8)
	s_barrier
	s_waitcnt lgkmcnt(0)
	v_mfma_f32_16x16x32_bf16 v[124:127], v[158:161], v[174:177], v[124:127]
	v_mfma_f32_16x16x32_bf16 v[120:123], v[166:169], v[174:177], v[120:123]
	v_mfma_f32_16x16x32_bf16 v[116:119], v[158:161], v[192:195], v[116:119]
	v_mfma_f32_16x16x32_bf16 v[112:115], v[166:169], v[192:195], v[112:115]
	v_mfma_f32_16x16x32_bf16 v[104:107], v[158:161], v[200:203], v[104:107]
	v_mfma_f32_16x16x32_bf16 v[96:99], v[166:169], v[200:203], v[96:99]
	v_mfma_f32_16x16x32_bf16 v[88:91], v[158:161], v[208:211], v[88:91]
	v_mfma_f32_16x16x32_bf16 v[80:83], v[166:169], v[208:211], v[80:83]
	v_mfma_f32_16x16x32_bf16 v[124:127], v[162:165], v[178:181], v[124:127]
	v_mfma_f32_16x16x32_bf16 v[120:123], v[170:173], v[178:181], v[120:123]
	v_mfma_f32_16x16x32_bf16 v[116:119], v[162:165], v[196:199], v[116:119]
	v_mfma_f32_16x16x32_bf16 v[112:115], v[170:173], v[196:199], v[112:115]
	v_mfma_f32_16x16x32_bf16 v[104:107], v[162:165], v[204:207], v[104:107]
	v_mfma_f32_16x16x32_bf16 v[96:99], v[170:173], v[204:207], v[96:99]
	v_mfma_f32_16x16x32_bf16 v[88:91], v[162:165], v[212:215], v[88:91]
	v_mfma_f32_16x16x32_bf16 v[80:83], v[170:173], v[212:215], v[80:83]
	s_barrier
	s_add_i32 s15, 0, 0x14000
	s_add_i32 s4, s14, s26
	v_lshl_add_u64 v[182:183], s[12:13], 0, v[128:129]
	s_mov_b32 m0, s4
	ds_read_b128 v[216:219], v249
	ds_read_b128 v[220:223], v249 offset:1024
	ds_read_b128 v[224:227], v249 offset:2048
	ds_read_b128 v[228:231], v249 offset:3072
	global_load_lds_dwordx4 v128, s[12:13]
	v_lshl_add_u64 v[232:233], s[12:13], 0, v[148:149]
	s_add_i32 m0, s4, 0x2000
	s_nop 0
	global_load_lds_dwordx4 v148, s[12:13]
	s_barrier
	s_waitcnt lgkmcnt(0)
	v_mfma_f32_16x16x32_bf16 v[108:111], v[216:219], v[174:177], v[108:111]
	v_mfma_f32_16x16x32_bf16 v[100:103], v[224:227], v[174:177], v[100:103]
	v_mfma_f32_16x16x32_bf16 v[92:95], v[216:219], v[192:195], v[92:95]
	v_mfma_f32_16x16x32_bf16 v[84:87], v[224:227], v[192:195], v[84:87]
	v_mfma_f32_16x16x32_bf16 v[76:79], v[216:219], v[200:203], v[76:79]
	v_mfma_f32_16x16x32_bf16 v[72:75], v[224:227], v[200:203], v[72:75]
	v_mfma_f32_16x16x32_bf16 v[68:71], v[216:219], v[208:211], v[68:71]
	v_mfma_f32_16x16x32_bf16 v[64:67], v[224:227], v[208:211], v[64:67]
	v_mfma_f32_16x16x32_bf16 v[108:111], v[220:223], v[178:181], v[108:111]
	v_mfma_f32_16x16x32_bf16 v[100:103], v[228:231], v[178:181], v[100:103]
	v_mfma_f32_16x16x32_bf16 v[92:95], v[220:223], v[196:199], v[92:95]
	v_mfma_f32_16x16x32_bf16 v[84:87], v[228:231], v[196:199], v[84:87]
	v_mfma_f32_16x16x32_bf16 v[76:79], v[220:223], v[204:207], v[76:79]
	v_mfma_f32_16x16x32_bf16 v[72:75], v[228:231], v[204:207], v[72:75]
	v_mfma_f32_16x16x32_bf16 v[68:71], v[220:223], v[212:215], v[68:71]
	v_mfma_f32_16x16x32_bf16 v[64:67], v[228:231], v[212:215], v[64:67]
	s_mov_b32 m0, s27
	v_lshl_add_u64 v[234:235], s[20:21], 0, v[128:129]
	s_barrier
	ds_read_b128 v[174:177], v156 offset:16384
	ds_read_b128 v[178:181], v156 offset:17408
	ds_read_b128 v[192:195], v156 offset:18432
	ds_read_b128 v[196:199], v156 offset:19456
	ds_read_b128 v[200:203], v156 offset:20480
	ds_read_b128 v[204:207], v156 offset:21504
	ds_read_b128 v[208:211], v156 offset:22528
	ds_read_b128 v[212:215], v156 offset:23552
	global_load_lds_dwordx4 v128, s[20:21]
	v_lshl_add_u64 v[236:237], s[20:21], 0, v[148:149]
	s_mov_b32 m0, s30
	s_nop 0
	global_load_lds_dwordx4 v148, s[20:21]
	s_barrier
	s_waitcnt lgkmcnt(0)
	v_mfma_f32_16x16x32_bf16 v[60:63], v[158:161], v[174:177], v[60:63]
	v_mfma_f32_16x16x32_bf16 v[56:59], v[166:169], v[174:177], v[56:59]
	v_mfma_f32_16x16x32_bf16 v[52:55], v[158:161], v[192:195], v[52:55]
	v_mfma_f32_16x16x32_bf16 v[48:51], v[166:169], v[192:195], v[48:51]
	v_mfma_f32_16x16x32_bf16 v[36:39], v[158:161], v[200:203], v[36:39]
	v_mfma_f32_16x16x32_bf16 v[32:35], v[166:169], v[200:203], v[32:35]
	v_mfma_f32_16x16x32_bf16 v[20:23], v[158:161], v[208:211], v[20:23]
	v_mfma_f32_16x16x32_bf16 v[16:19], v[166:169], v[208:211], v[16:19]
	v_mfma_f32_16x16x32_bf16 v[60:63], v[162:165], v[178:181], v[60:63]
	v_mfma_f32_16x16x32_bf16 v[56:59], v[170:173], v[178:181], v[56:59]
	v_mfma_f32_16x16x32_bf16 v[52:55], v[162:165], v[196:199], v[52:55]
	v_mfma_f32_16x16x32_bf16 v[48:51], v[170:173], v[196:199], v[48:51]
	v_mfma_f32_16x16x32_bf16 v[36:39], v[162:165], v[204:207], v[36:39]
	v_mfma_f32_16x16x32_bf16 v[32:35], v[170:173], v[204:207], v[32:35]
	v_mfma_f32_16x16x32_bf16 v[20:23], v[162:165], v[212:215], v[20:23]
	v_mfma_f32_16x16x32_bf16 v[16:19], v[170:173], v[212:215], v[16:19]
	s_barrier
; #define PG8_STAGE(bufoff, gbase, voff) do { _Pragma("unroll") for (int _i = 0; _i < 2; ++_i) \
;         __builtin_amdgcn_global_load_lds((const unsigned*)((const char*)(gbase) + (voff)[_i]), (PG8_LAS unsigned*)(lds + (bufoff) + ldsw + _i * 8192), 16, 0, 0); } while (0)
; #define PG8_LDA(dst, b, h) do { _Pragma("unroll") for (int m = 0; m < 4; ++m) _Pragma("unroll") for (int k = 0; k < 2; ++k) dst[m][k] = *(const PG8_LAS bf16x8*)(lds + PG8_SA(b, h) + aoff + m * 2048 + k * 1024); } while (0)
; #define PG8_LDB(dst, b, h) do { _Pragma("unroll") for (int n = 0; n < 2; ++n) _Pragma("unroll") for (int k = 0; k < 2; ++k) dst[n][k] = *(const PG8_LAS bf16x8*)(lds + PG8_SB(b, h) + boff + n * 2048 + k * 1024); } while (0)
; #define PG8_MMA(ai, bj, At, Bt) do { __builtin_amdgcn_s_setprio(1); _Pragma("unroll") for (int m = 0; m < 4; ++m) _Pragma("unroll") for (int n = 0; n < 2; ++n) _Pragma("unroll") for (int k = 0; k < 2; ++k) \
;         acc[ai][bj][m][n] = __builtin_amdgcn_mfma_f32_16x16x32_bf16(Bt[n][k], At[m][k], acc[ai][bj][m][n], 0, 0, 0); __builtin_amdgcn_s_setprio(0); } while (0)
; #define PG8_WAIT_V(n) asm volatile("s_waitcnt vmcnt(" #n ")" ::: "memory")
; #define PG8_WAIT_L(n) asm volatile("s_waitcnt lgkmcnt(" #n ")" ::: "memory")
; #define PG8_BAR __builtin_amdgcn_s_barrier()
; #define PG8_SCHED __builtin_amdgcn_sched_barrier(0)
; template <class Epi, class Sched, bool STAMP = false>
; __device__ __forceinline__ void gemm_phase(PG8_LAS unsigned char* lds, const Gemm g, const Sched& S, const Epi& E, unsigned long long* stamps) {
;     ...
;             PG8_WAIT_V(6); PG8_BAR; PG8_MMA(1, 1, At, B1); PG8_BAR;
;             PG8_LDB(B0, 1, 0); PG8_SCHED; PG8_LDA(At, 1, 0); PG8_STAGE(PG8_SA(0, 1), a2 + hstep, voffA);
;             PG8_WAIT_L(8); PG8_BAR; PG8_WAIT_L(0); PG8_MMA(0, 0, At, B0); PG8_BAR; PG8_SCHED;
;             PG8_LDB(B1, 1, 1); PG8_STAGE(PG8_SB(1, 0), b3, voffB);
;             PG8_BAR; PG8_WAIT_L(0); PG8_MMA(0, 1, At, B1); PG8_BAR;
;             PG8_LDA(At, 1, 1); PG8_STAGE(PG8_SA(1, 0), a3, voffA);
;             PG8_BAR; PG8_WAIT_L(0); PG8_MMA(1, 0, At, B0); PG8_BAR; PG8_SCHED;
	s_add_u32 s4, s12, 0x100000
	s_addc_u32 s5, s13, 0
	s_add_i32 s14, s15, s26
	s_mov_b32 m0, s14
	s_nop 0
	global_load_lds_dwordx4 v128, s[4:5]
	s_add_i32 m0, s14, 0x2000
	s_nop 0
	global_load_lds_dwordx4 v148, s[4:5]
	s_waitcnt vmcnt(6)
	s_barrier
	v_mfma_f32_16x16x32_bf16 v[44:47], v[216:219], v[174:177], v[44:47]
	v_mfma_f32_16x16x32_bf16 v[40:43], v[224:227], v[174:177], v[40:43]
	v_mfma_f32_16x16x32_bf16 v[28:31], v[216:219], v[192:195], v[28:31]
	v_mfma_f32_16x16x32_bf16 v[24:27], v[224:227], v[192:195], v[24:27]
	v_mfma_f32_16x16x32_bf16 v[12:15], v[216:219], v[200:203], v[12:15]
	v_mfma_f32_16x16x32_bf16 v[8:11], v[224:227], v[200:203], v[8:11]
	v_mfma_f32_16x16x32_bf16 v[4:7], v[216:219], v[208:211], v[4:7]
	v_mfma_f32_16x16x32_bf16 v[0:3], v[224:227], v[208:211], v[0:3]
	v_mfma_f32_16x16x32_bf16 v[44:47], v[220:223], v[178:181], v[44:47]
	v_mfma_f32_16x16x32_bf16 v[40:43], v[228:231], v[178:181], v[40:43]
	v_mfma_f32_16x16x32_bf16 v[28:31], v[220:223], v[196:199], v[28:31]
	v_mfma_f32_16x16x32_bf16 v[24:27], v[228:231], v[196:199], v[24:27]
	v_mfma_f32_16x16x32_bf16 v[12:15], v[220:223], v[204:207], v[12:15]
	v_mfma_f32_16x16x32_bf16 v[8:11], v[228:231], v[204:207], v[8:11]
	v_mfma_f32_16x16x32_bf16 v[4:7], v[220:223], v[212:215], v[4:7]
	v_mfma_f32_16x16x32_bf16 v[0:3], v[228:231], v[212:215], v[0:3]
	s_add_i32 s14, 0, 0x18000
	s_barrier
	ds_read_b128 v[158:161], v250
	ds_read_b128 v[162:165], v250 offset:1024
	ds_read_b128 v[166:169], v250 offset:2048
	ds_read_b128 v[170:173], v250 offset:3072
	s_add_u32 s4, s20, 0x100000
	s_addc_u32 s5, s21, 0
	s_mov_b32 m0, s31
	ds_read_b128 v[174:177], v156 offset:32768
	ds_read_b128 v[178:181], v156 offset:33792
	ds_read_b128 v[192:195], v156 offset:34816
	ds_read_b128 v[196:199], v156 offset:35840
	ds_read_b128 v[200:203], v156 offset:36864
	ds_read_b128 v[204:207], v156 offset:37888
	ds_read_b128 v[208:211], v156 offset:38912
	global_load_lds_dwordx4 v128, s[4:5]
	s_mov_b32 m0, s34
	ds_read_b128 v[212:215], v156 offset:39936
	global_load_lds_dwordx4 v148, s[4:5]
	s_waitcnt lgkmcnt(8)
	s_barrier
	s_waitcnt lgkmcnt(0)
	v_mfma_f32_16x16x32_bf16 v[124:127], v[158:161], v[174:177], v[124:127]
	v_mfma_f32_16x16x32_bf16 v[120:123], v[166:169], v[174:177], v[120:123]
	v_mfma_f32_16x16x32_bf16 v[116:119], v[158:161], v[192:195], v[116:119]
	v_mfma_f32_16x16x32_bf16 v[112:115], v[166:169], v[192:195], v[112:115]
	v_mfma_f32_16x16x32_bf16 v[104:107], v[158:161], v[200:203], v[104:107]
	v_mfma_f32_16x16x32_bf16 v[96:99], v[166:169], v[200:203], v[96:99]
	v_mfma_f32_16x16x32_bf16 v[88:91], v[158:161], v[208:211], v[88:91]
	v_mfma_f32_16x16x32_bf16 v[80:83], v[166:169], v[208:211], v[80:83]
	v_mfma_f32_16x16x32_bf16 v[124:127], v[162:165], v[178:181], v[124:127]
	v_mfma_f32_16x16x32_bf16 v[120:123], v[170:173], v[178:181], v[120:123]
	v_mfma_f32_16x16x32_bf16 v[116:119], v[162:165], v[196:199], v[116:119]
	v_mfma_f32_16x16x32_bf16 v[112:115], v[170:173], v[196:199], v[112:115]
	v_mfma_f32_16x16x32_bf16 v[104:107], v[162:165], v[204:207], v[104:107]
	v_mfma_f32_16x16x32_bf16 v[96:99], v[170:173], v[204:207], v[96:99]
	v_mfma_f32_16x16x32_bf16 v[88:91], v[162:165], v[212:215], v[88:91]
	v_mfma_f32_16x16x32_bf16 v[80:83], v[170:173], v[212:215], v[80:83]
	s_barrier
	s_add_i32 s15, 0, 0x1c000
	s_add_i32 s4, s14, s26
	v_lshl_add_u64 v[182:183], v[182:183], 0, s[18:19]
	s_mov_b32 m0, s4
	ds_read_b128 v[216:219], v251
	ds_read_b128 v[220:223], v251 offset:1024
	ds_read_b128 v[224:227], v251 offset:2048
	ds_read_b128 v[228:231], v251 offset:3072
	global_load_lds_dwordx4 v244, s[12:13]
	v_lshl_add_u64 v[182:183], v[232:233], 0, s[18:19]
	s_add_i32 m0, s4, 0x2000
	s_nop 0
	global_load_lds_dwordx4 v245, s[12:13]
	s_barrier
	s_waitcnt lgkmcnt(0)
	v_mfma_f32_16x16x32_bf16 v[108:111], v[216:219], v[174:177], v[108:111]
	v_mfma_f32_16x16x32_bf16 v[100:103], v[224:227], v[174:177], v[100:103]
	v_mfma_f32_16x16x32_bf16 v[92:95], v[216:219], v[192:195], v[92:95]
	v_mfma_f32_16x16x32_bf16 v[84:87], v[224:227], v[192:195], v[84:87]
	v_mfma_f32_16x16x32_bf16 v[76:79], v[216:219], v[200:203], v[76:79]
	v_mfma_f32_16x16x32_bf16 v[72:75], v[224:227], v[200:203], v[72:75]
	v_mfma_f32_16x16x32_bf16 v[68:71], v[216:219], v[208:211], v[68:71]
	v_mfma_f32_16x16x32_bf16 v[64:67], v[224:227], v[208:211], v[64:67]
	v_mfma_f32_16x16x32_bf16 v[108:111], v[220:223], v[178:181], v[108:111]
	v_mfma_f32_16x16x32_bf16 v[100:103], v[228:231], v[178:181], v[100:103]
	v_mfma_f32_16x16x32_bf16 v[92:95], v[220:223], v[196:199], v[92:95]
	v_mfma_f32_16x16x32_bf16 v[84:87], v[228:231], v[196:199], v[84:87]
	v_mfma_f32_16x16x32_bf16 v[76:79], v[220:223], v[204:207], v[76:79]
	v_mfma_f32_16x16x32_bf16 v[72:75], v[228:231], v[204:207], v[72:75]
	v_mfma_f32_16x16x32_bf16 v[68:71], v[220:223], v[212:215], v[68:71]
	v_mfma_f32_16x16x32_bf16 v[64:67], v[228:231], v[212:215], v[64:67]
	s_mov_b32 m0, s37
	v_lshl_add_u64 v[182:183], v[234:235], 0, s[18:19]
	s_barrier
	ds_read_b128 v[174:177], v156 offset:49152
	ds_read_b128 v[178:181], v156 offset:50176
	ds_read_b128 v[192:195], v156 offset:51200
	ds_read_b128 v[196:199], v156 offset:52224
	ds_read_b128 v[200:203], v156 offset:53248
	ds_read_b128 v[204:207], v156 offset:54272
	ds_read_b128 v[208:211], v156 offset:55296
	ds_read_b128 v[212:215], v156 offset:56320
	global_load_lds_dwordx4 v244, s[20:21]
	v_lshl_add_u64 v[182:183], v[236:237], 0, s[18:19]
	s_mov_b32 m0, s38
	s_nop 0
	global_load_lds_dwordx4 v245, s[20:21]
	s_barrier
; #define PG8_STAGE(bufoff, gbase, voff) do { _Pragma("unroll") for (int _i = 0; _i < 2; ++_i) \
;         __builtin_amdgcn_global_load_lds((const unsigned*)((const char*)(gbase) + (voff)[_i]), (PG8_LAS unsigned*)(lds + (bufoff) + ldsw + _i * 8192), 16, 0, 0); } while (0)
; #define PG8_MMA(ai, bj, At, Bt) do { __builtin_amdgcn_s_setprio(1); _Pragma("unroll") for (int m = 0; m < 4; ++m) _Pragma("unroll") for (int n = 0; n < 2; ++n) _Pragma("unroll") for (int k = 0; k < 2; ++k) \
;         acc[ai][bj][m][n] = __builtin_amdgcn_mfma_f32_16x16x32_bf16(Bt[n][k], At[m][k], acc[ai][bj][m][n], 0, 0, 0); __builtin_amdgcn_s_setprio(0); } while (0)
; #define PG8_WAIT_V(n) asm volatile("s_waitcnt vmcnt(" #n ")" ::: "memory")
; #define PG8_WAIT_L(n) asm volatile("s_waitcnt lgkmcnt(" #n ")" ::: "memory")
; #define PG8_BAR __builtin_amdgcn_s_barrier()
; #define PG8_SCHED __builtin_amdgcn_sched_barrier(0)
; template <class Epi, class Sched, bool STAMP = false>
; __device__ __forceinline__ void gemm_phase(PG8_LAS unsigned char* lds, const Gemm g, const Sched& S, const Epi& E, unsigned long long* stamps) {
;     ...
;             PG8_BAR; PG8_WAIT_L(0); PG8_MMA(1, 0, At, B0); PG8_BAR; PG8_SCHED;
;             PG8_STAGE(PG8_SB(1, 1), b3 + hstep, voffB);
;             PG8_WAIT_V(6); PG8_BAR; PG8_MMA(1, 1, At, B1); PG8_BAR;
;     __device__ __forceinline__ void operator()(const f32x4 (&acc)[2][2][4][2], const pg8::Unit& u, int wr, int wc, int fr, int fq) const {
;         const int row0 = (u.pm - 64) * 256 + wr * 64 + fr, col0 = u.pn * 256 + wc * 32 + 4 * fq;
; #pragma unroll
;         for (int ai = 0; ai < 2; ++ai)
; #pragma unroll
;             for (int m = 0; m < 4; ++m) { float* xp = PART + (size_t)(row0 + ai * 128 + m * 16) * ldp + col0;
; #pragma unroll
;                 for (int bj = 0; bj < 2; ++bj)
; #pragma unroll
;                     for (int n = 0; n < 2; ++n) *(f32x4*)(xp + bj * 128 + n * 16) = acc[ai][bj][m][n]; }
	s_waitcnt lgkmcnt(0)
	v_mfma_f32_16x16x32_bf16 v[60:63], v[158:161], v[174:177], v[60:63]
	v_mfma_f32_16x16x32_bf16 v[56:59], v[166:169], v[174:177], v[56:59]
	v_mfma_f32_16x16x32_bf16 v[52:55], v[158:161], v[192:195], v[52:55]
	v_mfma_f32_16x16x32_bf16 v[48:51], v[166:169], v[192:195], v[48:51]
	v_mfma_f32_16x16x32_bf16 v[36:39], v[158:161], v[200:203], v[36:39]
	v_mfma_f32_16x16x32_bf16 v[32:35], v[166:169], v[200:203], v[32:35]
	v_mfma_f32_16x16x32_bf16 v[20:23], v[158:161], v[208:211], v[20:23]
	v_mfma_f32_16x16x32_bf16 v[16:19], v[166:169], v[208:211], v[16:19]
	v_mfma_f32_16x16x32_bf16 v[60:63], v[162:165], v[178:181], v[60:63]
	v_mfma_f32_16x16x32_bf16 v[56:59], v[170:173], v[178:181], v[56:59]
	v_mfma_f32_16x16x32_bf16 v[52:55], v[162:165], v[196:199], v[52:55]
	v_mfma_f32_16x16x32_bf16 v[48:51], v[170:173], v[196:199], v[48:51]
	v_mfma_f32_16x16x32_bf16 v[36:39], v[162:165], v[204:207], v[36:39]
	v_mfma_f32_16x16x32_bf16 v[32:35], v[170:173], v[204:207], v[32:35]
	v_mfma_f32_16x16x32_bf16 v[20:23], v[162:165], v[212:215], v[20:23]
	v_mfma_f32_16x16x32_bf16 v[16:19], v[170:173], v[212:215], v[16:19]
	s_barrier
	s_add_u32 s4, s12, 0x100080
	s_addc_u32 s5, s13, 0
	s_add_i32 s12, s15, s26
	s_mov_b32 m0, s12
	s_nop 0
	global_load_lds_dwordx4 v128, s[4:5]
	s_add_i32 m0, s12, 0x2000
	s_nop 0
	global_load_lds_dwordx4 v148, s[4:5]
	s_waitcnt vmcnt(6)
	s_barrier
	v_mfma_f32_16x16x32_bf16 v[44:47], v[216:219], v[174:177], v[44:47]
	v_mfma_f32_16x16x32_bf16 v[40:43], v[224:227], v[174:177], v[40:43]
	v_mfma_f32_16x16x32_bf16 v[28:31], v[216:219], v[192:195], v[28:31]
	v_mfma_f32_16x16x32_bf16 v[24:27], v[224:227], v[192:195], v[24:27]
	v_mfma_f32_16x16x32_bf16 v[12:15], v[216:219], v[200:203], v[12:15]
	v_mfma_f32_16x16x32_bf16 v[8:11], v[224:227], v[200:203], v[8:11]
	v_mfma_f32_16x16x32_bf16 v[4:7], v[216:219], v[208:211], v[4:7]
	v_mfma_f32_16x16x32_bf16 v[0:3], v[224:227], v[208:211], v[0:3]
	v_mfma_f32_16x16x32_bf16 v[44:47], v[220:223], v[178:181], v[44:47]
	v_mfma_f32_16x16x32_bf16 v[40:43], v[228:231], v[178:181], v[40:43]
	v_mfma_f32_16x16x32_bf16 v[28:31], v[220:223], v[196:199], v[28:31]
	v_mfma_f32_16x16x32_bf16 v[24:27], v[228:231], v[196:199], v[24:27]
	v_mfma_f32_16x16x32_bf16 v[12:15], v[220:223], v[204:207], v[12:15]
	v_mfma_f32_16x16x32_bf16 v[8:11], v[228:231], v[204:207], v[8:11]
	v_mfma_f32_16x16x32_bf16 v[4:7], v[220:223], v[212:215], v[4:7]
	v_mfma_f32_16x16x32_bf16 v[0:3], v[228:231], v[212:215], v[0:3]
	s_add_i32 s39, s39, 2
	s_cmp_gt_u32 s39, 5
	s_mov_b64 s[4:5], s[6:7]
	s_barrier
	s_cbranch_scc0 .LBB0_1207
	s_lshl_b32 s0, s25, 22
	s_add_u32 s0, s10, s0
	s_addc_u32 s1, s42, 0
	s_add_u32 s0, s0, 0xdd00000
	s_addc_u32 s1, s1, 0
	s_lshl_b32 s2, s24, 8
	s_add_i32 s2, s2, s35
	v_add_u32_e32 v150, s2, v154
	v_add_u32_e32 v148, 0xffffc000, v150
	s_lshl_b32 s2, s23, 8
	v_lshl_or_b32 v128, v139, 2, s2
	v_ashrrev_i32_e32 v149, 31, v148
	v_or_b32_e32 v128, s36, v128
	v_lshlrev_b64 v[148:149], 12, v[148:149]
	v_lshl_add_u64 v[148:149], s[0:1], 0, v[148:149]
	v_lshlrev_b32_e32 v128, 2, v128
	v_lshl_add_u64 v[148:149], v[148:149], 0, v[128:129]
	global_store_dwordx4 v[148:149], v[124:127], off
	global_store_dwordx4 v[148:149], v[120:123], off offset:64
	global_store_dwordx4 v[148:149], v[108:111], off offset:512
	global_store_dwordx4 v[148:149], v[100:103], off offset:576
	s_cmpk_lt_u32 s22, 0x100
	v_readlane_b32 s39, v242, 28
	v_add_u32_e32 v100, 0xffffc010, v150
	v_ashrrev_i32_e32 v101, 31, v100
	v_lshlrev_b64 v[100:101], 12, v[100:101]
	v_lshl_add_u64 v[100:101], s[0:1], 0, v[100:101]
	v_lshl_add_u64 v[100:101], v[100:101], 0, v[128:129]
	global_store_dwordx4 v[100:101], v[116:119], off
	global_store_dwordx4 v[100:101], v[112:115], off offset:64
	global_store_dwordx4 v[100:101], v[92:95], off offset:512
	global_store_dwordx4 v[100:101], v[84:87], off offset:576
	s_mov_b32 s38, 0x1ffff
	s_nop 0
	v_add_u32_e32 v84, 0xffffc020, v150
	v_ashrrev_i32_e32 v85, 31, v84
	v_lshlrev_b64 v[84:85], 12, v[84:85]
	v_lshl_add_u64 v[84:85], s[0:1], 0, v[84:85]
	v_lshl_add_u64 v[84:85], v[84:85], 0, v[128:129]
	global_store_dwordx4 v[84:85], v[104:107], off
	global_store_dwordx4 v[84:85], v[96:99], off offset:64
	global_store_dwordx4 v[84:85], v[76:79], off offset:512
	global_store_dwordx4 v[84:85], v[72:75], off offset:576
	s_nop 1
	v_add_u32_e32 v72, 0xffffc030, v150
	v_ashrrev_i32_e32 v73, 31, v72
	v_lshlrev_b64 v[72:73], 12, v[72:73]
	v_lshl_add_u64 v[72:73], s[0:1], 0, v[72:73]
	v_lshl_add_u64 v[72:73], v[72:73], 0, v[128:129]
	s_mov_b64 s[0:1], 0x80000
	global_store_dwordx4 v[72:73], v[88:91], off
	global_store_dwordx4 v[72:73], v[80:83], off offset:64
	global_store_dwordx4 v[72:73], v[68:71], off offset:512
	global_store_dwordx4 v[72:73], v[64:67], off offset:576
	s_nop 1
	v_lshl_add_u64 v[64:65], v[148:149], 0, s[0:1]
	s_mov_b32 s0, 0x80000
	v_add_co_u32_e32 v66, vcc, s0, v148
	s_mov_b64 s[0:1], 0x90000
	s_nop 0
	v_addc_co_u32_e32 v67, vcc, 0, v149, vcc
	global_store_dwordx4 v[66:67], v[60:63], off
	global_store_dwordx4 v[64:65], v[56:59], off offset:64
	global_store_dwordx4 v[64:65], v[44:47], off offset:512
	global_store_dwordx4 v[64:65], v[40:43], off offset:576
	s_nop 1
	v_lshl_add_u64 v[40:41], v[148:149], 0, s[0:1]
	s_mov_b32 s0, 0x90000
	v_add_co_u32_e32 v42, vcc, s0, v148
	s_mov_b64 s[0:1], 0xa0000
	s_nop 0
	v_addc_co_u32_e32 v43, vcc, 0, v149, vcc
	global_store_dwordx4 v[42:43], v[52:55], off
	global_store_dwordx4 v[40:41], v[48:51], off offset:64
	global_store_dwordx4 v[40:41], v[28:31], off offset:512
	global_store_dwordx4 v[40:41], v[24:27], off offset:576
	s_nop 1
	v_lshl_add_u64 v[24:25], v[148:149], 0, s[0:1]
	s_mov_b32 s0, 0xa0000
	v_add_co_u32_e32 v26, vcc, s0, v148
	s_mov_b64 s[0:1], 0xb0000
	s_nop 0
	v_addc_co_u32_e32 v27, vcc, 0, v149, vcc
	global_store_dwordx4 v[26:27], v[36:39], off
	global_store_dwordx4 v[24:25], v[32:35], off offset:64
	global_store_dwordx4 v[24:25], v[12:15], off offset:512
	global_store_dwordx4 v[24:25], v[8:11], off offset:576
	s_nop 1
	v_add_co_u32_e32 v10, vcc, 0xb0000, v148
	v_lshl_add_u64 v[8:9], v[148:149], 0, s[0:1]
	s_nop 0
	v_addc_co_u32_e32 v11, vcc, 0, v149, vcc
	global_store_dwordx4 v[10:11], v[20:23], off
	global_store_dwordx4 v[8:9], v[16:19], off offset:64
	global_store_dwordx4 v[8:9], v[4:7], off offset:512
	global_store_dwordx4 v[8:9], v[0:3], off offset:576
	s_waitcnt vmcnt(0)
	s_cbranch_scc0 .LBB0_1210
	s_barrier

; #define PG8_STAGE(bufoff, gbase, voff) do { _Pragma("unroll") for (int _i = 0; _i < 2; ++_i) \
;         __builtin_amdgcn_global_load_lds((const unsigned*)((const char*)(gbase) + (voff)[_i]), (PG8_LAS unsigned*)(lds + (bufoff) + ldsw + _i * 8192), 16, 0, 0); } while (0)
; #define PG8_LDA(dst, b, h) do { _Pragma("unroll") for (int m = 0; m < 4; ++m) _Pragma("unroll") for (int k = 0; k < 2; ++k) dst[m][k] = *(const PG8_LAS bf16x8*)(lds + PG8_SA(b, h) + aoff + m * 2048 + k * 1024); } while (0)
; #define PG8_LDB(dst, b, h) do { _Pragma("unroll") for (int n = 0; n < 2; ++n) _Pragma("unroll") for (int k = 0; k < 2; ++k) dst[n][k] = *(const PG8_LAS bf16x8*)(lds + PG8_SB(b, h) + boff + n * 2048 + k * 1024); } while (0)
; #define PG8_MMA(ai, bj, At, Bt) do { __builtin_amdgcn_s_setprio(1); _Pragma("unroll") for (int m = 0; m < 4; ++m) _Pragma("unroll") for (int n = 0; n < 2; ++n) _Pragma("unroll") for (int k = 0; k < 2; ++k) \
;         acc[ai][bj][m][n] = __builtin_amdgcn_mfma_f32_16x16x32_bf16(Bt[n][k], At[m][k], acc[ai][bj][m][n], 0, 0, 0); __builtin_amdgcn_s_setprio(0); } while (0)
; #define PG8_WAIT_V(n) asm volatile("s_waitcnt vmcnt(" #n ")" ::: "memory")
; #define PG8_WAIT_L(n) asm volatile("s_waitcnt lgkmcnt(" #n ")" ::: "memory")
; #define PG8_BAR __builtin_amdgcn_s_barrier()
; #define PG8_SCHED __builtin_amdgcn_sched_barrier(0)
; template <class Epi, class Sched, bool STAMP = false>
; __device__ __forceinline__ void gemm_phase(PG8_LAS unsigned char* lds, const Gemm g, const Sched& S, const Epi& E, unsigned long long* stamps) {
;     ...
;             PG8_LDB(B0, 0, 0); PG8_SCHED; PG8_LDA(At, 0, 0); PG8_STAGE(PG8_SA(1, 1), a1 + hstep, voffA);
;             PG8_WAIT_L(8); PG8_BAR; PG8_WAIT_L(0); PG8_MMA(0, 0, At, B0); PG8_BAR; PG8_SCHED;
;             PG8_LDB(B1, 0, 1); PG8_STAGE(PG8_SB(0, 0), b2, voffB);
;             PG8_BAR; PG8_WAIT_L(0); PG8_MMA(0, 1, At, B1); PG8_BAR;
;             PG8_LDA(At, 0, 1); PG8_STAGE(PG8_SA(0, 0), a2, voffA);
;             PG8_BAR; PG8_WAIT_L(0); PG8_MMA(1, 0, At, B0); PG8_BAR; PG8_SCHED;
;             PG8_STAGE(PG8_SB(0, 1), b2 + hstep, voffB);
;             PG8_WAIT_V(6); PG8_BAR; PG8_MMA(1, 1, At, B1); PG8_BAR;
.LBB0_1340:
	s_add_u32 s14, s24, 0xfffc0080
	s_addc_u32 s15, s25, -1
	s_add_i32 s16, 0, 0x10000
	ds_read_b128 v[158:161], v248
	ds_read_b128 v[162:165], v248 offset:1024
	ds_read_b128 v[170:173], v248 offset:2048
	ds_read_b128 v[174:177], v248 offset:3072
	s_cmp_eq_u32 s61, 12
	s_cselect_b32 s31, s7, s15
	s_cselect_b32 s30, s57, s14
	s_cselect_b32 s27, s5, s60
	s_cselect_b32 s26, s58, s59
	s_add_i32 m0, s23, 0xc000
	ds_read_b128 v[178:181], v168
	ds_read_b128 v[192:195], v168 offset:1024
	ds_read_b128 v[196:199], v168 offset:2048
	ds_read_b128 v[200:203], v168 offset:3072
	ds_read_b128 v[204:207], v168 offset:4096
	ds_read_b128 v[208:211], v168 offset:5120
	ds_read_b128 v[212:215], v168 offset:6144
	global_load_lds_dwordx4 v154, s[24:25]
	s_add_i32 m0, s23, 0xe000
	ds_read_b128 v[216:219], v168 offset:7168
	global_load_lds_dwordx4 v156, s[24:25]
	s_waitcnt lgkmcnt(8)
	s_barrier
	s_waitcnt lgkmcnt(0)
	v_mfma_f32_16x16x32_bf16 v[124:127], v[158:161], v[178:181], v[124:127]
	v_mfma_f32_16x16x32_bf16 v[120:123], v[170:173], v[178:181], v[120:123]
	v_mfma_f32_16x16x32_bf16 v[108:111], v[158:161], v[196:199], v[108:111]
	v_mfma_f32_16x16x32_bf16 v[104:107], v[170:173], v[196:199], v[104:107]
	v_mfma_f32_16x16x32_bf16 v[92:95], v[158:161], v[204:207], v[92:95]
	v_mfma_f32_16x16x32_bf16 v[88:91], v[170:173], v[204:207], v[88:91]
	v_mfma_f32_16x16x32_bf16 v[76:79], v[158:161], v[212:215], v[76:79]
	v_mfma_f32_16x16x32_bf16 v[72:75], v[170:173], v[212:215], v[72:75]
	v_mfma_f32_16x16x32_bf16 v[124:127], v[162:165], v[192:195], v[124:127]
	v_mfma_f32_16x16x32_bf16 v[120:123], v[174:177], v[192:195], v[120:123]
	v_mfma_f32_16x16x32_bf16 v[108:111], v[162:165], v[200:203], v[108:111]
	v_mfma_f32_16x16x32_bf16 v[104:107], v[174:177], v[200:203], v[104:107]
	v_mfma_f32_16x16x32_bf16 v[92:95], v[162:165], v[208:211], v[92:95]
	v_mfma_f32_16x16x32_bf16 v[88:91], v[174:177], v[208:211], v[88:91]
	v_mfma_f32_16x16x32_bf16 v[76:79], v[162:165], v[216:219], v[76:79]
	v_mfma_f32_16x16x32_bf16 v[72:75], v[174:177], v[216:219], v[72:75]
	s_barrier
	s_add_i32 s17, 0, 0x14000
	s_add_i32 s14, s16, s43
	s_mov_b32 m0, s14
	ds_read_b128 v[220:223], v249
	ds_read_b128 v[224:227], v249 offset:1024
	ds_read_b128 v[228:231], v249 offset:2048
	global_load_lds_dwordx4 v128, s[26:27]
	s_add_i32 m0, s14, 0x2000
	ds_read_b128 v[232:235], v249 offset:3072
	global_load_lds_dwordx4 v148, s[26:27]
	s_barrier
	s_waitcnt lgkmcnt(0)
	v_mfma_f32_16x16x32_bf16 v[116:119], v[220:223], v[178:181], v[116:119]
	v_mfma_f32_16x16x32_bf16 v[112:115], v[228:231], v[178:181], v[112:115]
	v_mfma_f32_16x16x32_bf16 v[100:103], v[220:223], v[196:199], v[100:103]
	v_mfma_f32_16x16x32_bf16 v[96:99], v[228:231], v[196:199], v[96:99]
	v_mfma_f32_16x16x32_bf16 v[84:87], v[220:223], v[204:207], v[84:87]
	v_mfma_f32_16x16x32_bf16 v[80:83], v[228:231], v[204:207], v[80:83]
	v_mfma_f32_16x16x32_bf16 v[68:71], v[220:223], v[212:215], v[68:71]
	v_mfma_f32_16x16x32_bf16 v[64:67], v[228:231], v[212:215], v[64:67]
	v_mfma_f32_16x16x32_bf16 v[116:119], v[224:227], v[192:195], v[116:119]
	v_mfma_f32_16x16x32_bf16 v[112:115], v[232:235], v[192:195], v[112:115]
	v_mfma_f32_16x16x32_bf16 v[100:103], v[224:227], v[200:203], v[100:103]
	v_mfma_f32_16x16x32_bf16 v[96:99], v[232:235], v[200:203], v[96:99]
	v_mfma_f32_16x16x32_bf16 v[84:87], v[224:227], v[208:211], v[84:87]
	v_mfma_f32_16x16x32_bf16 v[80:83], v[232:235], v[208:211], v[80:83]
	v_mfma_f32_16x16x32_bf16 v[68:71], v[224:227], v[216:219], v[68:71]
	v_mfma_f32_16x16x32_bf16 v[64:67], v[232:235], v[216:219], v[64:67]
	s_mov_b32 m0, s23
	s_barrier
	ds_read_b128 v[178:181], v168 offset:16384
	ds_read_b128 v[192:195], v168 offset:17408
	ds_read_b128 v[196:199], v168 offset:18432
	ds_read_b128 v[200:203], v168 offset:19456
	ds_read_b128 v[204:207], v168 offset:20480
	ds_read_b128 v[208:211], v168 offset:21504
	ds_read_b128 v[212:215], v168 offset:22528
	global_load_lds_dwordx4 v152, s[30:31]
	s_mov_b32 m0, s45
	ds_read_b128 v[216:219], v168 offset:23552
	global_load_lds_dwordx4 v150, s[30:31]
	s_barrier
	s_waitcnt lgkmcnt(0)
	v_mfma_f32_16x16x32_bf16 v[60:63], v[158:161], v[178:181], v[60:63]
	v_mfma_f32_16x16x32_bf16 v[56:59], v[170:173], v[178:181], v[56:59]
	v_mfma_f32_16x16x32_bf16 v[44:47], v[158:161], v[196:199], v[44:47]
	v_mfma_f32_16x16x32_bf16 v[40:43], v[170:173], v[196:199], v[40:43]
	v_mfma_f32_16x16x32_bf16 v[28:31], v[158:161], v[204:207], v[28:31]
	v_mfma_f32_16x16x32_bf16 v[24:27], v[170:173], v[204:207], v[24:27]
	v_mfma_f32_16x16x32_bf16 v[12:15], v[158:161], v[212:215], v[12:15]
	v_mfma_f32_16x16x32_bf16 v[8:11], v[170:173], v[212:215], v[8:11]
	v_mfma_f32_16x16x32_bf16 v[60:63], v[162:165], v[192:195], v[60:63]
	v_mfma_f32_16x16x32_bf16 v[56:59], v[174:177], v[192:195], v[56:59]
	v_mfma_f32_16x16x32_bf16 v[44:47], v[162:165], v[200:203], v[44:47]
	v_mfma_f32_16x16x32_bf16 v[40:43], v[174:177], v[200:203], v[40:43]
	v_mfma_f32_16x16x32_bf16 v[28:31], v[162:165], v[208:211], v[28:31]
	v_mfma_f32_16x16x32_bf16 v[24:27], v[174:177], v[208:211], v[24:27]
	v_mfma_f32_16x16x32_bf16 v[12:15], v[162:165], v[216:219], v[12:15]
	v_mfma_f32_16x16x32_bf16 v[8:11], v[174:177], v[216:219], v[8:11]
	s_barrier
	s_add_u32 s14, s26, 0x40000
	s_addc_u32 s15, s27, 0
	s_add_i32 s16, s17, s43
	s_mov_b32 m0, s16
	s_nop 0
	global_load_lds_dwordx4 v128, s[14:15]
	s_add_i32 m0, s16, 0x2000
	s_nop 0
	global_load_lds_dwordx4 v148, s[14:15]
	s_waitcnt vmcnt(6)
	s_barrier
; #define PG8_STAGE(bufoff, gbase, voff) do { _Pragma("unroll") for (int _i = 0; _i < 2; ++_i) \
;         __builtin_amdgcn_global_load_lds((const unsigned*)((const char*)(gbase) + (voff)[_i]), (PG8_LAS unsigned*)(lds + (bufoff) + ldsw + _i * 8192), 16, 0, 0); } while (0)
; #define PG8_LDA(dst, b, h) do { _Pragma("unroll") for (int m = 0; m < 4; ++m) _Pragma("unroll") for (int k = 0; k < 2; ++k) dst[m][k] = *(const PG8_LAS bf16x8*)(lds + PG8_SA(b, h) + aoff + m * 2048 + k * 1024); } while (0)
; #define PG8_LDB(dst, b, h) do { _Pragma("unroll") for (int n = 0; n < 2; ++n) _Pragma("unroll") for (int k = 0; k < 2; ++k) dst[n][k] = *(const PG8_LAS bf16x8*)(lds + PG8_SB(b, h) + boff + n * 2048 + k * 1024); } while (0)
; #define PG8_MMA(ai, bj, At, Bt) do { __builtin_amdgcn_s_setprio(1); _Pragma("unroll") for (int m = 0; m < 4; ++m) _Pragma("unroll") for (int n = 0; n < 2; ++n) _Pragma("unroll") for (int k = 0; k < 2; ++k) \
;         acc[ai][bj][m][n] = __builtin_amdgcn_mfma_f32_16x16x32_bf16(Bt[n][k], At[m][k], acc[ai][bj][m][n], 0, 0, 0); __builtin_amdgcn_s_setprio(0); } while (0)
; #define PG8_WAIT_V(n) asm volatile("s_waitcnt vmcnt(" #n ")" ::: "memory")
; #define PG8_WAIT_L(n) asm volatile("s_waitcnt lgkmcnt(" #n ")" ::: "memory")
; #define PG8_BAR __builtin_amdgcn_s_barrier()
; #define PG8_SCHED __builtin_amdgcn_sched_barrier(0)
; template <class Epi, class Sched, bool STAMP = false>
; __device__ __forceinline__ void gemm_phase(PG8_LAS unsigned char* lds, const Gemm g, const Sched& S, const Epi& E, unsigned long long* stamps) {
;     ...
;             PG8_WAIT_V(6); PG8_BAR; PG8_MMA(1, 1, At, B1); PG8_BAR;
;             PG8_LDB(B0, 1, 0); PG8_SCHED; PG8_LDA(At, 1, 0); PG8_STAGE(PG8_SA(0, 1), a2 + hstep, voffA);
;             PG8_WAIT_L(8); PG8_BAR; PG8_WAIT_L(0); PG8_MMA(0, 0, At, B0); PG8_BAR; PG8_SCHED;
;             PG8_LDB(B1, 1, 1); PG8_STAGE(PG8_SB(1, 0), b3, voffB);
;             PG8_BAR; PG8_WAIT_L(0); PG8_MMA(0, 1, At, B1); PG8_BAR;
;             PG8_LDA(At, 1, 1); PG8_STAGE(PG8_SA(1, 0), a3, voffA);
;             PG8_BAR; PG8_WAIT_L(0); PG8_MMA(1, 0, At, B0); PG8_BAR; PG8_SCHED;
	v_mfma_f32_16x16x32_bf16 v[52:55], v[220:223], v[178:181], v[52:55]
	v_mfma_f32_16x16x32_bf16 v[48:51], v[228:231], v[178:181], v[48:51]
	v_mfma_f32_16x16x32_bf16 v[36:39], v[220:223], v[196:199], v[36:39]
	v_mfma_f32_16x16x32_bf16 v[32:35], v[228:231], v[196:199], v[32:35]
	v_mfma_f32_16x16x32_bf16 v[20:23], v[220:223], v[204:207], v[20:23]
	v_mfma_f32_16x16x32_bf16 v[16:19], v[228:231], v[204:207], v[16:19]
	v_mfma_f32_16x16x32_bf16 v[4:7], v[220:223], v[212:215], v[4:7]
	v_mfma_f32_16x16x32_bf16 v[0:3], v[228:231], v[212:215], v[0:3]
	v_mfma_f32_16x16x32_bf16 v[52:55], v[224:227], v[192:195], v[52:55]
	v_mfma_f32_16x16x32_bf16 v[48:51], v[232:235], v[192:195], v[48:51]
	v_mfma_f32_16x16x32_bf16 v[36:39], v[224:227], v[200:203], v[36:39]
	v_mfma_f32_16x16x32_bf16 v[32:35], v[232:235], v[200:203], v[32:35]
	v_mfma_f32_16x16x32_bf16 v[20:23], v[224:227], v[208:211], v[20:23]
	v_mfma_f32_16x16x32_bf16 v[16:19], v[232:235], v[208:211], v[16:19]
	v_mfma_f32_16x16x32_bf16 v[4:7], v[224:227], v[216:219], v[4:7]
	v_mfma_f32_16x16x32_bf16 v[0:3], v[232:235], v[216:219], v[0:3]
	s_add_i32 s16, 0, 0x18000
	s_barrier
	ds_read_b128 v[158:161], v250
	ds_read_b128 v[162:165], v250 offset:1024
	ds_read_b128 v[170:173], v250 offset:2048
	ds_read_b128 v[174:177], v250 offset:3072
	s_add_u32 s14, s30, 0x40000
	s_addc_u32 s15, s31, 0
	s_mov_b32 m0, s46
	ds_read_b128 v[178:181], v168 offset:32768
	ds_read_b128 v[192:195], v168 offset:33792
	ds_read_b128 v[196:199], v168 offset:34816
	ds_read_b128 v[200:203], v168 offset:35840
	ds_read_b128 v[204:207], v168 offset:36864
	ds_read_b128 v[208:211], v168 offset:37888
	ds_read_b128 v[212:215], v168 offset:38912
	global_load_lds_dwordx4 v152, s[14:15]
	s_mov_b32 m0, s47
	ds_read_b128 v[216:219], v168 offset:39936
	global_load_lds_dwordx4 v150, s[14:15]
	s_waitcnt lgkmcnt(8)
	s_barrier
	s_waitcnt lgkmcnt(0)
	v_mfma_f32_16x16x32_bf16 v[124:127], v[158:161], v[178:181], v[124:127]
	v_mfma_f32_16x16x32_bf16 v[120:123], v[170:173], v[178:181], v[120:123]
	v_mfma_f32_16x16x32_bf16 v[108:111], v[158:161], v[196:199], v[108:111]
	v_mfma_f32_16x16x32_bf16 v[104:107], v[170:173], v[196:199], v[104:107]
	v_mfma_f32_16x16x32_bf16 v[92:95], v[158:161], v[204:207], v[92:95]
	v_mfma_f32_16x16x32_bf16 v[88:91], v[170:173], v[204:207], v[88:91]
	v_mfma_f32_16x16x32_bf16 v[76:79], v[158:161], v[212:215], v[76:79]
	v_mfma_f32_16x16x32_bf16 v[72:75], v[170:173], v[212:215], v[72:75]
	v_mfma_f32_16x16x32_bf16 v[124:127], v[162:165], v[192:195], v[124:127]
	v_mfma_f32_16x16x32_bf16 v[120:123], v[174:177], v[192:195], v[120:123]
	v_mfma_f32_16x16x32_bf16 v[108:111], v[162:165], v[200:203], v[108:111]
	v_mfma_f32_16x16x32_bf16 v[104:107], v[174:177], v[200:203], v[104:107]
	v_mfma_f32_16x16x32_bf16 v[92:95], v[162:165], v[208:211], v[92:95]
	v_mfma_f32_16x16x32_bf16 v[88:91], v[174:177], v[208:211], v[88:91]
	v_mfma_f32_16x16x32_bf16 v[76:79], v[162:165], v[216:219], v[76:79]
	v_mfma_f32_16x16x32_bf16 v[72:75], v[174:177], v[216:219], v[72:75]
	s_barrier
	s_add_i32 s17, 0, 0x1c000
	s_add_i32 s14, s16, s43
	s_mov_b32 m0, s14
	ds_read_b128 v[220:223], v251
	ds_read_b128 v[224:227], v251 offset:1024
	ds_read_b128 v[228:231], v251 offset:2048
	global_load_lds_dwordx4 v244, s[26:27]
	s_add_i32 m0, s14, 0x2000
	ds_read_b128 v[232:235], v251 offset:3072
	global_load_lds_dwordx4 v245, s[26:27]
	s_barrier
	s_waitcnt lgkmcnt(0)
	v_mfma_f32_16x16x32_bf16 v[116:119], v[220:223], v[178:181], v[116:119]
	v_mfma_f32_16x16x32_bf16 v[112:115], v[228:231], v[178:181], v[112:115]
	v_mfma_f32_16x16x32_bf16 v[100:103], v[220:223], v[196:199], v[100:103]
	v_mfma_f32_16x16x32_bf16 v[96:99], v[228:231], v[196:199], v[96:99]
	v_mfma_f32_16x16x32_bf16 v[84:87], v[220:223], v[204:207], v[84:87]
	v_mfma_f32_16x16x32_bf16 v[80:83], v[228:231], v[204:207], v[80:83]
	v_mfma_f32_16x16x32_bf16 v[68:71], v[220:223], v[212:215], v[68:71]
	v_mfma_f32_16x16x32_bf16 v[64:67], v[228:231], v[212:215], v[64:67]
	v_mfma_f32_16x16x32_bf16 v[116:119], v[224:227], v[192:195], v[116:119]
	v_mfma_f32_16x16x32_bf16 v[112:115], v[232:235], v[192:195], v[112:115]
	v_mfma_f32_16x16x32_bf16 v[100:103], v[224:227], v[200:203], v[100:103]
	v_mfma_f32_16x16x32_bf16 v[96:99], v[232:235], v[200:203], v[96:99]
	v_mfma_f32_16x16x32_bf16 v[84:87], v[224:227], v[208:211], v[84:87]
	v_mfma_f32_16x16x32_bf16 v[80:83], v[232:235], v[208:211], v[80:83]
	v_mfma_f32_16x16x32_bf16 v[68:71], v[224:227], v[216:219], v[68:71]
	v_mfma_f32_16x16x32_bf16 v[64:67], v[232:235], v[216:219], v[64:67]
	s_mov_b32 m0, s48
	s_barrier
	ds_read_b128 v[178:181], v168 offset:49152
	ds_read_b128 v[192:195], v168 offset:50176
	ds_read_b128 v[196:199], v168 offset:51200
	ds_read_b128 v[200:203], v168 offset:52224
	ds_read_b128 v[204:207], v168 offset:53248
	ds_read_b128 v[208:211], v168 offset:54272
	ds_read_b128 v[212:215], v168 offset:55296
	global_load_lds_dwordx4 v246, s[30:31]
	s_mov_b32 m0, s49
	ds_read_b128 v[216:219], v168 offset:56320
	global_load_lds_dwordx4 v247, s[30:31]
	s_barrier
	s_waitcnt lgkmcnt(0)
	v_mfma_f32_16x16x32_bf16 v[60:63], v[158:161], v[178:181], v[60:63]
	v_mfma_f32_16x16x32_bf16 v[56:59], v[170:173], v[178:181], v[56:59]
	v_mfma_f32_16x16x32_bf16 v[44:47], v[158:161], v[196:199], v[44:47]
	v_mfma_f32_16x16x32_bf16 v[40:43], v[170:173], v[196:199], v[40:43]
	v_mfma_f32_16x16x32_bf16 v[28:31], v[158:161], v[204:207], v[28:31]
	v_mfma_f32_16x16x32_bf16 v[24:27], v[170:173], v[204:207], v[24:27]
	v_mfma_f32_16x16x32_bf16 v[12:15], v[158:161], v[212:215], v[12:15]
	v_mfma_f32_16x16x32_bf16 v[8:11], v[170:173], v[212:215], v[8:11]
	v_mfma_f32_16x16x32_bf16 v[60:63], v[162:165], v[192:195], v[60:63]
	v_mfma_f32_16x16x32_bf16 v[56:59], v[174:177], v[192:195], v[56:59]
	v_mfma_f32_16x16x32_bf16 v[44:47], v[162:165], v[200:203], v[44:47]
	v_mfma_f32_16x16x32_bf16 v[40:43], v[174:177], v[200:203], v[40:43]
	v_mfma_f32_16x16x32_bf16 v[28:31], v[162:165], v[208:211], v[28:31]
	v_mfma_f32_16x16x32_bf16 v[24:27], v[174:177], v[208:211], v[24:27]
	v_mfma_f32_16x16x32_bf16 v[12:15], v[162:165], v[216:219], v[12:15]
	v_mfma_f32_16x16x32_bf16 v[8:11], v[174:177], v[216:219], v[8:11]
	s_barrier
; __device__ __forceinline__ unsigned cvt_pk_bf16(float lo, float hi) { const f32x2_cv v = {lo, hi}; const bf16x2_cv b = __builtin_convertvector(v, bf16x2_cv); return __builtin_bit_cast(unsigned, b); }
; #define PG8_STAGE(bufoff, gbase, voff) do { _Pragma("unroll") for (int _i = 0; _i < 2; ++_i) \
;         __builtin_amdgcn_global_load_lds((const unsigned*)((const char*)(gbase) + (voff)[_i]), (PG8_LAS unsigned*)(lds + (bufoff) + ldsw + _i * 8192), 16, 0, 0); } while (0)
; #define PG8_MMA(ai, bj, At, Bt) do { __builtin_amdgcn_s_setprio(1); _Pragma("unroll") for (int m = 0; m < 4; ++m) _Pragma("unroll") for (int n = 0; n < 2; ++n) _Pragma("unroll") for (int k = 0; k < 2; ++k) \
;         acc[ai][bj][m][n] = __builtin_amdgcn_mfma_f32_16x16x32_bf16(Bt[n][k], At[m][k], acc[ai][bj][m][n], 0, 0, 0); __builtin_amdgcn_s_setprio(0); } while (0)
; #define PG8_WAIT_V(n) asm volatile("s_waitcnt vmcnt(" #n ")" ::: "memory")
; template <class Epi, class Sched, bool STAMP = false>
; __device__ __forceinline__ void gemm_phase(PG8_LAS unsigned char* lds, const Gemm g, const Sched& S, const Epi& E, unsigned long long* stamps) {
;     ...
;             PG8_STAGE(PG8_SB(1, 1), b3 + hstep, voffB);
;             PG8_WAIT_V(6); PG8_BAR; PG8_MMA(1, 1, At, B1); PG8_BAR;
;     __device__ __forceinline__ void operator()(const f32x4 (&acc)[2][2][4][2], const pg8::Unit& u, int wr, int wc, int fr, int fq) const {
;         const int row0 = u.pm * 256 + wr * 64 + fr, col0 = u.pn * 256 + wc * 32 + 8 * fq;
; #pragma unroll
;         for (int ai = 0; ai < 2; ++ai)
; #pragma unroll
;             for (int m = 0; m < 4; ++m) {
;                 const int row = row0 + ai * 128 + m * 16;
;                 const float s = (MODE == 2) ? 1.0f : rstd_of(rowss, row);
;                 bf16_t* rowp = O + (size_t)row * ldc + col0;
; #pragma unroll
;                 for (int bj = 0; bj < 2; ++bj) {
;                     f32x4 v0 = acc[ai][bj][m][0] * s, v1 = acc[ai][bj][m][1] * s;
;                     if (MODE == 1) {
; #pragma unroll
;                         for (int j = 0; j < 4; ++j) { const float a = fmaxf(v0[j], 0.f), b = fmaxf(v1[j], 0.f); v0[j] = a * a; v1[j] = b * b; } }
;                     u32x4 w; w.x = cvt_pk_bf16(v0[0], v0[1]); w.y = cvt_pk_bf16(v0[2], v0[3]); w.z = cvt_pk_bf16(v1[0], v1[1]); w.w = cvt_pk_bf16(v1[2], v1[3]);
;                     *(u32x4*)(rowp + bj * 128) = w; } }
	s_add_u32 s14, s26, 0x40080
	s_addc_u32 s15, s27, 0
	s_add_i32 s16, s17, s43
	s_mov_b32 m0, s16
	s_nop 0
	global_load_lds_dwordx4 v128, s[14:15]
	s_add_i32 m0, s16, 0x2000
	s_nop 0
	global_load_lds_dwordx4 v148, s[14:15]
	s_waitcnt vmcnt(6)
	s_barrier
	v_mfma_f32_16x16x32_bf16 v[52:55], v[220:223], v[178:181], v[52:55]
	v_mfma_f32_16x16x32_bf16 v[48:51], v[228:231], v[178:181], v[48:51]
	v_mfma_f32_16x16x32_bf16 v[36:39], v[220:223], v[196:199], v[36:39]
	v_mfma_f32_16x16x32_bf16 v[32:35], v[228:231], v[196:199], v[32:35]
	v_mfma_f32_16x16x32_bf16 v[20:23], v[220:223], v[204:207], v[20:23]
	v_mfma_f32_16x16x32_bf16 v[16:19], v[228:231], v[204:207], v[16:19]
	v_mfma_f32_16x16x32_bf16 v[4:7], v[220:223], v[212:215], v[4:7]
	v_mfma_f32_16x16x32_bf16 v[0:3], v[228:231], v[212:215], v[0:3]
	v_mfma_f32_16x16x32_bf16 v[52:55], v[224:227], v[192:195], v[52:55]
	v_mfma_f32_16x16x32_bf16 v[48:51], v[232:235], v[192:195], v[48:51]
	v_mfma_f32_16x16x32_bf16 v[36:39], v[224:227], v[200:203], v[36:39]
	v_mfma_f32_16x16x32_bf16 v[32:35], v[232:235], v[200:203], v[32:35]
	v_mfma_f32_16x16x32_bf16 v[20:23], v[224:227], v[208:211], v[20:23]
	v_mfma_f32_16x16x32_bf16 v[16:19], v[232:235], v[208:211], v[16:19]
	v_mfma_f32_16x16x32_bf16 v[4:7], v[224:227], v[216:219], v[4:7]
	v_mfma_f32_16x16x32_bf16 v[0:3], v[232:235], v[216:219], v[0:3]
	s_add_i32 s61, s61, 2
	s_add_u32 s24, s24, 0x100
	s_addc_u32 s25, s25, 0
	s_add_u32 s59, s59, 0x100
	s_addc_u32 s60, s60, 0
	s_cmp_gt_u32 s61, 13
	s_barrier
	s_cbranch_scc0 .LBB0_1340
	v_lshl_add_u32 v162, s22, 8, v139
	v_ashrrev_i32_e32 v163, 31, v162
	v_lshl_add_u64 v[158:159], v[162:163], 2, s[0:1]
	global_load_dword v164, v[158:159], off
	global_load_dword v231, v[158:159], off offset:64
	global_load_dword v232, v[158:159], off offset:128
	global_load_dword v233, v[158:159], off offset:192
	global_load_dword v234, v[158:159], off offset:512
	global_load_dword v235, v[158:159], off offset:576
	global_load_dword v236, v[158:159], off offset:640
	global_load_dword v237, v[158:159], off offset:704
	v_lshl_or_b32 v160, s56, 8, v167
	v_ashrrev_i32_e32 v161, 31, v160
	s_mov_b32 s5, 0x80000
	s_mov_b64 s[14:15], 0x80000
	s_mov_b32 s56, s4
	s_mov_b32 s22, s6
	s_mov_b64 s[26:27], s[20:21]
	s_mov_b64 s[24:25], s[12:13]
	s_waitcnt vmcnt(0)
	v_fmamk_f32 v164, v164, 0x3a800000, v187
	v_cmp_gt_f32_e32 vcc, s67, v164
	v_mul_f32_e32 v165, 0x4b800000, v164
	s_nop 0
	v_cndmask_b32_e32 v164, v164, v165, vcc
	v_rsq_f32_e32 v164, v164
	s_nop 0
	v_mul_f32_e32 v165, 0x45800000, v164
	v_cndmask_b32_e32 v170, v164, v165, vcc
	v_lshlrev_b64 v[164:165], 12, v[162:163]
	v_lshl_add_u64 v[172:173], s[2:3], 0, v[164:165]
	v_lshlrev_b64 v[164:165], 1, v[160:161]
	v_lshl_add_u64 v[160:161], v[172:173], 0, v[164:165]
	v_pk_mul_f32 v[126:127], v[126:127], v[170:171] op_sel_hi:[1,0]
	v_pk_mul_f32 v[124:125], v[124:125], v[170:171] op_sel_hi:[1,0]
	v_pk_mul_f32 v[172:173], v[122:123], v[170:171] op_sel_hi:[1,0]
	v_pk_mul_f32 v[122:123], v[120:121], v[170:171] op_sel_hi:[1,0]
	v_cvt_pk_bf16_f32 v120, v124, v125
	v_cvt_pk_bf16_f32 v121, v126, v127
	v_cvt_pk_bf16_f32 v122, v122, v123
	v_cvt_pk_bf16_f32 v123, v172, v173
	global_store_dwordx4 v[160:161], v[120:123], off
	v_pk_mul_f32 v[118:119], v[118:119], v[170:171] op_sel_hi:[1,0]
	v_pk_mul_f32 v[116:117], v[116:117], v[170:171] op_sel_hi:[1,0]
	v_pk_mul_f32 v[120:121], v[114:115], v[170:171] op_sel_hi:[1,0]
	v_pk_mul_f32 v[114:115], v[112:113], v[170:171] op_sel_hi:[1,0]
	v_cvt_pk_bf16_f32 v112, v116, v117
	v_cvt_pk_bf16_f32 v113, v118, v119
	v_cvt_pk_bf16_f32 v114, v114, v115
	v_cvt_pk_bf16_f32 v115, v120, v121
	global_store_dwordx4 v[160:161], v[112:115], off offset:256
	s_nop 1
	v_mov_b32_e32 v114, v231
	s_nop 0
	v_or_b32_e32 v112, 16, v162
	v_ashrrev_i32_e32 v113, 31, v112
	v_lshlrev_b64 v[112:113], 12, v[112:113]
	v_lshl_add_u64 v[112:113], s[2:3], 0, v[112:113]
	v_lshl_add_u64 v[112:113], v[112:113], 0, v[164:165]
	v_fmamk_f32 v114, v114, 0x3a800000, v187
	v_cmp_gt_f32_e32 vcc, s67, v114
	v_mul_f32_e32 v115, 0x4b800000, v114
	s_nop 0
	v_cndmask_b32_e32 v114, v114, v115, vcc
	v_rsq_f32_e32 v114, v114
	s_nop 0
	v_mul_f32_e32 v115, 0x45800000, v114
	v_cndmask_b32_e32 v114, v114, v115, vcc
	v_pk_mul_f32 v[110:111], v[110:111], v[114:115] op_sel_hi:[1,0]
	v_pk_mul_f32 v[108:109], v[108:109], v[114:115] op_sel_hi:[1,0]
	v_pk_mul_f32 v[116:117], v[106:107], v[114:115] op_sel_hi:[1,0]
	v_pk_mul_f32 v[106:107], v[104:105], v[114:115] op_sel_hi:[1,0]
	v_cvt_pk_bf16_f32 v104, v108, v109
	v_cvt_pk_bf16_f32 v105, v110, v111
	v_cvt_pk_bf16_f32 v106, v106, v107
	v_cvt_pk_bf16_f32 v107, v116, v117
	global_store_dwordx4 v[112:113], v[104:107], off
	v_pk_mul_f32 v[102:103], v[102:103], v[114:115] op_sel_hi:[1,0]
	v_pk_mul_f32 v[100:101], v[100:101], v[114:115] op_sel_hi:[1,0]
	v_pk_mul_f32 v[104:105], v[98:99], v[114:115] op_sel_hi:[1,0]
	v_pk_mul_f32 v[98:99], v[96:97], v[114:115] op_sel_hi:[1,0]
	v_cvt_pk_bf16_f32 v96, v100, v101
	v_cvt_pk_bf16_f32 v97, v102, v103
	v_cvt_pk_bf16_f32 v98, v98, v99
	v_cvt_pk_bf16_f32 v99, v104, v105
	global_store_dwordx4 v[112:113], v[96:99], off offset:256
	s_nop 1
	v_mov_b32_e32 v98, v232
	s_nop 0
	v_or_b32_e32 v96, 32, v162
	v_ashrrev_i32_e32 v97, 31, v96
	v_lshlrev_b64 v[96:97], 12, v[96:97]
	v_lshl_add_u64 v[96:97], s[2:3], 0, v[96:97]
	v_lshl_add_u64 v[96:97], v[96:97], 0, v[164:165]
	v_fmamk_f32 v98, v98, 0x3a800000, v187
	v_cmp_gt_f32_e32 vcc, s67, v98
	v_mul_f32_e32 v99, 0x4b800000, v98
	s_nop 0
	v_cndmask_b32_e32 v98, v98, v99, vcc
	v_rsq_f32_e32 v98, v98
	s_nop 0
	v_mul_f32_e32 v99, 0x45800000, v98
	v_cndmask_b32_e32 v98, v98, v99, vcc
	v_pk_mul_f32 v[94:95], v[94:95], v[98:99] op_sel_hi:[1,0]
; __device__ __forceinline__ unsigned cvt_pk_bf16(float lo, float hi) { const f32x2_cv v = {lo, hi}; const bf16x2_cv b = __builtin_convertvector(v, bf16x2_cv); return __builtin_bit_cast(unsigned, b); }
; __device__ __forceinline__ float rstd_of(const float* rowss, int row) { return rsqrtf(rowss[row] * (1.0f / 1024.0f) + 1e-6f); }
;     __device__ __forceinline__ void operator()(const f32x4 (&acc)[2][2][4][2], const pg8::Unit& u, int wr, int wc, int fr, int fq) const {
;         const int row0 = u.pm * 256 + wr * 64 + fr, col0 = u.pn * 256 + wc * 32 + 8 * fq;
; #pragma unroll
;         for (int ai = 0; ai < 2; ++ai)
; #pragma unroll
;             for (int m = 0; m < 4; ++m) {
;                 const int row = row0 + ai * 128 + m * 16;
;                 const float s = (MODE == 2) ? 1.0f : rstd_of(rowss, row);
;                 bf16_t* rowp = O + (size_t)row * ldc + col0;
; #pragma unroll
;                 for (int bj = 0; bj < 2; ++bj) {
;                     f32x4 v0 = acc[ai][bj][m][0] * s, v1 = acc[ai][bj][m][1] * s;
;                     if (MODE == 1) {
; #pragma unroll
;                         for (int j = 0; j < 4; ++j) { const float a = fmaxf(v0[j], 0.f), b = fmaxf(v1[j], 0.f); v0[j] = a * a; v1[j] = b * b; } }
;                     u32x4 w; w.x = cvt_pk_bf16(v0[0], v0[1]); w.y = cvt_pk_bf16(v0[2], v0[3]); w.z = cvt_pk_bf16(v1[0], v1[1]); w.w = cvt_pk_bf16(v1[2], v1[3]);
;                     *(u32x4*)(rowp + bj * 128) = w; } }
	v_pk_mul_f32 v[92:93], v[92:93], v[98:99] op_sel_hi:[1,0]
	v_pk_mul_f32 v[100:101], v[90:91], v[98:99] op_sel_hi:[1,0]
	v_pk_mul_f32 v[90:91], v[88:89], v[98:99] op_sel_hi:[1,0]
	v_cvt_pk_bf16_f32 v88, v92, v93
	v_cvt_pk_bf16_f32 v89, v94, v95
	v_cvt_pk_bf16_f32 v90, v90, v91
	v_cvt_pk_bf16_f32 v91, v100, v101
	global_store_dwordx4 v[96:97], v[88:91], off
	v_pk_mul_f32 v[86:87], v[86:87], v[98:99] op_sel_hi:[1,0]
	v_pk_mul_f32 v[84:85], v[84:85], v[98:99] op_sel_hi:[1,0]
	v_pk_mul_f32 v[88:89], v[82:83], v[98:99] op_sel_hi:[1,0]
	v_pk_mul_f32 v[82:83], v[80:81], v[98:99] op_sel_hi:[1,0]
	v_cvt_pk_bf16_f32 v80, v84, v85
	v_cvt_pk_bf16_f32 v81, v86, v87
	v_cvt_pk_bf16_f32 v82, v82, v83
	v_cvt_pk_bf16_f32 v83, v88, v89
	global_store_dwordx4 v[96:97], v[80:83], off offset:256
	s_nop 1
	v_mov_b32_e32 v82, v233
	s_nop 0
	v_or_b32_e32 v80, 48, v162
	v_ashrrev_i32_e32 v81, 31, v80
	v_lshlrev_b64 v[80:81], 12, v[80:81]
	v_lshl_add_u64 v[80:81], s[2:3], 0, v[80:81]
	v_lshl_add_u64 v[80:81], v[80:81], 0, v[164:165]
	v_fmamk_f32 v82, v82, 0x3a800000, v187
	v_cmp_gt_f32_e32 vcc, s67, v82
	v_mul_f32_e32 v83, 0x4b800000, v82
	s_nop 0
	v_cndmask_b32_e32 v82, v82, v83, vcc
	v_rsq_f32_e32 v82, v82
	s_nop 0
	v_mul_f32_e32 v83, 0x45800000, v82
	v_cndmask_b32_e32 v82, v82, v83, vcc
	v_pk_mul_f32 v[78:79], v[78:79], v[82:83] op_sel_hi:[1,0]
	v_pk_mul_f32 v[76:77], v[76:77], v[82:83] op_sel_hi:[1,0]
	v_pk_mul_f32 v[84:85], v[74:75], v[82:83] op_sel_hi:[1,0]
	v_pk_mul_f32 v[74:75], v[72:73], v[82:83] op_sel_hi:[1,0]
	v_cvt_pk_bf16_f32 v72, v76, v77
	v_cvt_pk_bf16_f32 v73, v78, v79
	v_cvt_pk_bf16_f32 v74, v74, v75
	v_cvt_pk_bf16_f32 v75, v84, v85
	global_store_dwordx4 v[80:81], v[72:75], off
	v_pk_mul_f32 v[70:71], v[70:71], v[82:83] op_sel_hi:[1,0]
	v_pk_mul_f32 v[68:69], v[68:69], v[82:83] op_sel_hi:[1,0]
	v_pk_mul_f32 v[72:73], v[66:67], v[82:83] op_sel_hi:[1,0]
	v_pk_mul_f32 v[66:67], v[64:65], v[82:83] op_sel_hi:[1,0]
	v_cvt_pk_bf16_f32 v64, v68, v69
	v_cvt_pk_bf16_f32 v65, v70, v71
	v_cvt_pk_bf16_f32 v66, v66, v67
	v_cvt_pk_bf16_f32 v67, v72, v73
	global_store_dwordx4 v[80:81], v[64:67], off offset:256
	s_nop 1
	v_mov_b32_e32 v64, v234
	s_nop 0
	v_lshl_add_u64 v[66:67], v[160:161], 0, s[14:15]
	s_mov_b64 s[14:15], 0x90000
	v_fmamk_f32 v64, v64, 0x3a800000, v187
	v_cmp_gt_f32_e32 vcc, s67, v64
	v_mul_f32_e32 v65, 0x4b800000, v64
	s_nop 0
	v_cndmask_b32_e32 v64, v64, v65, vcc
	v_rsq_f32_e32 v64, v64
	s_nop 0
	v_mul_f32_e32 v65, 0x45800000, v64
	v_cndmask_b32_e32 v64, v64, v65, vcc
	v_pk_mul_f32 v[60:61], v[60:61], v[64:65] op_sel_hi:[1,0]
	v_pk_mul_f32 v[62:63], v[62:63], v[64:65] op_sel_hi:[1,0]
	v_pk_mul_f32 v[68:69], v[58:59], v[64:65] op_sel_hi:[1,0]
	v_pk_mul_f32 v[58:59], v[56:57], v[64:65] op_sel_hi:[1,0]
	v_cvt_pk_bf16_f32 v56, v60, v61
	v_add_co_u32_e32 v60, vcc, s5, v160
	v_cvt_pk_bf16_f32 v57, v62, v63
	v_cvt_pk_bf16_f32 v58, v58, v59
	v_cvt_pk_bf16_f32 v59, v68, v69
	v_addc_co_u32_e32 v61, vcc, 0, v161, vcc
	global_store_dwordx4 v[60:61], v[56:59], off
	v_pk_mul_f32 v[54:55], v[54:55], v[64:65] op_sel_hi:[1,0]
	v_pk_mul_f32 v[52:53], v[52:53], v[64:65] op_sel_hi:[1,0]
	v_pk_mul_f32 v[56:57], v[50:51], v[64:65] op_sel_hi:[1,0]
	v_pk_mul_f32 v[50:51], v[48:49], v[64:65] op_sel_hi:[1,0]
	v_cvt_pk_bf16_f32 v48, v52, v53
	v_cvt_pk_bf16_f32 v49, v54, v55
	v_cvt_pk_bf16_f32 v50, v50, v51
	v_cvt_pk_bf16_f32 v51, v56, v57
	global_store_dwordx4 v[66:67], v[48:51], off offset:256
	s_nop 1
	v_mov_b32_e32 v48, v235
	s_mov_b32 s5, 0x90000
	v_lshl_add_u64 v[50:51], v[160:161], 0, s[14:15]
	s_mov_b64 s[14:15], 0xa0000
	v_fmamk_f32 v48, v48, 0x3a800000, v187
	v_cmp_gt_f32_e32 vcc, s67, v48
	v_mul_f32_e32 v49, 0x4b800000, v48
	s_nop 0
	v_cndmask_b32_e32 v48, v48, v49, vcc
; __device__ __forceinline__ unsigned cvt_pk_bf16(float lo, float hi) { const f32x2_cv v = {lo, hi}; const bf16x2_cv b = __builtin_convertvector(v, bf16x2_cv); return __builtin_bit_cast(unsigned, b); }
; #define PG8_WAIT_V(n) asm volatile("s_waitcnt vmcnt(" #n ")" ::: "memory")
; #define PG8_BAR __builtin_amdgcn_s_barrier()
; __device__ __forceinline__ float rstd_of(const float* rowss, int row) { return rsqrtf(rowss[row] * (1.0f / 1024.0f) + 1e-6f); }
; template <class Epi, class Sched, bool STAMP = false>
; __device__ __forceinline__ void gemm_phase(PG8_LAS unsigned char* lds, const Gemm g, const Sched& S, const Epi& E, unsigned long long* stamps) {
;     ...
;         if constexpr (!Epi::AFTER_DRAIN) { E(acc, cur, wr, wc, fr, fq); S.done(cur); }
;         if (!has_next) break;
; #pragma unroll
;         for (int a = 0; a < 2; ++a)
; #pragma unroll
;             for (int b = 0; b < 2; ++b)
; #pragma unroll
;                 for (int m = 0; m < 4; ++m)
; #pragma unroll
;                     for (int n = 0; n < 2; ++n) acc[a][b][m][n] = (f32x4){0.f, 0.f, 0.f, 0.f};
;         cur = nxt; cA = nA; cB = nB; ++ui;
;     }
;     PG8_WAIT_V(0);
;     if (wr == 0) PG8_BAR;
;     PG8_BAR;
;     __device__ __forceinline__ void operator()(const f32x4 (&acc)[2][2][4][2], const pg8::Unit& u, int wr, int wc, int fr, int fq) const {
;         const int row0 = u.pm * 256 + wr * 64 + fr, col0 = u.pn * 256 + wc * 32 + 8 * fq;
; #pragma unroll
;         for (int ai = 0; ai < 2; ++ai)
; #pragma unroll
;             for (int m = 0; m < 4; ++m) {
;                 const int row = row0 + ai * 128 + m * 16;
;                 const float s = (MODE == 2) ? 1.0f : rstd_of(rowss, row);
;                 bf16_t* rowp = O + (size_t)row * ldc + col0;
; #pragma unroll
;                 for (int bj = 0; bj < 2; ++bj) {
;                     f32x4 v0 = acc[ai][bj][m][0] * s, v1 = acc[ai][bj][m][1] * s;
;                     if (MODE == 1) {
; #pragma unroll
;                         for (int j = 0; j < 4; ++j) { const float a = fmaxf(v0[j], 0.f), b = fmaxf(v1[j], 0.f); v0[j] = a * a; v1[j] = b * b; } }
;                     u32x4 w; w.x = cvt_pk_bf16(v0[0], v0[1]); w.y = cvt_pk_bf16(v0[2], v0[3]); w.z = cvt_pk_bf16(v1[0], v1[1]); w.w = cvt_pk_bf16(v1[2], v1[3]);
;                     *(u32x4*)(rowp + bj * 128) = w; } }
	v_rsq_f32_e32 v48, v48
	s_nop 0
	v_mul_f32_e32 v49, 0x45800000, v48
	v_cndmask_b32_e32 v48, v48, v49, vcc
	v_pk_mul_f32 v[44:45], v[44:45], v[48:49] op_sel_hi:[1,0]
	v_pk_mul_f32 v[46:47], v[46:47], v[48:49] op_sel_hi:[1,0]
	v_pk_mul_f32 v[52:53], v[42:43], v[48:49] op_sel_hi:[1,0]
	v_pk_mul_f32 v[42:43], v[40:41], v[48:49] op_sel_hi:[1,0]
	v_cvt_pk_bf16_f32 v40, v44, v45
	v_add_co_u32_e32 v44, vcc, s5, v160
	v_cvt_pk_bf16_f32 v41, v46, v47
	v_cvt_pk_bf16_f32 v42, v42, v43
	v_cvt_pk_bf16_f32 v43, v52, v53
	v_addc_co_u32_e32 v45, vcc, 0, v161, vcc
	global_store_dwordx4 v[44:45], v[40:43], off
	v_pk_mul_f32 v[38:39], v[38:39], v[48:49] op_sel_hi:[1,0]
	v_pk_mul_f32 v[36:37], v[36:37], v[48:49] op_sel_hi:[1,0]
	v_pk_mul_f32 v[40:41], v[34:35], v[48:49] op_sel_hi:[1,0]
	v_pk_mul_f32 v[34:35], v[32:33], v[48:49] op_sel_hi:[1,0]
	v_cvt_pk_bf16_f32 v32, v36, v37
	v_cvt_pk_bf16_f32 v33, v38, v39
	v_cvt_pk_bf16_f32 v34, v34, v35
	v_cvt_pk_bf16_f32 v35, v40, v41
	global_store_dwordx4 v[50:51], v[32:35], off offset:256
	s_nop 1
	v_mov_b32_e32 v32, v236
	s_mov_b32 s5, 0xa0000
	v_lshl_add_u64 v[34:35], v[160:161], 0, s[14:15]
	s_mov_b64 s[14:15], 0xb0000
	v_fmamk_f32 v32, v32, 0x3a800000, v187
	v_cmp_gt_f32_e32 vcc, s67, v32
	v_mul_f32_e32 v33, 0x4b800000, v32
	s_nop 0
	v_cndmask_b32_e32 v32, v32, v33, vcc
	v_rsq_f32_e32 v32, v32
	s_nop 0
	v_mul_f32_e32 v33, 0x45800000, v32
	v_cndmask_b32_e32 v32, v32, v33, vcc
	v_pk_mul_f32 v[28:29], v[28:29], v[32:33] op_sel_hi:[1,0]
	v_pk_mul_f32 v[30:31], v[30:31], v[32:33] op_sel_hi:[1,0]
	v_pk_mul_f32 v[36:37], v[26:27], v[32:33] op_sel_hi:[1,0]
	v_pk_mul_f32 v[26:27], v[24:25], v[32:33] op_sel_hi:[1,0]
	v_cvt_pk_bf16_f32 v24, v28, v29
	v_add_co_u32_e32 v28, vcc, s5, v160
	v_cvt_pk_bf16_f32 v25, v30, v31
	v_cvt_pk_bf16_f32 v26, v26, v27
	v_cvt_pk_bf16_f32 v27, v36, v37
	v_addc_co_u32_e32 v29, vcc, 0, v161, vcc
	global_store_dwordx4 v[28:29], v[24:27], off
	v_pk_mul_f32 v[22:23], v[22:23], v[32:33] op_sel_hi:[1,0]
	v_pk_mul_f32 v[20:21], v[20:21], v[32:33] op_sel_hi:[1,0]
	v_pk_mul_f32 v[24:25], v[18:19], v[32:33] op_sel_hi:[1,0]
	v_pk_mul_f32 v[18:19], v[16:17], v[32:33] op_sel_hi:[1,0]
	v_cvt_pk_bf16_f32 v16, v20, v21
	v_cvt_pk_bf16_f32 v17, v22, v23
	v_cvt_pk_bf16_f32 v18, v18, v19
	v_cvt_pk_bf16_f32 v19, v24, v25
	global_store_dwordx4 v[34:35], v[16:19], off offset:256
	s_nop 1
	v_mov_b32_e32 v16, v237
	s_mov_b32 s5, 0xb0000
	v_lshl_add_u64 v[18:19], v[160:161], 0, s[14:15]
	v_fmamk_f32 v16, v16, 0x3a800000, v187
	v_cmp_gt_f32_e32 vcc, s67, v16
	v_mul_f32_e32 v17, 0x4b800000, v16
	s_nop 0
	v_cndmask_b32_e32 v16, v16, v17, vcc
	v_rsq_f32_e32 v16, v16
	s_nop 0
	v_mul_f32_e32 v17, 0x45800000, v16
	v_cndmask_b32_e32 v16, v16, v17, vcc
	v_pk_mul_f32 v[12:13], v[12:13], v[16:17] op_sel_hi:[1,0]
	v_pk_mul_f32 v[14:15], v[14:15], v[16:17] op_sel_hi:[1,0]
	v_pk_mul_f32 v[20:21], v[10:11], v[16:17] op_sel_hi:[1,0]
	v_pk_mul_f32 v[10:11], v[8:9], v[16:17] op_sel_hi:[1,0]
	v_cvt_pk_bf16_f32 v8, v12, v13
	v_add_co_u32_e32 v12, vcc, s5, v160
	v_cvt_pk_bf16_f32 v9, v14, v15
	v_cvt_pk_bf16_f32 v10, v10, v11
	v_cvt_pk_bf16_f32 v11, v20, v21
	v_addc_co_u32_e32 v13, vcc, 0, v161, vcc
	global_store_dwordx4 v[12:13], v[8:11], off
	v_pk_mul_f32 v[6:7], v[6:7], v[16:17] op_sel_hi:[1,0]
	v_pk_mul_f32 v[4:5], v[4:5], v[16:17] op_sel_hi:[1,0]
	v_pk_mul_f32 v[8:9], v[2:3], v[16:17] op_sel_hi:[1,0]
	v_pk_mul_f32 v[2:3], v[0:1], v[16:17] op_sel_hi:[1,0]
	v_cvt_pk_bf16_f32 v0, v4, v5
	v_cvt_pk_bf16_f32 v1, v6, v7
	v_cvt_pk_bf16_f32 v2, v2, v3
	v_cvt_pk_bf16_f32 v3, v8, v9
	s_and_b64 vcc, exec, s[38:39]
	global_store_dwordx4 v[18:19], v[0:3], off offset:256
	s_cbranch_vccz .LBB0_1337
	s_waitcnt vmcnt(0)
	s_cmpk_gt_u32 s42, 0xff
	s_cbranch_scc1 .LBB0_1344
	s_barrier

; #define PG8_STAGE(bufoff, gbase, voff) do { _Pragma("unroll") for (int _i = 0; _i < 2; ++_i) \
;         __builtin_amdgcn_global_load_lds((const unsigned*)((const char*)(gbase) + (voff)[_i]), (PG8_LAS unsigned*)(lds + (bufoff) + ldsw + _i * 8192), 16, 0, 0); } while (0)
; #define PG8_LDA(dst, b, h) do { _Pragma("unroll") for (int m = 0; m < 4; ++m) _Pragma("unroll") for (int k = 0; k < 2; ++k) dst[m][k] = *(const PG8_LAS bf16x8*)(lds + PG8_SA(b, h) + aoff + m * 2048 + k * 1024); } while (0)
; #define PG8_LDB(dst, b, h) do { _Pragma("unroll") for (int n = 0; n < 2; ++n) _Pragma("unroll") for (int k = 0; k < 2; ++k) dst[n][k] = *(const PG8_LAS bf16x8*)(lds + PG8_SB(b, h) + boff + n * 2048 + k * 1024); } while (0)
; #define PG8_WAIT_V(n) asm volatile("s_waitcnt vmcnt(" #n ")" ::: "memory")
; #define PG8_WAIT_L(n) asm volatile("s_waitcnt lgkmcnt(" #n ")" ::: "memory")
; #define PG8_BAR __builtin_amdgcn_s_barrier()
; #define PG8_SCHED __builtin_amdgcn_sched_barrier(0)
; template <class Epi, class Sched, bool STAMP = false>
; __device__ __forceinline__ void gemm_phase(PG8_LAS unsigned char* lds, const Gemm g, const Sched& S, const Epi& E, unsigned long long* stamps) {
;     ...
;             PG8_LDB(B0, 0, 0); PG8_SCHED; PG8_LDA(At, 0, 0); PG8_STAGE(PG8_SA(1, 1), a1 + hstep, voffA);
;             PG8_WAIT_L(8); PG8_BAR; PG8_WAIT_L(0); PG8_MMA(0, 0, At, B0); PG8_BAR; PG8_SCHED;
;             PG8_LDB(B1, 0, 1); PG8_STAGE(PG8_SB(0, 0), b2, voffB);
;             PG8_BAR; PG8_WAIT_L(0); PG8_MMA(0, 1, At, B1); PG8_BAR;
;             PG8_LDA(At, 0, 1); PG8_STAGE(PG8_SA(0, 0), a2, voffA);
;             PG8_BAR; PG8_WAIT_L(0); PG8_MMA(1, 0, At, B0); PG8_BAR; PG8_SCHED;
;             PG8_STAGE(PG8_SB(0, 1), b2 + hstep, voffB);
;             PG8_WAIT_V(6); PG8_BAR; PG8_MMA(1, 1, At, B1); PG8_BAR;
; __device__ __forceinline__ void run_rw_sample_tasks(LAS unsigned char* lds, unsigned char* ws) {
;     const int t = bidx(); OneUnit S; S.valid = t < 128; const int u = (t >> 2) & 31, sl = t & 3; S.pm = 64 + (u >> 3); S.pn = u & 7;
;     pg8::Gemm g; g.A = (const bf16_t*)(ws + OFF_XB) + sl * 256; g.Bt = (const bf16_t*)(ws + OFF_WRW) + sl * 256; g.M = T_ALL; g.N = 2048; g.K = 256; g.ld = 1024;
;     EpiPartial EA; EA.PART = (float*)(ws + OFF_GPART) + (size_t)sl * 1024 * 2048; EA.ldp = 2048;
;     pg8::gemm_phase<EpiPartial, OneUnit, false>(lds, g, S, EA, nullptr);
; }
.LBB0_1349:
	s_add_i32 s15, s14, 0x100
	s_and_b64 s[16:17], s[24:25], exec
	s_cselect_b32 s15, 0, s15
	s_cselect_b32 s16, 0, 0
	s_add_u32 s36, s12, s15
	s_addc_u32 s37, s13, s16
	s_add_i32 s25, 0, 0x10000
	s_add_u32 s38, s6, s15
	s_addc_u32 s39, s7, s16
	s_add_u32 s40, s20, s14
	s_addc_u32 s41, s21, 0
	s_add_i32 s63, s25, s46
	s_add_i32 m0, s10, 0xc000
	s_add_i32 s64, s10, 0xe000
	s_add_i32 s62, 0, 0x14000
	s_add_i32 s61, s63, 0x2000
	s_add_u32 s30, s38, 0x40000
	s_addc_u32 s31, s39, 0
	s_add_i32 s52, s62, s46
	ds_read_b128 v[154:157], v248
	ds_read_b128 v[158:161], v248 offset:1024
	ds_read_b128 v[162:165], v248 offset:2048
	ds_read_b128 v[166:169], v248 offset:3072
	s_add_i32 s29, s52, 0x2000
	s_add_i32 s17, 0, 0x18000
	s_add_u32 s26, s36, 0x40000
	s_addc_u32 s27, s37, 0
	s_add_i32 s16, s17, s46
	s_add_i32 s15, 0, 0x1c000
	s_add_i32 s14, s16, 0x2000
	s_add_u32 s24, s38, 0x40080
	s_addc_u32 s25, s39, 0
	s_add_i32 s60, s15, s46
	s_add_i32 s59, s60, 0x2000
	v_lshl_add_u64 v[182:183], s[40:41], 0, v[128:129]
	v_lshl_add_u64 v[182:183], v[182:183], 0, s[18:19]
	ds_read_b128 v[170:173], v152
	ds_read_b128 v[174:177], v152 offset:1024
	ds_read_b128 v[178:181], v152 offset:2048
	ds_read_b128 v[192:195], v152 offset:3072
	ds_read_b128 v[196:199], v152 offset:4096
	ds_read_b128 v[200:203], v152 offset:5120
	ds_read_b128 v[204:207], v152 offset:6144
	ds_read_b128 v[208:211], v152 offset:7168
	global_load_lds_dwordx4 v244, s[40:41]
	v_lshl_add_u64 v[182:183], s[40:41], 0, v[148:149]
	v_lshl_add_u64 v[182:183], v[182:183], 0, s[18:19]
	s_mov_b32 m0, s64
	s_nop 0
	global_load_lds_dwordx4 v245, s[40:41]
	s_waitcnt lgkmcnt(8)
	s_barrier
	s_waitcnt lgkmcnt(0)
	v_mfma_f32_16x16x32_bf16 v[124:127], v[154:157], v[170:173], v[124:127]
	v_mfma_f32_16x16x32_bf16 v[120:123], v[162:165], v[170:173], v[120:123]
	v_mfma_f32_16x16x32_bf16 v[116:119], v[154:157], v[178:181], v[116:119]
	v_mfma_f32_16x16x32_bf16 v[112:115], v[162:165], v[178:181], v[112:115]
	v_mfma_f32_16x16x32_bf16 v[104:107], v[154:157], v[196:199], v[104:107]
	v_mfma_f32_16x16x32_bf16 v[96:99], v[162:165], v[196:199], v[96:99]
	v_mfma_f32_16x16x32_bf16 v[88:91], v[154:157], v[204:207], v[88:91]
	v_mfma_f32_16x16x32_bf16 v[80:83], v[162:165], v[204:207], v[80:83]
	v_mfma_f32_16x16x32_bf16 v[124:127], v[158:161], v[174:177], v[124:127]
	v_mfma_f32_16x16x32_bf16 v[120:123], v[166:169], v[174:177], v[120:123]
	v_mfma_f32_16x16x32_bf16 v[116:119], v[158:161], v[192:195], v[116:119]
	v_mfma_f32_16x16x32_bf16 v[112:115], v[166:169], v[192:195], v[112:115]
	v_mfma_f32_16x16x32_bf16 v[104:107], v[158:161], v[200:203], v[104:107]
	v_mfma_f32_16x16x32_bf16 v[96:99], v[166:169], v[200:203], v[96:99]
	v_mfma_f32_16x16x32_bf16 v[88:91], v[158:161], v[208:211], v[88:91]
	v_mfma_f32_16x16x32_bf16 v[80:83], v[166:169], v[208:211], v[80:83]
	s_barrier
	s_mov_b32 m0, s63
	v_lshl_add_u64 v[182:183], s[38:39], 0, v[128:129]
	ds_read_b128 v[212:215], v249
	ds_read_b128 v[216:219], v249 offset:1024
	ds_read_b128 v[220:223], v249 offset:2048
	ds_read_b128 v[224:227], v249 offset:3072
	global_load_lds_dwordx4 v128, s[38:39]
	v_lshl_add_u64 v[228:229], s[38:39], 0, v[148:149]
	s_mov_b32 m0, s61
	s_nop 0
	global_load_lds_dwordx4 v148, s[38:39]
	s_barrier
	s_waitcnt lgkmcnt(0)
	v_mfma_f32_16x16x32_bf16 v[108:111], v[212:215], v[170:173], v[108:111]
	v_mfma_f32_16x16x32_bf16 v[100:103], v[220:223], v[170:173], v[100:103]
	v_mfma_f32_16x16x32_bf16 v[92:95], v[212:215], v[178:181], v[92:95]
	v_mfma_f32_16x16x32_bf16 v[84:87], v[220:223], v[178:181], v[84:87]
	v_mfma_f32_16x16x32_bf16 v[76:79], v[212:215], v[196:199], v[76:79]
	v_mfma_f32_16x16x32_bf16 v[72:75], v[220:223], v[196:199], v[72:75]
	v_mfma_f32_16x16x32_bf16 v[68:71], v[212:215], v[204:207], v[68:71]
	v_mfma_f32_16x16x32_bf16 v[64:67], v[220:223], v[204:207], v[64:67]
	v_mfma_f32_16x16x32_bf16 v[108:111], v[216:219], v[174:177], v[108:111]
	v_mfma_f32_16x16x32_bf16 v[100:103], v[224:227], v[174:177], v[100:103]
	v_mfma_f32_16x16x32_bf16 v[92:95], v[216:219], v[192:195], v[92:95]
	v_mfma_f32_16x16x32_bf16 v[84:87], v[224:227], v[192:195], v[84:87]
	v_mfma_f32_16x16x32_bf16 v[76:79], v[216:219], v[200:203], v[76:79]
	v_mfma_f32_16x16x32_bf16 v[72:75], v[224:227], v[200:203], v[72:75]
	v_mfma_f32_16x16x32_bf16 v[68:71], v[216:219], v[208:211], v[68:71]
	v_mfma_f32_16x16x32_bf16 v[64:67], v[224:227], v[208:211], v[64:67]
	s_mov_b32 m0, s10
	v_lshl_add_u64 v[230:231], s[36:37], 0, v[128:129]
	s_barrier
	ds_read_b128 v[170:173], v152 offset:16384
	ds_read_b128 v[174:177], v152 offset:17408
	ds_read_b128 v[178:181], v152 offset:18432
	ds_read_b128 v[192:195], v152 offset:19456
	ds_read_b128 v[196:199], v152 offset:20480
	ds_read_b128 v[200:203], v152 offset:21504
	ds_read_b128 v[204:207], v152 offset:22528
	ds_read_b128 v[208:211], v152 offset:23552
	global_load_lds_dwordx4 v128, s[36:37]
	v_lshl_add_u64 v[232:233], s[36:37], 0, v[148:149]
	s_mov_b32 m0, s47
	s_nop 0
	global_load_lds_dwordx4 v148, s[36:37]
	s_barrier
	s_waitcnt lgkmcnt(0)
	v_mfma_f32_16x16x32_bf16 v[60:63], v[154:157], v[170:173], v[60:63]
	v_mfma_f32_16x16x32_bf16 v[56:59], v[162:165], v[170:173], v[56:59]
	v_mfma_f32_16x16x32_bf16 v[52:55], v[154:157], v[178:181], v[52:55]
	v_mfma_f32_16x16x32_bf16 v[48:51], v[162:165], v[178:181], v[48:51]
	v_mfma_f32_16x16x32_bf16 v[36:39], v[154:157], v[196:199], v[36:39]
	v_mfma_f32_16x16x32_bf16 v[32:35], v[162:165], v[196:199], v[32:35]
	v_mfma_f32_16x16x32_bf16 v[20:23], v[154:157], v[204:207], v[20:23]
	v_mfma_f32_16x16x32_bf16 v[16:19], v[162:165], v[204:207], v[16:19]
	v_mfma_f32_16x16x32_bf16 v[60:63], v[158:161], v[174:177], v[60:63]
	v_mfma_f32_16x16x32_bf16 v[56:59], v[166:169], v[174:177], v[56:59]
	v_mfma_f32_16x16x32_bf16 v[52:55], v[158:161], v[192:195], v[52:55]
	v_mfma_f32_16x16x32_bf16 v[48:51], v[166:169], v[192:195], v[48:51]
	v_mfma_f32_16x16x32_bf16 v[36:39], v[158:161], v[200:203], v[36:39]
	v_mfma_f32_16x16x32_bf16 v[32:35], v[166:169], v[200:203], v[32:35]
	v_mfma_f32_16x16x32_bf16 v[20:23], v[158:161], v[208:211], v[20:23]
	v_mfma_f32_16x16x32_bf16 v[16:19], v[166:169], v[208:211], v[16:19]
	s_barrier
; #define PG8_STAGE(bufoff, gbase, voff) do { _Pragma("unroll") for (int _i = 0; _i < 2; ++_i) \
;         __builtin_amdgcn_global_load_lds((const unsigned*)((const char*)(gbase) + (voff)[_i]), (PG8_LAS unsigned*)(lds + (bufoff) + ldsw + _i * 8192), 16, 0, 0); } while (0)
; #define PG8_LDA(dst, b, h) do { _Pragma("unroll") for (int m = 0; m < 4; ++m) _Pragma("unroll") for (int k = 0; k < 2; ++k) dst[m][k] = *(const PG8_LAS bf16x8*)(lds + PG8_SA(b, h) + aoff + m * 2048 + k * 1024); } while (0)
; #define PG8_LDB(dst, b, h) do { _Pragma("unroll") for (int n = 0; n < 2; ++n) _Pragma("unroll") for (int k = 0; k < 2; ++k) dst[n][k] = *(const PG8_LAS bf16x8*)(lds + PG8_SB(b, h) + boff + n * 2048 + k * 1024); } while (0)
; #define PG8_MMA(ai, bj, At, Bt) do { __builtin_amdgcn_s_setprio(1); _Pragma("unroll") for (int m = 0; m < 4; ++m) _Pragma("unroll") for (int n = 0; n < 2; ++n) _Pragma("unroll") for (int k = 0; k < 2; ++k) \
;         acc[ai][bj][m][n] = __builtin_amdgcn_mfma_f32_16x16x32_bf16(Bt[n][k], At[m][k], acc[ai][bj][m][n], 0, 0, 0); __builtin_amdgcn_s_setprio(0); } while (0)
; #define PG8_WAIT_V(n) asm volatile("s_waitcnt vmcnt(" #n ")" ::: "memory")
; #define PG8_WAIT_L(n) asm volatile("s_waitcnt lgkmcnt(" #n ")" ::: "memory")
; #define PG8_BAR __builtin_amdgcn_s_barrier()
; #define PG8_SCHED __builtin_amdgcn_sched_barrier(0)
; template <class Epi, class Sched, bool STAMP = false>
; __device__ __forceinline__ void gemm_phase(PG8_LAS unsigned char* lds, const Gemm g, const Sched& S, const Epi& E, unsigned long long* stamps) {
;     ...
;             PG8_WAIT_V(6); PG8_BAR; PG8_MMA(1, 1, At, B1); PG8_BAR;
;             PG8_LDB(B0, 1, 0); PG8_SCHED; PG8_LDA(At, 1, 0); PG8_STAGE(PG8_SA(0, 1), a2 + hstep, voffA);
;             PG8_WAIT_L(8); PG8_BAR; PG8_WAIT_L(0); PG8_MMA(0, 0, At, B0); PG8_BAR; PG8_SCHED;
;             PG8_LDB(B1, 1, 1); PG8_STAGE(PG8_SB(1, 0), b3, voffB);
;             PG8_BAR; PG8_WAIT_L(0); PG8_MMA(0, 1, At, B1); PG8_BAR;
;             PG8_LDA(At, 1, 1); PG8_STAGE(PG8_SA(1, 0), a3, voffA);
;             PG8_BAR; PG8_WAIT_L(0); PG8_MMA(1, 0, At, B0); PG8_BAR; PG8_SCHED;
	s_mov_b32 m0, s52
	s_nop 0
	global_load_lds_dwordx4 v128, s[30:31]
	s_mov_b32 m0, s29
	s_nop 0
	global_load_lds_dwordx4 v148, s[30:31]
	s_waitcnt vmcnt(6)
	s_barrier
	v_mfma_f32_16x16x32_bf16 v[44:47], v[212:215], v[170:173], v[44:47]
	v_mfma_f32_16x16x32_bf16 v[40:43], v[220:223], v[170:173], v[40:43]
	v_mfma_f32_16x16x32_bf16 v[28:31], v[212:215], v[178:181], v[28:31]
	v_mfma_f32_16x16x32_bf16 v[24:27], v[220:223], v[178:181], v[24:27]
	v_mfma_f32_16x16x32_bf16 v[12:15], v[212:215], v[196:199], v[12:15]
	v_mfma_f32_16x16x32_bf16 v[8:11], v[220:223], v[196:199], v[8:11]
	v_mfma_f32_16x16x32_bf16 v[4:7], v[212:215], v[204:207], v[4:7]
	v_mfma_f32_16x16x32_bf16 v[0:3], v[220:223], v[204:207], v[0:3]
	v_mfma_f32_16x16x32_bf16 v[44:47], v[216:219], v[174:177], v[44:47]
	v_mfma_f32_16x16x32_bf16 v[40:43], v[224:227], v[174:177], v[40:43]
	v_mfma_f32_16x16x32_bf16 v[28:31], v[216:219], v[192:195], v[28:31]
	v_mfma_f32_16x16x32_bf16 v[24:27], v[224:227], v[192:195], v[24:27]
	v_mfma_f32_16x16x32_bf16 v[12:15], v[216:219], v[200:203], v[12:15]
	v_mfma_f32_16x16x32_bf16 v[8:11], v[224:227], v[200:203], v[8:11]
	v_mfma_f32_16x16x32_bf16 v[4:7], v[216:219], v[208:211], v[4:7]
	v_mfma_f32_16x16x32_bf16 v[0:3], v[224:227], v[208:211], v[0:3]
	s_barrier
	ds_read_b128 v[154:157], v250
	ds_read_b128 v[158:161], v250 offset:1024
	ds_read_b128 v[162:165], v250 offset:2048
	ds_read_b128 v[166:169], v250 offset:3072
	s_mov_b32 m0, s48
	ds_read_b128 v[170:173], v152 offset:32768
	ds_read_b128 v[174:177], v152 offset:33792
	ds_read_b128 v[178:181], v152 offset:34816
	ds_read_b128 v[192:195], v152 offset:35840
	ds_read_b128 v[196:199], v152 offset:36864
	ds_read_b128 v[200:203], v152 offset:37888
	ds_read_b128 v[204:207], v152 offset:38912
	global_load_lds_dwordx4 v128, s[26:27]
	s_mov_b32 m0, s49
	ds_read_b128 v[208:211], v152 offset:39936
	global_load_lds_dwordx4 v148, s[26:27]
	s_waitcnt lgkmcnt(8)
	s_barrier
	s_waitcnt lgkmcnt(0)
	v_mfma_f32_16x16x32_bf16 v[124:127], v[154:157], v[170:173], v[124:127]
	v_mfma_f32_16x16x32_bf16 v[120:123], v[162:165], v[170:173], v[120:123]
	v_mfma_f32_16x16x32_bf16 v[116:119], v[154:157], v[178:181], v[116:119]
	v_mfma_f32_16x16x32_bf16 v[112:115], v[162:165], v[178:181], v[112:115]
	v_mfma_f32_16x16x32_bf16 v[104:107], v[154:157], v[196:199], v[104:107]
	v_mfma_f32_16x16x32_bf16 v[96:99], v[162:165], v[196:199], v[96:99]
	v_mfma_f32_16x16x32_bf16 v[88:91], v[154:157], v[204:207], v[88:91]
	v_mfma_f32_16x16x32_bf16 v[80:83], v[162:165], v[204:207], v[80:83]
	v_mfma_f32_16x16x32_bf16 v[124:127], v[158:161], v[174:177], v[124:127]
	v_mfma_f32_16x16x32_bf16 v[120:123], v[166:169], v[174:177], v[120:123]
	v_mfma_f32_16x16x32_bf16 v[116:119], v[158:161], v[192:195], v[116:119]
	v_mfma_f32_16x16x32_bf16 v[112:115], v[166:169], v[192:195], v[112:115]
	v_mfma_f32_16x16x32_bf16 v[104:107], v[158:161], v[200:203], v[104:107]
	v_mfma_f32_16x16x32_bf16 v[96:99], v[166:169], v[200:203], v[96:99]
	v_mfma_f32_16x16x32_bf16 v[88:91], v[158:161], v[208:211], v[88:91]
	v_mfma_f32_16x16x32_bf16 v[80:83], v[166:169], v[208:211], v[80:83]
	s_barrier
	s_mov_b32 m0, s16
	v_lshl_add_u64 v[182:183], v[182:183], 0, s[18:19]
	ds_read_b128 v[212:215], v251
	ds_read_b128 v[216:219], v251 offset:1024
	ds_read_b128 v[220:223], v251 offset:2048
	ds_read_b128 v[224:227], v251 offset:3072
	global_load_lds_dwordx4 v244, s[38:39]
	v_lshl_add_u64 v[182:183], v[228:229], 0, s[18:19]
	s_mov_b32 m0, s14
	s_nop 0
	global_load_lds_dwordx4 v245, s[38:39]
	s_barrier
	s_waitcnt lgkmcnt(0)
	v_mfma_f32_16x16x32_bf16 v[108:111], v[212:215], v[170:173], v[108:111]
	v_mfma_f32_16x16x32_bf16 v[100:103], v[220:223], v[170:173], v[100:103]
	v_mfma_f32_16x16x32_bf16 v[92:95], v[212:215], v[178:181], v[92:95]
	v_mfma_f32_16x16x32_bf16 v[84:87], v[220:223], v[178:181], v[84:87]
	v_mfma_f32_16x16x32_bf16 v[76:79], v[212:215], v[196:199], v[76:79]
	v_mfma_f32_16x16x32_bf16 v[72:75], v[220:223], v[196:199], v[72:75]
	v_mfma_f32_16x16x32_bf16 v[68:71], v[212:215], v[204:207], v[68:71]
	v_mfma_f32_16x16x32_bf16 v[64:67], v[220:223], v[204:207], v[64:67]
	v_mfma_f32_16x16x32_bf16 v[108:111], v[216:219], v[174:177], v[108:111]
	v_mfma_f32_16x16x32_bf16 v[100:103], v[224:227], v[174:177], v[100:103]
	v_mfma_f32_16x16x32_bf16 v[92:95], v[216:219], v[192:195], v[92:95]
	v_mfma_f32_16x16x32_bf16 v[84:87], v[224:227], v[192:195], v[84:87]
	v_mfma_f32_16x16x32_bf16 v[76:79], v[216:219], v[200:203], v[76:79]
	v_mfma_f32_16x16x32_bf16 v[72:75], v[224:227], v[200:203], v[72:75]
	v_mfma_f32_16x16x32_bf16 v[68:71], v[216:219], v[208:211], v[68:71]
	v_mfma_f32_16x16x32_bf16 v[64:67], v[224:227], v[208:211], v[64:67]
	s_mov_b32 m0, s57
	v_lshl_add_u64 v[182:183], v[230:231], 0, s[18:19]
	s_barrier
	ds_read_b128 v[170:173], v152 offset:49152
	ds_read_b128 v[174:177], v152 offset:50176
	ds_read_b128 v[178:181], v152 offset:51200
	ds_read_b128 v[192:195], v152 offset:52224
	ds_read_b128 v[196:199], v152 offset:53248
	ds_read_b128 v[200:203], v152 offset:54272
	ds_read_b128 v[204:207], v152 offset:55296
	ds_read_b128 v[208:211], v152 offset:56320
	global_load_lds_dwordx4 v244, s[36:37]
	v_lshl_add_u64 v[182:183], v[232:233], 0, s[18:19]
	s_mov_b32 m0, s58
	s_nop 0
	global_load_lds_dwordx4 v245, s[36:37]
	s_barrier
; #define PG8_STAGE(bufoff, gbase, voff) do { _Pragma("unroll") for (int _i = 0; _i < 2; ++_i) \
;         __builtin_amdgcn_global_load_lds((const unsigned*)((const char*)(gbase) + (voff)[_i]), (PG8_LAS unsigned*)(lds + (bufoff) + ldsw + _i * 8192), 16, 0, 0); } while (0)
; #define PG8_MMA(ai, bj, At, Bt) do { __builtin_amdgcn_s_setprio(1); _Pragma("unroll") for (int m = 0; m < 4; ++m) _Pragma("unroll") for (int n = 0; n < 2; ++n) _Pragma("unroll") for (int k = 0; k < 2; ++k) \
;         acc[ai][bj][m][n] = __builtin_amdgcn_mfma_f32_16x16x32_bf16(Bt[n][k], At[m][k], acc[ai][bj][m][n], 0, 0, 0); __builtin_amdgcn_s_setprio(0); } while (0)
; #define PG8_WAIT_V(n) asm volatile("s_waitcnt vmcnt(" #n ")" ::: "memory")
; #define PG8_WAIT_L(n) asm volatile("s_waitcnt lgkmcnt(" #n ")" ::: "memory")
; #define PG8_BAR __builtin_amdgcn_s_barrier()
; #define PG8_SCHED __builtin_amdgcn_sched_barrier(0)
; template <class Epi, class Sched, bool STAMP = false>
; __device__ __forceinline__ void gemm_phase(PG8_LAS unsigned char* lds, const Gemm g, const Sched& S, const Epi& E, unsigned long long* stamps) {
;     ...
;             PG8_BAR; PG8_WAIT_L(0); PG8_MMA(1, 0, At, B0); PG8_BAR; PG8_SCHED;
;             PG8_STAGE(PG8_SB(1, 1), b3 + hstep, voffB);
;             PG8_WAIT_V(6); PG8_BAR; PG8_MMA(1, 1, At, B1); PG8_BAR;
;     __device__ __forceinline__ void operator()(const f32x4 (&acc)[2][2][4][2], const pg8::Unit& u, int wr, int wc, int fr, int fq) const {
;         const int row0 = (u.pm - 64) * 256 + wr * 64 + fr, col0 = u.pn * 256 + wc * 32 + 4 * fq;
; #pragma unroll
;         for (int ai = 0; ai < 2; ++ai)
; #pragma unroll
;             for (int m = 0; m < 4; ++m) { float* xp = PART + (size_t)(row0 + ai * 128 + m * 16) * ldp + col0;
; #pragma unroll
;                 for (int bj = 0; bj < 2; ++bj)
; #pragma unroll
;                     for (int n = 0; n < 2; ++n) *(f32x4*)(xp + bj * 128 + n * 16) = acc[ai][bj][m][n]; }
	s_waitcnt lgkmcnt(0)
	v_mfma_f32_16x16x32_bf16 v[60:63], v[154:157], v[170:173], v[60:63]
	v_mfma_f32_16x16x32_bf16 v[56:59], v[162:165], v[170:173], v[56:59]
	v_mfma_f32_16x16x32_bf16 v[52:55], v[154:157], v[178:181], v[52:55]
	v_mfma_f32_16x16x32_bf16 v[48:51], v[162:165], v[178:181], v[48:51]
	v_mfma_f32_16x16x32_bf16 v[36:39], v[154:157], v[196:199], v[36:39]
	v_mfma_f32_16x16x32_bf16 v[32:35], v[162:165], v[196:199], v[32:35]
	v_mfma_f32_16x16x32_bf16 v[20:23], v[154:157], v[204:207], v[20:23]
	v_mfma_f32_16x16x32_bf16 v[16:19], v[162:165], v[204:207], v[16:19]
	v_mfma_f32_16x16x32_bf16 v[60:63], v[158:161], v[174:177], v[60:63]
	v_mfma_f32_16x16x32_bf16 v[56:59], v[166:169], v[174:177], v[56:59]
	v_mfma_f32_16x16x32_bf16 v[52:55], v[158:161], v[192:195], v[52:55]
	v_mfma_f32_16x16x32_bf16 v[48:51], v[166:169], v[192:195], v[48:51]
	v_mfma_f32_16x16x32_bf16 v[36:39], v[158:161], v[200:203], v[36:39]
	v_mfma_f32_16x16x32_bf16 v[32:35], v[166:169], v[200:203], v[32:35]
	v_mfma_f32_16x16x32_bf16 v[20:23], v[158:161], v[208:211], v[20:23]
	v_mfma_f32_16x16x32_bf16 v[16:19], v[166:169], v[208:211], v[16:19]
	s_barrier
	s_mov_b32 m0, s60
	s_nop 0
	global_load_lds_dwordx4 v128, s[24:25]
	s_mov_b32 m0, s59
	s_nop 0
	global_load_lds_dwordx4 v148, s[24:25]
	s_waitcnt vmcnt(6)
	s_barrier
	v_mfma_f32_16x16x32_bf16 v[44:47], v[212:215], v[170:173], v[44:47]
	v_mfma_f32_16x16x32_bf16 v[40:43], v[220:223], v[170:173], v[40:43]
	v_mfma_f32_16x16x32_bf16 v[28:31], v[212:215], v[178:181], v[28:31]
	v_mfma_f32_16x16x32_bf16 v[24:27], v[220:223], v[178:181], v[24:27]
	v_mfma_f32_16x16x32_bf16 v[12:15], v[212:215], v[196:199], v[12:15]
	v_mfma_f32_16x16x32_bf16 v[8:11], v[220:223], v[196:199], v[8:11]
	v_mfma_f32_16x16x32_bf16 v[4:7], v[212:215], v[204:207], v[4:7]
	v_mfma_f32_16x16x32_bf16 v[0:3], v[220:223], v[204:207], v[0:3]
	v_mfma_f32_16x16x32_bf16 v[44:47], v[216:219], v[174:177], v[44:47]
	v_mfma_f32_16x16x32_bf16 v[40:43], v[224:227], v[174:177], v[40:43]
	v_mfma_f32_16x16x32_bf16 v[28:31], v[216:219], v[192:195], v[28:31]
	v_mfma_f32_16x16x32_bf16 v[24:27], v[224:227], v[192:195], v[24:27]
	v_mfma_f32_16x16x32_bf16 v[12:15], v[216:219], v[200:203], v[12:15]
	v_mfma_f32_16x16x32_bf16 v[8:11], v[224:227], v[200:203], v[8:11]
	v_mfma_f32_16x16x32_bf16 v[4:7], v[216:219], v[208:211], v[4:7]
	v_mfma_f32_16x16x32_bf16 v[0:3], v[224:227], v[208:211], v[0:3]
	s_andn2_b64 vcc, exec, s[22:23]
	s_mov_b64 s[24:25], -1
	s_mov_b64 s[22:23], 0
	s_movk_i32 s14, 0x100
	s_barrier
	s_cbranch_vccz .LBB0_1349
	s_lshl_b32 s6, s45, 23
	s_add_u32 s6, s4, s6
	s_addc_u32 s7, s5, 0
	s_lshl_b32 s10, s44, 8
	s_add_i32 s10, s10, s53
	v_add_u32_e32 v150, s10, v150
	v_add_u32_e32 v148, 0xffffc000, v150
	s_lshl_b32 s10, s43, 8
	v_lshl_or_b32 v128, v139, 2, s10
	v_ashrrev_i32_e32 v149, 31, v148
	v_or_b32_e32 v128, s56, v128
	v_lshlrev_b64 v[148:149], 13, v[148:149]
	v_lshl_add_u64 v[148:149], s[6:7], 0, v[148:149]
	v_lshlrev_b32_e32 v128, 2, v128
	v_lshl_add_u64 v[148:149], v[148:149], 0, v[128:129]
	global_store_dwordx4 v[148:149], v[124:127], off
	global_store_dwordx4 v[148:149], v[120:123], off offset:64
	global_store_dwordx4 v[148:149], v[108:111], off offset:512
	global_store_dwordx4 v[148:149], v[100:103], off offset:576
	s_cmpk_lt_u32 s42, 0x100
	s_movk_i32 s58, 0xff60
	v_add_u32_e32 v100, 0xffffc010, v150
	v_ashrrev_i32_e32 v101, 31, v100
	v_lshlrev_b64 v[100:101], 13, v[100:101]
	v_lshl_add_u64 v[100:101], s[6:7], 0, v[100:101]
	v_lshl_add_u64 v[100:101], v[100:101], 0, v[128:129]
	global_store_dwordx4 v[100:101], v[116:119], off
	global_store_dwordx4 v[100:101], v[112:115], off offset:64
	global_store_dwordx4 v[100:101], v[92:95], off offset:512
	global_store_dwordx4 v[100:101], v[84:87], off offset:576
	s_nop 1
	v_add_u32_e32 v84, 0xffffc020, v150
	v_ashrrev_i32_e32 v85, 31, v84
	v_lshlrev_b64 v[84:85], 13, v[84:85]
	v_lshl_add_u64 v[84:85], s[6:7], 0, v[84:85]
	v_lshl_add_u64 v[84:85], v[84:85], 0, v[128:129]
	global_store_dwordx4 v[84:85], v[104:107], off
	global_store_dwordx4 v[84:85], v[96:99], off offset:64
	global_store_dwordx4 v[84:85], v[76:79], off offset:512
	global_store_dwordx4 v[84:85], v[72:75], off offset:576
	s_nop 1
	v_add_u32_e32 v72, 0xffffc030, v150
	v_ashrrev_i32_e32 v73, 31, v72
	v_lshlrev_b64 v[72:73], 13, v[72:73]
	v_lshl_add_u64 v[72:73], s[6:7], 0, v[72:73]
	v_lshl_add_u64 v[72:73], v[72:73], 0, v[128:129]
	s_mov_b64 s[6:7], 0x100000
	global_store_dwordx4 v[72:73], v[88:91], off
	global_store_dwordx4 v[72:73], v[80:83], off offset:64
	global_store_dwordx4 v[72:73], v[68:71], off offset:512
	global_store_dwordx4 v[72:73], v[64:67], off offset:576
	s_nop 1
	v_lshl_add_u64 v[64:65], v[148:149], 0, s[6:7]
	s_mov_b32 s6, 0x100000
	v_add_co_u32_e32 v66, vcc, s6, v148
	s_mov_b64 s[6:7], 0x120000
	s_nop 0
	v_addc_co_u32_e32 v67, vcc, 0, v149, vcc
	global_store_dwordx4 v[66:67], v[60:63], off
	global_store_dwordx4 v[64:65], v[56:59], off offset:64
	global_store_dwordx4 v[64:65], v[44:47], off offset:512
	global_store_dwordx4 v[64:65], v[40:43], off offset:576
	s_nop 1
	v_lshl_add_u64 v[40:41], v[148:149], 0, s[6:7]
	s_mov_b32 s6, 0x120000
	v_add_co_u32_e32 v42, vcc, s6, v148
	s_mov_b64 s[6:7], 0x140000
	s_nop 0
	v_addc_co_u32_e32 v43, vcc, 0, v149, vcc
	global_store_dwordx4 v[42:43], v[52:55], off
	global_store_dwordx4 v[40:41], v[48:51], off offset:64
	global_store_dwordx4 v[40:41], v[28:31], off offset:512
	global_store_dwordx4 v[40:41], v[24:27], off offset:576
	s_nop 1
	v_lshl_add_u64 v[24:25], v[148:149], 0, s[6:7]
	s_mov_b32 s6, 0x140000
	v_add_co_u32_e32 v26, vcc, s6, v148
	s_mov_b64 s[6:7], 0x160000
	s_nop 0
	v_addc_co_u32_e32 v27, vcc, 0, v149, vcc
	global_store_dwordx4 v[26:27], v[36:39], off
	global_store_dwordx4 v[24:25], v[32:35], off offset:64
	global_store_dwordx4 v[24:25], v[12:15], off offset:512
	global_store_dwordx4 v[24:25], v[8:11], off offset:576
	s_nop 1
	v_add_co_u32_e32 v10, vcc, 0x160000, v148
	v_lshl_add_u64 v[8:9], v[148:149], 0, s[6:7]
	s_nop 0
	v_addc_co_u32_e32 v11, vcc, 0, v149, vcc
	global_store_dwordx4 v[10:11], v[20:23], off
	global_store_dwordx4 v[8:9], v[16:19], off offset:64
	global_store_dwordx4 v[8:9], v[4:7], off offset:512
	global_store_dwordx4 v[8:9], v[0:3], off offset:576
	s_waitcnt vmcnt(0)
	s_cbranch_scc0 .LBB0_1352
	s_barrier
